# indexer score pass: canonicalising self-max in front of each relu removed (hazard distances re-checked)
# speedup vs baseline: 1.0191x; 1.0071x over previous
; #define LAS __attribute__((address_space(3)))
; __device__ __forceinline__ unsigned fkey(float f) { const unsigned u = __float_as_uint(f); return (u & 0x80000000u) ? ~u : (u | 0x80000000u); }
; #define SEL_HADD(idx_) __hip_atomic_fetch_add(&hist[(idx_)], 1u, __ATOMIC_RELAXED, __HIP_MEMORY_SCOPE_WORKGROUP)
; __device__ __forceinline__ void sel_unit(LAS char* lds, int b, int u, const bf16_t* QI, const bf16_t* KIDX, const float* WIDX, unsigned long long* MASK) {
;     ...
;     const int nj = (c - wid + 8) >> 3;
;     u32x4 sc[8][4];
; #pragma unroll
;     for (int j = 0; j < 8; ++j) {
;         if (j < nj) {
;             int t = wid + 8 * j; asm volatile("" : "+s"(t));
; #pragma unroll
;             for (int kh = 0; kh < 2; ++kh) {
;             bf16x8 kf[2][2];
; #pragma unroll
;             for (int kb = 0; kb < 2; ++kb)
; #pragma unroll
;                 for (int ks = 0; ks < 2; ++ks) kf[kb][ks] = *(const bf16x8*)(KIDX + (rowbase + 64 * t + 32 * kh + 16 * kb + q16) * 64 + 32 * ks + 8 * kg);
; #pragma unroll
;             for (int kb = 0; kb < 2; ++kb) {
;                 f32x4 s = (f32x4){0.f, 0.f, 0.f, 0.f};
; #pragma unroll
;                 for (int hh = 0; hh < 8; ++hh) {
;                     f32x4 a = (f32x4){0.f, 0.f, 0.f, 0.f};
; #pragma unroll
;                     for (int ks = 0; ks < 2; ++ks) {
;                         const bf16x8 qv = *(const LAS bf16x8*)(lds + L_QI + q16 * 1024 + (((hh * 8 + 4 * ks + kg) ^ q16) << 4));
;                         a = __builtin_amdgcn_mfma_f32_16x16x32_bf16(kf[kb][ks], qv, a, 0, 0, 0);
;                     }
;                     const float wh = wl[hh * 16];
; #pragma unroll
;                     for (int i = 0; i < 4; ++i) s[i] += wh * fmaxf(a[i], 0.f);
;                 }
;                 u32x4 kk; kk.x = fkey(s[0]); kk.y = fkey(s[1]); kk.z = fkey(s[2]); kk.w = fkey(s[3]);
;                 sc[j][2 * kh + kb] = kk;
; #pragma unroll
;                 for (int i = 0; i < 4; ++i) SEL_HADD((kk[i] >> 24) * 16 + q16);
;                 __builtin_amdgcn_sched_barrier(0);
;             }
.LBB0_656:
	s_or_b64 exec, exec, s[2:3]
	s_ashr_i32 s46, s47, 6
	s_sub_i32 s2, s34, s46
	s_add_i32 s2, s2, 8
	s_ashr_i32 s4, s2, 3
	v_bfe_u32 v2, v2, 4, 2
	v_lshl_add_u32 v60, v59, 2, 0
	v_or_b32_e32 v18, s0, v59
	s_movk_i32 s0, 0x3fc
	s_cmp_gt_i32 s4, 0
	v_lshlrev_b32_e32 v0, 4, v2
	v_mad_u32_u24 v150, v59, s0, v60
	s_movk_i32 s0, 0xfc04
	s_cselect_b64 s[22:23], -1, 0
	v_mov_b32_e32 v19, s1
	v_lshl_add_u64 v[20:21], s[62:63], 0, v[0:1]
	v_mad_i32_i24 v0, v59, s0, v150
	s_and_b64 vcc, exec, s[22:23]
	v_xor_b32_e32 v182, v2, v59
	v_bitop3_b32 v183, v2, v59, 4 bitop3:0x36
	v_add_u32_e32 v137, 0x8800, v60
	v_bitop3_b32 v184, v2, v59, 8 bitop3:0x36
	v_bitop3_b32 v185, v2, v59, 12 bitop3:0x36
	v_bitop3_b32 v179, v2, v59, 16 bitop3:0x36
	v_bitop3_b32 v180, v2, v59, 20 bitop3:0x36
	v_bitop3_b32 v176, v2, v59, 24 bitop3:0x36
	v_bitop3_b32 v159, v2, v59, 28 bitop3:0x36
	v_bitop3_b32 v158, v2, v59, 32 bitop3:0x36
	v_bitop3_b32 v157, v2, v59, 36 bitop3:0x36
	v_bitop3_b32 v156, v2, v59, 40 bitop3:0x36
	v_bitop3_b32 v155, v2, v59, 44 bitop3:0x36
	v_bitop3_b32 v154, v2, v59, 48 bitop3:0x36
	v_bitop3_b32 v153, v2, v59, 52 bitop3:0x36
	v_bitop3_b32 v152, v2, v59, 56 bitop3:0x36
	v_bitop3_b32 v151, v2, v59, 60 bitop3:0x36
	s_waitcnt lgkmcnt(0)
	s_barrier
	s_cbranch_vccz .LBB0_658
	s_mov_b32 s0, s46
	s_lshl_b32 s0, s0, 6
	s_ashr_i32 s1, s0, 31
	v_lshl_add_u64 v[2:3], v[18:19], 0, s[0:1]
	v_lshlrev_b64 v[2:3], 7, v[2:3]
	v_lshl_add_u64 v[22:23], v[20:21], 0, v[2:3]
	global_load_dwordx4 v[14:17], v[22:23], off
	global_load_dwordx4 v[10:13], v[22:23], off offset:64
	v_lshl_add_u32 v88, v182, 4, v150
	v_lshl_add_u32 v87, v183, 4, v150
	v_lshl_add_u32 v85, v185, 4, v150
	v_lshl_add_u32 v83, v180, 4, v150
	v_lshl_add_u32 v82, v159, 4, v150
	v_lshl_add_u32 v86, v184, 4, v150
	ds_read_b128 v[2:5], v88
	v_lshl_add_u32 v84, v179, 4, v150
	ds_read_b128 v[6:9], v87
	ds_read_b128 v[24:27], v86
	v_lshl_add_u32 v81, v176, 4, v150
	ds_read_b128 v[28:31], v85
	ds_read_b128 v[32:35], v84
	ds_read_b128 v[36:39], v83
	ds_read_b128 v[40:43], v81
	v_lshl_add_u32 v80, v158, 4, v150
	ds_read_b128 v[44:47], v82
	ds_read_b128 v[48:51], v80
	v_lshl_add_u32 v79, v157, 4, v150
	ds_read_b128 v[52:55], v79
	v_lshl_add_u32 v76, v156, 4, v150
	v_lshl_add_u32 v75, v155, 4, v150
	ds_read_b128 v[62:65], v76
	ds_read_b128 v[66:69], v75
	v_lshl_add_u32 v78, v154, 4, v150
	v_lshl_add_u32 v77, v153, 4, v150
	v_lshl_add_u32 v74, v152, 4, v150
	s_waitcnt vmcnt(1) lgkmcnt(11)
	v_mfma_f32_16x16x32_bf16 v[2:5], v[14:17], v[2:5], 0
	s_waitcnt lgkmcnt(9)
	v_mfma_f32_16x16x32_bf16 v[24:27], v[14:17], v[24:27], 0
	s_waitcnt lgkmcnt(7)
	v_mfma_f32_16x16x32_bf16 v[32:35], v[14:17], v[32:35], 0
	s_waitcnt lgkmcnt(5)
	v_mfma_f32_16x16x32_bf16 v[40:43], v[14:17], v[40:43], 0
	s_waitcnt lgkmcnt(3)
	v_mfma_f32_16x16x32_bf16 v[48:51], v[14:17], v[48:51], 0
	s_waitcnt vmcnt(0)
	v_mfma_f32_16x16x32_bf16 v[70:73], v[10:13], v[6:9], v[2:5]
	v_mfma_f32_16x16x32_bf16 v[24:27], v[10:13], v[28:31], v[24:27]
	v_mfma_f32_16x16x32_bf16 v[28:31], v[10:13], v[36:39], v[32:35]
	v_mfma_f32_16x16x32_bf16 v[32:35], v[10:13], v[44:47], v[40:43]
	ds_read2_b32 v[44:45], v137 offset0:80 offset1:96
	ds_read2_b32 v[46:47], v137 offset0:112 offset1:128
	s_nop 3
	s_waitcnt lgkmcnt(4)
	v_mfma_f32_16x16x32_bf16 v[36:39], v[10:13], v[52:55], v[48:51]
	s_nop 0
	ds_read2_b32 v[48:49], v137 offset0:144 offset1:160
	global_load_dwordx4 v[6:9], v[22:23], off offset:2048
	global_load_dwordx4 v[2:5], v[22:23], off offset:2112
	s_waitcnt lgkmcnt(4)
	v_mfma_f32_16x16x32_bf16 v[62:65], v[14:17], v[62:65], 0
	s_nop 0
	v_max_f32_e32 v54, v24, v24
	s_nop 0
	s_waitcnt lgkmcnt(3)
	v_mfma_f32_16x16x32_bf16 v[40:43], v[10:13], v[66:69], v[62:65]
	v_max_f32_e32 v61, v39, v39
	v_max_f32_e32 v24, 0, v73
	v_max_f32_e32 v39, 0, v25
	v_max_f32_e32 v64, 0, v26
	v_max_f32_e32 v25, 0, v27
	v_max_f32_e32 v26, 0, v31
	v_max_f32_e32 v27, 0, v35
	v_max_f32_e32 v50, v70, v70
	v_max_f32_e32 v51, v71, v71
	v_max_f32_e32 v53, 0, v37
	s_waitcnt lgkmcnt(2)
	v_mul_f32_e32 v56, v45, v64
	v_pk_mul_f32 v[64:65], v[44:45], v[24:25]
	s_waitcnt lgkmcnt(1)
	v_pk_mul_f32 v[70:71], v[46:47], v[26:27]
	ds_read_b128 v[24:27], v78
	v_max_f32_e32 v62, v40, v40
	v_max_f32_e32 v40, 0, v28
	v_max_f32_e32 v28, 0, v30
	v_max_f32_e32 v63, v41, v41
	v_max_f32_e32 v41, 0, v29
	v_max_f32_e32 v29, 0, v34
	v_max_f32_e32 v30, 0, v38
	v_mul_f32_e32 v66, v46, v28
	v_max_f32_e32 v28, 0, v42
	v_mul_f32_e32 v68, v47, v29
	s_waitcnt lgkmcnt(1)
	v_mul_f32_e32 v90, v48, v30
	v_mul_f32_e32 v92, v49, v28
	ds_read_b128 v[28:31], v77
	s_waitcnt lgkmcnt(1)
	v_mfma_f32_16x16x32_bf16 v[24:27], v[14:17], v[24:27], 0
	v_max_f32_e32 v37, 0, v51
	s_waitcnt lgkmcnt(0)
	v_mfma_f32_16x16x32_bf16 v[24:27], v[10:13], v[28:31], v[24:27]
	ds_read_b128 v[28:31], v74
	v_max_f32_e32 v51, 0, v33
	v_max_f32_e32 v55, v36, v36
	v_max_f32_e32 v36, 0, v50
	v_max_f32_e32 v50, 0, v32
	v_max_f32_e32 v32, 0, v61
	v_max_f32_e32 v33, 0, v43
	v_lshl_add_u32 v73, v151, 4, v150
	v_pk_mul_f32 v[94:95], v[48:49], v[32:33]
	ds_read_b128 v[32:35], v73
	s_waitcnt lgkmcnt(1)
	v_mfma_f32_16x16x32_bf16 v[14:17], v[14:17], v[28:31], 0
	s_nop 0
	v_max_f32_e32 v42, 0, v72
	v_max_f32_e32 v38, 0, v54
	s_waitcnt lgkmcnt(0)
	v_mfma_f32_16x16x32_bf16 v[10:13], v[10:13], v[32:35], v[14:17]
	v_max_f32_e32 v52, 0, v55
	v_max_f32_e32 v54, 0, v62
	v_max_f32_e32 v55, 0, v63
	ds_read2_b32 v[62:63], v137 offset0:176 offset1:192
	s_nop 0
	s_nop 2
	v_max_f32_e32 v28, 0, v27
	v_max_f32_e32 v29, 0, v13
	s_waitcnt lgkmcnt(0)
; #define LAS __attribute__((address_space(3)))
; __device__ __forceinline__ unsigned fkey(float f) { const unsigned u = __float_as_uint(f); return (u & 0x80000000u) ? ~u : (u | 0x80000000u); }
; #define SEL_HADD(idx_) __hip_atomic_fetch_add(&hist[(idx_)], 1u, __ATOMIC_RELAXED, __HIP_MEMORY_SCOPE_WORKGROUP)
; __device__ __forceinline__ void sel_unit(LAS char* lds, int b, int u, const bf16_t* QI, const bf16_t* KIDX, const float* WIDX, unsigned long long* MASK) {
;     ...
;     for (int j = 0; j < 8; ++j) {
;         if (j < nj) {
;             int t = wid + 8 * j; asm volatile("" : "+s"(t));
; #pragma unroll
;             for (int kh = 0; kh < 2; ++kh) {
;             bf16x8 kf[2][2];
; #pragma unroll
;             for (int kb = 0; kb < 2; ++kb)
; #pragma unroll
;                 for (int ks = 0; ks < 2; ++ks) kf[kb][ks] = *(const bf16x8*)(KIDX + (rowbase + 64 * t + 32 * kh + 16 * kb + q16) * 64 + 32 * ks + 8 * kg);
; #pragma unroll
;             for (int kb = 0; kb < 2; ++kb) {
;                 f32x4 s = (f32x4){0.f, 0.f, 0.f, 0.f};
; #pragma unroll
;                 for (int hh = 0; hh < 8; ++hh) {
;                     f32x4 a = (f32x4){0.f, 0.f, 0.f, 0.f};
; #pragma unroll
;                     for (int ks = 0; ks < 2; ++ks) {
;                         const bf16x8 qv = *(const LAS bf16x8*)(lds + L_QI + q16 * 1024 + (((hh * 8 + 4 * ks + kg) ^ q16) << 4));
;                         a = __builtin_amdgcn_mfma_f32_16x16x32_bf16(kf[kb][ks], qv, a, 0, 0, 0);
;                     }
;                     const float wh = wl[hh * 16];
; #pragma unroll
;                     for (int i = 0; i < 4; ++i) s[i] += wh * fmaxf(a[i], 0.f);
;                 }
;                 u32x4 kk; kk.x = fkey(s[0]); kk.y = fkey(s[1]); kk.z = fkey(s[2]); kk.w = fkey(s[3]);
;                 sc[j][2 * kh + kb] = kk;
; #pragma unroll
;                 for (int i = 0; i < 4; ++i) SEL_HADD((kk[i] >> 24) * 16 + q16);
;                 __builtin_amdgcn_sched_barrier(0);
;             }
	v_pk_mul_f32 v[14:15], v[62:63], v[28:29]
	v_pk_fma_f32 v[16:17], v[44:45], v[36:37], 0 op_sel_hi:[0,1,0]
	v_mov_b32_e32 v28, v45
	v_pk_fma_f32 v[16:17], v[28:29], v[38:39], v[16:17] op_sel_hi:[0,1,1]
	v_pk_fma_f32 v[16:17], v[46:47], v[40:41], v[16:17] op_sel_hi:[0,1,1]
	v_mov_b32_e32 v28, v47
	v_pk_fma_f32 v[16:17], v[28:29], v[50:51], v[16:17] op_sel_hi:[0,1,1]
	v_pk_fma_f32 v[16:17], v[48:49], v[52:53], v[16:17] op_sel_hi:[0,1,1]
	v_mov_b32_e32 v28, v49
	v_max_f32_e32 v24, 0, v24
	v_max_f32_e32 v25, 0, v25
	v_pk_fma_f32 v[16:17], v[28:29], v[54:55], v[16:17] op_sel_hi:[0,1,1]
	v_max_f32_e32 v10, 0, v10
	v_max_f32_e32 v11, 0, v11
	v_pk_fma_f32 v[16:17], v[62:63], v[24:25], v[16:17] op_sel_hi:[0,1,1]
	v_mov_b32_e32 v24, v63
	v_pk_fma_f32 v[10:11], v[24:25], v[10:11], v[16:17] op_sel_hi:[0,1,1]
	v_and_b32_e32 v17, 0x7fffffff, v11
	v_and_b32_e32 v16, 0x7fffffff, v10
	v_mul_f32_e32 v42, v44, v42
	v_xor_b32_e32 v13, -1, v11
	v_pk_add_f32 v[16:17], v[16:17], 0 neg_lo:[1,1] neg_hi:[1,1]
	v_cmp_gt_i32_e32 vcc, 0, v11
	v_mov_b32_e32 v43, v64
	v_xor_b32_e32 v24, -1, v10
	v_cndmask_b32_e32 v61, v17, v13, vcc
	v_cmp_gt_i32_e32 vcc, 0, v10
	v_pk_add_f32 v[10:11], v[42:43], 0 op_sel_hi:[1,0]
	v_mov_b32_e32 v57, v65
	v_pk_add_f32 v[10:11], v[10:11], v[56:57]
	v_mov_b32_e32 v67, v70
	v_pk_add_f32 v[10:11], v[10:11], v[66:67]
	v_mov_b32_e32 v69, v71
	v_pk_add_f32 v[10:11], v[10:11], v[68:69]
	v_mov_b32_e32 v91, v94
	v_max_f32_e32 v26, 0, v26
	v_pk_add_f32 v[10:11], v[10:11], v[90:91]
	v_mov_b32_e32 v93, v95
	v_mul_f32_e32 v26, v62, v26
	v_max_f32_e32 v12, 0, v12
	v_pk_add_f32 v[10:11], v[10:11], v[92:93]
	v_mov_b32_e32 v27, v14
	v_mul_f32_e32 v12, v63, v12
	v_pk_add_f32 v[10:11], v[10:11], v[26:27]
	v_mov_b32_e32 v13, v15
	v_pk_add_f32 v[10:11], v[10:11], v[12:13]
	v_cndmask_b32_e32 v62, v16, v24, vcc
	v_and_b32_e32 v13, 0x7fffffff, v11
	v_and_b32_e32 v12, 0x7fffffff, v10
	v_xor_b32_e32 v14, -1, v11
	v_pk_add_f32 v[12:13], v[12:13], 0 neg_lo:[1,1] neg_hi:[1,1]
	v_cmp_gt_i32_e32 vcc, 0, v11
	v_xor_b32_e32 v15, -1, v10
	s_nop 0
	v_cndmask_b32_e32 v63, v13, v14, vcc
	v_cmp_gt_i32_e32 vcc, 0, v10
	v_lshrrev_b32_e32 v10, 24, v62
	v_lshl_add_u32 v10, v10, 6, v0
	ds_add_u32 v10, v205 offset:16384
	v_lshrrev_b32_e32 v10, 24, v61
	v_cndmask_b32_e32 v64, v12, v15, vcc
	v_lshl_add_u32 v10, v10, 6, v0
	ds_add_u32 v10, v205 offset:16384
	v_lshrrev_b32_e32 v10, 24, v64
	v_lshl_add_u32 v10, v10, 6, v0
	ds_add_u32 v10, v205 offset:16384
	v_lshrrev_b32_e32 v10, 24, v63
	v_lshl_add_u32 v10, v10, 6, v0
	ds_add_u32 v10, v205 offset:16384
	ds_read_b128 v[10:13], v88
	ds_read_b128 v[14:17], v87
	ds_read_b128 v[24:27], v86
	ds_read_b128 v[28:31], v85
	ds_read2_b32 v[32:33], v137 offset0:80 offset1:96
	ds_read2_b32 v[40:41], v137 offset0:112 offset1:128
	s_waitcnt vmcnt(1) lgkmcnt(5)
	v_mfma_f32_16x16x32_bf16 v[10:13], v[6:9], v[10:13], 0
	ds_read2_b32 v[52:53], v137 offset0:144 offset1:160
	s_waitcnt vmcnt(0) lgkmcnt(5)
	v_mfma_f32_16x16x32_bf16 v[10:13], v[2:5], v[14:17], v[10:13]
	ds_read_b128 v[14:17], v84
	s_waitcnt lgkmcnt(5)
	v_mfma_f32_16x16x32_bf16 v[24:27], v[6:9], v[24:27], 0
	s_nop 4
	v_max_f32_e32 v34, 0, v10
	v_max_f32_e32 v10, 0, v12
	v_max_f32_e32 v35, 0, v11
	s_waitcnt lgkmcnt(3)
	v_mul_f32_e32 v36, v32, v10
	v_max_f32_e32 v38, 0, v13
	v_mfma_f32_16x16x32_bf16 v[10:13], v[2:5], v[28:31], v[24:27]
	s_nop 2
	ds_read_b128 v[24:27], v83
	s_waitcnt lgkmcnt(1)
	v_mfma_f32_16x16x32_bf16 v[14:17], v[6:9], v[14:17], 0
	s_nop 1
	v_max_f32_e32 v28, 0, v10
	v_max_f32_e32 v29, 0, v11
	v_max_f32_e32 v10, 0, v12
	v_mul_f32_e32 v30, v33, v10
	v_max_f32_e32 v39, 0, v13
	s_waitcnt lgkmcnt(0)
	v_mfma_f32_16x16x32_bf16 v[10:13], v[2:5], v[24:27], v[14:17]
	ds_read_b128 v[24:27], v82
	v_pk_mul_f32 v[38:39], v[32:33], v[38:39]
	s_nop 0
	ds_read_b128 v[14:17], v81
	s_waitcnt lgkmcnt(0)
	v_mfma_f32_16x16x32_bf16 v[14:17], v[6:9], v[14:17], 0
	s_nop 1
	v_max_f32_e32 v42, 0, v10
	v_max_f32_e32 v43, 0, v11
	v_max_f32_e32 v10, 0, v12
	v_mul_f32_e32 v44, v40, v10
	s_nop 0
	v_max_f32_e32 v46, 0, v13
	v_mfma_f32_16x16x32_bf16 v[10:13], v[2:5], v[24:27], v[14:17]
	ds_read_b128 v[24:27], v79
	v_mov_b32_e32 v37, v38
	v_mov_b32_e32 v31, v39
	ds_read_b128 v[14:17], v80
	s_waitcnt lgkmcnt(0)
	v_mfma_f32_16x16x32_bf16 v[14:17], v[6:9], v[14:17], 0
	s_nop 1
	v_max_f32_e32 v48, 0, v10
	v_max_f32_e32 v49, 0, v11
	v_max_f32_e32 v10, 0, v12
	v_mul_f32_e32 v50, v41, v10
	s_nop 0
	v_max_f32_e32 v47, 0, v13
	v_mfma_f32_16x16x32_bf16 v[10:13], v[2:5], v[24:27], v[14:17]
	ds_read_b128 v[24:27], v75
	v_pk_mul_f32 v[46:47], v[40:41], v[46:47]
	s_nop 0
	ds_read_b128 v[14:17], v76
	s_waitcnt lgkmcnt(0)
	v_mfma_f32_16x16x32_bf16 v[14:17], v[6:9], v[14:17], 0
	s_nop 1
	v_max_f32_e32 v54, 0, v10
	v_max_f32_e32 v55, 0, v11
	v_max_f32_e32 v10, 0, v12
	v_mul_f32_e32 v56, v52, v10
	s_nop 0
	v_max_f32_e32 v66, 0, v13
	v_mfma_f32_16x16x32_bf16 v[10:13], v[2:5], v[24:27], v[14:17]
	ds_read_b128 v[24:27], v77
	v_mov_b32_e32 v45, v46
	v_mov_b32_e32 v51, v47
	ds_read_b128 v[14:17], v78
	s_waitcnt lgkmcnt(0)
	v_mfma_f32_16x16x32_bf16 v[14:17], v[6:9], v[14:17], 0
	s_nop 1
	v_max_f32_e32 v68, 0, v10
	v_max_f32_e32 v69, 0, v11
	v_max_f32_e32 v10, 0, v12
	v_mul_f32_e32 v70, v53, v10
	s_nop 0
	v_max_f32_e32 v67, 0, v13
	v_mfma_f32_16x16x32_bf16 v[10:13], v[2:5], v[24:27], v[14:17]
	ds_read_b128 v[24:27], v73
	v_pk_mul_f32 v[90:91], v[52:53], v[66:67]
	ds_read2_b32 v[66:67], v137 offset0:176 offset1:192
	ds_read_b128 v[14:17], v74
	s_waitcnt lgkmcnt(0)
; #define LAS __attribute__((address_space(3)))
; __device__ __forceinline__ unsigned fkey(float f) { const unsigned u = __float_as_uint(f); return (u & 0x80000000u) ? ~u : (u | 0x80000000u); }
; #define SEL_HADD(idx_) __hip_atomic_fetch_add(&hist[(idx_)], 1u, __ATOMIC_RELAXED, __HIP_MEMORY_SCOPE_WORKGROUP)
; __device__ __forceinline__ void sel_unit(LAS char* lds, int b, int u, const bf16_t* QI, const bf16_t* KIDX, const float* WIDX, unsigned long long* MASK) {
;     ...
;     for (int j = 0; j < 8; ++j) {
;         if (j < nj) {
;             int t = wid + 8 * j; asm volatile("" : "+s"(t));
; #pragma unroll
;             for (int kh = 0; kh < 2; ++kh) {
;             bf16x8 kf[2][2];
; #pragma unroll
;             for (int kb = 0; kb < 2; ++kb)
; #pragma unroll
;                 for (int ks = 0; ks < 2; ++ks) kf[kb][ks] = *(const bf16x8*)(KIDX + (rowbase + 64 * t + 32 * kh + 16 * kb + q16) * 64 + 32 * ks + 8 * kg);
; #pragma unroll
;             for (int kb = 0; kb < 2; ++kb) {
;                 f32x4 s = (f32x4){0.f, 0.f, 0.f, 0.f};
; #pragma unroll
;                 for (int hh = 0; hh < 8; ++hh) {
;                     f32x4 a = (f32x4){0.f, 0.f, 0.f, 0.f};
; #pragma unroll
;                     for (int ks = 0; ks < 2; ++ks) {
;                         const bf16x8 qv = *(const LAS bf16x8*)(lds + L_QI + q16 * 1024 + (((hh * 8 + 4 * ks + kg) ^ q16) << 4));
;                         a = __builtin_amdgcn_mfma_f32_16x16x32_bf16(kf[kb][ks], qv, a, 0, 0, 0);
;                     }
;                     const float wh = wl[hh * 16];
; #pragma unroll
;                     for (int i = 0; i < 4; ++i) s[i] += wh * fmaxf(a[i], 0.f);
;                 }
;                 u32x4 kk; kk.x = fkey(s[0]); kk.y = fkey(s[1]); kk.z = fkey(s[2]); kk.w = fkey(s[3]);
;                 sc[j][2 * kh + kb] = kk;
; #pragma unroll
;                 for (int i = 0; i < 4; ++i) SEL_HADD((kk[i] >> 24) * 16 + q16);
;                 __builtin_amdgcn_sched_barrier(0);
;             }
	v_mfma_f32_16x16x32_bf16 v[6:9], v[6:9], v[14:17], 0
	s_nop 1
	s_nop 0
	v_max_f32_e32 v14, 0, v13
	s_nop 0
	v_mfma_f32_16x16x32_bf16 v[2:5], v[2:5], v[24:27], v[6:9]
	s_nop 0
	v_max_f32_e32 v10, 0, v10
	v_max_f32_e32 v11, 0, v11
	v_pk_fma_f32 v[8:9], v[32:33], v[34:35], 0 op_sel_hi:[0,1,0]
	s_nop 0
	s_nop 2
	v_max_f32_e32 v15, 0, v5
	v_pk_mul_f32 v[6:7], v[66:67], v[14:15]
	v_mov_b32_e32 v14, v33
	v_pk_fma_f32 v[8:9], v[14:15], v[28:29], v[8:9] op_sel_hi:[0,1,1]
	v_pk_fma_f32 v[8:9], v[40:41], v[42:43], v[8:9] op_sel_hi:[0,1,1]
	v_mov_b32_e32 v14, v41
	v_pk_fma_f32 v[8:9], v[14:15], v[48:49], v[8:9] op_sel_hi:[0,1,1]
	v_pk_fma_f32 v[8:9], v[52:53], v[54:55], v[8:9] op_sel_hi:[0,1,1]
	v_mov_b32_e32 v14, v53
	v_pk_fma_f32 v[8:9], v[14:15], v[68:69], v[8:9] op_sel_hi:[0,1,1]
	v_max_f32_e32 v2, 0, v2
	v_max_f32_e32 v3, 0, v3
	v_pk_fma_f32 v[8:9], v[66:67], v[10:11], v[8:9] op_sel_hi:[0,1,1]
	v_mov_b32_e32 v10, v67
	v_pk_fma_f32 v[2:3], v[10:11], v[2:3], v[8:9] op_sel_hi:[0,1,1]
	v_and_b32_e32 v9, 0x7fffffff, v3
	v_and_b32_e32 v8, 0x7fffffff, v2
	v_xor_b32_e32 v5, -1, v3
	v_pk_add_f32 v[8:9], v[8:9], 0 neg_lo:[1,1] neg_hi:[1,1]
	v_cmp_gt_i32_e32 vcc, 0, v3
	v_xor_b32_e32 v10, -1, v2
	v_mov_b32_e32 v57, v90
	v_cndmask_b32_e32 v65, v9, v5, vcc
	v_cmp_gt_i32_e32 vcc, 0, v2
	v_pk_add_f32 v[2:3], v[36:37], 0 op_sel_hi:[1,0]
	v_max_f32_e32 v12, 0, v12
	v_pk_add_f32 v[2:3], v[2:3], v[30:31]
	v_pk_add_f32 v[2:3], v[2:3], v[44:45]
	v_mov_b32_e32 v71, v91
	v_pk_add_f32 v[2:3], v[2:3], v[50:51]
	v_mul_f32_e32 v12, v66, v12
	v_pk_add_f32 v[2:3], v[2:3], v[56:57]
	v_max_f32_e32 v4, 0, v4
	v_pk_add_f32 v[2:3], v[2:3], v[70:71]
	v_mov_b32_e32 v13, v6
	v_mul_f32_e32 v4, v67, v4
	v_pk_add_f32 v[2:3], v[2:3], v[12:13]
	v_mov_b32_e32 v5, v7
	v_pk_add_f32 v[2:3], v[2:3], v[4:5]
	v_cndmask_b32_e32 v66, v8, v10, vcc
	v_and_b32_e32 v5, 0x7fffffff, v3
	v_and_b32_e32 v4, 0x7fffffff, v2
	v_xor_b32_e32 v6, -1, v3
	v_pk_add_f32 v[4:5], v[4:5], 0 neg_lo:[1,1] neg_hi:[1,1]
	v_cmp_gt_i32_e32 vcc, 0, v3
	v_xor_b32_e32 v7, -1, v2
	s_nop 0
	v_cndmask_b32_e32 v67, v5, v6, vcc
	v_cmp_gt_i32_e32 vcc, 0, v2
	v_lshrrev_b32_e32 v2, 24, v66
	v_lshl_add_u32 v2, v2, 6, v0
	ds_add_u32 v2, v205 offset:16384
	v_lshrrev_b32_e32 v2, 24, v65
	v_cndmask_b32_e32 v68, v4, v7, vcc
	v_lshl_add_u32 v2, v2, 6, v0
	ds_add_u32 v2, v205 offset:16384
	v_lshrrev_b32_e32 v2, 24, v68
	v_lshl_add_u32 v2, v2, 6, v0
	ds_add_u32 v2, v205 offset:16384
	v_lshrrev_b32_e32 v2, 24, v67
	v_lshl_add_u32 v2, v2, 6, v0
	ds_add_u32 v2, v205 offset:16384
	v_add_co_u32_e32 v2, vcc, s96, v22
	s_nop 1
	v_addc_co_u32_e32 v3, vcc, 0, v23, vcc
	global_load_dwordx4 v[14:17], v[2:3], off
	global_load_dwordx4 v[10:13], v[2:3], off offset:64
	global_load_dwordx4 v[6:9], v[2:3], off offset:2048
	s_nop 0
	global_load_dwordx4 v[2:5], v[2:3], off offset:2112
	ds_read_b128 v[22:25], v88
	ds_read_b128 v[26:29], v87
	s_waitcnt vmcnt(3) lgkmcnt(1)
	v_mfma_f32_16x16x32_bf16 v[22:25], v[14:17], v[22:25], 0
	ds_read_b128 v[32:35], v85
	ds_read_b128 v[38:41], v83
	ds_read_b128 v[44:47], v82
	s_waitcnt vmcnt(2) lgkmcnt(3)
	v_mfma_f32_16x16x32_bf16 v[26:29], v[10:13], v[26:29], v[22:25]
	ds_read_b128 v[50:53], v79
	ds_read_b128 v[90:93], v75
	ds_read_b128 v[94:97], v77
	ds_read2_b32 v[24:25], v137 offset0:80 offset1:96
	s_nop 3
	v_max_f32_e32 v26, 0, v26
	v_max_f32_e32 v27, 0, v27
	v_max_f32_e32 v22, v28, v28
	v_max_f32_e32 v23, v29, v29
	ds_read_b128 v[28:31], v86
	s_waitcnt lgkmcnt(0)
	v_mfma_f32_16x16x32_bf16 v[28:31], v[14:17], v[28:31], 0
	v_max_f32_e32 v36, 0, v23
	v_max_f32_e32 v22, 0, v22
	v_mul_f32_e32 v22, v24, v22
	v_mfma_f32_16x16x32_bf16 v[28:31], v[10:13], v[32:35], v[28:31]
	s_nop 7
	v_max_f32_e32 v32, 0, v28
	v_max_f32_e32 v33, 0, v29
	v_max_f32_e32 v23, 0, v30
	v_mul_f32_e32 v28, v25, v23
	v_max_f32_e32 v37, 0, v31
	v_pk_mul_f32 v[30:31], v[24:25], v[36:37]
	ds_read_b128 v[34:37], v84
	s_waitcnt lgkmcnt(0)
	v_mfma_f32_16x16x32_bf16 v[34:37], v[14:17], v[34:37], 0
	v_mov_b32_e32 v29, v31
	v_mfma_f32_16x16x32_bf16 v[38:41], v[10:13], v[38:41], v[34:37]
	s_nop 5
	ds_read2_b32 v[36:37], v137 offset0:112 offset1:128
	s_nop 0
	v_max_f32_e32 v38, 0, v38
	v_max_f32_e32 v39, 0, v39
	v_max_f32_e32 v23, 0, v40
	s_waitcnt lgkmcnt(0)
	v_mul_f32_e32 v34, v36, v23
	v_max_f32_e32 v23, v41, v41
	ds_read_b128 v[40:43], v81
	s_waitcnt lgkmcnt(0)
	v_mfma_f32_16x16x32_bf16 v[40:43], v[14:17], v[40:43], 0
	v_max_f32_e32 v48, 0, v23
	v_mfma_f32_16x16x32_bf16 v[40:43], v[10:13], v[44:47], v[40:43]
	s_nop 7
	v_max_f32_e32 v44, 0, v40
	v_max_f32_e32 v45, 0, v41
	v_max_f32_e32 v23, 0, v42
	v_mul_f32_e32 v40, v37, v23
	v_max_f32_e32 v49, 0, v43
	v_pk_mul_f32 v[42:43], v[36:37], v[48:49]
	ds_read_b128 v[46:49], v80
	s_waitcnt lgkmcnt(0)
	v_mfma_f32_16x16x32_bf16 v[46:49], v[14:17], v[46:49], 0
	v_mov_b32_e32 v35, v42
	v_mov_b32_e32 v41, v43
	v_mfma_f32_16x16x32_bf16 v[50:53], v[10:13], v[50:53], v[46:49]
	s_nop 4
	ds_read2_b32 v[48:49], v137 offset0:144 offset1:160
	s_nop 1
	v_max_f32_e32 v50, 0, v50
	v_max_f32_e32 v51, 0, v51
	v_max_f32_e32 v23, 0, v52
	s_waitcnt lgkmcnt(0)
	v_mul_f32_e32 v46, v48, v23
	v_max_f32_e32 v23, v53, v53
	ds_read_b128 v[52:55], v76
	s_waitcnt lgkmcnt(0)
	v_mfma_f32_16x16x32_bf16 v[52:55], v[14:17], v[52:55], 0
	v_max_f32_e32 v70, 0, v23
	v_mfma_f32_16x16x32_bf16 v[52:55], v[10:13], v[90:93], v[52:55]
	ds_read_b128 v[90:93], v78
	s_waitcnt lgkmcnt(0)
	v_mfma_f32_16x16x32_bf16 v[90:93], v[14:17], v[90:93], 0
	s_nop 4
	v_max_f32_e32 v56, 0, v52
	v_max_f32_e32 v57, 0, v53
	v_max_f32_e32 v23, 0, v54
	v_mfma_f32_16x16x32_bf16 v[90:93], v[10:13], v[94:97], v[90:93]
	v_mul_f32_e32 v52, v49, v23
	s_nop 0
	v_max_f32_e32 v71, 0, v55
	v_pk_mul_f32 v[54:55], v[48:49], v[70:71]
	ds_read2_b32 v[70:71], v137 offset0:176 offset1:192
	s_nop 2
	v_max_f32_e32 v94, 0, v90
	v_max_f32_e32 v95, 0, v91
	v_max_f32_e32 v23, 0, v92
	s_waitcnt lgkmcnt(0)
; #define LAS __attribute__((address_space(3)))
; __device__ __forceinline__ unsigned fkey(float f) { const unsigned u = __float_as_uint(f); return (u & 0x80000000u) ? ~u : (u | 0x80000000u); }
; #define SEL_HADD(idx_) __hip_atomic_fetch_add(&hist[(idx_)], 1u, __ATOMIC_RELAXED, __HIP_MEMORY_SCOPE_WORKGROUP)
; __device__ __forceinline__ void sel_unit(LAS char* lds, int b, int u, const bf16_t* QI, const bf16_t* KIDX, const float* WIDX, unsigned long long* MASK) {
;     ...
;     for (int j = 0; j < 8; ++j) {
;         if (j < nj) {
;             int t = wid + 8 * j; asm volatile("" : "+s"(t));
; #pragma unroll
;             for (int kh = 0; kh < 2; ++kh) {
;             bf16x8 kf[2][2];
; #pragma unroll
;             for (int kb = 0; kb < 2; ++kb)
; #pragma unroll
;                 for (int ks = 0; ks < 2; ++ks) kf[kb][ks] = *(const bf16x8*)(KIDX + (rowbase + 64 * t + 32 * kh + 16 * kb + q16) * 64 + 32 * ks + 8 * kg);
; #pragma unroll
;             for (int kb = 0; kb < 2; ++kb) {
;                 f32x4 s = (f32x4){0.f, 0.f, 0.f, 0.f};
; #pragma unroll
;                 for (int hh = 0; hh < 8; ++hh) {
;                     f32x4 a = (f32x4){0.f, 0.f, 0.f, 0.f};
; #pragma unroll
;                     for (int ks = 0; ks < 2; ++ks) {
;                         const bf16x8 qv = *(const LAS bf16x8*)(lds + L_QI + q16 * 1024 + (((hh * 8 + 4 * ks + kg) ^ q16) << 4));
;                         a = __builtin_amdgcn_mfma_f32_16x16x32_bf16(kf[kb][ks], qv, a, 0, 0, 0);
;                     }
;                     const float wh = wl[hh * 16];
; #pragma unroll
;                     for (int i = 0; i < 4; ++i) s[i] += wh * fmaxf(a[i], 0.f);
;                 }
;                 u32x4 kk; kk.x = fkey(s[0]); kk.y = fkey(s[1]); kk.z = fkey(s[2]); kk.w = fkey(s[3]);
;                 sc[j][2 * kh + kb] = kk;
; #pragma unroll
;                 for (int i = 0; i < 4; ++i) SEL_HADD((kk[i] >> 24) * 16 + q16);
;                 __builtin_amdgcn_sched_barrier(0);
;             }
	v_mul_f32_e32 v96, v70, v23
	v_max_f32_e32 v23, v93, v93
	ds_read_b128 v[90:93], v74
	s_waitcnt lgkmcnt(0)
	v_mfma_f32_16x16x32_bf16 v[14:17], v[14:17], v[90:93], 0
	ds_read_b128 v[90:93], v73
	v_max_f32_e32 v98, 0, v23
	v_mov_b32_e32 v47, v54
	s_waitcnt lgkmcnt(0)
	v_mfma_f32_16x16x32_bf16 v[10:13], v[10:13], v[90:93], v[14:17]
	v_mov_b32_e32 v53, v55
	s_nop 1
	v_pk_fma_f32 v[16:17], v[24:25], v[26:27], 0 op_sel_hi:[0,1,0]
	v_mov_b32_e32 v24, v25
	v_pk_fma_f32 v[16:17], v[24:25], v[32:33], v[16:17] op_sel_hi:[0,1,1]
	v_pk_fma_f32 v[16:17], v[36:37], v[38:39], v[16:17] op_sel_hi:[0,1,1]
	v_mov_b32_e32 v24, v37
	v_pk_fma_f32 v[16:17], v[24:25], v[44:45], v[16:17] op_sel_hi:[0,1,1]
	v_pk_fma_f32 v[16:17], v[48:49], v[50:51], v[16:17] op_sel_hi:[0,1,1]
	v_mov_b32_e32 v24, v49
	v_pk_fma_f32 v[16:17], v[24:25], v[56:57], v[16:17] op_sel_hi:[0,1,1]
	v_max_f32_e32 v10, 0, v10
	v_max_f32_e32 v11, 0, v11
	v_pk_fma_f32 v[16:17], v[70:71], v[94:95], v[16:17] op_sel_hi:[0,1,1]
	v_mov_b32_e32 v24, v71
	v_pk_fma_f32 v[10:11], v[24:25], v[10:11], v[16:17] op_sel_hi:[0,1,1]
	v_and_b32_e32 v17, 0x7fffffff, v11
	v_and_b32_e32 v16, 0x7fffffff, v10
	v_max_f32_e32 v99, 0, v13
	v_xor_b32_e32 v23, -1, v10
	v_pk_add_f32 v[16:17], v[16:17], 0 neg_lo:[1,1] neg_hi:[1,1]
	v_cmp_gt_i32_e32 vcc, 0, v10
	v_pk_mul_f32 v[14:15], v[70:71], v[98:99]
	v_xor_b32_e32 v13, -1, v11
	v_cndmask_b32_e32 v70, v16, v23, vcc
	v_mov_b32_e32 v23, v30
	v_cmp_gt_i32_e64 s[2:3], 0, v11
	v_pk_add_f32 v[10:11], v[22:23], 0 op_sel_hi:[1,0]
	v_pk_add_f32 v[10:11], v[10:11], v[28:29]
	v_max_f32_e32 v12, 0, v12
	v_pk_add_f32 v[10:11], v[10:11], v[34:35]
	v_mov_b32_e32 v97, v14
	v_pk_add_f32 v[10:11], v[10:11], v[40:41]
	v_mul_f32_e32 v12, v71, v12
	v_pk_add_f32 v[10:11], v[10:11], v[46:47]
	v_cndmask_b32_e64 v69, v17, v13, s[2:3]
	v_pk_add_f32 v[10:11], v[10:11], v[52:53]
	v_mov_b32_e32 v13, v15
	v_pk_add_f32 v[10:11], v[10:11], v[96:97]
	s_nop 0
	v_pk_add_f32 v[10:11], v[10:11], v[12:13]
	s_nop 0
	v_xor_b32_e32 v15, -1, v10
	v_and_b32_e32 v12, 0x7fffffff, v10
	v_cmp_gt_i32_e32 vcc, 0, v10
	v_lshrrev_b32_e32 v10, 24, v70
	v_and_b32_e32 v13, 0x7fffffff, v11
	v_lshl_add_u32 v10, v10, 6, v0
	v_pk_add_f32 v[12:13], v[12:13], 0 neg_lo:[1,1] neg_hi:[1,1]
	ds_add_u32 v10, v205 offset:16384
	v_lshrrev_b32_e32 v10, 24, v69
	v_cndmask_b32_e32 v72, v12, v15, vcc
	v_lshl_add_u32 v10, v10, 6, v0
	v_xor_b32_e32 v14, -1, v11
	v_cmp_gt_i32_e64 s[2:3], 0, v11
	ds_add_u32 v10, v205 offset:16384
	v_lshrrev_b32_e32 v10, 24, v72
	v_cndmask_b32_e64 v71, v13, v14, s[2:3]
	v_lshl_add_u32 v10, v10, 6, v0
	ds_add_u32 v10, v205 offset:16384
	v_lshrrev_b32_e32 v10, 24, v71
	v_lshl_add_u32 v10, v10, 6, v0
	ds_add_u32 v10, v205 offset:16384
	ds_read_b128 v[10:13], v88
	ds_read_b128 v[14:17], v87
	ds_read_b128 v[22:25], v86
	ds_read_b128 v[26:29], v85
	ds_read2_b32 v[48:49], v137 offset0:144 offset1:160
	s_waitcnt vmcnt(1) lgkmcnt(4)
	v_mfma_f32_16x16x32_bf16 v[10:13], v[6:9], v[10:13], 0
	ds_read_b128 v[36:39], v82
	ds_read_b128 v[42:45], v79
	s_waitcnt lgkmcnt(4)
	v_mfma_f32_16x16x32_bf16 v[22:25], v[6:9], v[22:25], 0
	s_waitcnt vmcnt(0)
	v_mfma_f32_16x16x32_bf16 v[14:17], v[2:5], v[14:17], v[10:13]
	s_waitcnt lgkmcnt(3)
	v_mfma_f32_16x16x32_bf16 v[24:27], v[2:5], v[26:29], v[22:25]
	s_nop 0
	ds_read2_b32 v[12:13], v137 offset0:80 offset1:96
	s_nop 3
	v_max_f32_e32 v30, 0, v17
	v_max_f32_e32 v14, 0, v14
	v_max_f32_e32 v24, 0, v24
	v_max_f32_e32 v25, 0, v25
	v_max_f32_e32 v11, 0, v26
	v_max_f32_e32 v15, 0, v15
	v_max_f32_e32 v10, v16, v16
	s_waitcnt lgkmcnt(0)
	v_mul_f32_e32 v16, v13, v11
	v_max_f32_e32 v11, v27, v27
	ds_read_b128 v[26:29], v84
	v_max_f32_e32 v31, 0, v11
	v_pk_mul_f32 v[22:23], v[12:13], v[30:31]
	ds_read_b128 v[30:33], v83
	s_waitcnt lgkmcnt(1)
	v_mfma_f32_16x16x32_bf16 v[26:29], v[6:9], v[26:29], 0
	v_max_f32_e32 v10, 0, v10
	v_mul_f32_e32 v10, v12, v10
	v_mov_b32_e32 v17, v23
	s_waitcnt lgkmcnt(0)
	v_mfma_f32_16x16x32_bf16 v[30:33], v[2:5], v[30:33], v[26:29]
	s_nop 2
	ds_read2_b32 v[28:29], v137 offset0:112 offset1:128
	s_nop 3
	v_max_f32_e32 v30, 0, v30
	v_max_f32_e32 v31, 0, v31
	v_max_f32_e32 v11, 0, v32
	s_waitcnt lgkmcnt(0)
	v_mul_f32_e32 v26, v28, v11
	v_max_f32_e32 v11, v33, v33
	ds_read_b128 v[32:35], v81
	s_waitcnt lgkmcnt(0)
	v_mfma_f32_16x16x32_bf16 v[32:35], v[6:9], v[32:35], 0
	v_max_f32_e32 v40, 0, v11
	v_mfma_f32_16x16x32_bf16 v[32:35], v[2:5], v[36:39], v[32:35]
	s_nop 7
	v_max_f32_e32 v36, 0, v32
	v_max_f32_e32 v37, 0, v33
	v_max_f32_e32 v11, 0, v34
	v_mul_f32_e32 v32, v29, v11
	v_max_f32_e32 v41, 0, v35
	v_pk_mul_f32 v[34:35], v[28:29], v[40:41]
	ds_read_b128 v[38:41], v80
	s_waitcnt lgkmcnt(0)
	v_mfma_f32_16x16x32_bf16 v[38:41], v[6:9], v[38:41], 0
	v_mov_b32_e32 v27, v34
	v_mov_b32_e32 v33, v35
	v_mfma_f32_16x16x32_bf16 v[38:41], v[2:5], v[42:45], v[38:41]
	ds_read_b128 v[44:47], v75
	s_nop 6
	v_max_f32_e32 v50, 0, v38
	v_max_f32_e32 v51, 0, v39
	v_max_f32_e32 v11, 0, v40
	v_mul_f32_e32 v38, v48, v11
	v_max_f32_e32 v11, v41, v41
	ds_read_b128 v[40:43], v76
	s_waitcnt lgkmcnt(0)
	v_mfma_f32_16x16x32_bf16 v[40:43], v[6:9], v[40:43], 0
	v_max_f32_e32 v52, 0, v11
	v_mfma_f32_16x16x32_bf16 v[40:43], v[2:5], v[44:47], v[40:43]
	ds_read_b128 v[44:47], v77
	s_nop 6
	v_max_f32_e32 v54, 0, v40
	v_max_f32_e32 v55, 0, v41
	v_max_f32_e32 v11, 0, v42
	v_mul_f32_e32 v56, v49, v11
	v_max_f32_e32 v11, v43, v43
	ds_read_b128 v[40:43], v78
	s_waitcnt lgkmcnt(0)
	v_mfma_f32_16x16x32_bf16 v[40:43], v[6:9], v[40:43], 0
	v_max_f32_e32 v53, 0, v11
	v_pk_mul_f32 v[52:53], v[48:49], v[52:53]
	v_mfma_f32_16x16x32_bf16 v[40:43], v[2:5], v[44:47], v[40:43]
	ds_read2_b32 v[44:45], v137 offset0:176 offset1:192
	v_mov_b32_e32 v39, v52
	v_mov_b32_e32 v57, v53
	s_nop 4
	v_max_f32_e32 v46, 0, v40
	v_max_f32_e32 v47, 0, v41
	v_max_f32_e32 v11, 0, v42
	s_waitcnt lgkmcnt(0)
; #define LAS __attribute__((address_space(3)))
; __device__ __forceinline__ unsigned fkey(float f) { const unsigned u = __float_as_uint(f); return (u & 0x80000000u) ? ~u : (u | 0x80000000u); }
; #define SEL_HADD(idx_) __hip_atomic_fetch_add(&hist[(idx_)], 1u, __ATOMIC_RELAXED, __HIP_MEMORY_SCOPE_WORKGROUP)
; __device__ __forceinline__ void sel_unit(LAS char* lds, int b, int u, const bf16_t* QI, const bf16_t* KIDX, const float* WIDX, unsigned long long* MASK) {
;     ...
;     for (int j = 0; j < 8; ++j) {
;         if (j < nj) {
;             int t = wid + 8 * j; asm volatile("" : "+s"(t));
; #pragma unroll
;             for (int kh = 0; kh < 2; ++kh) {
;             bf16x8 kf[2][2];
; #pragma unroll
;             for (int kb = 0; kb < 2; ++kb)
; #pragma unroll
;                 for (int ks = 0; ks < 2; ++ks) kf[kb][ks] = *(const bf16x8*)(KIDX + (rowbase + 64 * t + 32 * kh + 16 * kb + q16) * 64 + 32 * ks + 8 * kg);
; #pragma unroll
;             for (int kb = 0; kb < 2; ++kb) {
;                 f32x4 s = (f32x4){0.f, 0.f, 0.f, 0.f};
; #pragma unroll
;                 for (int hh = 0; hh < 8; ++hh) {
;                     f32x4 a = (f32x4){0.f, 0.f, 0.f, 0.f};
; #pragma unroll
;                     for (int ks = 0; ks < 2; ++ks) {
;                         const bf16x8 qv = *(const LAS bf16x8*)(lds + L_QI + q16 * 1024 + (((hh * 8 + 4 * ks + kg) ^ q16) << 4));
;                         a = __builtin_amdgcn_mfma_f32_16x16x32_bf16(kf[kb][ks], qv, a, 0, 0, 0);
;                     }
;                     const float wh = wl[hh * 16];
; #pragma unroll
;                     for (int i = 0; i < 4; ++i) s[i] += wh * fmaxf(a[i], 0.f);
;                 }
;                 u32x4 kk; kk.x = fkey(s[0]); kk.y = fkey(s[1]); kk.z = fkey(s[2]); kk.w = fkey(s[3]);
;                 sc[j][2 * kh + kb] = kk;
; #pragma unroll
;                 for (int i = 0; i < 4; ++i) SEL_HADD((kk[i] >> 24) * 16 + q16);
;                 __builtin_amdgcn_sched_barrier(0);
;             }
	v_mul_f32_e32 v76, v44, v11
	v_max_f32_e32 v11, v43, v43
	ds_read_b128 v[40:43], v74
	s_waitcnt lgkmcnt(0)
	v_mfma_f32_16x16x32_bf16 v[6:9], v[6:9], v[40:43], 0
	ds_read_b128 v[40:43], v73
	v_max_f32_e32 v78, 0, v11
	s_waitcnt lgkmcnt(0)
	v_mfma_f32_16x16x32_bf16 v[2:5], v[2:5], v[40:43], v[6:9]
	s_nop 3
	v_fma_f32 v8, v12, v14, 0
	v_fma_f32 v9, v12, v15, 0
	v_mov_b32_e32 v12, v13
	v_pk_fma_f32 v[8:9], v[12:13], v[24:25], v[8:9] op_sel_hi:[0,1,1]
	v_pk_fma_f32 v[8:9], v[28:29], v[30:31], v[8:9] op_sel_hi:[0,1,1]
	v_mov_b32_e32 v12, v29
	v_pk_fma_f32 v[8:9], v[12:13], v[36:37], v[8:9] op_sel_hi:[0,1,1]
	v_pk_fma_f32 v[8:9], v[48:49], v[50:51], v[8:9] op_sel_hi:[0,1,1]
	v_mov_b32_e32 v12, v49
	v_pk_fma_f32 v[8:9], v[12:13], v[54:55], v[8:9] op_sel_hi:[0,1,1]
	v_max_f32_e32 v2, 0, v2
	v_max_f32_e32 v3, 0, v3
	v_pk_fma_f32 v[8:9], v[44:45], v[46:47], v[8:9] op_sel_hi:[0,1,1]
	v_mov_b32_e32 v12, v45
	v_pk_fma_f32 v[2:3], v[12:13], v[2:3], v[8:9] op_sel_hi:[0,1,1]
	v_and_b32_e32 v9, 0x7fffffff, v3
	v_and_b32_e32 v8, 0x7fffffff, v2
	v_xor_b32_e32 v11, -1, v2
	v_pk_add_f32 v[8:9], v[8:9], 0 neg_lo:[1,1] neg_hi:[1,1]
	v_cmp_gt_i32_e32 vcc, 0, v2
	v_max_f32_e32 v79, 0, v5
	s_nop 0
	v_cndmask_b32_e32 v74, v8, v11, vcc
	v_mov_b32_e32 v11, v22
	v_xor_b32_e32 v5, -1, v3
	v_cmp_gt_i32_e64 s[2:3], 0, v3
	v_pk_add_f32 v[2:3], v[10:11], 0 op_sel_hi:[1,0]
	v_pk_add_f32 v[2:3], v[2:3], v[16:17]
	v_pk_mul_f32 v[6:7], v[44:45], v[78:79]
	v_pk_add_f32 v[2:3], v[2:3], v[26:27]
	v_max_f32_e32 v4, 0, v4
	v_pk_add_f32 v[2:3], v[2:3], v[32:33]
	v_mov_b32_e32 v77, v6
	v_pk_add_f32 v[2:3], v[2:3], v[38:39]
	v_mul_f32_e32 v4, v45, v4
	v_pk_add_f32 v[2:3], v[2:3], v[56:57]
	v_cndmask_b32_e64 v73, v9, v5, s[2:3]
	v_pk_add_f32 v[2:3], v[2:3], v[76:77]
	v_mov_b32_e32 v5, v7
	v_pk_add_f32 v[2:3], v[2:3], v[4:5]
	s_nop 0
	v_xor_b32_e32 v7, -1, v2
	v_and_b32_e32 v4, 0x7fffffff, v2
	v_cmp_gt_i32_e32 vcc, 0, v2
	v_lshrrev_b32_e32 v2, 24, v74
	v_and_b32_e32 v5, 0x7fffffff, v3
	v_lshl_add_u32 v2, v2, 6, v0
	v_pk_add_f32 v[4:5], v[4:5], 0 neg_lo:[1,1] neg_hi:[1,1]
	ds_add_u32 v2, v205 offset:16384
	v_lshrrev_b32_e32 v2, 24, v73
	v_cndmask_b32_e32 v76, v4, v7, vcc
	v_lshl_add_u32 v2, v2, 6, v0
	v_xor_b32_e32 v6, -1, v3
	v_cmp_gt_i32_e64 s[2:3], 0, v3
	ds_add_u32 v2, v205 offset:16384
	v_lshrrev_b32_e32 v2, 24, v76
	v_cndmask_b32_e64 v75, v5, v6, s[2:3]
	v_lshl_add_u32 v2, v2, 6, v0
	ds_add_u32 v2, v205 offset:16384
	v_lshrrev_b32_e32 v2, 24, v75
	v_lshl_add_u32 v2, v2, 6, v0
	ds_add_u32 v2, v205 offset:16384
.LBB0_658:
	s_cmp_gt_i32 s4, 1
	s_cselect_b64 s[18:19], -1, 0
	s_cmp_lt_i32 s4, 2
	s_cbranch_scc1 .LBB0_660
	s_add_i32 s0, s46, 8
	s_lshl_b32 s0, s0, 6
	s_ashr_i32 s1, s0, 31
	v_lshl_add_u64 v[2:3], v[18:19], 0, s[0:1]
	v_lshlrev_b64 v[2:3], 7, v[2:3]
	v_lshl_add_u64 v[22:23], v[20:21], 0, v[2:3]
	global_load_dwordx4 v[14:17], v[22:23], off
	global_load_dwordx4 v[10:13], v[22:23], off offset:64
	v_lshl_add_u32 v95, v182, 4, v150
	v_lshl_add_u32 v96, v183, 4, v150
	v_lshl_add_u32 v93, v185, 4, v150
	v_lshl_add_u32 v89, v180, 4, v150
	v_lshl_add_u32 v94, v159, 4, v150
	v_lshl_add_u32 v92, v184, 4, v150
	ds_read_b128 v[2:5], v95
	v_lshl_add_u32 v90, v179, 4, v150
	ds_read_b128 v[6:9], v96
	ds_read_b128 v[24:27], v92
	v_lshl_add_u32 v91, v176, 4, v150
	ds_read_b128 v[28:31], v93
	ds_read_b128 v[32:35], v90
	ds_read_b128 v[36:39], v89
	ds_read_b128 v[40:43], v91
	v_lshl_add_u32 v97, v158, 4, v150
	ds_read_b128 v[44:47], v94
	ds_read_b128 v[48:51], v97
	v_lshl_add_u32 v98, v157, 4, v150
	ds_read_b128 v[52:55], v98
	v_lshl_add_u32 v99, v156, 4, v150
	v_lshl_add_u32 v100, v155, 4, v150
	ds_read_b128 v[78:81], v99
	ds_read_b128 v[82:85], v100
	v_lshl_add_u32 v101, v154, 4, v150
	s_waitcnt vmcnt(1) lgkmcnt(11)
	v_mfma_f32_16x16x32_bf16 v[2:5], v[14:17], v[2:5], 0
	s_waitcnt lgkmcnt(9)
	v_mfma_f32_16x16x32_bf16 v[24:27], v[14:17], v[24:27], 0
	s_waitcnt lgkmcnt(7)
	v_mfma_f32_16x16x32_bf16 v[32:35], v[14:17], v[32:35], 0
	s_waitcnt lgkmcnt(5)
	v_mfma_f32_16x16x32_bf16 v[40:43], v[14:17], v[40:43], 0
	s_waitcnt lgkmcnt(3)
	v_mfma_f32_16x16x32_bf16 v[48:51], v[14:17], v[48:51], 0
	s_waitcnt vmcnt(0)
	v_mfma_f32_16x16x32_bf16 v[102:105], v[10:13], v[6:9], v[2:5]
	v_mfma_f32_16x16x32_bf16 v[24:27], v[10:13], v[28:31], v[24:27]
	v_mfma_f32_16x16x32_bf16 v[28:31], v[10:13], v[36:39], v[32:35]
	v_mfma_f32_16x16x32_bf16 v[32:35], v[10:13], v[44:47], v[40:43]
	ds_read2_b32 v[44:45], v137 offset0:80 offset1:96
	ds_read2_b32 v[46:47], v137 offset0:112 offset1:128
	s_nop 3
	s_waitcnt lgkmcnt(4)
	v_mfma_f32_16x16x32_bf16 v[36:39], v[10:13], v[52:55], v[48:51]
	s_nop 0
	ds_read2_b32 v[48:49], v137 offset0:144 offset1:160
	global_load_dwordx4 v[6:9], v[22:23], off offset:2048
	global_load_dwordx4 v[2:5], v[22:23], off offset:2112
	s_waitcnt lgkmcnt(4)
	v_mfma_f32_16x16x32_bf16 v[78:81], v[14:17], v[78:81], 0
	s_nop 0
	v_max_f32_e32 v54, v24, v24
	s_nop 0
	s_waitcnt lgkmcnt(3)
	v_mfma_f32_16x16x32_bf16 v[40:43], v[10:13], v[82:85], v[78:81]
	v_max_f32_e32 v77, v39, v39
	v_max_f32_e32 v24, 0, v105
	v_max_f32_e32 v39, 0, v25
	v_max_f32_e32 v80, 0, v26
	v_max_f32_e32 v25, 0, v27
	v_max_f32_e32 v26, 0, v31
	v_max_f32_e32 v27, 0, v35
	v_max_f32_e32 v53, 0, v37
	s_waitcnt lgkmcnt(2)
	v_mul_f32_e32 v56, v45, v80
	v_pk_mul_f32 v[80:81], v[44:45], v[24:25]
	s_waitcnt lgkmcnt(1)
	v_pk_mul_f32 v[86:87], v[46:47], v[26:27]
	ds_read_b128 v[24:27], v101
	v_max_f32_e32 v78, v40, v40
	v_max_f32_e32 v40, 0, v28
	v_max_f32_e32 v28, 0, v30
	v_max_f32_e32 v50, v102, v102
	v_max_f32_e32 v79, v41, v41
	v_max_f32_e32 v41, 0, v29
	v_max_f32_e32 v29, 0, v34
	v_max_f32_e32 v30, 0, v38
	v_mul_f32_e32 v82, v46, v28
	v_max_f32_e32 v28, 0, v42
	v_lshl_add_u32 v102, v153, 4, v150
	v_mul_f32_e32 v84, v47, v29
	s_waitcnt lgkmcnt(1)
; #define LAS __attribute__((address_space(3)))
; __device__ __forceinline__ unsigned fkey(float f) { const unsigned u = __float_as_uint(f); return (u & 0x80000000u) ? ~u : (u | 0x80000000u); }
; #define SEL_HADD(idx_) __hip_atomic_fetch_add(&hist[(idx_)], 1u, __ATOMIC_RELAXED, __HIP_MEMORY_SCOPE_WORKGROUP)
; __device__ __forceinline__ void sel_unit(LAS char* lds, int b, int u, const bf16_t* QI, const bf16_t* KIDX, const float* WIDX, unsigned long long* MASK) {
;     ...
;             for (int kh = 0; kh < 2; ++kh) {
;             bf16x8 kf[2][2];
; #pragma unroll
;             for (int kb = 0; kb < 2; ++kb)
; #pragma unroll
;                 for (int ks = 0; ks < 2; ++ks) kf[kb][ks] = *(const bf16x8*)(KIDX + (rowbase + 64 * t + 32 * kh + 16 * kb + q16) * 64 + 32 * ks + 8 * kg);
; #pragma unroll
;             for (int kb = 0; kb < 2; ++kb) {
;                 f32x4 s = (f32x4){0.f, 0.f, 0.f, 0.f};
; #pragma unroll
;                 for (int hh = 0; hh < 8; ++hh) {
;                     f32x4 a = (f32x4){0.f, 0.f, 0.f, 0.f};
; #pragma unroll
;                     for (int ks = 0; ks < 2; ++ks) {
;                         const bf16x8 qv = *(const LAS bf16x8*)(lds + L_QI + q16 * 1024 + (((hh * 8 + 4 * ks + kg) ^ q16) << 4));
;                         a = __builtin_amdgcn_mfma_f32_16x16x32_bf16(kf[kb][ks], qv, a, 0, 0, 0);
;                     }
;                     const float wh = wl[hh * 16];
; #pragma unroll
;                     for (int i = 0; i < 4; ++i) s[i] += wh * fmaxf(a[i], 0.f);
;                 }
;                 u32x4 kk; kk.x = fkey(s[0]); kk.y = fkey(s[1]); kk.z = fkey(s[2]); kk.w = fkey(s[3]);
;                 sc[j][2 * kh + kb] = kk;
; #pragma unroll
;                 for (int i = 0; i < 4; ++i) SEL_HADD((kk[i] >> 24) * 16 + q16);
;                 __builtin_amdgcn_sched_barrier(0);
	v_mul_f32_e32 v106, v48, v30
	v_mul_f32_e32 v108, v49, v28
	ds_read_b128 v[28:31], v102
	s_waitcnt lgkmcnt(1)
	v_mfma_f32_16x16x32_bf16 v[24:27], v[14:17], v[24:27], 0
	v_max_f32_e32 v51, v103, v103
	v_lshl_add_u32 v103, v152, 4, v150
	s_waitcnt lgkmcnt(0)
	v_mfma_f32_16x16x32_bf16 v[24:27], v[10:13], v[28:31], v[24:27]
	ds_read_b128 v[28:31], v103
	v_max_f32_e32 v37, 0, v51
	v_max_f32_e32 v51, 0, v33
	v_max_f32_e32 v52, v104, v104
	v_max_f32_e32 v55, v36, v36
	v_max_f32_e32 v36, 0, v50
	v_max_f32_e32 v50, 0, v32
	v_max_f32_e32 v32, 0, v77
	v_max_f32_e32 v33, 0, v43
	v_lshl_add_u32 v104, v151, 4, v150
	v_pk_mul_f32 v[110:111], v[48:49], v[32:33]
	ds_read_b128 v[32:35], v104
	s_waitcnt lgkmcnt(1)
	v_mfma_f32_16x16x32_bf16 v[14:17], v[14:17], v[28:31], 0
	v_max_f32_e32 v42, 0, v52
	v_max_f32_e32 v38, 0, v54
	v_max_f32_e32 v52, 0, v55
	s_waitcnt lgkmcnt(0)
	v_mfma_f32_16x16x32_bf16 v[10:13], v[10:13], v[32:35], v[14:17]
	v_max_f32_e32 v54, 0, v78
	v_max_f32_e32 v55, 0, v79
	ds_read2_b32 v[78:79], v137 offset0:176 offset1:192
	s_nop 0
	v_max_f32_e32 v28, 0, v27
	s_nop 2
	v_max_f32_e32 v29, 0, v13
	s_waitcnt lgkmcnt(0)
	v_pk_mul_f32 v[14:15], v[78:79], v[28:29]
	v_pk_fma_f32 v[16:17], v[44:45], v[36:37], 0 op_sel_hi:[0,1,0]
	v_mov_b32_e32 v28, v45
	v_pk_fma_f32 v[16:17], v[28:29], v[38:39], v[16:17] op_sel_hi:[0,1,1]
	v_pk_fma_f32 v[16:17], v[46:47], v[40:41], v[16:17] op_sel_hi:[0,1,1]
	v_mov_b32_e32 v28, v47
	v_pk_fma_f32 v[16:17], v[28:29], v[50:51], v[16:17] op_sel_hi:[0,1,1]
	v_pk_fma_f32 v[16:17], v[48:49], v[52:53], v[16:17] op_sel_hi:[0,1,1]
	v_mov_b32_e32 v28, v49
	v_max_f32_e32 v24, 0, v24
	v_max_f32_e32 v25, 0, v25
	v_pk_fma_f32 v[16:17], v[28:29], v[54:55], v[16:17] op_sel_hi:[0,1,1]
	v_max_f32_e32 v10, 0, v10
	v_max_f32_e32 v11, 0, v11
	v_pk_fma_f32 v[16:17], v[78:79], v[24:25], v[16:17] op_sel_hi:[0,1,1]
	v_mov_b32_e32 v24, v79
	v_pk_fma_f32 v[10:11], v[24:25], v[10:11], v[16:17] op_sel_hi:[0,1,1]
	v_and_b32_e32 v17, 0x7fffffff, v11
	v_and_b32_e32 v16, 0x7fffffff, v10
	v_mul_f32_e32 v42, v44, v42
	v_xor_b32_e32 v13, -1, v11
	v_pk_add_f32 v[16:17], v[16:17], 0 neg_lo:[1,1] neg_hi:[1,1]
	v_cmp_gt_i32_e32 vcc, 0, v11
	v_mov_b32_e32 v43, v80
	v_xor_b32_e32 v24, -1, v10
	v_cndmask_b32_e32 v77, v17, v13, vcc
	v_cmp_gt_i32_e32 vcc, 0, v10
	v_pk_add_f32 v[10:11], v[42:43], 0 op_sel_hi:[1,0]
	v_mov_b32_e32 v57, v81
	v_pk_add_f32 v[10:11], v[10:11], v[56:57]
	v_mov_b32_e32 v83, v86
	v_pk_add_f32 v[10:11], v[10:11], v[82:83]
	v_mov_b32_e32 v85, v87
	v_pk_add_f32 v[10:11], v[10:11], v[84:85]
	v_mov_b32_e32 v107, v110
	v_max_f32_e32 v26, 0, v26
	v_pk_add_f32 v[10:11], v[10:11], v[106:107]
	v_mov_b32_e32 v109, v111
	v_mul_f32_e32 v26, v78, v26
	v_max_f32_e32 v12, 0, v12
	v_pk_add_f32 v[10:11], v[10:11], v[108:109]
	v_mov_b32_e32 v27, v14
	v_mul_f32_e32 v12, v79, v12
	v_pk_add_f32 v[10:11], v[10:11], v[26:27]
	v_mov_b32_e32 v13, v15
	v_pk_add_f32 v[10:11], v[10:11], v[12:13]
	v_cndmask_b32_e32 v78, v16, v24, vcc
	v_and_b32_e32 v13, 0x7fffffff, v11
	v_and_b32_e32 v12, 0x7fffffff, v10
	v_xor_b32_e32 v14, -1, v11
	v_pk_add_f32 v[12:13], v[12:13], 0 neg_lo:[1,1] neg_hi:[1,1]
	v_cmp_gt_i32_e32 vcc, 0, v11
	v_xor_b32_e32 v15, -1, v10
	s_nop 0
	v_cndmask_b32_e32 v79, v13, v14, vcc
	v_cmp_gt_i32_e32 vcc, 0, v10
	v_lshrrev_b32_e32 v10, 24, v78
	v_lshl_add_u32 v10, v10, 6, v0
	ds_add_u32 v10, v205 offset:16384
	v_lshrrev_b32_e32 v10, 24, v77
	v_cndmask_b32_e32 v80, v12, v15, vcc
	v_lshl_add_u32 v10, v10, 6, v0
	ds_add_u32 v10, v205 offset:16384
	v_lshrrev_b32_e32 v10, 24, v80
	v_lshl_add_u32 v10, v10, 6, v0
	ds_add_u32 v10, v205 offset:16384
	v_lshrrev_b32_e32 v10, 24, v79
	v_lshl_add_u32 v10, v10, 6, v0
	ds_add_u32 v10, v205 offset:16384
	ds_read_b128 v[10:13], v95
	ds_read_b128 v[14:17], v96
	ds_read_b128 v[24:27], v92
	ds_read_b128 v[28:31], v93
	ds_read2_b32 v[32:33], v137 offset0:80 offset1:96
	ds_read2_b32 v[40:41], v137 offset0:112 offset1:128
	s_waitcnt vmcnt(1) lgkmcnt(5)
	v_mfma_f32_16x16x32_bf16 v[10:13], v[6:9], v[10:13], 0
	ds_read2_b32 v[52:53], v137 offset0:144 offset1:160
	s_waitcnt vmcnt(0) lgkmcnt(5)
	v_mfma_f32_16x16x32_bf16 v[10:13], v[2:5], v[14:17], v[10:13]
	ds_read_b128 v[14:17], v90
	s_waitcnt lgkmcnt(5)
	v_mfma_f32_16x16x32_bf16 v[24:27], v[6:9], v[24:27], 0
	s_nop 4
	v_max_f32_e32 v34, 0, v10
	v_max_f32_e32 v10, 0, v12
	v_max_f32_e32 v35, 0, v11
	s_waitcnt lgkmcnt(3)
	v_mul_f32_e32 v36, v32, v10
	v_max_f32_e32 v38, 0, v13
	v_mfma_f32_16x16x32_bf16 v[10:13], v[2:5], v[28:31], v[24:27]
	s_nop 2
	ds_read_b128 v[24:27], v89
	s_waitcnt lgkmcnt(1)
	v_mfma_f32_16x16x32_bf16 v[14:17], v[6:9], v[14:17], 0
	s_nop 1
	v_max_f32_e32 v28, 0, v10
	v_max_f32_e32 v29, 0, v11
	v_max_f32_e32 v10, 0, v12
	v_mul_f32_e32 v30, v33, v10
	v_max_f32_e32 v39, 0, v13
	s_waitcnt lgkmcnt(0)
	v_mfma_f32_16x16x32_bf16 v[10:13], v[2:5], v[24:27], v[14:17]
	ds_read_b128 v[24:27], v94
	v_pk_mul_f32 v[38:39], v[32:33], v[38:39]
	s_nop 0
	ds_read_b128 v[14:17], v91
	s_waitcnt lgkmcnt(0)
	v_mfma_f32_16x16x32_bf16 v[14:17], v[6:9], v[14:17], 0
	s_nop 1
	v_max_f32_e32 v42, 0, v10
	v_max_f32_e32 v43, 0, v11
	v_max_f32_e32 v10, 0, v12
	v_mul_f32_e32 v44, v40, v10
	s_nop 0
	v_max_f32_e32 v46, 0, v13
	v_mfma_f32_16x16x32_bf16 v[10:13], v[2:5], v[24:27], v[14:17]
	ds_read_b128 v[24:27], v98
	v_mov_b32_e32 v37, v38
	v_mov_b32_e32 v31, v39
	ds_read_b128 v[14:17], v97
	s_waitcnt lgkmcnt(0)
	v_mfma_f32_16x16x32_bf16 v[14:17], v[6:9], v[14:17], 0
	s_nop 1
	v_max_f32_e32 v48, 0, v10
	v_max_f32_e32 v49, 0, v11
	v_max_f32_e32 v10, 0, v12
	v_mul_f32_e32 v50, v41, v10
	s_nop 0
	v_max_f32_e32 v47, 0, v13
	v_mfma_f32_16x16x32_bf16 v[10:13], v[2:5], v[24:27], v[14:17]
	ds_read_b128 v[24:27], v100
	v_pk_mul_f32 v[46:47], v[40:41], v[46:47]
	s_nop 0
	ds_read_b128 v[14:17], v99
	s_waitcnt lgkmcnt(0)
; #define LAS __attribute__((address_space(3)))
; __device__ __forceinline__ unsigned fkey(float f) { const unsigned u = __float_as_uint(f); return (u & 0x80000000u) ? ~u : (u | 0x80000000u); }
; #define SEL_HADD(idx_) __hip_atomic_fetch_add(&hist[(idx_)], 1u, __ATOMIC_RELAXED, __HIP_MEMORY_SCOPE_WORKGROUP)
; __device__ __forceinline__ void sel_unit(LAS char* lds, int b, int u, const bf16_t* QI, const bf16_t* KIDX, const float* WIDX, unsigned long long* MASK) {
;     ...
;             for (int kh = 0; kh < 2; ++kh) {
;             bf16x8 kf[2][2];
; #pragma unroll
;             for (int kb = 0; kb < 2; ++kb)
; #pragma unroll
;                 for (int ks = 0; ks < 2; ++ks) kf[kb][ks] = *(const bf16x8*)(KIDX + (rowbase + 64 * t + 32 * kh + 16 * kb + q16) * 64 + 32 * ks + 8 * kg);
; #pragma unroll
;             for (int kb = 0; kb < 2; ++kb) {
;                 f32x4 s = (f32x4){0.f, 0.f, 0.f, 0.f};
; #pragma unroll
;                 for (int hh = 0; hh < 8; ++hh) {
;                     f32x4 a = (f32x4){0.f, 0.f, 0.f, 0.f};
; #pragma unroll
;                     for (int ks = 0; ks < 2; ++ks) {
;                         const bf16x8 qv = *(const LAS bf16x8*)(lds + L_QI + q16 * 1024 + (((hh * 8 + 4 * ks + kg) ^ q16) << 4));
;                         a = __builtin_amdgcn_mfma_f32_16x16x32_bf16(kf[kb][ks], qv, a, 0, 0, 0);
;                     }
;                     const float wh = wl[hh * 16];
; #pragma unroll
;                     for (int i = 0; i < 4; ++i) s[i] += wh * fmaxf(a[i], 0.f);
;                 }
;                 u32x4 kk; kk.x = fkey(s[0]); kk.y = fkey(s[1]); kk.z = fkey(s[2]); kk.w = fkey(s[3]);
;                 sc[j][2 * kh + kb] = kk;
; #pragma unroll
;                 for (int i = 0; i < 4; ++i) SEL_HADD((kk[i] >> 24) * 16 + q16);
;                 __builtin_amdgcn_sched_barrier(0);
	v_mfma_f32_16x16x32_bf16 v[14:17], v[6:9], v[14:17], 0
	s_nop 1
	v_max_f32_e32 v54, 0, v10
	v_max_f32_e32 v55, 0, v11
	v_max_f32_e32 v10, 0, v12
	v_mul_f32_e32 v56, v52, v10
	s_nop 0
	v_max_f32_e32 v82, 0, v13
	v_mfma_f32_16x16x32_bf16 v[10:13], v[2:5], v[24:27], v[14:17]
	ds_read_b128 v[24:27], v102
	v_mov_b32_e32 v45, v46
	v_mov_b32_e32 v51, v47
	ds_read_b128 v[14:17], v101
	s_waitcnt lgkmcnt(0)
	v_mfma_f32_16x16x32_bf16 v[14:17], v[6:9], v[14:17], 0
	s_nop 1
	v_max_f32_e32 v84, 0, v10
	v_max_f32_e32 v85, 0, v11
	v_max_f32_e32 v10, 0, v12
	v_mul_f32_e32 v86, v53, v10
	s_nop 0
	v_max_f32_e32 v83, 0, v13
	v_mfma_f32_16x16x32_bf16 v[10:13], v[2:5], v[24:27], v[14:17]
	ds_read_b128 v[24:27], v104
	v_pk_mul_f32 v[106:107], v[52:53], v[82:83]
	ds_read2_b32 v[82:83], v137 offset0:176 offset1:192
	ds_read_b128 v[14:17], v103
	s_waitcnt lgkmcnt(0)
	v_mfma_f32_16x16x32_bf16 v[6:9], v[6:9], v[14:17], 0
	s_nop 1
	s_nop 0
	v_max_f32_e32 v14, 0, v13
	s_nop 0
	v_mfma_f32_16x16x32_bf16 v[2:5], v[2:5], v[24:27], v[6:9]
	s_nop 0
	v_max_f32_e32 v10, 0, v10
	v_max_f32_e32 v11, 0, v11
	v_pk_fma_f32 v[8:9], v[32:33], v[34:35], 0 op_sel_hi:[0,1,0]
	s_nop 0
	s_nop 2
	v_max_f32_e32 v15, 0, v5
	v_pk_mul_f32 v[6:7], v[82:83], v[14:15]
	v_mov_b32_e32 v14, v33
	v_pk_fma_f32 v[8:9], v[14:15], v[28:29], v[8:9] op_sel_hi:[0,1,1]
	v_pk_fma_f32 v[8:9], v[40:41], v[42:43], v[8:9] op_sel_hi:[0,1,1]
	v_mov_b32_e32 v14, v41
	v_pk_fma_f32 v[8:9], v[14:15], v[48:49], v[8:9] op_sel_hi:[0,1,1]
	v_pk_fma_f32 v[8:9], v[52:53], v[54:55], v[8:9] op_sel_hi:[0,1,1]
	v_mov_b32_e32 v14, v53
	v_pk_fma_f32 v[8:9], v[14:15], v[84:85], v[8:9] op_sel_hi:[0,1,1]
	v_max_f32_e32 v2, 0, v2
	v_max_f32_e32 v3, 0, v3
	v_pk_fma_f32 v[8:9], v[82:83], v[10:11], v[8:9] op_sel_hi:[0,1,1]
	v_mov_b32_e32 v10, v83
	v_pk_fma_f32 v[2:3], v[10:11], v[2:3], v[8:9] op_sel_hi:[0,1,1]
	v_and_b32_e32 v9, 0x7fffffff, v3
	v_and_b32_e32 v8, 0x7fffffff, v2
	v_xor_b32_e32 v5, -1, v3
	v_pk_add_f32 v[8:9], v[8:9], 0 neg_lo:[1,1] neg_hi:[1,1]
	v_cmp_gt_i32_e32 vcc, 0, v3
	v_xor_b32_e32 v10, -1, v2
	v_mov_b32_e32 v57, v106
	v_cndmask_b32_e32 v81, v9, v5, vcc
	v_cmp_gt_i32_e32 vcc, 0, v2
	v_pk_add_f32 v[2:3], v[36:37], 0 op_sel_hi:[1,0]
	v_max_f32_e32 v12, 0, v12
	v_pk_add_f32 v[2:3], v[2:3], v[30:31]
	v_pk_add_f32 v[2:3], v[2:3], v[44:45]
	v_mov_b32_e32 v87, v107
	v_pk_add_f32 v[2:3], v[2:3], v[50:51]
	v_mul_f32_e32 v12, v82, v12
	v_pk_add_f32 v[2:3], v[2:3], v[56:57]
	v_max_f32_e32 v4, 0, v4
	v_pk_add_f32 v[2:3], v[2:3], v[86:87]
	v_mov_b32_e32 v13, v6
	v_mul_f32_e32 v4, v83, v4
	v_pk_add_f32 v[2:3], v[2:3], v[12:13]
	v_mov_b32_e32 v5, v7
	v_pk_add_f32 v[2:3], v[2:3], v[4:5]
	v_cndmask_b32_e32 v82, v8, v10, vcc
	v_and_b32_e32 v5, 0x7fffffff, v3
	v_and_b32_e32 v4, 0x7fffffff, v2
	v_xor_b32_e32 v6, -1, v3
	v_pk_add_f32 v[4:5], v[4:5], 0 neg_lo:[1,1] neg_hi:[1,1]
	v_cmp_gt_i32_e32 vcc, 0, v3
	v_xor_b32_e32 v7, -1, v2
	s_nop 0
	v_cndmask_b32_e32 v83, v5, v6, vcc
	v_cmp_gt_i32_e32 vcc, 0, v2
	v_lshrrev_b32_e32 v2, 24, v82
	v_lshl_add_u32 v2, v2, 6, v0
	ds_add_u32 v2, v205 offset:16384
	v_lshrrev_b32_e32 v2, 24, v81
	v_cndmask_b32_e32 v84, v4, v7, vcc
	v_lshl_add_u32 v2, v2, 6, v0
	ds_add_u32 v2, v205 offset:16384
	v_lshrrev_b32_e32 v2, 24, v84
	v_lshl_add_u32 v2, v2, 6, v0
	ds_add_u32 v2, v205 offset:16384
	v_lshrrev_b32_e32 v2, 24, v83
	v_lshl_add_u32 v2, v2, 6, v0
	ds_add_u32 v2, v205 offset:16384
	v_add_co_u32_e32 v2, vcc, s96, v22
	s_nop 1
	v_addc_co_u32_e32 v3, vcc, 0, v23, vcc
	global_load_dwordx4 v[14:17], v[2:3], off
	global_load_dwordx4 v[10:13], v[2:3], off offset:64
	global_load_dwordx4 v[6:9], v[2:3], off offset:2048
	s_nop 0
	global_load_dwordx4 v[2:5], v[2:3], off offset:2112
	ds_read_b128 v[22:25], v95
	ds_read_b128 v[26:29], v96
	s_waitcnt vmcnt(3) lgkmcnt(1)
	v_mfma_f32_16x16x32_bf16 v[22:25], v[14:17], v[22:25], 0
	ds_read_b128 v[32:35], v93
	ds_read_b128 v[38:41], v89
	ds_read_b128 v[44:47], v94
	s_waitcnt vmcnt(2) lgkmcnt(3)
	v_mfma_f32_16x16x32_bf16 v[26:29], v[10:13], v[26:29], v[22:25]
	ds_read_b128 v[50:53], v98
	ds_read_b128 v[106:109], v100
	ds_read_b128 v[110:113], v102
	ds_read2_b32 v[24:25], v137 offset0:80 offset1:96
	s_nop 3
	v_max_f32_e32 v26, 0, v26
	v_max_f32_e32 v27, 0, v27
	v_max_f32_e32 v22, v28, v28
	v_max_f32_e32 v23, v29, v29
	ds_read_b128 v[28:31], v92
	s_waitcnt lgkmcnt(0)
	v_mfma_f32_16x16x32_bf16 v[28:31], v[14:17], v[28:31], 0
	v_max_f32_e32 v36, 0, v23
	v_max_f32_e32 v22, 0, v22
	v_mul_f32_e32 v22, v24, v22
	v_mfma_f32_16x16x32_bf16 v[28:31], v[10:13], v[32:35], v[28:31]
	s_nop 7
	v_max_f32_e32 v32, 0, v28
	v_max_f32_e32 v33, 0, v29
	v_max_f32_e32 v23, 0, v30
	v_mul_f32_e32 v28, v25, v23
	v_max_f32_e32 v37, 0, v31
	v_pk_mul_f32 v[30:31], v[24:25], v[36:37]
	ds_read_b128 v[34:37], v90
	s_waitcnt lgkmcnt(0)
	v_mfma_f32_16x16x32_bf16 v[34:37], v[14:17], v[34:37], 0
	v_mov_b32_e32 v29, v31
	v_mfma_f32_16x16x32_bf16 v[38:41], v[10:13], v[38:41], v[34:37]
	s_nop 5
	ds_read2_b32 v[36:37], v137 offset0:112 offset1:128
	s_nop 0
	v_max_f32_e32 v38, 0, v38
	v_max_f32_e32 v39, 0, v39
	v_max_f32_e32 v23, 0, v40
	s_waitcnt lgkmcnt(0)
	v_mul_f32_e32 v34, v36, v23
	v_max_f32_e32 v23, v41, v41
	ds_read_b128 v[40:43], v91
	s_waitcnt lgkmcnt(0)
	v_mfma_f32_16x16x32_bf16 v[40:43], v[14:17], v[40:43], 0
	v_max_f32_e32 v48, 0, v23
	v_mfma_f32_16x16x32_bf16 v[40:43], v[10:13], v[44:47], v[40:43]
	s_nop 7
	v_max_f32_e32 v44, 0, v40
	v_max_f32_e32 v45, 0, v41
	v_max_f32_e32 v23, 0, v42
	v_mul_f32_e32 v40, v37, v23
	v_max_f32_e32 v49, 0, v43
	v_pk_mul_f32 v[42:43], v[36:37], v[48:49]
	ds_read_b128 v[46:49], v97
	s_waitcnt lgkmcnt(0)
; #define LAS __attribute__((address_space(3)))
; __device__ __forceinline__ unsigned fkey(float f) { const unsigned u = __float_as_uint(f); return (u & 0x80000000u) ? ~u : (u | 0x80000000u); }
; #define SEL_HADD(idx_) __hip_atomic_fetch_add(&hist[(idx_)], 1u, __ATOMIC_RELAXED, __HIP_MEMORY_SCOPE_WORKGROUP)
; __device__ __forceinline__ void sel_unit(LAS char* lds, int b, int u, const bf16_t* QI, const bf16_t* KIDX, const float* WIDX, unsigned long long* MASK) {
;     ...
;             for (int kh = 0; kh < 2; ++kh) {
;             bf16x8 kf[2][2];
; #pragma unroll
;             for (int kb = 0; kb < 2; ++kb)
; #pragma unroll
;                 for (int ks = 0; ks < 2; ++ks) kf[kb][ks] = *(const bf16x8*)(KIDX + (rowbase + 64 * t + 32 * kh + 16 * kb + q16) * 64 + 32 * ks + 8 * kg);
; #pragma unroll
;             for (int kb = 0; kb < 2; ++kb) {
;                 f32x4 s = (f32x4){0.f, 0.f, 0.f, 0.f};
; #pragma unroll
;                 for (int hh = 0; hh < 8; ++hh) {
;                     f32x4 a = (f32x4){0.f, 0.f, 0.f, 0.f};
; #pragma unroll
;                     for (int ks = 0; ks < 2; ++ks) {
;                         const bf16x8 qv = *(const LAS bf16x8*)(lds + L_QI + q16 * 1024 + (((hh * 8 + 4 * ks + kg) ^ q16) << 4));
;                         a = __builtin_amdgcn_mfma_f32_16x16x32_bf16(kf[kb][ks], qv, a, 0, 0, 0);
;                     }
;                     const float wh = wl[hh * 16];
; #pragma unroll
;                     for (int i = 0; i < 4; ++i) s[i] += wh * fmaxf(a[i], 0.f);
;                 }
;                 u32x4 kk; kk.x = fkey(s[0]); kk.y = fkey(s[1]); kk.z = fkey(s[2]); kk.w = fkey(s[3]);
;                 sc[j][2 * kh + kb] = kk;
; #pragma unroll
;                 for (int i = 0; i < 4; ++i) SEL_HADD((kk[i] >> 24) * 16 + q16);
;                 __builtin_amdgcn_sched_barrier(0);
	v_mfma_f32_16x16x32_bf16 v[46:49], v[14:17], v[46:49], 0
	v_mov_b32_e32 v35, v42
	v_mov_b32_e32 v41, v43
	v_mfma_f32_16x16x32_bf16 v[50:53], v[10:13], v[50:53], v[46:49]
	s_nop 4
	ds_read2_b32 v[48:49], v137 offset0:144 offset1:160
	s_nop 1
	v_max_f32_e32 v50, 0, v50
	v_max_f32_e32 v51, 0, v51
	v_max_f32_e32 v23, 0, v52
	s_waitcnt lgkmcnt(0)
	v_mul_f32_e32 v46, v48, v23
	v_max_f32_e32 v23, v53, v53
	ds_read_b128 v[52:55], v99
	s_waitcnt lgkmcnt(0)
	v_mfma_f32_16x16x32_bf16 v[52:55], v[14:17], v[52:55], 0
	v_max_f32_e32 v86, 0, v23
	v_mfma_f32_16x16x32_bf16 v[52:55], v[10:13], v[106:109], v[52:55]
	ds_read_b128 v[106:109], v101
	s_waitcnt lgkmcnt(0)
	v_mfma_f32_16x16x32_bf16 v[106:109], v[14:17], v[106:109], 0
	s_nop 4
	v_max_f32_e32 v56, 0, v52
	v_max_f32_e32 v57, 0, v53
	v_max_f32_e32 v23, 0, v54
	v_mfma_f32_16x16x32_bf16 v[106:109], v[10:13], v[110:113], v[106:109]
	v_mul_f32_e32 v52, v49, v23
	s_nop 0
	v_max_f32_e32 v87, 0, v55
	v_pk_mul_f32 v[54:55], v[48:49], v[86:87]
	ds_read2_b32 v[86:87], v137 offset0:176 offset1:192
	s_nop 2
	v_max_f32_e32 v110, 0, v106
	v_max_f32_e32 v111, 0, v107
	v_max_f32_e32 v23, 0, v108
	s_waitcnt lgkmcnt(0)
	v_mul_f32_e32 v112, v86, v23
	v_max_f32_e32 v23, v109, v109
	ds_read_b128 v[106:109], v103
	s_waitcnt lgkmcnt(0)
	v_mfma_f32_16x16x32_bf16 v[14:17], v[14:17], v[106:109], 0
	ds_read_b128 v[106:109], v104
	v_max_f32_e32 v114, 0, v23
	v_mov_b32_e32 v47, v54
	s_waitcnt lgkmcnt(0)
	v_mfma_f32_16x16x32_bf16 v[10:13], v[10:13], v[106:109], v[14:17]
	v_mov_b32_e32 v53, v55
	s_nop 1
	v_pk_fma_f32 v[16:17], v[24:25], v[26:27], 0 op_sel_hi:[0,1,0]
	v_mov_b32_e32 v24, v25
	v_pk_fma_f32 v[16:17], v[24:25], v[32:33], v[16:17] op_sel_hi:[0,1,1]
	v_pk_fma_f32 v[16:17], v[36:37], v[38:39], v[16:17] op_sel_hi:[0,1,1]
	v_mov_b32_e32 v24, v37
	v_pk_fma_f32 v[16:17], v[24:25], v[44:45], v[16:17] op_sel_hi:[0,1,1]
	v_pk_fma_f32 v[16:17], v[48:49], v[50:51], v[16:17] op_sel_hi:[0,1,1]
	v_mov_b32_e32 v24, v49
	v_pk_fma_f32 v[16:17], v[24:25], v[56:57], v[16:17] op_sel_hi:[0,1,1]
	v_max_f32_e32 v10, 0, v10
	v_max_f32_e32 v11, 0, v11
	v_pk_fma_f32 v[16:17], v[86:87], v[110:111], v[16:17] op_sel_hi:[0,1,1]
	v_mov_b32_e32 v24, v87
	v_pk_fma_f32 v[10:11], v[24:25], v[10:11], v[16:17] op_sel_hi:[0,1,1]
	v_and_b32_e32 v17, 0x7fffffff, v11
	v_and_b32_e32 v16, 0x7fffffff, v10
	v_max_f32_e32 v115, 0, v13
	v_xor_b32_e32 v23, -1, v10
	v_pk_add_f32 v[16:17], v[16:17], 0 neg_lo:[1,1] neg_hi:[1,1]
	v_cmp_gt_i32_e32 vcc, 0, v10
	v_pk_mul_f32 v[14:15], v[86:87], v[114:115]
	v_xor_b32_e32 v13, -1, v11
	v_cndmask_b32_e32 v86, v16, v23, vcc
	v_mov_b32_e32 v23, v30
	v_cmp_gt_i32_e64 s[2:3], 0, v11
	v_pk_add_f32 v[10:11], v[22:23], 0 op_sel_hi:[1,0]
	v_pk_add_f32 v[10:11], v[10:11], v[28:29]
	v_max_f32_e32 v12, 0, v12
	v_pk_add_f32 v[10:11], v[10:11], v[34:35]
	v_mov_b32_e32 v113, v14
	v_pk_add_f32 v[10:11], v[10:11], v[40:41]
	v_mul_f32_e32 v12, v87, v12
	v_pk_add_f32 v[10:11], v[10:11], v[46:47]
	v_cndmask_b32_e64 v85, v17, v13, s[2:3]
	v_pk_add_f32 v[10:11], v[10:11], v[52:53]
	v_mov_b32_e32 v13, v15
	v_pk_add_f32 v[10:11], v[10:11], v[112:113]
	s_nop 0
	v_pk_add_f32 v[10:11], v[10:11], v[12:13]
	s_nop 0
	v_xor_b32_e32 v15, -1, v10
	v_and_b32_e32 v12, 0x7fffffff, v10
	v_cmp_gt_i32_e32 vcc, 0, v10
	v_lshrrev_b32_e32 v10, 24, v86
	v_and_b32_e32 v13, 0x7fffffff, v11
	v_lshl_add_u32 v10, v10, 6, v0
	v_pk_add_f32 v[12:13], v[12:13], 0 neg_lo:[1,1] neg_hi:[1,1]
	ds_add_u32 v10, v205 offset:16384
	v_lshrrev_b32_e32 v10, 24, v85
	v_cndmask_b32_e32 v88, v12, v15, vcc
	v_lshl_add_u32 v10, v10, 6, v0
	v_xor_b32_e32 v14, -1, v11
	v_cmp_gt_i32_e64 s[2:3], 0, v11
	ds_add_u32 v10, v205 offset:16384
	v_lshrrev_b32_e32 v10, 24, v88
	v_cndmask_b32_e64 v87, v13, v14, s[2:3]
	v_lshl_add_u32 v10, v10, 6, v0
	ds_add_u32 v10, v205 offset:16384
	v_lshrrev_b32_e32 v10, 24, v87
	v_lshl_add_u32 v10, v10, 6, v0
	ds_add_u32 v10, v205 offset:16384
	ds_read_b128 v[10:13], v95
	ds_read_b128 v[14:17], v96
	ds_read_b128 v[22:25], v92
	ds_read_b128 v[26:29], v93
	ds_read2_b32 v[30:31], v137 offset0:80 offset1:96
	ds_read2_b32 v[38:39], v137 offset0:112 offset1:128
	s_waitcnt vmcnt(1) lgkmcnt(5)
	v_mfma_f32_16x16x32_bf16 v[10:13], v[6:9], v[10:13], 0
	ds_read2_b32 v[50:51], v137 offset0:144 offset1:160
	s_waitcnt vmcnt(0) lgkmcnt(5)
	v_mfma_f32_16x16x32_bf16 v[10:13], v[2:5], v[14:17], v[10:13]
	ds_read_b128 v[14:17], v90
	s_waitcnt lgkmcnt(5)
	v_mfma_f32_16x16x32_bf16 v[22:25], v[6:9], v[22:25], 0
	s_nop 4
	v_max_f32_e32 v32, 0, v10
	v_max_f32_e32 v10, 0, v12
	v_max_f32_e32 v33, 0, v11
	s_waitcnt lgkmcnt(3)
	v_mul_f32_e32 v34, v30, v10
	v_max_f32_e32 v36, 0, v13
	v_mfma_f32_16x16x32_bf16 v[10:13], v[2:5], v[26:29], v[22:25]
	s_nop 2
	ds_read_b128 v[22:25], v89
	s_waitcnt lgkmcnt(1)
	v_mfma_f32_16x16x32_bf16 v[14:17], v[6:9], v[14:17], 0
	s_nop 1
	v_max_f32_e32 v26, 0, v10
	v_max_f32_e32 v27, 0, v11
	v_max_f32_e32 v10, 0, v12
	v_mul_f32_e32 v28, v31, v10
	v_max_f32_e32 v37, 0, v13
	s_waitcnt lgkmcnt(0)
	v_mfma_f32_16x16x32_bf16 v[10:13], v[2:5], v[22:25], v[14:17]
	ds_read_b128 v[22:25], v94
	ds_read2_b32 v[94:95], v137 offset0:176 offset1:192
	v_pk_mul_f32 v[36:37], v[30:31], v[36:37]
	ds_read_b128 v[14:17], v91
	s_waitcnt lgkmcnt(0)
	v_mfma_f32_16x16x32_bf16 v[14:17], v[6:9], v[14:17], 0
	s_nop 1
	v_max_f32_e32 v40, 0, v10
	v_max_f32_e32 v41, 0, v11
	v_max_f32_e32 v10, 0, v12
	v_mul_f32_e32 v42, v38, v10
	s_nop 0
	v_max_f32_e32 v44, 0, v13
	v_mfma_f32_16x16x32_bf16 v[10:13], v[2:5], v[22:25], v[14:17]
	ds_read_b128 v[22:25], v98
	v_mov_b32_e32 v35, v36
	v_mov_b32_e32 v29, v37
	ds_read_b128 v[14:17], v97
	s_waitcnt lgkmcnt(0)
; #define LAS __attribute__((address_space(3)))
; __device__ __forceinline__ unsigned fkey(float f) { const unsigned u = __float_as_uint(f); return (u & 0x80000000u) ? ~u : (u | 0x80000000u); }
; #define SEL_HADD(idx_) __hip_atomic_fetch_add(&hist[(idx_)], 1u, __ATOMIC_RELAXED, __HIP_MEMORY_SCOPE_WORKGROUP)
; __device__ __forceinline__ void sel_unit(LAS char* lds, int b, int u, const bf16_t* QI, const bf16_t* KIDX, const float* WIDX, unsigned long long* MASK) {
;     ...
;     for (int j = 0; j < 8; ++j) {
;         if (j < nj) {
;             int t = wid + 8 * j; asm volatile("" : "+s"(t));
; #pragma unroll
;             for (int kh = 0; kh < 2; ++kh) {
;             bf16x8 kf[2][2];
; #pragma unroll
;             for (int kb = 0; kb < 2; ++kb)
; #pragma unroll
;                 for (int ks = 0; ks < 2; ++ks) kf[kb][ks] = *(const bf16x8*)(KIDX + (rowbase + 64 * t + 32 * kh + 16 * kb + q16) * 64 + 32 * ks + 8 * kg);
; #pragma unroll
;             for (int kb = 0; kb < 2; ++kb) {
;                 f32x4 s = (f32x4){0.f, 0.f, 0.f, 0.f};
; #pragma unroll
;                 for (int hh = 0; hh < 8; ++hh) {
;                     f32x4 a = (f32x4){0.f, 0.f, 0.f, 0.f};
; #pragma unroll
;                     for (int ks = 0; ks < 2; ++ks) {
;                         const bf16x8 qv = *(const LAS bf16x8*)(lds + L_QI + q16 * 1024 + (((hh * 8 + 4 * ks + kg) ^ q16) << 4));
;                         a = __builtin_amdgcn_mfma_f32_16x16x32_bf16(kf[kb][ks], qv, a, 0, 0, 0);
;                     }
;                     const float wh = wl[hh * 16];
; #pragma unroll
;                     for (int i = 0; i < 4; ++i) s[i] += wh * fmaxf(a[i], 0.f);
;                 }
;                 u32x4 kk; kk.x = fkey(s[0]); kk.y = fkey(s[1]); kk.z = fkey(s[2]); kk.w = fkey(s[3]);
;                 sc[j][2 * kh + kb] = kk;
; #pragma unroll
;                 for (int i = 0; i < 4; ++i) SEL_HADD((kk[i] >> 24) * 16 + q16);
;                 __builtin_amdgcn_sched_barrier(0);
	v_mfma_f32_16x16x32_bf16 v[14:17], v[6:9], v[14:17], 0
	s_nop 1
	v_max_f32_e32 v46, 0, v10
	v_max_f32_e32 v47, 0, v11
	v_max_f32_e32 v10, 0, v12
	v_mul_f32_e32 v48, v39, v10
	s_nop 0
	v_max_f32_e32 v45, 0, v13
	v_mfma_f32_16x16x32_bf16 v[10:13], v[2:5], v[22:25], v[14:17]
	ds_read_b128 v[22:25], v100
	v_pk_mul_f32 v[44:45], v[38:39], v[44:45]
	s_nop 0
	ds_read_b128 v[14:17], v99
	s_waitcnt lgkmcnt(0)
	v_mfma_f32_16x16x32_bf16 v[14:17], v[6:9], v[14:17], 0
	s_nop 1
	v_max_f32_e32 v52, 0, v10
	v_max_f32_e32 v53, 0, v11
	v_max_f32_e32 v10, 0, v12
	v_mul_f32_e32 v54, v50, v10
	s_nop 0
	v_max_f32_e32 v56, 0, v13
	v_mfma_f32_16x16x32_bf16 v[10:13], v[2:5], v[22:25], v[14:17]
	ds_read_b128 v[22:25], v102
	v_mov_b32_e32 v43, v44
	v_mov_b32_e32 v49, v45
	ds_read_b128 v[14:17], v101
	s_waitcnt lgkmcnt(0)
	v_mfma_f32_16x16x32_bf16 v[14:17], v[6:9], v[14:17], 0
	s_nop 1
	v_max_f32_e32 v90, 0, v10
	v_max_f32_e32 v91, 0, v11
	v_max_f32_e32 v10, 0, v12
	v_mul_f32_e32 v92, v51, v10
	s_nop 0
	v_max_f32_e32 v57, 0, v13
	v_mfma_f32_16x16x32_bf16 v[10:13], v[2:5], v[22:25], v[14:17]
	ds_read_b128 v[22:25], v104
	v_pk_mul_f32 v[56:57], v[50:51], v[56:57]
	s_nop 0
	ds_read_b128 v[14:17], v103
	s_waitcnt lgkmcnt(0)
	v_mfma_f32_16x16x32_bf16 v[6:9], v[6:9], v[14:17], 0
	s_nop 1
	s_nop 0
	v_max_f32_e32 v14, 0, v13
	s_nop 0
	v_mfma_f32_16x16x32_bf16 v[2:5], v[2:5], v[22:25], v[6:9]
	s_nop 0
	v_max_f32_e32 v10, 0, v10
	v_max_f32_e32 v11, 0, v11
	v_pk_fma_f32 v[8:9], v[30:31], v[32:33], 0 op_sel_hi:[0,1,0]
	s_nop 0
	s_nop 2
	v_max_f32_e32 v15, 0, v5
	v_pk_mul_f32 v[6:7], v[94:95], v[14:15]
	v_mov_b32_e32 v14, v31
	v_pk_fma_f32 v[8:9], v[14:15], v[26:27], v[8:9] op_sel_hi:[0,1,1]
	v_pk_fma_f32 v[8:9], v[38:39], v[40:41], v[8:9] op_sel_hi:[0,1,1]
	v_mov_b32_e32 v14, v39
	v_pk_fma_f32 v[8:9], v[14:15], v[46:47], v[8:9] op_sel_hi:[0,1,1]
	v_pk_fma_f32 v[8:9], v[50:51], v[52:53], v[8:9] op_sel_hi:[0,1,1]
	v_mov_b32_e32 v14, v51
	v_pk_fma_f32 v[8:9], v[14:15], v[90:91], v[8:9] op_sel_hi:[0,1,1]
	v_max_f32_e32 v2, 0, v2
	v_max_f32_e32 v3, 0, v3
	v_pk_fma_f32 v[8:9], v[94:95], v[10:11], v[8:9] op_sel_hi:[0,1,1]
	v_mov_b32_e32 v10, v95
	v_pk_fma_f32 v[2:3], v[10:11], v[2:3], v[8:9] op_sel_hi:[0,1,1]
	v_and_b32_e32 v9, 0x7fffffff, v3
	v_and_b32_e32 v8, 0x7fffffff, v2
	v_xor_b32_e32 v5, -1, v3
	v_pk_add_f32 v[8:9], v[8:9], 0 neg_lo:[1,1] neg_hi:[1,1]
	v_cmp_gt_i32_e32 vcc, 0, v3
	v_xor_b32_e32 v10, -1, v2
	v_mov_b32_e32 v55, v56
	v_cndmask_b32_e32 v89, v9, v5, vcc
	v_cmp_gt_i32_e32 vcc, 0, v2
	v_pk_add_f32 v[2:3], v[34:35], 0 op_sel_hi:[1,0]
	v_max_f32_e32 v12, 0, v12
	v_pk_add_f32 v[2:3], v[2:3], v[28:29]
	v_pk_add_f32 v[2:3], v[2:3], v[42:43]
	v_mov_b32_e32 v93, v57
	v_pk_add_f32 v[2:3], v[2:3], v[48:49]
	v_mul_f32_e32 v12, v94, v12
	v_pk_add_f32 v[2:3], v[2:3], v[54:55]
	v_max_f32_e32 v4, 0, v4
	v_pk_add_f32 v[2:3], v[2:3], v[92:93]
	v_mov_b32_e32 v13, v6
	v_mul_f32_e32 v4, v95, v4
	v_pk_add_f32 v[2:3], v[2:3], v[12:13]
	v_mov_b32_e32 v5, v7
	v_pk_add_f32 v[2:3], v[2:3], v[4:5]
	v_cndmask_b32_e32 v90, v8, v10, vcc
	v_and_b32_e32 v5, 0x7fffffff, v3
	v_and_b32_e32 v4, 0x7fffffff, v2
	v_xor_b32_e32 v6, -1, v3
	v_pk_add_f32 v[4:5], v[4:5], 0 neg_lo:[1,1] neg_hi:[1,1]
	v_cmp_gt_i32_e32 vcc, 0, v3
	v_xor_b32_e32 v7, -1, v2
	s_nop 0
	v_cndmask_b32_e32 v91, v5, v6, vcc
	v_cmp_gt_i32_e32 vcc, 0, v2
	v_lshrrev_b32_e32 v2, 24, v90
	v_lshl_add_u32 v2, v2, 6, v0
	ds_add_u32 v2, v205 offset:16384
	v_lshrrev_b32_e32 v2, 24, v89
	v_cndmask_b32_e32 v92, v4, v7, vcc
	v_lshl_add_u32 v2, v2, 6, v0
	ds_add_u32 v2, v205 offset:16384
	v_lshrrev_b32_e32 v2, 24, v92
	v_lshl_add_u32 v2, v2, 6, v0
	ds_add_u32 v2, v205 offset:16384
	v_lshrrev_b32_e32 v2, 24, v91
	v_lshl_add_u32 v2, v2, 6, v0
	ds_add_u32 v2, v205 offset:16384
.LBB0_660:
	s_cmp_gt_i32 s4, 2
	s_cselect_b64 s[54:55], -1, 0
	s_cmp_lt_i32 s4, 3
	s_cbranch_scc1 .LBB0_662
	s_add_i32 s0, s46, 16
	s_lshl_b32 s0, s0, 6
	s_ashr_i32 s1, s0, 31
	v_lshl_add_u64 v[2:3], v[18:19], 0, s[0:1]
	v_lshlrev_b64 v[2:3], 7, v[2:3]
	v_lshl_add_u64 v[22:23], v[20:21], 0, v[2:3]
	global_load_dwordx4 v[14:17], v[22:23], off
	global_load_dwordx4 v[10:13], v[22:23], off offset:64
	v_lshl_add_u32 v111, v182, 4, v150
	v_lshl_add_u32 v112, v183, 4, v150
	v_lshl_add_u32 v109, v185, 4, v150
	v_lshl_add_u32 v105, v180, 4, v150
	v_lshl_add_u32 v110, v159, 4, v150
	v_lshl_add_u32 v108, v184, 4, v150
	ds_read_b128 v[2:5], v111
	v_lshl_add_u32 v106, v179, 4, v150
	ds_read_b128 v[6:9], v112
	ds_read_b128 v[24:27], v108
	v_lshl_add_u32 v107, v176, 4, v150
	ds_read_b128 v[28:31], v109
	ds_read_b128 v[32:35], v106
	ds_read_b128 v[36:39], v105
	ds_read_b128 v[40:43], v107
	v_lshl_add_u32 v113, v158, 4, v150
	ds_read_b128 v[44:47], v110
	ds_read_b128 v[48:51], v113
	v_lshl_add_u32 v114, v157, 4, v150
	ds_read_b128 v[52:55], v114
	v_lshl_add_u32 v115, v156, 4, v150
	v_lshl_add_u32 v116, v155, 4, v150
	ds_read_b128 v[94:97], v115
	ds_read_b128 v[98:101], v116
	v_lshl_add_u32 v117, v154, 4, v150
	s_waitcnt vmcnt(1) lgkmcnt(11)
	v_mfma_f32_16x16x32_bf16 v[2:5], v[14:17], v[2:5], 0
	s_waitcnt lgkmcnt(9)
	v_mfma_f32_16x16x32_bf16 v[24:27], v[14:17], v[24:27], 0
	s_waitcnt lgkmcnt(7)
	v_mfma_f32_16x16x32_bf16 v[32:35], v[14:17], v[32:35], 0
	s_waitcnt lgkmcnt(5)
	v_mfma_f32_16x16x32_bf16 v[40:43], v[14:17], v[40:43], 0
	s_waitcnt lgkmcnt(3)
	v_mfma_f32_16x16x32_bf16 v[48:51], v[14:17], v[48:51], 0
	s_waitcnt vmcnt(0)
	v_mfma_f32_16x16x32_bf16 v[118:121], v[10:13], v[6:9], v[2:5]
	v_mfma_f32_16x16x32_bf16 v[24:27], v[10:13], v[28:31], v[24:27]
	v_mfma_f32_16x16x32_bf16 v[28:31], v[10:13], v[36:39], v[32:35]
	v_mfma_f32_16x16x32_bf16 v[32:35], v[10:13], v[44:47], v[40:43]
	ds_read2_b32 v[44:45], v137 offset0:80 offset1:96
	ds_read2_b32 v[46:47], v137 offset0:112 offset1:128
	s_nop 3
	s_waitcnt lgkmcnt(4)
; #define LAS __attribute__((address_space(3)))
; __device__ __forceinline__ unsigned fkey(float f) { const unsigned u = __float_as_uint(f); return (u & 0x80000000u) ? ~u : (u | 0x80000000u); }
; #define SEL_HADD(idx_) __hip_atomic_fetch_add(&hist[(idx_)], 1u, __ATOMIC_RELAXED, __HIP_MEMORY_SCOPE_WORKGROUP)
; __device__ __forceinline__ void sel_unit(LAS char* lds, int b, int u, const bf16_t* QI, const bf16_t* KIDX, const float* WIDX, unsigned long long* MASK) {
;     ...
;             for (int kh = 0; kh < 2; ++kh) {
;             bf16x8 kf[2][2];
; #pragma unroll
;             for (int kb = 0; kb < 2; ++kb)
; #pragma unroll
;                 for (int ks = 0; ks < 2; ++ks) kf[kb][ks] = *(const bf16x8*)(KIDX + (rowbase + 64 * t + 32 * kh + 16 * kb + q16) * 64 + 32 * ks + 8 * kg);
; #pragma unroll
;             for (int kb = 0; kb < 2; ++kb) {
;                 f32x4 s = (f32x4){0.f, 0.f, 0.f, 0.f};
; #pragma unroll
;                 for (int hh = 0; hh < 8; ++hh) {
;                     f32x4 a = (f32x4){0.f, 0.f, 0.f, 0.f};
; #pragma unroll
;                     for (int ks = 0; ks < 2; ++ks) {
;                         const bf16x8 qv = *(const LAS bf16x8*)(lds + L_QI + q16 * 1024 + (((hh * 8 + 4 * ks + kg) ^ q16) << 4));
;                         a = __builtin_amdgcn_mfma_f32_16x16x32_bf16(kf[kb][ks], qv, a, 0, 0, 0);
;                     }
;                     const float wh = wl[hh * 16];
; #pragma unroll
;                     for (int i = 0; i < 4; ++i) s[i] += wh * fmaxf(a[i], 0.f);
;                 }
;                 u32x4 kk; kk.x = fkey(s[0]); kk.y = fkey(s[1]); kk.z = fkey(s[2]); kk.w = fkey(s[3]);
;                 sc[j][2 * kh + kb] = kk;
; #pragma unroll
;                 for (int i = 0; i < 4; ++i) SEL_HADD((kk[i] >> 24) * 16 + q16);
;                 __builtin_amdgcn_sched_barrier(0);
	v_mfma_f32_16x16x32_bf16 v[36:39], v[10:13], v[52:55], v[48:51]
	s_nop 0
	ds_read2_b32 v[48:49], v137 offset0:144 offset1:160
	global_load_dwordx4 v[6:9], v[22:23], off offset:2048
	global_load_dwordx4 v[2:5], v[22:23], off offset:2112
	s_waitcnt lgkmcnt(4)
	v_mfma_f32_16x16x32_bf16 v[94:97], v[14:17], v[94:97], 0
	s_nop 0
	v_max_f32_e32 v54, v24, v24
	s_nop 0
	s_waitcnt lgkmcnt(3)
	v_mfma_f32_16x16x32_bf16 v[40:43], v[10:13], v[98:101], v[94:97]
	v_max_f32_e32 v93, v39, v39
	v_max_f32_e32 v24, 0, v121
	v_max_f32_e32 v39, 0, v25
	v_max_f32_e32 v96, 0, v26
	v_max_f32_e32 v25, 0, v27
	v_max_f32_e32 v26, 0, v31
	v_max_f32_e32 v27, 0, v35
	v_max_f32_e32 v53, 0, v37
	s_waitcnt lgkmcnt(2)
	v_mul_f32_e32 v56, v45, v96
	v_pk_mul_f32 v[96:97], v[44:45], v[24:25]
	s_waitcnt lgkmcnt(1)
	v_pk_mul_f32 v[102:103], v[46:47], v[26:27]
	ds_read_b128 v[24:27], v117
	v_max_f32_e32 v94, v40, v40
	v_max_f32_e32 v40, 0, v28
	v_max_f32_e32 v28, 0, v30
	v_max_f32_e32 v50, v118, v118
	v_max_f32_e32 v95, v41, v41
	v_max_f32_e32 v41, 0, v29
	v_max_f32_e32 v29, 0, v34
	v_max_f32_e32 v30, 0, v38
	v_mul_f32_e32 v98, v46, v28
	v_max_f32_e32 v28, 0, v42
	v_lshl_add_u32 v118, v153, 4, v150
	v_mul_f32_e32 v100, v47, v29
	s_waitcnt lgkmcnt(1)
	v_mul_f32_e32 v122, v48, v30
	v_mul_f32_e32 v124, v49, v28
	ds_read_b128 v[28:31], v118
	s_waitcnt lgkmcnt(1)
	v_mfma_f32_16x16x32_bf16 v[24:27], v[14:17], v[24:27], 0
	v_max_f32_e32 v51, v119, v119
	v_lshl_add_u32 v119, v152, 4, v150
	s_waitcnt lgkmcnt(0)
	v_mfma_f32_16x16x32_bf16 v[24:27], v[10:13], v[28:31], v[24:27]
	ds_read_b128 v[28:31], v119
	v_max_f32_e32 v37, 0, v51
	v_max_f32_e32 v51, 0, v33
	v_max_f32_e32 v52, v120, v120
	v_max_f32_e32 v55, v36, v36
	v_max_f32_e32 v36, 0, v50
	v_max_f32_e32 v50, 0, v32
	v_max_f32_e32 v32, 0, v93
	v_max_f32_e32 v33, 0, v43
	v_lshl_add_u32 v120, v151, 4, v150
	v_pk_mul_f32 v[126:127], v[48:49], v[32:33]
	ds_read_b128 v[32:35], v120
	s_waitcnt lgkmcnt(1)
	v_mfma_f32_16x16x32_bf16 v[14:17], v[14:17], v[28:31], 0
	v_max_f32_e32 v42, 0, v52
	v_max_f32_e32 v38, 0, v54
	v_max_f32_e32 v52, 0, v55
	s_waitcnt lgkmcnt(0)
	v_mfma_f32_16x16x32_bf16 v[10:13], v[10:13], v[32:35], v[14:17]
	v_max_f32_e32 v54, 0, v94
	v_max_f32_e32 v55, 0, v95
	ds_read2_b32 v[94:95], v137 offset0:176 offset1:192
	s_nop 0
	v_max_f32_e32 v28, 0, v27
	s_nop 2
	v_max_f32_e32 v29, 0, v13
	s_waitcnt lgkmcnt(0)
	v_pk_mul_f32 v[14:15], v[94:95], v[28:29]
	v_pk_fma_f32 v[16:17], v[44:45], v[36:37], 0 op_sel_hi:[0,1,0]
	v_mov_b32_e32 v28, v45
	v_pk_fma_f32 v[16:17], v[28:29], v[38:39], v[16:17] op_sel_hi:[0,1,1]
	v_pk_fma_f32 v[16:17], v[46:47], v[40:41], v[16:17] op_sel_hi:[0,1,1]
	v_mov_b32_e32 v28, v47
	v_pk_fma_f32 v[16:17], v[28:29], v[50:51], v[16:17] op_sel_hi:[0,1,1]
	v_pk_fma_f32 v[16:17], v[48:49], v[52:53], v[16:17] op_sel_hi:[0,1,1]
	v_mov_b32_e32 v28, v49
	v_max_f32_e32 v24, 0, v24
	v_max_f32_e32 v25, 0, v25
	v_pk_fma_f32 v[16:17], v[28:29], v[54:55], v[16:17] op_sel_hi:[0,1,1]
	v_max_f32_e32 v10, 0, v10
	v_max_f32_e32 v11, 0, v11
	v_pk_fma_f32 v[16:17], v[94:95], v[24:25], v[16:17] op_sel_hi:[0,1,1]
	v_mov_b32_e32 v24, v95
	v_pk_fma_f32 v[10:11], v[24:25], v[10:11], v[16:17] op_sel_hi:[0,1,1]
	v_and_b32_e32 v17, 0x7fffffff, v11
	v_and_b32_e32 v16, 0x7fffffff, v10
	v_mul_f32_e32 v42, v44, v42
	v_xor_b32_e32 v13, -1, v11
	v_pk_add_f32 v[16:17], v[16:17], 0 neg_lo:[1,1] neg_hi:[1,1]
	v_cmp_gt_i32_e32 vcc, 0, v11
	v_mov_b32_e32 v43, v96
	v_xor_b32_e32 v24, -1, v10
	v_cndmask_b32_e32 v93, v17, v13, vcc
	v_cmp_gt_i32_e32 vcc, 0, v10
	v_pk_add_f32 v[10:11], v[42:43], 0 op_sel_hi:[1,0]
	v_mov_b32_e32 v57, v97
	v_pk_add_f32 v[10:11], v[10:11], v[56:57]
	v_mov_b32_e32 v99, v102
	v_pk_add_f32 v[10:11], v[10:11], v[98:99]
	v_mov_b32_e32 v101, v103
	v_pk_add_f32 v[10:11], v[10:11], v[100:101]
	v_mov_b32_e32 v123, v126
	v_max_f32_e32 v26, 0, v26
	v_pk_add_f32 v[10:11], v[10:11], v[122:123]
	v_mov_b32_e32 v125, v127
	v_mul_f32_e32 v26, v94, v26
	v_max_f32_e32 v12, 0, v12
	v_pk_add_f32 v[10:11], v[10:11], v[124:125]
	v_mov_b32_e32 v27, v14
	v_mul_f32_e32 v12, v95, v12
	v_pk_add_f32 v[10:11], v[10:11], v[26:27]
	v_mov_b32_e32 v13, v15
	v_pk_add_f32 v[10:11], v[10:11], v[12:13]
	v_cndmask_b32_e32 v94, v16, v24, vcc
	v_and_b32_e32 v13, 0x7fffffff, v11
	v_and_b32_e32 v12, 0x7fffffff, v10
	v_xor_b32_e32 v14, -1, v11
	v_pk_add_f32 v[12:13], v[12:13], 0 neg_lo:[1,1] neg_hi:[1,1]
	v_cmp_gt_i32_e32 vcc, 0, v11
	v_xor_b32_e32 v15, -1, v10
	s_nop 0
	v_cndmask_b32_e32 v95, v13, v14, vcc
	v_cmp_gt_i32_e32 vcc, 0, v10
	v_lshrrev_b32_e32 v10, 24, v94
	v_lshl_add_u32 v10, v10, 6, v0
	ds_add_u32 v10, v205 offset:16384
	v_lshrrev_b32_e32 v10, 24, v93
	v_cndmask_b32_e32 v96, v12, v15, vcc
	v_lshl_add_u32 v10, v10, 6, v0
	ds_add_u32 v10, v205 offset:16384
	v_lshrrev_b32_e32 v10, 24, v96
	v_lshl_add_u32 v10, v10, 6, v0
	ds_add_u32 v10, v205 offset:16384
	v_lshrrev_b32_e32 v10, 24, v95
	v_lshl_add_u32 v10, v10, 6, v0
	ds_add_u32 v10, v205 offset:16384
	ds_read_b128 v[10:13], v111
	ds_read_b128 v[14:17], v112
	ds_read_b128 v[24:27], v108
	ds_read_b128 v[28:31], v109
	ds_read2_b32 v[50:51], v137 offset0:144 offset1:160
	s_waitcnt vmcnt(1) lgkmcnt(4)
	v_mfma_f32_16x16x32_bf16 v[10:13], v[6:9], v[10:13], 0
	ds_read_b128 v[38:41], v110
	ds_read_b128 v[44:47], v114
	s_waitcnt lgkmcnt(4)
	v_mfma_f32_16x16x32_bf16 v[24:27], v[6:9], v[24:27], 0
	s_waitcnt vmcnt(0)
	v_mfma_f32_16x16x32_bf16 v[14:17], v[2:5], v[14:17], v[10:13]
	s_waitcnt lgkmcnt(3)
	v_mfma_f32_16x16x32_bf16 v[26:29], v[2:5], v[28:31], v[24:27]
	s_nop 0
	ds_read2_b32 v[12:13], v137 offset0:80 offset1:96
	s_nop 3
	v_max_f32_e32 v32, 0, v17
	v_max_f32_e32 v14, 0, v14
	v_max_f32_e32 v26, 0, v26
	v_max_f32_e32 v27, 0, v27
	v_max_f32_e32 v11, 0, v28
	v_max_f32_e32 v15, 0, v15
	v_max_f32_e32 v10, v16, v16
	s_waitcnt lgkmcnt(0)
; #define LAS __attribute__((address_space(3)))
; __device__ __forceinline__ unsigned fkey(float f) { const unsigned u = __float_as_uint(f); return (u & 0x80000000u) ? ~u : (u | 0x80000000u); }
; #define SEL_HADD(idx_) __hip_atomic_fetch_add(&hist[(idx_)], 1u, __ATOMIC_RELAXED, __HIP_MEMORY_SCOPE_WORKGROUP)
; __device__ __forceinline__ void sel_unit(LAS char* lds, int b, int u, const bf16_t* QI, const bf16_t* KIDX, const float* WIDX, unsigned long long* MASK) {
;     ...
;             for (int kh = 0; kh < 2; ++kh) {
;             bf16x8 kf[2][2];
; #pragma unroll
;             for (int kb = 0; kb < 2; ++kb)
; #pragma unroll
;                 for (int ks = 0; ks < 2; ++ks) kf[kb][ks] = *(const bf16x8*)(KIDX + (rowbase + 64 * t + 32 * kh + 16 * kb + q16) * 64 + 32 * ks + 8 * kg);
; #pragma unroll
;             for (int kb = 0; kb < 2; ++kb) {
;                 f32x4 s = (f32x4){0.f, 0.f, 0.f, 0.f};
; #pragma unroll
;                 for (int hh = 0; hh < 8; ++hh) {
;                     f32x4 a = (f32x4){0.f, 0.f, 0.f, 0.f};
; #pragma unroll
;                     for (int ks = 0; ks < 2; ++ks) {
;                         const bf16x8 qv = *(const LAS bf16x8*)(lds + L_QI + q16 * 1024 + (((hh * 8 + 4 * ks + kg) ^ q16) << 4));
;                         a = __builtin_amdgcn_mfma_f32_16x16x32_bf16(kf[kb][ks], qv, a, 0, 0, 0);
;                     }
;                     const float wh = wl[hh * 16];
; #pragma unroll
;                     for (int i = 0; i < 4; ++i) s[i] += wh * fmaxf(a[i], 0.f);
;                 }
;                 u32x4 kk; kk.x = fkey(s[0]); kk.y = fkey(s[1]); kk.z = fkey(s[2]); kk.w = fkey(s[3]);
;                 sc[j][2 * kh + kb] = kk;
; #pragma unroll
;                 for (int i = 0; i < 4; ++i) SEL_HADD((kk[i] >> 24) * 16 + q16);
;                 __builtin_amdgcn_sched_barrier(0);
	v_mul_f32_e32 v16, v13, v11
	v_max_f32_e32 v11, v29, v29
	ds_read_b128 v[28:31], v106
	v_max_f32_e32 v33, 0, v11
	v_pk_mul_f32 v[24:25], v[12:13], v[32:33]
	ds_read_b128 v[32:35], v105
	s_waitcnt lgkmcnt(1)
	v_mfma_f32_16x16x32_bf16 v[28:31], v[6:9], v[28:31], 0
	v_max_f32_e32 v10, 0, v10
	v_mul_f32_e32 v10, v12, v10
	v_mov_b32_e32 v17, v25
	s_waitcnt lgkmcnt(0)
	v_mfma_f32_16x16x32_bf16 v[32:35], v[2:5], v[32:35], v[28:31]
	s_nop 2
	ds_read2_b32 v[30:31], v137 offset0:112 offset1:128
	s_nop 3
	v_max_f32_e32 v32, 0, v32
	v_max_f32_e32 v33, 0, v33
	v_max_f32_e32 v11, 0, v34
	s_waitcnt lgkmcnt(0)
	v_mul_f32_e32 v28, v30, v11
	v_max_f32_e32 v11, v35, v35
	ds_read_b128 v[34:37], v107
	s_waitcnt lgkmcnt(0)
	v_mfma_f32_16x16x32_bf16 v[34:37], v[6:9], v[34:37], 0
	v_max_f32_e32 v42, 0, v11
	v_mfma_f32_16x16x32_bf16 v[34:37], v[2:5], v[38:41], v[34:37]
	s_nop 7
	v_max_f32_e32 v38, 0, v34
	v_max_f32_e32 v39, 0, v35
	v_max_f32_e32 v11, 0, v36
	v_mul_f32_e32 v34, v31, v11
	v_max_f32_e32 v43, 0, v37
	v_pk_mul_f32 v[36:37], v[30:31], v[42:43]
	ds_read_b128 v[40:43], v113
	s_waitcnt lgkmcnt(0)
	v_mfma_f32_16x16x32_bf16 v[40:43], v[6:9], v[40:43], 0
	v_mov_b32_e32 v29, v36
	v_mov_b32_e32 v35, v37
	v_mfma_f32_16x16x32_bf16 v[40:43], v[2:5], v[44:47], v[40:43]
	ds_read_b128 v[46:49], v116
	s_nop 6
	v_max_f32_e32 v52, 0, v40
	v_max_f32_e32 v53, 0, v41
	v_max_f32_e32 v11, 0, v42
	v_mul_f32_e32 v40, v50, v11
	v_max_f32_e32 v11, v43, v43
	ds_read_b128 v[42:45], v115
	s_waitcnt lgkmcnt(0)
	v_mfma_f32_16x16x32_bf16 v[42:45], v[6:9], v[42:45], 0
	v_max_f32_e32 v54, 0, v11
	v_mfma_f32_16x16x32_bf16 v[42:45], v[2:5], v[46:49], v[42:45]
	ds_read_b128 v[46:49], v118
	s_nop 6
	v_max_f32_e32 v56, 0, v42
	v_max_f32_e32 v57, 0, v43
	v_max_f32_e32 v11, 0, v44
	v_mul_f32_e32 v100, v51, v11
	v_max_f32_e32 v11, v45, v45
	ds_read_b128 v[42:45], v117
	s_waitcnt lgkmcnt(0)
	v_mfma_f32_16x16x32_bf16 v[42:45], v[6:9], v[42:45], 0
	v_max_f32_e32 v55, 0, v11
	v_pk_mul_f32 v[54:55], v[50:51], v[54:55]
	v_mfma_f32_16x16x32_bf16 v[42:45], v[2:5], v[46:49], v[42:45]
	ds_read2_b32 v[46:47], v137 offset0:176 offset1:192
	v_mov_b32_e32 v41, v54
	v_mov_b32_e32 v101, v55
	s_nop 4
	v_max_f32_e32 v48, 0, v42
	v_max_f32_e32 v49, 0, v43
	v_max_f32_e32 v11, 0, v44
	s_waitcnt lgkmcnt(0)
	v_mul_f32_e32 v102, v46, v11
	v_max_f32_e32 v11, v45, v45
	ds_read_b128 v[42:45], v119
	s_waitcnt lgkmcnt(0)
	v_mfma_f32_16x16x32_bf16 v[6:9], v[6:9], v[42:45], 0
	ds_read_b128 v[42:45], v120
	v_max_f32_e32 v98, 0, v11
	s_waitcnt lgkmcnt(0)
	v_mfma_f32_16x16x32_bf16 v[2:5], v[2:5], v[42:45], v[6:9]
	s_nop 3
	v_fma_f32 v8, v12, v14, 0
	v_fma_f32 v9, v12, v15, 0
	v_mov_b32_e32 v12, v13
	v_pk_fma_f32 v[8:9], v[12:13], v[26:27], v[8:9] op_sel_hi:[0,1,1]
	v_pk_fma_f32 v[8:9], v[30:31], v[32:33], v[8:9] op_sel_hi:[0,1,1]
	v_mov_b32_e32 v12, v31
	v_pk_fma_f32 v[8:9], v[12:13], v[38:39], v[8:9] op_sel_hi:[0,1,1]
	v_pk_fma_f32 v[8:9], v[50:51], v[52:53], v[8:9] op_sel_hi:[0,1,1]
	v_mov_b32_e32 v12, v51
	v_pk_fma_f32 v[8:9], v[12:13], v[56:57], v[8:9] op_sel_hi:[0,1,1]
	v_max_f32_e32 v2, 0, v2
	v_max_f32_e32 v3, 0, v3
	v_pk_fma_f32 v[8:9], v[46:47], v[48:49], v[8:9] op_sel_hi:[0,1,1]
	v_mov_b32_e32 v12, v47
	v_pk_fma_f32 v[2:3], v[12:13], v[2:3], v[8:9] op_sel_hi:[0,1,1]
	v_and_b32_e32 v9, 0x7fffffff, v3
	v_and_b32_e32 v8, 0x7fffffff, v2
	v_max_f32_e32 v99, 0, v5
	v_xor_b32_e32 v11, -1, v2
	v_pk_add_f32 v[8:9], v[8:9], 0 neg_lo:[1,1] neg_hi:[1,1]
	v_cmp_gt_i32_e32 vcc, 0, v2
	v_pk_mul_f32 v[6:7], v[46:47], v[98:99]
	v_xor_b32_e32 v5, -1, v3
	v_cndmask_b32_e32 v98, v8, v11, vcc
	v_mov_b32_e32 v11, v24
	v_cmp_gt_i32_e64 s[2:3], 0, v3
	v_pk_add_f32 v[2:3], v[10:11], 0 op_sel_hi:[1,0]
	v_pk_add_f32 v[2:3], v[2:3], v[16:17]
	v_max_f32_e32 v4, 0, v4
	v_pk_add_f32 v[2:3], v[2:3], v[28:29]
	v_mov_b32_e32 v103, v6
	v_pk_add_f32 v[2:3], v[2:3], v[34:35]
	v_mul_f32_e32 v4, v47, v4
	v_pk_add_f32 v[2:3], v[2:3], v[40:41]
	v_cndmask_b32_e64 v97, v9, v5, s[2:3]
	v_pk_add_f32 v[2:3], v[2:3], v[100:101]
	v_mov_b32_e32 v5, v7
	v_pk_add_f32 v[2:3], v[2:3], v[102:103]
	s_nop 0
	v_pk_add_f32 v[2:3], v[2:3], v[4:5]
	s_nop 0
	v_xor_b32_e32 v7, -1, v2
	v_and_b32_e32 v4, 0x7fffffff, v2
	v_cmp_gt_i32_e32 vcc, 0, v2
	v_lshrrev_b32_e32 v2, 24, v98
	v_and_b32_e32 v5, 0x7fffffff, v3
	v_lshl_add_u32 v2, v2, 6, v0
	v_pk_add_f32 v[4:5], v[4:5], 0 neg_lo:[1,1] neg_hi:[1,1]
	ds_add_u32 v2, v205 offset:16384
	v_lshrrev_b32_e32 v2, 24, v97
	v_cndmask_b32_e32 v100, v4, v7, vcc
	v_lshl_add_u32 v2, v2, 6, v0
	v_xor_b32_e32 v6, -1, v3
	v_cmp_gt_i32_e64 s[2:3], 0, v3
	ds_add_u32 v2, v205 offset:16384
	v_lshrrev_b32_e32 v2, 24, v100
	v_cndmask_b32_e64 v99, v5, v6, s[2:3]
	v_lshl_add_u32 v2, v2, 6, v0
	ds_add_u32 v2, v205 offset:16384
	v_lshrrev_b32_e32 v2, 24, v99
	v_lshl_add_u32 v2, v2, 6, v0
	ds_add_u32 v2, v205 offset:16384
	v_add_co_u32_e32 v2, vcc, s96, v22
	s_nop 1
	v_addc_co_u32_e32 v3, vcc, 0, v23, vcc
	global_load_dwordx4 v[14:17], v[2:3], off
	global_load_dwordx4 v[10:13], v[2:3], off offset:64
	global_load_dwordx4 v[6:9], v[2:3], off offset:2048
	s_nop 0
	global_load_dwordx4 v[2:5], v[2:3], off offset:2112
	ds_read_b128 v[22:25], v111
	ds_read_b128 v[26:29], v112
	s_waitcnt vmcnt(3) lgkmcnt(1)
	v_mfma_f32_16x16x32_bf16 v[22:25], v[14:17], v[22:25], 0
	ds_read_b128 v[32:35], v109
	ds_read_b128 v[38:41], v105
	ds_read_b128 v[44:47], v110
	s_waitcnt vmcnt(2) lgkmcnt(3)
	v_mfma_f32_16x16x32_bf16 v[26:29], v[10:13], v[26:29], v[22:25]
	ds_read_b128 v[50:53], v114
	ds_read_b128 v[122:125], v116
	ds_read_b128 v[126:129], v118
	ds_read2_b32 v[24:25], v137 offset0:80 offset1:96
	s_nop 3
	v_max_f32_e32 v26, 0, v26
	v_max_f32_e32 v27, 0, v27
	v_max_f32_e32 v22, v28, v28
	v_max_f32_e32 v23, v29, v29
	ds_read_b128 v[28:31], v108
	s_waitcnt lgkmcnt(0)
; #define LAS __attribute__((address_space(3)))
; __device__ __forceinline__ unsigned fkey(float f) { const unsigned u = __float_as_uint(f); return (u & 0x80000000u) ? ~u : (u | 0x80000000u); }
; #define SEL_HADD(idx_) __hip_atomic_fetch_add(&hist[(idx_)], 1u, __ATOMIC_RELAXED, __HIP_MEMORY_SCOPE_WORKGROUP)
; __device__ __forceinline__ void sel_unit(LAS char* lds, int b, int u, const bf16_t* QI, const bf16_t* KIDX, const float* WIDX, unsigned long long* MASK) {
;     ...
;             for (int kh = 0; kh < 2; ++kh) {
;             bf16x8 kf[2][2];
; #pragma unroll
;             for (int kb = 0; kb < 2; ++kb)
; #pragma unroll
;                 for (int ks = 0; ks < 2; ++ks) kf[kb][ks] = *(const bf16x8*)(KIDX + (rowbase + 64 * t + 32 * kh + 16 * kb + q16) * 64 + 32 * ks + 8 * kg);
; #pragma unroll
;             for (int kb = 0; kb < 2; ++kb) {
;                 f32x4 s = (f32x4){0.f, 0.f, 0.f, 0.f};
; #pragma unroll
;                 for (int hh = 0; hh < 8; ++hh) {
;                     f32x4 a = (f32x4){0.f, 0.f, 0.f, 0.f};
; #pragma unroll
;                     for (int ks = 0; ks < 2; ++ks) {
;                         const bf16x8 qv = *(const LAS bf16x8*)(lds + L_QI + q16 * 1024 + (((hh * 8 + 4 * ks + kg) ^ q16) << 4));
;                         a = __builtin_amdgcn_mfma_f32_16x16x32_bf16(kf[kb][ks], qv, a, 0, 0, 0);
;                     }
;                     const float wh = wl[hh * 16];
; #pragma unroll
;                     for (int i = 0; i < 4; ++i) s[i] += wh * fmaxf(a[i], 0.f);
;                 }
;                 u32x4 kk; kk.x = fkey(s[0]); kk.y = fkey(s[1]); kk.z = fkey(s[2]); kk.w = fkey(s[3]);
;                 sc[j][2 * kh + kb] = kk;
; #pragma unroll
;                 for (int i = 0; i < 4; ++i) SEL_HADD((kk[i] >> 24) * 16 + q16);
;                 __builtin_amdgcn_sched_barrier(0);
	v_mfma_f32_16x16x32_bf16 v[28:31], v[14:17], v[28:31], 0
	v_max_f32_e32 v36, 0, v23
	v_max_f32_e32 v22, 0, v22
	v_mul_f32_e32 v22, v24, v22
	v_mfma_f32_16x16x32_bf16 v[28:31], v[10:13], v[32:35], v[28:31]
	s_nop 7
	v_max_f32_e32 v32, 0, v28
	v_max_f32_e32 v33, 0, v29
	v_max_f32_e32 v23, 0, v30
	v_mul_f32_e32 v28, v25, v23
	v_max_f32_e32 v37, 0, v31
	v_pk_mul_f32 v[30:31], v[24:25], v[36:37]
	ds_read_b128 v[34:37], v106
	s_waitcnt lgkmcnt(0)
	v_mfma_f32_16x16x32_bf16 v[34:37], v[14:17], v[34:37], 0
	v_mov_b32_e32 v29, v31
	v_mfma_f32_16x16x32_bf16 v[38:41], v[10:13], v[38:41], v[34:37]
	s_nop 5
	ds_read2_b32 v[36:37], v137 offset0:112 offset1:128
	s_nop 0
	v_max_f32_e32 v38, 0, v38
	v_max_f32_e32 v39, 0, v39
	v_max_f32_e32 v23, 0, v40
	s_waitcnt lgkmcnt(0)
	v_mul_f32_e32 v34, v36, v23
	v_max_f32_e32 v23, v41, v41
	ds_read_b128 v[40:43], v107
	s_waitcnt lgkmcnt(0)
	v_mfma_f32_16x16x32_bf16 v[40:43], v[14:17], v[40:43], 0
	v_max_f32_e32 v48, 0, v23
	v_mfma_f32_16x16x32_bf16 v[40:43], v[10:13], v[44:47], v[40:43]
	s_nop 7
	v_max_f32_e32 v44, 0, v40
	v_max_f32_e32 v45, 0, v41
	v_max_f32_e32 v23, 0, v42
	v_mul_f32_e32 v40, v37, v23
	v_max_f32_e32 v49, 0, v43
	v_pk_mul_f32 v[42:43], v[36:37], v[48:49]
	ds_read_b128 v[46:49], v113
	s_waitcnt lgkmcnt(0)
	v_mfma_f32_16x16x32_bf16 v[46:49], v[14:17], v[46:49], 0
	v_mov_b32_e32 v35, v42
	v_mov_b32_e32 v41, v43
	v_mfma_f32_16x16x32_bf16 v[50:53], v[10:13], v[50:53], v[46:49]
	s_nop 4
	ds_read2_b32 v[48:49], v137 offset0:144 offset1:160
	s_nop 1
	v_max_f32_e32 v50, 0, v50
	v_max_f32_e32 v51, 0, v51
	v_max_f32_e32 v23, 0, v52
	s_waitcnt lgkmcnt(0)
	v_mul_f32_e32 v46, v48, v23
	v_max_f32_e32 v23, v53, v53
	ds_read_b128 v[52:55], v115
	s_waitcnt lgkmcnt(0)
	v_mfma_f32_16x16x32_bf16 v[52:55], v[14:17], v[52:55], 0
	v_max_f32_e32 v102, 0, v23
	v_mfma_f32_16x16x32_bf16 v[52:55], v[10:13], v[122:125], v[52:55]
	ds_read_b128 v[122:125], v117
	s_waitcnt lgkmcnt(0)
	v_mfma_f32_16x16x32_bf16 v[122:125], v[14:17], v[122:125], 0
	s_nop 4
	v_max_f32_e32 v56, 0, v52
	v_max_f32_e32 v57, 0, v53
	v_max_f32_e32 v23, 0, v54
	v_mfma_f32_16x16x32_bf16 v[122:125], v[10:13], v[126:129], v[122:125]
	v_mul_f32_e32 v52, v49, v23
	s_nop 0
	v_max_f32_e32 v103, 0, v55
	v_pk_mul_f32 v[54:55], v[48:49], v[102:103]
	ds_read2_b32 v[102:103], v137 offset0:176 offset1:192
	s_nop 2
	v_max_f32_e32 v126, 0, v122
	v_max_f32_e32 v127, 0, v123
	v_max_f32_e32 v23, 0, v124
	s_waitcnt lgkmcnt(0)
	v_mul_f32_e32 v128, v102, v23
	v_max_f32_e32 v23, v125, v125
	ds_read_b128 v[122:125], v119
	s_waitcnt lgkmcnt(0)
	v_mfma_f32_16x16x32_bf16 v[14:17], v[14:17], v[122:125], 0
	ds_read_b128 v[122:125], v120
	v_max_f32_e32 v130, 0, v23
	v_mov_b32_e32 v47, v54
	s_waitcnt lgkmcnt(0)
	v_mfma_f32_16x16x32_bf16 v[10:13], v[10:13], v[122:125], v[14:17]
	v_mov_b32_e32 v53, v55
	s_nop 1
	v_pk_fma_f32 v[16:17], v[24:25], v[26:27], 0 op_sel_hi:[0,1,0]
	v_mov_b32_e32 v24, v25
	v_pk_fma_f32 v[16:17], v[24:25], v[32:33], v[16:17] op_sel_hi:[0,1,1]
	v_pk_fma_f32 v[16:17], v[36:37], v[38:39], v[16:17] op_sel_hi:[0,1,1]
	v_mov_b32_e32 v24, v37
	v_pk_fma_f32 v[16:17], v[24:25], v[44:45], v[16:17] op_sel_hi:[0,1,1]
	v_pk_fma_f32 v[16:17], v[48:49], v[50:51], v[16:17] op_sel_hi:[0,1,1]
	v_mov_b32_e32 v24, v49
	v_pk_fma_f32 v[16:17], v[24:25], v[56:57], v[16:17] op_sel_hi:[0,1,1]
	v_max_f32_e32 v10, 0, v10
	v_max_f32_e32 v11, 0, v11
	v_pk_fma_f32 v[16:17], v[102:103], v[126:127], v[16:17] op_sel_hi:[0,1,1]
	v_mov_b32_e32 v24, v103
	v_pk_fma_f32 v[10:11], v[24:25], v[10:11], v[16:17] op_sel_hi:[0,1,1]
	v_and_b32_e32 v17, 0x7fffffff, v11
	v_and_b32_e32 v16, 0x7fffffff, v10
	v_max_f32_e32 v131, 0, v13
	v_xor_b32_e32 v23, -1, v10
	v_pk_add_f32 v[16:17], v[16:17], 0 neg_lo:[1,1] neg_hi:[1,1]
	v_cmp_gt_i32_e32 vcc, 0, v10
	v_pk_mul_f32 v[14:15], v[102:103], v[130:131]
	v_xor_b32_e32 v13, -1, v11
	v_cndmask_b32_e32 v102, v16, v23, vcc
	v_mov_b32_e32 v23, v30
	v_cmp_gt_i32_e64 s[2:3], 0, v11
	v_pk_add_f32 v[10:11], v[22:23], 0 op_sel_hi:[1,0]
	v_pk_add_f32 v[10:11], v[10:11], v[28:29]
	v_max_f32_e32 v12, 0, v12
	v_pk_add_f32 v[10:11], v[10:11], v[34:35]
	v_mov_b32_e32 v129, v14
	v_pk_add_f32 v[10:11], v[10:11], v[40:41]
	v_mul_f32_e32 v12, v103, v12
	v_pk_add_f32 v[10:11], v[10:11], v[46:47]
	v_cndmask_b32_e64 v101, v17, v13, s[2:3]
	v_pk_add_f32 v[10:11], v[10:11], v[52:53]
	v_mov_b32_e32 v13, v15
	v_pk_add_f32 v[10:11], v[10:11], v[128:129]
	s_nop 0
	v_pk_add_f32 v[10:11], v[10:11], v[12:13]
	s_nop 0
	v_xor_b32_e32 v15, -1, v10
	v_and_b32_e32 v12, 0x7fffffff, v10
	v_cmp_gt_i32_e32 vcc, 0, v10
	v_lshrrev_b32_e32 v10, 24, v102
	v_and_b32_e32 v13, 0x7fffffff, v11
	v_lshl_add_u32 v10, v10, 6, v0
	v_pk_add_f32 v[12:13], v[12:13], 0 neg_lo:[1,1] neg_hi:[1,1]
	ds_add_u32 v10, v205 offset:16384
	v_lshrrev_b32_e32 v10, 24, v101
	v_cndmask_b32_e32 v104, v12, v15, vcc
	v_lshl_add_u32 v10, v10, 6, v0
	v_xor_b32_e32 v14, -1, v11
	v_cmp_gt_i32_e64 s[2:3], 0, v11
	ds_add_u32 v10, v205 offset:16384
	v_lshrrev_b32_e32 v10, 24, v104
	v_cndmask_b32_e64 v103, v13, v14, s[2:3]
	v_lshl_add_u32 v10, v10, 6, v0
	ds_add_u32 v10, v205 offset:16384
	v_lshrrev_b32_e32 v10, 24, v103
	v_lshl_add_u32 v10, v10, 6, v0
	ds_add_u32 v10, v205 offset:16384
	ds_read_b128 v[10:13], v111
	ds_read_b128 v[14:17], v112
	ds_read_b128 v[22:25], v108
	ds_read_b128 v[26:29], v109
	ds_read2_b32 v[30:31], v137 offset0:80 offset1:96
	ds_read2_b32 v[38:39], v137 offset0:112 offset1:128
	s_waitcnt vmcnt(1) lgkmcnt(5)
	v_mfma_f32_16x16x32_bf16 v[10:13], v[6:9], v[10:13], 0
	ds_read2_b32 v[50:51], v137 offset0:144 offset1:160
	s_waitcnt vmcnt(0) lgkmcnt(5)
	v_mfma_f32_16x16x32_bf16 v[10:13], v[2:5], v[14:17], v[10:13]
	ds_read_b128 v[14:17], v106
	s_waitcnt lgkmcnt(5)
; #define LAS __attribute__((address_space(3)))
; __device__ __forceinline__ unsigned fkey(float f) { const unsigned u = __float_as_uint(f); return (u & 0x80000000u) ? ~u : (u | 0x80000000u); }
; #define SEL_HADD(idx_) __hip_atomic_fetch_add(&hist[(idx_)], 1u, __ATOMIC_RELAXED, __HIP_MEMORY_SCOPE_WORKGROUP)
; __device__ __forceinline__ void sel_unit(LAS char* lds, int b, int u, const bf16_t* QI, const bf16_t* KIDX, const float* WIDX, unsigned long long* MASK) {
;     ...
;             for (int kh = 0; kh < 2; ++kh) {
;             bf16x8 kf[2][2];
; #pragma unroll
;             for (int kb = 0; kb < 2; ++kb)
; #pragma unroll
;                 for (int ks = 0; ks < 2; ++ks) kf[kb][ks] = *(const bf16x8*)(KIDX + (rowbase + 64 * t + 32 * kh + 16 * kb + q16) * 64 + 32 * ks + 8 * kg);
; #pragma unroll
;             for (int kb = 0; kb < 2; ++kb) {
;                 f32x4 s = (f32x4){0.f, 0.f, 0.f, 0.f};
; #pragma unroll
;                 for (int hh = 0; hh < 8; ++hh) {
;                     f32x4 a = (f32x4){0.f, 0.f, 0.f, 0.f};
; #pragma unroll
;                     for (int ks = 0; ks < 2; ++ks) {
;                         const bf16x8 qv = *(const LAS bf16x8*)(lds + L_QI + q16 * 1024 + (((hh * 8 + 4 * ks + kg) ^ q16) << 4));
;                         a = __builtin_amdgcn_mfma_f32_16x16x32_bf16(kf[kb][ks], qv, a, 0, 0, 0);
;                     }
;                     const float wh = wl[hh * 16];
; #pragma unroll
;                     for (int i = 0; i < 4; ++i) s[i] += wh * fmaxf(a[i], 0.f);
;                 }
;                 u32x4 kk; kk.x = fkey(s[0]); kk.y = fkey(s[1]); kk.z = fkey(s[2]); kk.w = fkey(s[3]);
;                 sc[j][2 * kh + kb] = kk;
; #pragma unroll
;                 for (int i = 0; i < 4; ++i) SEL_HADD((kk[i] >> 24) * 16 + q16);
;                 __builtin_amdgcn_sched_barrier(0);
	v_mfma_f32_16x16x32_bf16 v[22:25], v[6:9], v[22:25], 0
	s_nop 4
	v_max_f32_e32 v32, 0, v10
	v_max_f32_e32 v10, 0, v12
	v_max_f32_e32 v33, 0, v11
	s_waitcnt lgkmcnt(3)
	v_mul_f32_e32 v34, v30, v10
	v_max_f32_e32 v36, 0, v13
	v_mfma_f32_16x16x32_bf16 v[10:13], v[2:5], v[26:29], v[22:25]
	s_nop 2
	ds_read_b128 v[22:25], v105
	s_waitcnt lgkmcnt(1)
	v_mfma_f32_16x16x32_bf16 v[14:17], v[6:9], v[14:17], 0
	s_nop 1
	v_max_f32_e32 v26, 0, v10
	v_max_f32_e32 v27, 0, v11
	v_max_f32_e32 v10, 0, v12
	v_mul_f32_e32 v28, v31, v10
	v_max_f32_e32 v37, 0, v13
	s_waitcnt lgkmcnt(0)
	v_mfma_f32_16x16x32_bf16 v[10:13], v[2:5], v[22:25], v[14:17]
	ds_read_b128 v[22:25], v110
	ds_read2_b32 v[110:111], v137 offset0:176 offset1:192
	v_pk_mul_f32 v[36:37], v[30:31], v[36:37]
	ds_read_b128 v[14:17], v107
	s_waitcnt lgkmcnt(0)
	v_mfma_f32_16x16x32_bf16 v[14:17], v[6:9], v[14:17], 0
	s_nop 1
	v_max_f32_e32 v40, 0, v10
	v_max_f32_e32 v41, 0, v11
	v_max_f32_e32 v10, 0, v12
	v_mul_f32_e32 v42, v38, v10
	s_nop 0
	v_max_f32_e32 v44, 0, v13
	v_mfma_f32_16x16x32_bf16 v[10:13], v[2:5], v[22:25], v[14:17]
	ds_read_b128 v[22:25], v114
	v_mov_b32_e32 v35, v36
	v_mov_b32_e32 v29, v37
	ds_read_b128 v[14:17], v113
	s_waitcnt lgkmcnt(0)
	v_mfma_f32_16x16x32_bf16 v[14:17], v[6:9], v[14:17], 0
	s_nop 1
	v_max_f32_e32 v46, 0, v10
	v_max_f32_e32 v47, 0, v11
	v_max_f32_e32 v10, 0, v12
	v_mul_f32_e32 v48, v39, v10
	s_nop 0
	v_max_f32_e32 v45, 0, v13
	v_mfma_f32_16x16x32_bf16 v[10:13], v[2:5], v[22:25], v[14:17]
	ds_read_b128 v[22:25], v116
	v_pk_mul_f32 v[44:45], v[38:39], v[44:45]
	s_nop 0
	ds_read_b128 v[14:17], v115
	s_waitcnt lgkmcnt(0)
	v_mfma_f32_16x16x32_bf16 v[14:17], v[6:9], v[14:17], 0
	s_nop 1
	v_max_f32_e32 v52, 0, v10
	v_max_f32_e32 v53, 0, v11
	v_max_f32_e32 v10, 0, v12
	v_mul_f32_e32 v54, v50, v10
	s_nop 0
	v_max_f32_e32 v56, 0, v13
	v_mfma_f32_16x16x32_bf16 v[10:13], v[2:5], v[22:25], v[14:17]
	ds_read_b128 v[22:25], v118
	v_mov_b32_e32 v43, v44
	v_mov_b32_e32 v49, v45
	ds_read_b128 v[14:17], v117
	s_waitcnt lgkmcnt(0)
	v_mfma_f32_16x16x32_bf16 v[14:17], v[6:9], v[14:17], 0
	s_nop 1
	v_max_f32_e32 v106, 0, v10
	v_max_f32_e32 v107, 0, v11
	v_max_f32_e32 v10, 0, v12
	v_mul_f32_e32 v108, v51, v10
	s_nop 0
	v_max_f32_e32 v57, 0, v13
	v_mfma_f32_16x16x32_bf16 v[10:13], v[2:5], v[22:25], v[14:17]
	ds_read_b128 v[22:25], v120
	v_pk_mul_f32 v[56:57], v[50:51], v[56:57]
	s_nop 0
	ds_read_b128 v[14:17], v119
	s_waitcnt lgkmcnt(0)
	v_mfma_f32_16x16x32_bf16 v[6:9], v[6:9], v[14:17], 0
	s_nop 1
	s_nop 0
	v_max_f32_e32 v14, 0, v13
	s_nop 0
	v_mfma_f32_16x16x32_bf16 v[2:5], v[2:5], v[22:25], v[6:9]
	s_nop 0
	v_max_f32_e32 v10, 0, v10
	v_max_f32_e32 v11, 0, v11
	v_pk_fma_f32 v[8:9], v[30:31], v[32:33], 0 op_sel_hi:[0,1,0]
	s_nop 0
	s_nop 2
	v_max_f32_e32 v15, 0, v5
	v_pk_mul_f32 v[6:7], v[110:111], v[14:15]
	v_mov_b32_e32 v14, v31
	v_pk_fma_f32 v[8:9], v[14:15], v[26:27], v[8:9] op_sel_hi:[0,1,1]
	v_pk_fma_f32 v[8:9], v[38:39], v[40:41], v[8:9] op_sel_hi:[0,1,1]
	v_mov_b32_e32 v14, v39
	v_pk_fma_f32 v[8:9], v[14:15], v[46:47], v[8:9] op_sel_hi:[0,1,1]
	v_pk_fma_f32 v[8:9], v[50:51], v[52:53], v[8:9] op_sel_hi:[0,1,1]
	v_mov_b32_e32 v14, v51
	v_pk_fma_f32 v[8:9], v[14:15], v[106:107], v[8:9] op_sel_hi:[0,1,1]
	v_max_f32_e32 v2, 0, v2
	v_max_f32_e32 v3, 0, v3
	v_pk_fma_f32 v[8:9], v[110:111], v[10:11], v[8:9] op_sel_hi:[0,1,1]
	v_mov_b32_e32 v10, v111
	v_pk_fma_f32 v[2:3], v[10:11], v[2:3], v[8:9] op_sel_hi:[0,1,1]
	v_and_b32_e32 v9, 0x7fffffff, v3
	v_and_b32_e32 v8, 0x7fffffff, v2
	v_xor_b32_e32 v5, -1, v3
	v_pk_add_f32 v[8:9], v[8:9], 0 neg_lo:[1,1] neg_hi:[1,1]
	v_cmp_gt_i32_e32 vcc, 0, v3
	v_xor_b32_e32 v10, -1, v2
	v_mov_b32_e32 v55, v56
	v_cndmask_b32_e32 v105, v9, v5, vcc
	v_cmp_gt_i32_e32 vcc, 0, v2
	v_pk_add_f32 v[2:3], v[34:35], 0 op_sel_hi:[1,0]
	v_max_f32_e32 v12, 0, v12
	v_pk_add_f32 v[2:3], v[2:3], v[28:29]
	v_pk_add_f32 v[2:3], v[2:3], v[42:43]
	v_mov_b32_e32 v109, v57
	v_pk_add_f32 v[2:3], v[2:3], v[48:49]
	v_mul_f32_e32 v12, v110, v12
	v_pk_add_f32 v[2:3], v[2:3], v[54:55]
	v_max_f32_e32 v4, 0, v4
	v_pk_add_f32 v[2:3], v[2:3], v[108:109]
	v_mov_b32_e32 v13, v6
	v_mul_f32_e32 v4, v111, v4
	v_pk_add_f32 v[2:3], v[2:3], v[12:13]
	v_mov_b32_e32 v5, v7
	v_pk_add_f32 v[2:3], v[2:3], v[4:5]
	v_cndmask_b32_e32 v106, v8, v10, vcc
	v_and_b32_e32 v5, 0x7fffffff, v3
	v_and_b32_e32 v4, 0x7fffffff, v2
	v_xor_b32_e32 v6, -1, v3
	v_pk_add_f32 v[4:5], v[4:5], 0 neg_lo:[1,1] neg_hi:[1,1]
	v_cmp_gt_i32_e32 vcc, 0, v3
	v_xor_b32_e32 v7, -1, v2
	s_nop 0
	v_cndmask_b32_e32 v107, v5, v6, vcc
	v_cmp_gt_i32_e32 vcc, 0, v2
	v_lshrrev_b32_e32 v2, 24, v106
	v_lshl_add_u32 v2, v2, 6, v0
	ds_add_u32 v2, v205 offset:16384
	v_lshrrev_b32_e32 v2, 24, v105
	v_cndmask_b32_e32 v108, v4, v7, vcc
	v_lshl_add_u32 v2, v2, 6, v0
	ds_add_u32 v2, v205 offset:16384
	v_lshrrev_b32_e32 v2, 24, v108
	v_lshl_add_u32 v2, v2, 6, v0
	ds_add_u32 v2, v205 offset:16384
	v_lshrrev_b32_e32 v2, 24, v107
	v_lshl_add_u32 v2, v2, 6, v0
	ds_add_u32 v2, v205 offset:16384
; #define LAS __attribute__((address_space(3)))
; __device__ __forceinline__ unsigned fkey(float f) { const unsigned u = __float_as_uint(f); return (u & 0x80000000u) ? ~u : (u | 0x80000000u); }
; #define SEL_HADD(idx_) __hip_atomic_fetch_add(&hist[(idx_)], 1u, __ATOMIC_RELAXED, __HIP_MEMORY_SCOPE_WORKGROUP)
; __device__ __forceinline__ void sel_unit(LAS char* lds, int b, int u, const bf16_t* QI, const bf16_t* KIDX, const float* WIDX, unsigned long long* MASK) {
;     ...
;     for (int j = 0; j < 8; ++j) {
;         if (j < nj) {
;             int t = wid + 8 * j; asm volatile("" : "+s"(t));
; #pragma unroll
;             for (int kh = 0; kh < 2; ++kh) {
;             bf16x8 kf[2][2];
; #pragma unroll
;             for (int kb = 0; kb < 2; ++kb)
; #pragma unroll
;                 for (int ks = 0; ks < 2; ++ks) kf[kb][ks] = *(const bf16x8*)(KIDX + (rowbase + 64 * t + 32 * kh + 16 * kb + q16) * 64 + 32 * ks + 8 * kg);
; #pragma unroll
;             for (int kb = 0; kb < 2; ++kb) {
;                 f32x4 s = (f32x4){0.f, 0.f, 0.f, 0.f};
; #pragma unroll
;                 for (int hh = 0; hh < 8; ++hh) {
;                     f32x4 a = (f32x4){0.f, 0.f, 0.f, 0.f};
; #pragma unroll
;                     for (int ks = 0; ks < 2; ++ks) {
;                         const bf16x8 qv = *(const LAS bf16x8*)(lds + L_QI + q16 * 1024 + (((hh * 8 + 4 * ks + kg) ^ q16) << 4));
;                         a = __builtin_amdgcn_mfma_f32_16x16x32_bf16(kf[kb][ks], qv, a, 0, 0, 0);
;                     }
;                     const float wh = wl[hh * 16];
; #pragma unroll
;                     for (int i = 0; i < 4; ++i) s[i] += wh * fmaxf(a[i], 0.f);
;                 }
;                 u32x4 kk; kk.x = fkey(s[0]); kk.y = fkey(s[1]); kk.z = fkey(s[2]); kk.w = fkey(s[3]);
;                 sc[j][2 * kh + kb] = kk;
; #pragma unroll
;                 for (int i = 0; i < 4; ++i) SEL_HADD((kk[i] >> 24) * 16 + q16);
;                 __builtin_amdgcn_sched_barrier(0);
.LBB0_662:
	s_cmp_gt_i32 s4, 3
	s_cselect_b64 s[56:57], -1, 0
	s_cmp_lt_i32 s4, 4
	s_cbranch_scc1 .LBB0_664
	s_add_i32 s0, s46, 24
	s_lshl_b32 s0, s0, 6
	s_ashr_i32 s1, s0, 31
	v_lshl_add_u64 v[2:3], v[18:19], 0, s[0:1]
	v_lshlrev_b64 v[2:3], 7, v[2:3]
	v_lshl_add_u64 v[22:23], v[20:21], 0, v[2:3]
	global_load_dwordx4 v[14:17], v[22:23], off
	global_load_dwordx4 v[10:13], v[22:23], off offset:64
	v_lshl_add_u32 v127, v182, 4, v150
	v_lshl_add_u32 v128, v183, 4, v150
	v_lshl_add_u32 v125, v185, 4, v150
	v_lshl_add_u32 v121, v180, 4, v150
	v_lshl_add_u32 v126, v159, 4, v150
	v_lshl_add_u32 v124, v184, 4, v150
	ds_read_b128 v[2:5], v127
	v_lshl_add_u32 v122, v179, 4, v150
	ds_read_b128 v[6:9], v128
	ds_read_b128 v[24:27], v124
	v_lshl_add_u32 v123, v176, 4, v150
	ds_read_b128 v[28:31], v125
	ds_read_b128 v[32:35], v122
	ds_read_b128 v[36:39], v121
	ds_read_b128 v[40:43], v123
	v_lshl_add_u32 v129, v158, 4, v150
	ds_read_b128 v[44:47], v126
	ds_read_b128 v[48:51], v129
	v_lshl_add_u32 v130, v157, 4, v150
	ds_read_b128 v[52:55], v130
	v_lshl_add_u32 v131, v156, 4, v150
	v_lshl_add_u32 v132, v155, 4, v150
	ds_read_b128 v[110:113], v131
	ds_read_b128 v[114:117], v132
	v_lshl_add_u32 v133, v154, 4, v150
	v_lshl_add_u32 v134, v153, 4, v150
	v_lshl_add_u32 v135, v152, 4, v150
	v_lshl_add_u32 v136, v151, 4, v150
	s_waitcnt vmcnt(1) lgkmcnt(11)
	v_mfma_f32_16x16x32_bf16 v[2:5], v[14:17], v[2:5], 0
	s_waitcnt lgkmcnt(9)
	v_mfma_f32_16x16x32_bf16 v[24:27], v[14:17], v[24:27], 0
	s_waitcnt lgkmcnt(7)
	v_mfma_f32_16x16x32_bf16 v[32:35], v[14:17], v[32:35], 0
	s_waitcnt lgkmcnt(5)
	v_mfma_f32_16x16x32_bf16 v[40:43], v[14:17], v[40:43], 0
	s_waitcnt lgkmcnt(3)
	v_mfma_f32_16x16x32_bf16 v[48:51], v[14:17], v[48:51], 0
	s_waitcnt vmcnt(0)
	v_mfma_f32_16x16x32_bf16 v[138:141], v[10:13], v[6:9], v[2:5]
	v_mfma_f32_16x16x32_bf16 v[24:27], v[10:13], v[28:31], v[24:27]
	v_mfma_f32_16x16x32_bf16 v[28:31], v[10:13], v[36:39], v[32:35]
	v_mfma_f32_16x16x32_bf16 v[32:35], v[10:13], v[44:47], v[40:43]
	ds_read2_b32 v[44:45], v137 offset0:80 offset1:96
	ds_read2_b32 v[46:47], v137 offset0:112 offset1:128
	s_nop 3
	s_waitcnt lgkmcnt(4)
	v_mfma_f32_16x16x32_bf16 v[36:39], v[10:13], v[52:55], v[48:51]
	s_nop 0
	ds_read2_b32 v[48:49], v137 offset0:144 offset1:160
	global_load_dwordx4 v[6:9], v[22:23], off offset:2048
	global_load_dwordx4 v[2:5], v[22:23], off offset:2112
	s_waitcnt lgkmcnt(4)
	v_mfma_f32_16x16x32_bf16 v[110:113], v[14:17], v[110:113], 0
	s_nop 0
	v_max_f32_e32 v54, v24, v24
	s_nop 0
	s_waitcnt lgkmcnt(3)
	v_mfma_f32_16x16x32_bf16 v[40:43], v[10:13], v[114:117], v[110:113]
	v_max_f32_e32 v109, v39, v39
	v_max_f32_e32 v24, 0, v141
	v_max_f32_e32 v39, 0, v25
	v_max_f32_e32 v112, 0, v26
	v_max_f32_e32 v25, 0, v27
	v_max_f32_e32 v26, 0, v31
	v_max_f32_e32 v27, 0, v35
	v_max_f32_e32 v53, 0, v37
	s_waitcnt lgkmcnt(2)
	v_mul_f32_e32 v56, v45, v112
	v_pk_mul_f32 v[112:113], v[44:45], v[24:25]
	s_waitcnt lgkmcnt(1)
	v_pk_mul_f32 v[118:119], v[46:47], v[26:27]
	ds_read_b128 v[24:27], v133
	v_max_f32_e32 v110, v40, v40
	v_max_f32_e32 v40, 0, v28
	v_max_f32_e32 v28, 0, v30
	v_max_f32_e32 v111, v41, v41
	v_max_f32_e32 v41, 0, v29
	v_max_f32_e32 v29, 0, v34
	v_max_f32_e32 v30, 0, v38
	v_mul_f32_e32 v114, v46, v28
	v_max_f32_e32 v28, 0, v42
	v_max_f32_e32 v50, v138, v138
	v_max_f32_e32 v52, v140, v140
	v_mul_f32_e32 v116, v47, v29
	s_waitcnt lgkmcnt(1)
	v_mul_f32_e32 v138, v48, v30
	v_mul_f32_e32 v140, v49, v28
	ds_read_b128 v[28:31], v134
	s_waitcnt lgkmcnt(1)
	v_mfma_f32_16x16x32_bf16 v[24:27], v[14:17], v[24:27], 0
	s_waitcnt lgkmcnt(0)
	v_mfma_f32_16x16x32_bf16 v[24:27], v[10:13], v[28:31], v[24:27]
	ds_read_b128 v[28:31], v135
	v_max_f32_e32 v37, 0, v139
	v_max_f32_e32 v51, 0, v33
	v_max_f32_e32 v55, v36, v36
	v_max_f32_e32 v36, 0, v50
	v_max_f32_e32 v50, 0, v32
	v_max_f32_e32 v32, 0, v109
	v_max_f32_e32 v33, 0, v43
	v_pk_mul_f32 v[142:143], v[48:49], v[32:33]
	ds_read_b128 v[32:35], v136
	s_waitcnt lgkmcnt(1)
	v_mfma_f32_16x16x32_bf16 v[14:17], v[14:17], v[28:31], 0
	v_max_f32_e32 v42, 0, v52
	v_max_f32_e32 v38, 0, v54
	v_max_f32_e32 v52, 0, v55
	s_waitcnt lgkmcnt(0)
	v_mfma_f32_16x16x32_bf16 v[10:13], v[10:13], v[32:35], v[14:17]
	v_max_f32_e32 v54, 0, v110
	v_max_f32_e32 v55, 0, v111
	ds_read2_b32 v[110:111], v137 offset0:176 offset1:192
	s_nop 0
	v_max_f32_e32 v28, 0, v27
	s_nop 2
	v_max_f32_e32 v29, 0, v13
	s_waitcnt lgkmcnt(0)
; #define LAS __attribute__((address_space(3)))
; __device__ __forceinline__ unsigned fkey(float f) { const unsigned u = __float_as_uint(f); return (u & 0x80000000u) ? ~u : (u | 0x80000000u); }
; #define SEL_HADD(idx_) __hip_atomic_fetch_add(&hist[(idx_)], 1u, __ATOMIC_RELAXED, __HIP_MEMORY_SCOPE_WORKGROUP)
; __device__ __forceinline__ void sel_unit(LAS char* lds, int b, int u, const bf16_t* QI, const bf16_t* KIDX, const float* WIDX, unsigned long long* MASK) {
;     ...
;             for (int kh = 0; kh < 2; ++kh) {
;             bf16x8 kf[2][2];
; #pragma unroll
;             for (int kb = 0; kb < 2; ++kb)
; #pragma unroll
;                 for (int ks = 0; ks < 2; ++ks) kf[kb][ks] = *(const bf16x8*)(KIDX + (rowbase + 64 * t + 32 * kh + 16 * kb + q16) * 64 + 32 * ks + 8 * kg);
; #pragma unroll
;             for (int kb = 0; kb < 2; ++kb) {
;                 f32x4 s = (f32x4){0.f, 0.f, 0.f, 0.f};
; #pragma unroll
;                 for (int hh = 0; hh < 8; ++hh) {
;                     f32x4 a = (f32x4){0.f, 0.f, 0.f, 0.f};
; #pragma unroll
;                     for (int ks = 0; ks < 2; ++ks) {
;                         const bf16x8 qv = *(const LAS bf16x8*)(lds + L_QI + q16 * 1024 + (((hh * 8 + 4 * ks + kg) ^ q16) << 4));
;                         a = __builtin_amdgcn_mfma_f32_16x16x32_bf16(kf[kb][ks], qv, a, 0, 0, 0);
;                     }
;                     const float wh = wl[hh * 16];
; #pragma unroll
;                     for (int i = 0; i < 4; ++i) s[i] += wh * fmaxf(a[i], 0.f);
;                 }
;                 u32x4 kk; kk.x = fkey(s[0]); kk.y = fkey(s[1]); kk.z = fkey(s[2]); kk.w = fkey(s[3]);
;                 sc[j][2 * kh + kb] = kk;
; #pragma unroll
;                 for (int i = 0; i < 4; ++i) SEL_HADD((kk[i] >> 24) * 16 + q16);
;                 __builtin_amdgcn_sched_barrier(0);
	v_pk_mul_f32 v[14:15], v[110:111], v[28:29]
	v_pk_fma_f32 v[16:17], v[44:45], v[36:37], 0 op_sel_hi:[0,1,0]
	v_mov_b32_e32 v28, v45
	v_pk_fma_f32 v[16:17], v[28:29], v[38:39], v[16:17] op_sel_hi:[0,1,1]
	v_pk_fma_f32 v[16:17], v[46:47], v[40:41], v[16:17] op_sel_hi:[0,1,1]
	v_mov_b32_e32 v28, v47
	v_pk_fma_f32 v[16:17], v[28:29], v[50:51], v[16:17] op_sel_hi:[0,1,1]
	v_pk_fma_f32 v[16:17], v[48:49], v[52:53], v[16:17] op_sel_hi:[0,1,1]
	v_mov_b32_e32 v28, v49
	v_max_f32_e32 v24, 0, v24
	v_max_f32_e32 v25, 0, v25
	v_pk_fma_f32 v[16:17], v[28:29], v[54:55], v[16:17] op_sel_hi:[0,1,1]
	v_max_f32_e32 v10, 0, v10
	v_max_f32_e32 v11, 0, v11
	v_pk_fma_f32 v[16:17], v[110:111], v[24:25], v[16:17] op_sel_hi:[0,1,1]
	v_mov_b32_e32 v24, v111
	v_pk_fma_f32 v[10:11], v[24:25], v[10:11], v[16:17] op_sel_hi:[0,1,1]
	v_and_b32_e32 v17, 0x7fffffff, v11
	v_and_b32_e32 v16, 0x7fffffff, v10
	v_mul_f32_e32 v42, v44, v42
	v_xor_b32_e32 v13, -1, v11
	v_pk_add_f32 v[16:17], v[16:17], 0 neg_lo:[1,1] neg_hi:[1,1]
	v_cmp_gt_i32_e32 vcc, 0, v11
	v_mov_b32_e32 v43, v112
	v_xor_b32_e32 v24, -1, v10
	v_cndmask_b32_e32 v109, v17, v13, vcc
	v_cmp_gt_i32_e32 vcc, 0, v10
	v_pk_add_f32 v[10:11], v[42:43], 0 op_sel_hi:[1,0]
	v_mov_b32_e32 v57, v113
	v_pk_add_f32 v[10:11], v[10:11], v[56:57]
	v_mov_b32_e32 v115, v118
	v_pk_add_f32 v[10:11], v[10:11], v[114:115]
	v_mov_b32_e32 v117, v119
	v_pk_add_f32 v[10:11], v[10:11], v[116:117]
	v_mov_b32_e32 v139, v142
	v_max_f32_e32 v26, 0, v26
	v_pk_add_f32 v[10:11], v[10:11], v[138:139]
	v_mov_b32_e32 v141, v143
	v_mul_f32_e32 v26, v110, v26
	v_max_f32_e32 v12, 0, v12
	v_pk_add_f32 v[10:11], v[10:11], v[140:141]
	v_mov_b32_e32 v27, v14
	v_mul_f32_e32 v12, v111, v12
	v_pk_add_f32 v[10:11], v[10:11], v[26:27]
	v_mov_b32_e32 v13, v15
	v_pk_add_f32 v[10:11], v[10:11], v[12:13]
	v_cndmask_b32_e32 v110, v16, v24, vcc
	v_and_b32_e32 v13, 0x7fffffff, v11
	v_and_b32_e32 v12, 0x7fffffff, v10
	v_xor_b32_e32 v14, -1, v11
	v_pk_add_f32 v[12:13], v[12:13], 0 neg_lo:[1,1] neg_hi:[1,1]
	v_cmp_gt_i32_e32 vcc, 0, v11
	v_xor_b32_e32 v15, -1, v10
	s_nop 0
	v_cndmask_b32_e32 v111, v13, v14, vcc
	v_cmp_gt_i32_e32 vcc, 0, v10
	v_lshrrev_b32_e32 v10, 24, v110
	v_lshl_add_u32 v10, v10, 6, v0
	ds_add_u32 v10, v205 offset:16384
	v_lshrrev_b32_e32 v10, 24, v109
	v_cndmask_b32_e32 v112, v12, v15, vcc
	v_lshl_add_u32 v10, v10, 6, v0
	ds_add_u32 v10, v205 offset:16384
	v_lshrrev_b32_e32 v10, 24, v112
	v_lshl_add_u32 v10, v10, 6, v0
	ds_add_u32 v10, v205 offset:16384
	v_lshrrev_b32_e32 v10, 24, v111
	v_lshl_add_u32 v10, v10, 6, v0
	ds_add_u32 v10, v205 offset:16384
	ds_read_b128 v[10:13], v127
	ds_read_b128 v[14:17], v128
	ds_read_b128 v[24:27], v124
	ds_read_b128 v[28:31], v125
	ds_read2_b32 v[32:33], v137 offset0:80 offset1:96
	ds_read2_b32 v[40:41], v137 offset0:112 offset1:128
	s_waitcnt vmcnt(1) lgkmcnt(5)
	v_mfma_f32_16x16x32_bf16 v[10:13], v[6:9], v[10:13], 0
	ds_read2_b32 v[52:53], v137 offset0:144 offset1:160
	s_waitcnt vmcnt(0) lgkmcnt(5)
	v_mfma_f32_16x16x32_bf16 v[10:13], v[2:5], v[14:17], v[10:13]
	ds_read_b128 v[14:17], v122
	s_waitcnt lgkmcnt(5)
	v_mfma_f32_16x16x32_bf16 v[24:27], v[6:9], v[24:27], 0
	s_nop 4
	v_max_f32_e32 v34, 0, v10
	v_max_f32_e32 v10, 0, v12
	v_max_f32_e32 v35, 0, v11
	s_waitcnt lgkmcnt(3)
	v_mul_f32_e32 v36, v32, v10
	v_max_f32_e32 v38, 0, v13
	v_mfma_f32_16x16x32_bf16 v[10:13], v[2:5], v[28:31], v[24:27]
	s_nop 2
	ds_read_b128 v[24:27], v121
	s_waitcnt lgkmcnt(1)
	v_mfma_f32_16x16x32_bf16 v[14:17], v[6:9], v[14:17], 0
	s_nop 1
	v_max_f32_e32 v28, 0, v10
	v_max_f32_e32 v29, 0, v11
	v_max_f32_e32 v10, 0, v12
	v_mul_f32_e32 v30, v33, v10
	v_max_f32_e32 v39, 0, v13
	s_waitcnt lgkmcnt(0)
	v_mfma_f32_16x16x32_bf16 v[10:13], v[2:5], v[24:27], v[14:17]
	ds_read_b128 v[24:27], v126
	v_pk_mul_f32 v[38:39], v[32:33], v[38:39]
	s_nop 0
	ds_read_b128 v[14:17], v123
	s_waitcnt lgkmcnt(0)
	v_mfma_f32_16x16x32_bf16 v[14:17], v[6:9], v[14:17], 0
	s_nop 1
	v_max_f32_e32 v42, 0, v10
	v_max_f32_e32 v43, 0, v11
	v_max_f32_e32 v10, 0, v12
	v_mul_f32_e32 v44, v40, v10
	s_nop 0
	v_max_f32_e32 v46, 0, v13
	v_mfma_f32_16x16x32_bf16 v[10:13], v[2:5], v[24:27], v[14:17]
	ds_read_b128 v[24:27], v130
	v_mov_b32_e32 v37, v38
	v_mov_b32_e32 v31, v39
	ds_read_b128 v[14:17], v129
	s_waitcnt lgkmcnt(0)
	v_mfma_f32_16x16x32_bf16 v[14:17], v[6:9], v[14:17], 0
	s_nop 1
	v_max_f32_e32 v48, 0, v10
	v_max_f32_e32 v49, 0, v11
	v_max_f32_e32 v10, 0, v12
	v_mul_f32_e32 v50, v41, v10
	s_nop 0
	v_max_f32_e32 v47, 0, v13
	v_mfma_f32_16x16x32_bf16 v[10:13], v[2:5], v[24:27], v[14:17]
	ds_read_b128 v[24:27], v132
	v_pk_mul_f32 v[46:47], v[40:41], v[46:47]
	s_nop 0
	ds_read_b128 v[14:17], v131
	s_waitcnt lgkmcnt(0)
	v_mfma_f32_16x16x32_bf16 v[14:17], v[6:9], v[14:17], 0
	s_nop 1
	v_max_f32_e32 v54, 0, v10
	v_max_f32_e32 v55, 0, v11
	v_max_f32_e32 v10, 0, v12
	v_mul_f32_e32 v56, v52, v10
	s_nop 0
	v_max_f32_e32 v114, 0, v13
	v_mfma_f32_16x16x32_bf16 v[10:13], v[2:5], v[24:27], v[14:17]
	ds_read_b128 v[24:27], v134
	v_mov_b32_e32 v45, v46
	v_mov_b32_e32 v51, v47
	ds_read_b128 v[14:17], v133
	s_waitcnt lgkmcnt(0)
	v_mfma_f32_16x16x32_bf16 v[14:17], v[6:9], v[14:17], 0
	s_nop 1
	v_max_f32_e32 v116, 0, v10
	v_max_f32_e32 v117, 0, v11
	v_max_f32_e32 v10, 0, v12
	v_mul_f32_e32 v118, v53, v10
	s_nop 0
	v_max_f32_e32 v115, 0, v13
	v_mfma_f32_16x16x32_bf16 v[10:13], v[2:5], v[24:27], v[14:17]
	ds_read_b128 v[24:27], v136
	v_pk_mul_f32 v[138:139], v[52:53], v[114:115]
	ds_read2_b32 v[114:115], v137 offset0:176 offset1:192
	ds_read_b128 v[14:17], v135
	s_waitcnt lgkmcnt(0)
; #define LAS __attribute__((address_space(3)))
; __device__ __forceinline__ unsigned fkey(float f) { const unsigned u = __float_as_uint(f); return (u & 0x80000000u) ? ~u : (u | 0x80000000u); }
; #define SEL_HADD(idx_) __hip_atomic_fetch_add(&hist[(idx_)], 1u, __ATOMIC_RELAXED, __HIP_MEMORY_SCOPE_WORKGROUP)
; __device__ __forceinline__ void sel_unit(LAS char* lds, int b, int u, const bf16_t* QI, const bf16_t* KIDX, const float* WIDX, unsigned long long* MASK) {
;     ...
;             for (int kh = 0; kh < 2; ++kh) {
;             bf16x8 kf[2][2];
; #pragma unroll
;             for (int kb = 0; kb < 2; ++kb)
; #pragma unroll
;                 for (int ks = 0; ks < 2; ++ks) kf[kb][ks] = *(const bf16x8*)(KIDX + (rowbase + 64 * t + 32 * kh + 16 * kb + q16) * 64 + 32 * ks + 8 * kg);
; #pragma unroll
;             for (int kb = 0; kb < 2; ++kb) {
;                 f32x4 s = (f32x4){0.f, 0.f, 0.f, 0.f};
; #pragma unroll
;                 for (int hh = 0; hh < 8; ++hh) {
;                     f32x4 a = (f32x4){0.f, 0.f, 0.f, 0.f};
; #pragma unroll
;                     for (int ks = 0; ks < 2; ++ks) {
;                         const bf16x8 qv = *(const LAS bf16x8*)(lds + L_QI + q16 * 1024 + (((hh * 8 + 4 * ks + kg) ^ q16) << 4));
;                         a = __builtin_amdgcn_mfma_f32_16x16x32_bf16(kf[kb][ks], qv, a, 0, 0, 0);
;                     }
;                     const float wh = wl[hh * 16];
; #pragma unroll
;                     for (int i = 0; i < 4; ++i) s[i] += wh * fmaxf(a[i], 0.f);
;                 }
;                 u32x4 kk; kk.x = fkey(s[0]); kk.y = fkey(s[1]); kk.z = fkey(s[2]); kk.w = fkey(s[3]);
;                 sc[j][2 * kh + kb] = kk;
; #pragma unroll
;                 for (int i = 0; i < 4; ++i) SEL_HADD((kk[i] >> 24) * 16 + q16);
;                 __builtin_amdgcn_sched_barrier(0);
	v_mfma_f32_16x16x32_bf16 v[6:9], v[6:9], v[14:17], 0
	s_nop 1
	s_nop 0
	v_max_f32_e32 v14, 0, v13
	s_nop 0
	v_mfma_f32_16x16x32_bf16 v[2:5], v[2:5], v[24:27], v[6:9]
	s_nop 0
	v_max_f32_e32 v10, 0, v10
	v_max_f32_e32 v11, 0, v11
	v_pk_fma_f32 v[8:9], v[32:33], v[34:35], 0 op_sel_hi:[0,1,0]
	s_nop 0
	s_nop 2
	v_max_f32_e32 v15, 0, v5
	v_pk_mul_f32 v[6:7], v[114:115], v[14:15]
	v_mov_b32_e32 v14, v33
	v_pk_fma_f32 v[8:9], v[14:15], v[28:29], v[8:9] op_sel_hi:[0,1,1]
	v_pk_fma_f32 v[8:9], v[40:41], v[42:43], v[8:9] op_sel_hi:[0,1,1]
	v_mov_b32_e32 v14, v41
	v_pk_fma_f32 v[8:9], v[14:15], v[48:49], v[8:9] op_sel_hi:[0,1,1]
	v_pk_fma_f32 v[8:9], v[52:53], v[54:55], v[8:9] op_sel_hi:[0,1,1]
	v_mov_b32_e32 v14, v53
	v_pk_fma_f32 v[8:9], v[14:15], v[116:117], v[8:9] op_sel_hi:[0,1,1]
	v_max_f32_e32 v2, 0, v2
	v_max_f32_e32 v3, 0, v3
	v_pk_fma_f32 v[8:9], v[114:115], v[10:11], v[8:9] op_sel_hi:[0,1,1]
	v_mov_b32_e32 v10, v115
	v_pk_fma_f32 v[2:3], v[10:11], v[2:3], v[8:9] op_sel_hi:[0,1,1]
	v_and_b32_e32 v9, 0x7fffffff, v3
	v_and_b32_e32 v8, 0x7fffffff, v2
	v_xor_b32_e32 v5, -1, v3
	v_pk_add_f32 v[8:9], v[8:9], 0 neg_lo:[1,1] neg_hi:[1,1]
	v_cmp_gt_i32_e32 vcc, 0, v3
	v_xor_b32_e32 v10, -1, v2
	v_mov_b32_e32 v57, v138
	v_cndmask_b32_e32 v113, v9, v5, vcc
	v_cmp_gt_i32_e32 vcc, 0, v2
	v_pk_add_f32 v[2:3], v[36:37], 0 op_sel_hi:[1,0]
	v_max_f32_e32 v12, 0, v12
	v_pk_add_f32 v[2:3], v[2:3], v[30:31]
	v_pk_add_f32 v[2:3], v[2:3], v[44:45]
	v_mov_b32_e32 v119, v139
	v_pk_add_f32 v[2:3], v[2:3], v[50:51]
	v_mul_f32_e32 v12, v114, v12
	v_pk_add_f32 v[2:3], v[2:3], v[56:57]
	v_max_f32_e32 v4, 0, v4
	v_pk_add_f32 v[2:3], v[2:3], v[118:119]
	v_mov_b32_e32 v13, v6
	v_mul_f32_e32 v4, v115, v4
	v_pk_add_f32 v[2:3], v[2:3], v[12:13]
	v_mov_b32_e32 v5, v7
	v_pk_add_f32 v[2:3], v[2:3], v[4:5]
	v_cndmask_b32_e32 v114, v8, v10, vcc
	v_and_b32_e32 v5, 0x7fffffff, v3
	v_and_b32_e32 v4, 0x7fffffff, v2
	v_xor_b32_e32 v6, -1, v3
	v_pk_add_f32 v[4:5], v[4:5], 0 neg_lo:[1,1] neg_hi:[1,1]
	v_cmp_gt_i32_e32 vcc, 0, v3
	v_xor_b32_e32 v7, -1, v2
	s_nop 0
	v_cndmask_b32_e32 v115, v5, v6, vcc
	v_cmp_gt_i32_e32 vcc, 0, v2
	v_lshrrev_b32_e32 v2, 24, v114
	v_lshl_add_u32 v2, v2, 6, v0
	ds_add_u32 v2, v205 offset:16384
	v_lshrrev_b32_e32 v2, 24, v113
	v_cndmask_b32_e32 v116, v4, v7, vcc
	v_lshl_add_u32 v2, v2, 6, v0
	ds_add_u32 v2, v205 offset:16384
	v_lshrrev_b32_e32 v2, 24, v116
	v_lshl_add_u32 v2, v2, 6, v0
	ds_add_u32 v2, v205 offset:16384
	v_lshrrev_b32_e32 v2, 24, v115
	v_lshl_add_u32 v2, v2, 6, v0
	ds_add_u32 v2, v205 offset:16384
	v_add_co_u32_e32 v2, vcc, s96, v22
	s_nop 1
	v_addc_co_u32_e32 v3, vcc, 0, v23, vcc
	global_load_dwordx4 v[14:17], v[2:3], off
	global_load_dwordx4 v[10:13], v[2:3], off offset:64
	global_load_dwordx4 v[6:9], v[2:3], off offset:2048
	s_nop 0
	global_load_dwordx4 v[2:5], v[2:3], off offset:2112
	ds_read_b128 v[22:25], v127
	ds_read_b128 v[26:29], v128
	s_waitcnt vmcnt(3) lgkmcnt(1)
	v_mfma_f32_16x16x32_bf16 v[22:25], v[14:17], v[22:25], 0
	ds_read_b128 v[32:35], v125
	ds_read_b128 v[38:41], v121
	ds_read_b128 v[44:47], v126
	s_waitcnt vmcnt(2) lgkmcnt(3)
	v_mfma_f32_16x16x32_bf16 v[26:29], v[10:13], v[26:29], v[22:25]
	ds_read_b128 v[50:53], v130
	ds_read_b128 v[138:141], v132
	ds_read_b128 v[142:145], v134
	ds_read2_b32 v[24:25], v137 offset0:80 offset1:96
	s_nop 3
	v_max_f32_e32 v26, 0, v26
	v_max_f32_e32 v27, 0, v27
	v_max_f32_e32 v22, v28, v28
	v_max_f32_e32 v23, v29, v29
	ds_read_b128 v[28:31], v124
	s_waitcnt lgkmcnt(0)
	v_mfma_f32_16x16x32_bf16 v[28:31], v[14:17], v[28:31], 0
	v_max_f32_e32 v36, 0, v23
	v_max_f32_e32 v22, 0, v22
	v_mul_f32_e32 v22, v24, v22
	v_mfma_f32_16x16x32_bf16 v[28:31], v[10:13], v[32:35], v[28:31]
	s_nop 7
	v_max_f32_e32 v32, 0, v28
	v_max_f32_e32 v33, 0, v29
	v_max_f32_e32 v23, 0, v30
	v_mul_f32_e32 v28, v25, v23
	v_max_f32_e32 v37, 0, v31
	v_pk_mul_f32 v[30:31], v[24:25], v[36:37]
	ds_read_b128 v[34:37], v122
	s_waitcnt lgkmcnt(0)
	v_mfma_f32_16x16x32_bf16 v[34:37], v[14:17], v[34:37], 0
	v_mov_b32_e32 v29, v31
	v_mfma_f32_16x16x32_bf16 v[38:41], v[10:13], v[38:41], v[34:37]
	s_nop 5
	ds_read2_b32 v[36:37], v137 offset0:112 offset1:128
	s_nop 0
	v_max_f32_e32 v38, 0, v38
	v_max_f32_e32 v39, 0, v39
	v_max_f32_e32 v23, 0, v40
	s_waitcnt lgkmcnt(0)
	v_mul_f32_e32 v34, v36, v23
	v_max_f32_e32 v23, v41, v41
	ds_read_b128 v[40:43], v123
	s_waitcnt lgkmcnt(0)
	v_mfma_f32_16x16x32_bf16 v[40:43], v[14:17], v[40:43], 0
	v_max_f32_e32 v48, 0, v23
	v_mfma_f32_16x16x32_bf16 v[40:43], v[10:13], v[44:47], v[40:43]
	s_nop 7
	v_max_f32_e32 v44, 0, v40
	v_max_f32_e32 v45, 0, v41
	v_max_f32_e32 v23, 0, v42
	v_mul_f32_e32 v40, v37, v23
	v_max_f32_e32 v49, 0, v43
	v_pk_mul_f32 v[42:43], v[36:37], v[48:49]
	ds_read_b128 v[46:49], v129
	s_waitcnt lgkmcnt(0)
	v_mfma_f32_16x16x32_bf16 v[46:49], v[14:17], v[46:49], 0
	v_mov_b32_e32 v35, v42
	v_mov_b32_e32 v41, v43
	v_mfma_f32_16x16x32_bf16 v[50:53], v[10:13], v[50:53], v[46:49]
	s_nop 4
	ds_read2_b32 v[48:49], v137 offset0:144 offset1:160
	s_nop 1
	v_max_f32_e32 v50, 0, v50
	v_max_f32_e32 v51, 0, v51
	v_max_f32_e32 v23, 0, v52
	s_waitcnt lgkmcnt(0)
	v_mul_f32_e32 v46, v48, v23
	v_max_f32_e32 v23, v53, v53
	ds_read_b128 v[52:55], v131
	s_waitcnt lgkmcnt(0)
	v_mfma_f32_16x16x32_bf16 v[52:55], v[14:17], v[52:55], 0
	v_max_f32_e32 v118, 0, v23
	v_mfma_f32_16x16x32_bf16 v[52:55], v[10:13], v[138:141], v[52:55]
	ds_read_b128 v[138:141], v133
	s_waitcnt lgkmcnt(0)
; #define LAS __attribute__((address_space(3)))
; __device__ __forceinline__ unsigned fkey(float f) { const unsigned u = __float_as_uint(f); return (u & 0x80000000u) ? ~u : (u | 0x80000000u); }
; #define SEL_HADD(idx_) __hip_atomic_fetch_add(&hist[(idx_)], 1u, __ATOMIC_RELAXED, __HIP_MEMORY_SCOPE_WORKGROUP)
; __device__ __forceinline__ void sel_unit(LAS char* lds, int b, int u, const bf16_t* QI, const bf16_t* KIDX, const float* WIDX, unsigned long long* MASK) {
;     ...
;             for (int kh = 0; kh < 2; ++kh) {
;             bf16x8 kf[2][2];
; #pragma unroll
;             for (int kb = 0; kb < 2; ++kb)
; #pragma unroll
;                 for (int ks = 0; ks < 2; ++ks) kf[kb][ks] = *(const bf16x8*)(KIDX + (rowbase + 64 * t + 32 * kh + 16 * kb + q16) * 64 + 32 * ks + 8 * kg);
; #pragma unroll
;             for (int kb = 0; kb < 2; ++kb) {
;                 f32x4 s = (f32x4){0.f, 0.f, 0.f, 0.f};
; #pragma unroll
;                 for (int hh = 0; hh < 8; ++hh) {
;                     f32x4 a = (f32x4){0.f, 0.f, 0.f, 0.f};
; #pragma unroll
;                     for (int ks = 0; ks < 2; ++ks) {
;                         const bf16x8 qv = *(const LAS bf16x8*)(lds + L_QI + q16 * 1024 + (((hh * 8 + 4 * ks + kg) ^ q16) << 4));
;                         a = __builtin_amdgcn_mfma_f32_16x16x32_bf16(kf[kb][ks], qv, a, 0, 0, 0);
;                     }
;                     const float wh = wl[hh * 16];
; #pragma unroll
;                     for (int i = 0; i < 4; ++i) s[i] += wh * fmaxf(a[i], 0.f);
;                 }
;                 u32x4 kk; kk.x = fkey(s[0]); kk.y = fkey(s[1]); kk.z = fkey(s[2]); kk.w = fkey(s[3]);
;                 sc[j][2 * kh + kb] = kk;
; #pragma unroll
;                 for (int i = 0; i < 4; ++i) SEL_HADD((kk[i] >> 24) * 16 + q16);
;                 __builtin_amdgcn_sched_barrier(0);
	v_mfma_f32_16x16x32_bf16 v[138:141], v[14:17], v[138:141], 0
	s_nop 4
	v_max_f32_e32 v56, 0, v52
	v_max_f32_e32 v57, 0, v53
	v_max_f32_e32 v23, 0, v54
	v_mfma_f32_16x16x32_bf16 v[138:141], v[10:13], v[142:145], v[138:141]
	v_mul_f32_e32 v52, v49, v23
	s_nop 0
	v_max_f32_e32 v119, 0, v55
	v_pk_mul_f32 v[54:55], v[48:49], v[118:119]
	ds_read2_b32 v[118:119], v137 offset0:176 offset1:192
	s_nop 2
	v_max_f32_e32 v142, 0, v138
	v_max_f32_e32 v143, 0, v139
	v_max_f32_e32 v23, 0, v140
	s_waitcnt lgkmcnt(0)
	v_mul_f32_e32 v144, v118, v23
	v_max_f32_e32 v23, v141, v141
	ds_read_b128 v[138:141], v135
	s_waitcnt lgkmcnt(0)
	v_mfma_f32_16x16x32_bf16 v[14:17], v[14:17], v[138:141], 0
	ds_read_b128 v[138:141], v136
	v_max_f32_e32 v146, 0, v23
	v_mov_b32_e32 v47, v54
	s_waitcnt lgkmcnt(0)
	v_mfma_f32_16x16x32_bf16 v[10:13], v[10:13], v[138:141], v[14:17]
	v_mov_b32_e32 v53, v55
	s_nop 1
	v_pk_fma_f32 v[16:17], v[24:25], v[26:27], 0 op_sel_hi:[0,1,0]
	v_mov_b32_e32 v24, v25
	v_pk_fma_f32 v[16:17], v[24:25], v[32:33], v[16:17] op_sel_hi:[0,1,1]
	v_pk_fma_f32 v[16:17], v[36:37], v[38:39], v[16:17] op_sel_hi:[0,1,1]
	v_mov_b32_e32 v24, v37
	v_pk_fma_f32 v[16:17], v[24:25], v[44:45], v[16:17] op_sel_hi:[0,1,1]
	v_pk_fma_f32 v[16:17], v[48:49], v[50:51], v[16:17] op_sel_hi:[0,1,1]
	v_mov_b32_e32 v24, v49
	v_pk_fma_f32 v[16:17], v[24:25], v[56:57], v[16:17] op_sel_hi:[0,1,1]
	v_max_f32_e32 v10, 0, v10
	v_max_f32_e32 v11, 0, v11
	v_pk_fma_f32 v[16:17], v[118:119], v[142:143], v[16:17] op_sel_hi:[0,1,1]
	v_mov_b32_e32 v24, v119
	v_pk_fma_f32 v[10:11], v[24:25], v[10:11], v[16:17] op_sel_hi:[0,1,1]
	v_and_b32_e32 v17, 0x7fffffff, v11
	v_and_b32_e32 v16, 0x7fffffff, v10
	v_max_f32_e32 v147, 0, v13
	v_xor_b32_e32 v23, -1, v10
	v_pk_add_f32 v[16:17], v[16:17], 0 neg_lo:[1,1] neg_hi:[1,1]
	v_cmp_gt_i32_e32 vcc, 0, v10
	v_pk_mul_f32 v[14:15], v[118:119], v[146:147]
	v_xor_b32_e32 v13, -1, v11
	v_cndmask_b32_e32 v118, v16, v23, vcc
	v_mov_b32_e32 v23, v30
	v_cmp_gt_i32_e64 s[2:3], 0, v11
	v_pk_add_f32 v[10:11], v[22:23], 0 op_sel_hi:[1,0]
	v_pk_add_f32 v[10:11], v[10:11], v[28:29]
	v_max_f32_e32 v12, 0, v12
	v_pk_add_f32 v[10:11], v[10:11], v[34:35]
	v_mov_b32_e32 v145, v14
	v_pk_add_f32 v[10:11], v[10:11], v[40:41]
	v_mul_f32_e32 v12, v119, v12
	v_pk_add_f32 v[10:11], v[10:11], v[46:47]
	v_cndmask_b32_e64 v117, v17, v13, s[2:3]
	v_pk_add_f32 v[10:11], v[10:11], v[52:53]
	v_mov_b32_e32 v13, v15
	v_pk_add_f32 v[10:11], v[10:11], v[144:145]
	s_nop 0
	v_pk_add_f32 v[10:11], v[10:11], v[12:13]
	s_nop 0
	v_xor_b32_e32 v15, -1, v10
	v_and_b32_e32 v12, 0x7fffffff, v10
	v_cmp_gt_i32_e32 vcc, 0, v10
	v_lshrrev_b32_e32 v10, 24, v118
	v_and_b32_e32 v13, 0x7fffffff, v11
	v_lshl_add_u32 v10, v10, 6, v0
	v_pk_add_f32 v[12:13], v[12:13], 0 neg_lo:[1,1] neg_hi:[1,1]
	ds_add_u32 v10, v205 offset:16384
	v_lshrrev_b32_e32 v10, 24, v117
	v_cndmask_b32_e32 v120, v12, v15, vcc
	v_lshl_add_u32 v10, v10, 6, v0
	v_xor_b32_e32 v14, -1, v11
	v_cmp_gt_i32_e64 s[2:3], 0, v11
	ds_add_u32 v10, v205 offset:16384
	v_lshrrev_b32_e32 v10, 24, v120
	v_cndmask_b32_e64 v119, v13, v14, s[2:3]
	v_lshl_add_u32 v10, v10, 6, v0
	ds_add_u32 v10, v205 offset:16384
	v_lshrrev_b32_e32 v10, 24, v119
	v_lshl_add_u32 v10, v10, 6, v0
	ds_add_u32 v10, v205 offset:16384
	ds_read_b128 v[10:13], v127
	ds_read_b128 v[14:17], v128
	ds_read_b128 v[22:25], v124
	ds_read_b128 v[26:29], v125
	ds_read2_b32 v[30:31], v137 offset0:80 offset1:96
	ds_read2_b32 v[38:39], v137 offset0:112 offset1:128
	s_waitcnt vmcnt(1) lgkmcnt(5)
	v_mfma_f32_16x16x32_bf16 v[10:13], v[6:9], v[10:13], 0
	ds_read2_b32 v[50:51], v137 offset0:144 offset1:160
	s_waitcnt vmcnt(0) lgkmcnt(5)
	v_mfma_f32_16x16x32_bf16 v[10:13], v[2:5], v[14:17], v[10:13]
	ds_read_b128 v[14:17], v122
	s_waitcnt lgkmcnt(5)
	v_mfma_f32_16x16x32_bf16 v[22:25], v[6:9], v[22:25], 0
	s_nop 4
	v_max_f32_e32 v32, 0, v10
	v_max_f32_e32 v10, 0, v12
	v_max_f32_e32 v33, 0, v11
	s_waitcnt lgkmcnt(3)
	v_mul_f32_e32 v34, v30, v10
	v_max_f32_e32 v36, 0, v13
	v_mfma_f32_16x16x32_bf16 v[10:13], v[2:5], v[26:29], v[22:25]
	s_nop 2
	ds_read_b128 v[22:25], v121
	s_waitcnt lgkmcnt(1)
	v_mfma_f32_16x16x32_bf16 v[14:17], v[6:9], v[14:17], 0
	s_nop 1
	v_max_f32_e32 v26, 0, v10
	v_max_f32_e32 v27, 0, v11
	v_max_f32_e32 v10, 0, v12
	v_mul_f32_e32 v28, v31, v10
	v_max_f32_e32 v37, 0, v13
	s_waitcnt lgkmcnt(0)
	v_mfma_f32_16x16x32_bf16 v[10:13], v[2:5], v[22:25], v[14:17]
	ds_read_b128 v[22:25], v126
	ds_read2_b32 v[126:127], v137 offset0:176 offset1:192
	v_pk_mul_f32 v[36:37], v[30:31], v[36:37]
	ds_read_b128 v[14:17], v123
	s_waitcnt lgkmcnt(0)
	v_mfma_f32_16x16x32_bf16 v[14:17], v[6:9], v[14:17], 0
	s_nop 1
	v_max_f32_e32 v40, 0, v10
	v_max_f32_e32 v41, 0, v11
	v_max_f32_e32 v10, 0, v12
	v_mul_f32_e32 v42, v38, v10
	s_nop 0
	v_max_f32_e32 v44, 0, v13
	v_mfma_f32_16x16x32_bf16 v[10:13], v[2:5], v[22:25], v[14:17]
	ds_read_b128 v[22:25], v130
	v_mov_b32_e32 v35, v36
	v_mov_b32_e32 v29, v37
	ds_read_b128 v[14:17], v129
	s_waitcnt lgkmcnt(0)
	v_mfma_f32_16x16x32_bf16 v[14:17], v[6:9], v[14:17], 0
	s_nop 1
	v_max_f32_e32 v46, 0, v10
	v_max_f32_e32 v47, 0, v11
	v_max_f32_e32 v10, 0, v12
	v_mul_f32_e32 v48, v39, v10
	s_nop 0
	v_max_f32_e32 v45, 0, v13
	v_mfma_f32_16x16x32_bf16 v[10:13], v[2:5], v[22:25], v[14:17]
	ds_read_b128 v[22:25], v132
	v_pk_mul_f32 v[44:45], v[38:39], v[44:45]
	s_nop 0
	ds_read_b128 v[14:17], v131
	s_waitcnt lgkmcnt(0)
	v_mfma_f32_16x16x32_bf16 v[14:17], v[6:9], v[14:17], 0
	s_nop 1
	v_max_f32_e32 v52, 0, v10
	v_max_f32_e32 v53, 0, v11
	v_max_f32_e32 v10, 0, v12
	v_mul_f32_e32 v54, v50, v10
	s_nop 0
	v_max_f32_e32 v56, 0, v13
	v_mfma_f32_16x16x32_bf16 v[10:13], v[2:5], v[22:25], v[14:17]
	ds_read_b128 v[22:25], v134
	v_mov_b32_e32 v43, v44
	v_mov_b32_e32 v49, v45
	ds_read_b128 v[14:17], v133
	s_waitcnt lgkmcnt(0)
; #define LAS __attribute__((address_space(3)))
; __device__ __forceinline__ unsigned fkey(float f) { const unsigned u = __float_as_uint(f); return (u & 0x80000000u) ? ~u : (u | 0x80000000u); }
; #define SEL_HADD(idx_) __hip_atomic_fetch_add(&hist[(idx_)], 1u, __ATOMIC_RELAXED, __HIP_MEMORY_SCOPE_WORKGROUP)
; __device__ __forceinline__ void sel_unit(LAS char* lds, int b, int u, const bf16_t* QI, const bf16_t* KIDX, const float* WIDX, unsigned long long* MASK) {
;     ...
;     for (int j = 0; j < 8; ++j) {
;         if (j < nj) {
;             int t = wid + 8 * j; asm volatile("" : "+s"(t));
; #pragma unroll
;             for (int kh = 0; kh < 2; ++kh) {
;             bf16x8 kf[2][2];
; #pragma unroll
;             for (int kb = 0; kb < 2; ++kb)
; #pragma unroll
;                 for (int ks = 0; ks < 2; ++ks) kf[kb][ks] = *(const bf16x8*)(KIDX + (rowbase + 64 * t + 32 * kh + 16 * kb + q16) * 64 + 32 * ks + 8 * kg);
; #pragma unroll
;             for (int kb = 0; kb < 2; ++kb) {
;                 f32x4 s = (f32x4){0.f, 0.f, 0.f, 0.f};
; #pragma unroll
;                 for (int hh = 0; hh < 8; ++hh) {
;                     f32x4 a = (f32x4){0.f, 0.f, 0.f, 0.f};
; #pragma unroll
;                     for (int ks = 0; ks < 2; ++ks) {
;                         const bf16x8 qv = *(const LAS bf16x8*)(lds + L_QI + q16 * 1024 + (((hh * 8 + 4 * ks + kg) ^ q16) << 4));
;                         a = __builtin_amdgcn_mfma_f32_16x16x32_bf16(kf[kb][ks], qv, a, 0, 0, 0);
;                     }
;                     const float wh = wl[hh * 16];
; #pragma unroll
;                     for (int i = 0; i < 4; ++i) s[i] += wh * fmaxf(a[i], 0.f);
;                 }
;                 u32x4 kk; kk.x = fkey(s[0]); kk.y = fkey(s[1]); kk.z = fkey(s[2]); kk.w = fkey(s[3]);
;                 sc[j][2 * kh + kb] = kk;
; #pragma unroll
;                 for (int i = 0; i < 4; ++i) SEL_HADD((kk[i] >> 24) * 16 + q16);
;                 __builtin_amdgcn_sched_barrier(0);
	v_mfma_f32_16x16x32_bf16 v[14:17], v[6:9], v[14:17], 0
	s_nop 1
	v_max_f32_e32 v122, 0, v10
	v_max_f32_e32 v123, 0, v11
	v_max_f32_e32 v10, 0, v12
	v_mul_f32_e32 v124, v51, v10
	s_nop 0
	v_max_f32_e32 v57, 0, v13
	v_mfma_f32_16x16x32_bf16 v[10:13], v[2:5], v[22:25], v[14:17]
	ds_read_b128 v[22:25], v136
	v_pk_mul_f32 v[56:57], v[50:51], v[56:57]
	s_nop 0
	ds_read_b128 v[14:17], v135
	s_waitcnt lgkmcnt(0)
	v_mfma_f32_16x16x32_bf16 v[6:9], v[6:9], v[14:17], 0
	s_nop 1
	s_nop 0
	v_max_f32_e32 v14, 0, v13
	s_nop 0
	v_mfma_f32_16x16x32_bf16 v[2:5], v[2:5], v[22:25], v[6:9]
	s_nop 0
	v_max_f32_e32 v10, 0, v10
	v_max_f32_e32 v11, 0, v11
	v_pk_fma_f32 v[8:9], v[30:31], v[32:33], 0 op_sel_hi:[0,1,0]
	s_nop 0
	s_nop 2
	v_max_f32_e32 v15, 0, v5
	v_pk_mul_f32 v[6:7], v[126:127], v[14:15]
	v_mov_b32_e32 v14, v31
	v_pk_fma_f32 v[8:9], v[14:15], v[26:27], v[8:9] op_sel_hi:[0,1,1]
	v_pk_fma_f32 v[8:9], v[38:39], v[40:41], v[8:9] op_sel_hi:[0,1,1]
	v_mov_b32_e32 v14, v39
	v_pk_fma_f32 v[8:9], v[14:15], v[46:47], v[8:9] op_sel_hi:[0,1,1]
	v_pk_fma_f32 v[8:9], v[50:51], v[52:53], v[8:9] op_sel_hi:[0,1,1]
	v_mov_b32_e32 v14, v51
	v_pk_fma_f32 v[8:9], v[14:15], v[122:123], v[8:9] op_sel_hi:[0,1,1]
	v_max_f32_e32 v2, 0, v2
	v_max_f32_e32 v3, 0, v3
	v_pk_fma_f32 v[8:9], v[126:127], v[10:11], v[8:9] op_sel_hi:[0,1,1]
	v_mov_b32_e32 v10, v127
	v_pk_fma_f32 v[2:3], v[10:11], v[2:3], v[8:9] op_sel_hi:[0,1,1]
	v_and_b32_e32 v9, 0x7fffffff, v3
	v_and_b32_e32 v8, 0x7fffffff, v2
	v_xor_b32_e32 v5, -1, v3
	v_pk_add_f32 v[8:9], v[8:9], 0 neg_lo:[1,1] neg_hi:[1,1]
	v_cmp_gt_i32_e32 vcc, 0, v3
	v_xor_b32_e32 v10, -1, v2
	v_mov_b32_e32 v55, v56
	v_cndmask_b32_e32 v121, v9, v5, vcc
	v_cmp_gt_i32_e32 vcc, 0, v2
	v_pk_add_f32 v[2:3], v[34:35], 0 op_sel_hi:[1,0]
	v_max_f32_e32 v12, 0, v12
	v_pk_add_f32 v[2:3], v[2:3], v[28:29]
	v_pk_add_f32 v[2:3], v[2:3], v[42:43]
	v_mov_b32_e32 v125, v57
	v_pk_add_f32 v[2:3], v[2:3], v[48:49]
	v_mul_f32_e32 v12, v126, v12
	v_pk_add_f32 v[2:3], v[2:3], v[54:55]
	v_max_f32_e32 v4, 0, v4
	v_pk_add_f32 v[2:3], v[2:3], v[124:125]
	v_mov_b32_e32 v13, v6
	v_mul_f32_e32 v4, v127, v4
	v_pk_add_f32 v[2:3], v[2:3], v[12:13]
	v_mov_b32_e32 v5, v7
	v_pk_add_f32 v[2:3], v[2:3], v[4:5]
	v_cndmask_b32_e32 v122, v8, v10, vcc
	v_and_b32_e32 v5, 0x7fffffff, v3
	v_and_b32_e32 v4, 0x7fffffff, v2
	v_xor_b32_e32 v6, -1, v3
	v_pk_add_f32 v[4:5], v[4:5], 0 neg_lo:[1,1] neg_hi:[1,1]
	v_cmp_gt_i32_e32 vcc, 0, v3
	v_xor_b32_e32 v7, -1, v2
	s_nop 0
	v_cndmask_b32_e32 v123, v5, v6, vcc
	v_cmp_gt_i32_e32 vcc, 0, v2
	v_lshrrev_b32_e32 v2, 24, v122
	v_lshl_add_u32 v2, v2, 6, v0
	ds_add_u32 v2, v205 offset:16384
	v_lshrrev_b32_e32 v2, 24, v121
	v_cndmask_b32_e32 v124, v4, v7, vcc
	v_lshl_add_u32 v2, v2, 6, v0
	ds_add_u32 v2, v205 offset:16384
	v_lshrrev_b32_e32 v2, 24, v124
	v_lshl_add_u32 v2, v2, 6, v0
	ds_add_u32 v2, v205 offset:16384
	v_lshrrev_b32_e32 v2, 24, v123
	v_lshl_add_u32 v2, v2, 6, v0
	ds_add_u32 v2, v205 offset:16384
.LBB0_664:
	s_cmp_gt_i32 s4, 4
	s_cselect_b64 s[24:25], -1, 0
	s_cmp_lt_i32 s4, 5
	s_cbranch_scc1 .LBB0_666
	s_add_i32 s0, s46, 32
	s_lshl_b32 s0, s0, 6
	s_ashr_i32 s1, s0, 31
	v_lshl_add_u64 v[2:3], v[18:19], 0, s[0:1]
	v_lshlrev_b64 v[2:3], 7, v[2:3]
	v_lshl_add_u64 v[22:23], v[20:21], 0, v[2:3]
	global_load_dwordx4 v[14:17], v[22:23], off
	global_load_dwordx4 v[10:13], v[22:23], off offset:64
	v_lshl_add_u32 v144, v182, 4, v150
	v_lshl_add_u32 v145, v183, 4, v150
	v_lshl_add_u32 v142, v185, 4, v150
	v_lshl_add_u32 v138, v180, 4, v150
	v_lshl_add_u32 v143, v159, 4, v150
	v_lshl_add_u32 v141, v184, 4, v150
	ds_read_b128 v[2:5], v144
	v_lshl_add_u32 v139, v179, 4, v150
	ds_read_b128 v[6:9], v145
	ds_read_b128 v[24:27], v141
	v_lshl_add_u32 v140, v176, 4, v150
	ds_read_b128 v[28:31], v142
	ds_read_b128 v[32:35], v139
	ds_read_b128 v[36:39], v138
	ds_read_b128 v[40:43], v140
	v_lshl_add_u32 v146, v158, 4, v150
	ds_read_b128 v[44:47], v143
	ds_read_b128 v[48:51], v146
	v_lshl_add_u32 v147, v157, 4, v150
	ds_read_b128 v[52:55], v147
	v_lshl_add_u32 v148, v156, 4, v150
	v_lshl_add_u32 v149, v155, 4, v150
	ds_read_b128 v[126:129], v148
	ds_read_b128 v[130:133], v149
	v_lshl_add_u32 v177, v154, 4, v150
	v_lshl_add_u32 v178, v153, 4, v150
	v_lshl_add_u32 v181, v152, 4, v150
	v_lshl_add_u32 v186, v151, 4, v150
	s_waitcnt vmcnt(1) lgkmcnt(11)
	v_mfma_f32_16x16x32_bf16 v[2:5], v[14:17], v[2:5], 0
	s_waitcnt lgkmcnt(9)
	v_mfma_f32_16x16x32_bf16 v[24:27], v[14:17], v[24:27], 0
	s_waitcnt lgkmcnt(7)
	v_mfma_f32_16x16x32_bf16 v[32:35], v[14:17], v[32:35], 0
	s_waitcnt lgkmcnt(5)
	v_mfma_f32_16x16x32_bf16 v[40:43], v[14:17], v[40:43], 0
	s_waitcnt lgkmcnt(3)
	v_mfma_f32_16x16x32_bf16 v[48:51], v[14:17], v[48:51], 0
	s_waitcnt vmcnt(0)
	v_mfma_f32_16x16x32_bf16 v[160:163], v[10:13], v[6:9], v[2:5]
	v_mfma_f32_16x16x32_bf16 v[24:27], v[10:13], v[28:31], v[24:27]
	v_mfma_f32_16x16x32_bf16 v[28:31], v[10:13], v[36:39], v[32:35]
	v_mfma_f32_16x16x32_bf16 v[32:35], v[10:13], v[44:47], v[40:43]
	ds_read2_b32 v[44:45], v137 offset0:80 offset1:96
	ds_read2_b32 v[46:47], v137 offset0:112 offset1:128
	s_nop 3
	s_waitcnt lgkmcnt(4)
	v_mfma_f32_16x16x32_bf16 v[36:39], v[10:13], v[52:55], v[48:51]
	s_nop 0
	ds_read2_b32 v[48:49], v137 offset0:144 offset1:160
	global_load_dwordx4 v[6:9], v[22:23], off offset:2048
	global_load_dwordx4 v[2:5], v[22:23], off offset:2112
	s_waitcnt lgkmcnt(4)
	v_mfma_f32_16x16x32_bf16 v[126:129], v[14:17], v[126:129], 0
	s_nop 0
	v_max_f32_e32 v54, v24, v24
	s_nop 0
	s_waitcnt lgkmcnt(3)
	v_mfma_f32_16x16x32_bf16 v[40:43], v[10:13], v[130:133], v[126:129]
	v_max_f32_e32 v125, v39, v39
	v_max_f32_e32 v24, 0, v163
	v_max_f32_e32 v39, 0, v25
	v_max_f32_e32 v128, 0, v26
	v_max_f32_e32 v25, 0, v27
	v_max_f32_e32 v26, 0, v31
	v_max_f32_e32 v27, 0, v35
	v_max_f32_e32 v53, 0, v37
	s_waitcnt lgkmcnt(2)
; #define LAS __attribute__((address_space(3)))
; __device__ __forceinline__ unsigned fkey(float f) { const unsigned u = __float_as_uint(f); return (u & 0x80000000u) ? ~u : (u | 0x80000000u); }
; #define SEL_HADD(idx_) __hip_atomic_fetch_add(&hist[(idx_)], 1u, __ATOMIC_RELAXED, __HIP_MEMORY_SCOPE_WORKGROUP)
; __device__ __forceinline__ void sel_unit(LAS char* lds, int b, int u, const bf16_t* QI, const bf16_t* KIDX, const float* WIDX, unsigned long long* MASK) {
;     ...
;             for (int kh = 0; kh < 2; ++kh) {
;             bf16x8 kf[2][2];
; #pragma unroll
;             for (int kb = 0; kb < 2; ++kb)
; #pragma unroll
;                 for (int ks = 0; ks < 2; ++ks) kf[kb][ks] = *(const bf16x8*)(KIDX + (rowbase + 64 * t + 32 * kh + 16 * kb + q16) * 64 + 32 * ks + 8 * kg);
; #pragma unroll
;             for (int kb = 0; kb < 2; ++kb) {
;                 f32x4 s = (f32x4){0.f, 0.f, 0.f, 0.f};
; #pragma unroll
;                 for (int hh = 0; hh < 8; ++hh) {
;                     f32x4 a = (f32x4){0.f, 0.f, 0.f, 0.f};
; #pragma unroll
;                     for (int ks = 0; ks < 2; ++ks) {
;                         const bf16x8 qv = *(const LAS bf16x8*)(lds + L_QI + q16 * 1024 + (((hh * 8 + 4 * ks + kg) ^ q16) << 4));
;                         a = __builtin_amdgcn_mfma_f32_16x16x32_bf16(kf[kb][ks], qv, a, 0, 0, 0);
;                     }
;                     const float wh = wl[hh * 16];
; #pragma unroll
;                     for (int i = 0; i < 4; ++i) s[i] += wh * fmaxf(a[i], 0.f);
;                 }
;                 u32x4 kk; kk.x = fkey(s[0]); kk.y = fkey(s[1]); kk.z = fkey(s[2]); kk.w = fkey(s[3]);
;                 sc[j][2 * kh + kb] = kk;
; #pragma unroll
;                 for (int i = 0; i < 4; ++i) SEL_HADD((kk[i] >> 24) * 16 + q16);
;                 __builtin_amdgcn_sched_barrier(0);
	v_mul_f32_e32 v56, v45, v128
	v_pk_mul_f32 v[128:129], v[44:45], v[24:25]
	s_waitcnt lgkmcnt(1)
	v_pk_mul_f32 v[134:135], v[46:47], v[26:27]
	ds_read_b128 v[24:27], v177
	v_max_f32_e32 v126, v40, v40
	v_max_f32_e32 v40, 0, v28
	v_max_f32_e32 v28, 0, v30
	v_max_f32_e32 v127, v41, v41
	v_max_f32_e32 v41, 0, v29
	v_max_f32_e32 v29, 0, v34
	v_max_f32_e32 v30, 0, v38
	v_mul_f32_e32 v130, v46, v28
	v_max_f32_e32 v28, 0, v42
	v_max_f32_e32 v50, v160, v160
	v_max_f32_e32 v52, v162, v162
	v_mul_f32_e32 v132, v47, v29
	s_waitcnt lgkmcnt(1)
	v_mul_f32_e32 v160, v48, v30
	v_mul_f32_e32 v162, v49, v28
	ds_read_b128 v[28:31], v178
	s_waitcnt lgkmcnt(1)
	v_mfma_f32_16x16x32_bf16 v[24:27], v[14:17], v[24:27], 0
	s_waitcnt lgkmcnt(0)
	v_mfma_f32_16x16x32_bf16 v[24:27], v[10:13], v[28:31], v[24:27]
	ds_read_b128 v[28:31], v181
	v_max_f32_e32 v37, 0, v161
	v_max_f32_e32 v51, 0, v33
	v_max_f32_e32 v55, v36, v36
	v_max_f32_e32 v36, 0, v50
	v_max_f32_e32 v50, 0, v32
	v_max_f32_e32 v32, 0, v125
	v_max_f32_e32 v33, 0, v43
	v_pk_mul_f32 v[164:165], v[48:49], v[32:33]
	ds_read_b128 v[32:35], v186
	s_waitcnt lgkmcnt(1)
	v_mfma_f32_16x16x32_bf16 v[14:17], v[14:17], v[28:31], 0
	v_max_f32_e32 v42, 0, v52
	v_max_f32_e32 v38, 0, v54
	v_max_f32_e32 v52, 0, v55
	s_waitcnt lgkmcnt(0)
	v_mfma_f32_16x16x32_bf16 v[10:13], v[10:13], v[32:35], v[14:17]
	v_max_f32_e32 v54, 0, v126
	v_max_f32_e32 v55, 0, v127
	ds_read2_b32 v[126:127], v137 offset0:176 offset1:192
	s_nop 0
	v_max_f32_e32 v28, 0, v27
	s_nop 2
	v_max_f32_e32 v29, 0, v13
	s_waitcnt lgkmcnt(0)
	v_pk_mul_f32 v[14:15], v[126:127], v[28:29]
	v_pk_fma_f32 v[16:17], v[44:45], v[36:37], 0 op_sel_hi:[0,1,0]
	v_mov_b32_e32 v28, v45
	v_pk_fma_f32 v[16:17], v[28:29], v[38:39], v[16:17] op_sel_hi:[0,1,1]
	v_pk_fma_f32 v[16:17], v[46:47], v[40:41], v[16:17] op_sel_hi:[0,1,1]
	v_mov_b32_e32 v28, v47
	v_pk_fma_f32 v[16:17], v[28:29], v[50:51], v[16:17] op_sel_hi:[0,1,1]
	v_pk_fma_f32 v[16:17], v[48:49], v[52:53], v[16:17] op_sel_hi:[0,1,1]
	v_mov_b32_e32 v28, v49
	v_max_f32_e32 v24, 0, v24
	v_max_f32_e32 v25, 0, v25
	v_pk_fma_f32 v[16:17], v[28:29], v[54:55], v[16:17] op_sel_hi:[0,1,1]
	v_max_f32_e32 v10, 0, v10
	v_max_f32_e32 v11, 0, v11
	v_pk_fma_f32 v[16:17], v[126:127], v[24:25], v[16:17] op_sel_hi:[0,1,1]
	v_mov_b32_e32 v24, v127
	v_pk_fma_f32 v[10:11], v[24:25], v[10:11], v[16:17] op_sel_hi:[0,1,1]
	v_and_b32_e32 v17, 0x7fffffff, v11
	v_and_b32_e32 v16, 0x7fffffff, v10
	v_mul_f32_e32 v42, v44, v42
	v_xor_b32_e32 v13, -1, v11
	v_pk_add_f32 v[16:17], v[16:17], 0 neg_lo:[1,1] neg_hi:[1,1]
	v_cmp_gt_i32_e32 vcc, 0, v11
	v_mov_b32_e32 v43, v128
	v_xor_b32_e32 v24, -1, v10
	v_cndmask_b32_e32 v125, v17, v13, vcc
	v_cmp_gt_i32_e32 vcc, 0, v10
	v_pk_add_f32 v[10:11], v[42:43], 0 op_sel_hi:[1,0]
	v_mov_b32_e32 v57, v129
	v_pk_add_f32 v[10:11], v[10:11], v[56:57]
	v_mov_b32_e32 v131, v134
	v_pk_add_f32 v[10:11], v[10:11], v[130:131]
	v_mov_b32_e32 v133, v135
	v_pk_add_f32 v[10:11], v[10:11], v[132:133]
	v_mov_b32_e32 v161, v164
	v_max_f32_e32 v26, 0, v26
	v_pk_add_f32 v[10:11], v[10:11], v[160:161]
	v_mov_b32_e32 v163, v165
	v_mul_f32_e32 v26, v126, v26
	v_max_f32_e32 v12, 0, v12
	v_pk_add_f32 v[10:11], v[10:11], v[162:163]
	v_mov_b32_e32 v27, v14
	v_mul_f32_e32 v12, v127, v12
	v_pk_add_f32 v[10:11], v[10:11], v[26:27]
	v_mov_b32_e32 v13, v15
	v_pk_add_f32 v[10:11], v[10:11], v[12:13]
	v_cndmask_b32_e32 v126, v16, v24, vcc
	v_and_b32_e32 v13, 0x7fffffff, v11
	v_and_b32_e32 v12, 0x7fffffff, v10
	v_xor_b32_e32 v14, -1, v11
	v_pk_add_f32 v[12:13], v[12:13], 0 neg_lo:[1,1] neg_hi:[1,1]
	v_cmp_gt_i32_e32 vcc, 0, v11
	v_xor_b32_e32 v15, -1, v10
	s_nop 0
	v_cndmask_b32_e32 v127, v13, v14, vcc
	v_cmp_gt_i32_e32 vcc, 0, v10
	v_lshrrev_b32_e32 v10, 24, v126
	v_lshl_add_u32 v10, v10, 6, v0
	ds_add_u32 v10, v205 offset:16384
	v_lshrrev_b32_e32 v10, 24, v125
	v_cndmask_b32_e32 v128, v12, v15, vcc
	v_lshl_add_u32 v10, v10, 6, v0
	ds_add_u32 v10, v205 offset:16384
	v_lshrrev_b32_e32 v10, 24, v128
	v_lshl_add_u32 v10, v10, 6, v0
	ds_add_u32 v10, v205 offset:16384
	v_lshrrev_b32_e32 v10, 24, v127
	v_lshl_add_u32 v10, v10, 6, v0
	ds_add_u32 v10, v205 offset:16384
	ds_read_b128 v[10:13], v144
	ds_read_b128 v[14:17], v145
	ds_read_b128 v[24:27], v141
	ds_read_b128 v[28:31], v142
	ds_read2_b32 v[32:33], v137 offset0:80 offset1:96
	ds_read2_b32 v[40:41], v137 offset0:112 offset1:128
	s_waitcnt vmcnt(1) lgkmcnt(5)
	v_mfma_f32_16x16x32_bf16 v[10:13], v[6:9], v[10:13], 0
	ds_read2_b32 v[52:53], v137 offset0:144 offset1:160
	s_waitcnt vmcnt(0) lgkmcnt(5)
	v_mfma_f32_16x16x32_bf16 v[10:13], v[2:5], v[14:17], v[10:13]
	ds_read_b128 v[14:17], v139
	s_waitcnt lgkmcnt(5)
	v_mfma_f32_16x16x32_bf16 v[24:27], v[6:9], v[24:27], 0
	s_nop 4
	v_max_f32_e32 v34, 0, v10
	v_max_f32_e32 v10, 0, v12
	v_max_f32_e32 v35, 0, v11
	s_waitcnt lgkmcnt(3)
	v_mul_f32_e32 v36, v32, v10
	v_max_f32_e32 v38, 0, v13
	v_mfma_f32_16x16x32_bf16 v[10:13], v[2:5], v[28:31], v[24:27]
	s_nop 2
	ds_read_b128 v[24:27], v138
	s_waitcnt lgkmcnt(1)
	v_mfma_f32_16x16x32_bf16 v[14:17], v[6:9], v[14:17], 0
	s_nop 1
	v_max_f32_e32 v28, 0, v10
	v_max_f32_e32 v29, 0, v11
	v_max_f32_e32 v10, 0, v12
	v_mul_f32_e32 v30, v33, v10
	v_max_f32_e32 v39, 0, v13
	s_waitcnt lgkmcnt(0)
	v_mfma_f32_16x16x32_bf16 v[10:13], v[2:5], v[24:27], v[14:17]
	ds_read_b128 v[24:27], v143
	v_pk_mul_f32 v[38:39], v[32:33], v[38:39]
	s_nop 0
	ds_read_b128 v[14:17], v140
	s_waitcnt lgkmcnt(0)
	v_mfma_f32_16x16x32_bf16 v[14:17], v[6:9], v[14:17], 0
	s_nop 1
	v_max_f32_e32 v42, 0, v10
	v_max_f32_e32 v43, 0, v11
	v_max_f32_e32 v10, 0, v12
	v_mul_f32_e32 v44, v40, v10
	s_nop 0
	v_max_f32_e32 v46, 0, v13
	v_mfma_f32_16x16x32_bf16 v[10:13], v[2:5], v[24:27], v[14:17]
	ds_read_b128 v[24:27], v147
	v_mov_b32_e32 v37, v38
	v_mov_b32_e32 v31, v39
	ds_read_b128 v[14:17], v146
	s_waitcnt lgkmcnt(0)
; #define LAS __attribute__((address_space(3)))
; __device__ __forceinline__ unsigned fkey(float f) { const unsigned u = __float_as_uint(f); return (u & 0x80000000u) ? ~u : (u | 0x80000000u); }
; #define SEL_HADD(idx_) __hip_atomic_fetch_add(&hist[(idx_)], 1u, __ATOMIC_RELAXED, __HIP_MEMORY_SCOPE_WORKGROUP)
; __device__ __forceinline__ void sel_unit(LAS char* lds, int b, int u, const bf16_t* QI, const bf16_t* KIDX, const float* WIDX, unsigned long long* MASK) {
;     ...
;             for (int kh = 0; kh < 2; ++kh) {
;             bf16x8 kf[2][2];
; #pragma unroll
;             for (int kb = 0; kb < 2; ++kb)
; #pragma unroll
;                 for (int ks = 0; ks < 2; ++ks) kf[kb][ks] = *(const bf16x8*)(KIDX + (rowbase + 64 * t + 32 * kh + 16 * kb + q16) * 64 + 32 * ks + 8 * kg);
; #pragma unroll
;             for (int kb = 0; kb < 2; ++kb) {
;                 f32x4 s = (f32x4){0.f, 0.f, 0.f, 0.f};
; #pragma unroll
;                 for (int hh = 0; hh < 8; ++hh) {
;                     f32x4 a = (f32x4){0.f, 0.f, 0.f, 0.f};
; #pragma unroll
;                     for (int ks = 0; ks < 2; ++ks) {
;                         const bf16x8 qv = *(const LAS bf16x8*)(lds + L_QI + q16 * 1024 + (((hh * 8 + 4 * ks + kg) ^ q16) << 4));
;                         a = __builtin_amdgcn_mfma_f32_16x16x32_bf16(kf[kb][ks], qv, a, 0, 0, 0);
;                     }
;                     const float wh = wl[hh * 16];
; #pragma unroll
;                     for (int i = 0; i < 4; ++i) s[i] += wh * fmaxf(a[i], 0.f);
;                 }
;                 u32x4 kk; kk.x = fkey(s[0]); kk.y = fkey(s[1]); kk.z = fkey(s[2]); kk.w = fkey(s[3]);
;                 sc[j][2 * kh + kb] = kk;
; #pragma unroll
;                 for (int i = 0; i < 4; ++i) SEL_HADD((kk[i] >> 24) * 16 + q16);
;                 __builtin_amdgcn_sched_barrier(0);
	v_mfma_f32_16x16x32_bf16 v[14:17], v[6:9], v[14:17], 0
	s_nop 1
	v_max_f32_e32 v48, 0, v10
	v_max_f32_e32 v49, 0, v11
	v_max_f32_e32 v10, 0, v12
	v_mul_f32_e32 v50, v41, v10
	s_nop 0
	v_max_f32_e32 v47, 0, v13
	v_mfma_f32_16x16x32_bf16 v[10:13], v[2:5], v[24:27], v[14:17]
	ds_read_b128 v[24:27], v149
	v_pk_mul_f32 v[46:47], v[40:41], v[46:47]
	s_nop 0
	ds_read_b128 v[14:17], v148
	s_waitcnt lgkmcnt(0)
	v_mfma_f32_16x16x32_bf16 v[14:17], v[6:9], v[14:17], 0
	s_nop 1
	v_max_f32_e32 v54, 0, v10
	v_max_f32_e32 v55, 0, v11
	v_max_f32_e32 v10, 0, v12
	v_mul_f32_e32 v56, v52, v10
	s_nop 0
	v_max_f32_e32 v130, 0, v13
	v_mfma_f32_16x16x32_bf16 v[10:13], v[2:5], v[24:27], v[14:17]
	ds_read_b128 v[24:27], v178
	v_mov_b32_e32 v45, v46
	v_mov_b32_e32 v51, v47
	ds_read_b128 v[14:17], v177
	s_waitcnt lgkmcnt(0)
	v_mfma_f32_16x16x32_bf16 v[14:17], v[6:9], v[14:17], 0
	s_nop 1
	v_max_f32_e32 v132, 0, v10
	v_max_f32_e32 v133, 0, v11
	v_max_f32_e32 v10, 0, v12
	v_mul_f32_e32 v134, v53, v10
	s_nop 0
	v_max_f32_e32 v131, 0, v13
	v_mfma_f32_16x16x32_bf16 v[10:13], v[2:5], v[24:27], v[14:17]
	ds_read_b128 v[24:27], v186
	v_pk_mul_f32 v[160:161], v[52:53], v[130:131]
	ds_read2_b32 v[130:131], v137 offset0:176 offset1:192
	ds_read_b128 v[14:17], v181
	s_waitcnt lgkmcnt(0)
	v_mfma_f32_16x16x32_bf16 v[6:9], v[6:9], v[14:17], 0
	s_nop 1
	s_nop 0
	v_max_f32_e32 v14, 0, v13
	s_nop 0
	v_mfma_f32_16x16x32_bf16 v[2:5], v[2:5], v[24:27], v[6:9]
	s_nop 0
	v_max_f32_e32 v10, 0, v10
	v_max_f32_e32 v11, 0, v11
	v_pk_fma_f32 v[8:9], v[32:33], v[34:35], 0 op_sel_hi:[0,1,0]
	s_nop 0
	s_nop 2
	v_max_f32_e32 v15, 0, v5
	v_pk_mul_f32 v[6:7], v[130:131], v[14:15]
	v_mov_b32_e32 v14, v33
	v_pk_fma_f32 v[8:9], v[14:15], v[28:29], v[8:9] op_sel_hi:[0,1,1]
	v_pk_fma_f32 v[8:9], v[40:41], v[42:43], v[8:9] op_sel_hi:[0,1,1]
	v_mov_b32_e32 v14, v41
	v_pk_fma_f32 v[8:9], v[14:15], v[48:49], v[8:9] op_sel_hi:[0,1,1]
	v_pk_fma_f32 v[8:9], v[52:53], v[54:55], v[8:9] op_sel_hi:[0,1,1]
	v_mov_b32_e32 v14, v53
	v_pk_fma_f32 v[8:9], v[14:15], v[132:133], v[8:9] op_sel_hi:[0,1,1]
	v_max_f32_e32 v2, 0, v2
	v_max_f32_e32 v3, 0, v3
	v_pk_fma_f32 v[8:9], v[130:131], v[10:11], v[8:9] op_sel_hi:[0,1,1]
	v_mov_b32_e32 v10, v131
	v_pk_fma_f32 v[2:3], v[10:11], v[2:3], v[8:9] op_sel_hi:[0,1,1]
	v_and_b32_e32 v9, 0x7fffffff, v3
	v_and_b32_e32 v8, 0x7fffffff, v2
	v_xor_b32_e32 v5, -1, v3
	v_pk_add_f32 v[8:9], v[8:9], 0 neg_lo:[1,1] neg_hi:[1,1]
	v_cmp_gt_i32_e32 vcc, 0, v3
	v_xor_b32_e32 v10, -1, v2
	v_mov_b32_e32 v57, v160
	v_cndmask_b32_e32 v129, v9, v5, vcc
	v_cmp_gt_i32_e32 vcc, 0, v2
	v_pk_add_f32 v[2:3], v[36:37], 0 op_sel_hi:[1,0]
	v_max_f32_e32 v12, 0, v12
	v_pk_add_f32 v[2:3], v[2:3], v[30:31]
	v_pk_add_f32 v[2:3], v[2:3], v[44:45]
	v_mov_b32_e32 v135, v161
	v_pk_add_f32 v[2:3], v[2:3], v[50:51]
	v_mul_f32_e32 v12, v130, v12
	v_pk_add_f32 v[2:3], v[2:3], v[56:57]
	v_max_f32_e32 v4, 0, v4
	v_pk_add_f32 v[2:3], v[2:3], v[134:135]
	v_mov_b32_e32 v13, v6
	v_mul_f32_e32 v4, v131, v4
	v_pk_add_f32 v[2:3], v[2:3], v[12:13]
	v_mov_b32_e32 v5, v7
	v_pk_add_f32 v[2:3], v[2:3], v[4:5]
	v_cndmask_b32_e32 v130, v8, v10, vcc
	v_and_b32_e32 v5, 0x7fffffff, v3
	v_and_b32_e32 v4, 0x7fffffff, v2
	v_xor_b32_e32 v6, -1, v3
	v_pk_add_f32 v[4:5], v[4:5], 0 neg_lo:[1,1] neg_hi:[1,1]
	v_cmp_gt_i32_e32 vcc, 0, v3
	v_xor_b32_e32 v7, -1, v2
	s_nop 0
	v_cndmask_b32_e32 v131, v5, v6, vcc
	v_cmp_gt_i32_e32 vcc, 0, v2
	v_lshrrev_b32_e32 v2, 24, v130
	v_lshl_add_u32 v2, v2, 6, v0
	ds_add_u32 v2, v205 offset:16384
	v_lshrrev_b32_e32 v2, 24, v129
	v_cndmask_b32_e32 v132, v4, v7, vcc
	v_lshl_add_u32 v2, v2, 6, v0
	ds_add_u32 v2, v205 offset:16384
	v_lshrrev_b32_e32 v2, 24, v132
	v_lshl_add_u32 v2, v2, 6, v0
	ds_add_u32 v2, v205 offset:16384
	v_lshrrev_b32_e32 v2, 24, v131
	v_lshl_add_u32 v2, v2, 6, v0
	ds_add_u32 v2, v205 offset:16384
	v_add_co_u32_e32 v2, vcc, s96, v22
	s_nop 1
	v_addc_co_u32_e32 v3, vcc, 0, v23, vcc
	global_load_dwordx4 v[14:17], v[2:3], off
	global_load_dwordx4 v[10:13], v[2:3], off offset:64
	global_load_dwordx4 v[6:9], v[2:3], off offset:2048
	s_nop 0
	global_load_dwordx4 v[2:5], v[2:3], off offset:2112
	ds_read_b128 v[22:25], v144
	ds_read_b128 v[26:29], v145
	s_waitcnt vmcnt(3) lgkmcnt(1)
	v_mfma_f32_16x16x32_bf16 v[22:25], v[14:17], v[22:25], 0
	ds_read_b128 v[32:35], v142
	ds_read_b128 v[38:41], v138
	ds_read_b128 v[44:47], v143
	s_waitcnt vmcnt(2) lgkmcnt(3)
	v_mfma_f32_16x16x32_bf16 v[26:29], v[10:13], v[26:29], v[22:25]
	ds_read_b128 v[50:53], v147
	ds_read_b128 v[160:163], v149
	ds_read_b128 v[164:167], v178
	ds_read2_b32 v[24:25], v137 offset0:80 offset1:96
	s_nop 3
	v_max_f32_e32 v26, 0, v26
	v_max_f32_e32 v27, 0, v27
	v_max_f32_e32 v22, v28, v28
	v_max_f32_e32 v23, v29, v29
	ds_read_b128 v[28:31], v141
	s_waitcnt lgkmcnt(0)
	v_mfma_f32_16x16x32_bf16 v[28:31], v[14:17], v[28:31], 0
	v_max_f32_e32 v36, 0, v23
	v_max_f32_e32 v22, 0, v22
	v_mul_f32_e32 v22, v24, v22
	v_mfma_f32_16x16x32_bf16 v[28:31], v[10:13], v[32:35], v[28:31]
	s_nop 7
	v_max_f32_e32 v32, 0, v28
	v_max_f32_e32 v33, 0, v29
	v_max_f32_e32 v23, 0, v30
	v_mul_f32_e32 v28, v25, v23
	v_max_f32_e32 v37, 0, v31
	v_pk_mul_f32 v[30:31], v[24:25], v[36:37]
	ds_read_b128 v[34:37], v139
	s_waitcnt lgkmcnt(0)
	v_mfma_f32_16x16x32_bf16 v[34:37], v[14:17], v[34:37], 0
	v_mov_b32_e32 v29, v31
	v_mfma_f32_16x16x32_bf16 v[38:41], v[10:13], v[38:41], v[34:37]
	s_nop 5
	ds_read2_b32 v[36:37], v137 offset0:112 offset1:128
	s_nop 0
	v_max_f32_e32 v38, 0, v38
	v_max_f32_e32 v39, 0, v39
	v_max_f32_e32 v23, 0, v40
	s_waitcnt lgkmcnt(0)
	v_mul_f32_e32 v34, v36, v23
	v_max_f32_e32 v23, v41, v41
	ds_read_b128 v[40:43], v140
	s_waitcnt lgkmcnt(0)
; #define LAS __attribute__((address_space(3)))
; __device__ __forceinline__ unsigned fkey(float f) { const unsigned u = __float_as_uint(f); return (u & 0x80000000u) ? ~u : (u | 0x80000000u); }
; #define SEL_HADD(idx_) __hip_atomic_fetch_add(&hist[(idx_)], 1u, __ATOMIC_RELAXED, __HIP_MEMORY_SCOPE_WORKGROUP)
; __device__ __forceinline__ void sel_unit(LAS char* lds, int b, int u, const bf16_t* QI, const bf16_t* KIDX, const float* WIDX, unsigned long long* MASK) {
;     ...
;             for (int kh = 0; kh < 2; ++kh) {
;             bf16x8 kf[2][2];
; #pragma unroll
;             for (int kb = 0; kb < 2; ++kb)
; #pragma unroll
;                 for (int ks = 0; ks < 2; ++ks) kf[kb][ks] = *(const bf16x8*)(KIDX + (rowbase + 64 * t + 32 * kh + 16 * kb + q16) * 64 + 32 * ks + 8 * kg);
; #pragma unroll
;             for (int kb = 0; kb < 2; ++kb) {
;                 f32x4 s = (f32x4){0.f, 0.f, 0.f, 0.f};
; #pragma unroll
;                 for (int hh = 0; hh < 8; ++hh) {
;                     f32x4 a = (f32x4){0.f, 0.f, 0.f, 0.f};
; #pragma unroll
;                     for (int ks = 0; ks < 2; ++ks) {
;                         const bf16x8 qv = *(const LAS bf16x8*)(lds + L_QI + q16 * 1024 + (((hh * 8 + 4 * ks + kg) ^ q16) << 4));
;                         a = __builtin_amdgcn_mfma_f32_16x16x32_bf16(kf[kb][ks], qv, a, 0, 0, 0);
;                     }
;                     const float wh = wl[hh * 16];
; #pragma unroll
;                     for (int i = 0; i < 4; ++i) s[i] += wh * fmaxf(a[i], 0.f);
;                 }
;                 u32x4 kk; kk.x = fkey(s[0]); kk.y = fkey(s[1]); kk.z = fkey(s[2]); kk.w = fkey(s[3]);
;                 sc[j][2 * kh + kb] = kk;
; #pragma unroll
;                 for (int i = 0; i < 4; ++i) SEL_HADD((kk[i] >> 24) * 16 + q16);
;                 __builtin_amdgcn_sched_barrier(0);
	v_mfma_f32_16x16x32_bf16 v[40:43], v[14:17], v[40:43], 0
	v_max_f32_e32 v48, 0, v23
	v_mfma_f32_16x16x32_bf16 v[40:43], v[10:13], v[44:47], v[40:43]
	s_nop 7
	v_max_f32_e32 v44, 0, v40
	v_max_f32_e32 v45, 0, v41
	v_max_f32_e32 v23, 0, v42
	v_mul_f32_e32 v40, v37, v23
	v_max_f32_e32 v49, 0, v43
	v_pk_mul_f32 v[42:43], v[36:37], v[48:49]
	ds_read_b128 v[46:49], v146
	s_waitcnt lgkmcnt(0)
	v_mfma_f32_16x16x32_bf16 v[46:49], v[14:17], v[46:49], 0
	v_mov_b32_e32 v35, v42
	v_mov_b32_e32 v41, v43
	v_mfma_f32_16x16x32_bf16 v[50:53], v[10:13], v[50:53], v[46:49]
	s_nop 4
	ds_read2_b32 v[48:49], v137 offset0:144 offset1:160
	s_nop 1
	v_max_f32_e32 v50, 0, v50
	v_max_f32_e32 v51, 0, v51
	v_max_f32_e32 v23, 0, v52
	s_waitcnt lgkmcnt(0)
	v_mul_f32_e32 v46, v48, v23
	v_max_f32_e32 v23, v53, v53
	ds_read_b128 v[52:55], v148
	s_waitcnt lgkmcnt(0)
	v_mfma_f32_16x16x32_bf16 v[52:55], v[14:17], v[52:55], 0
	v_max_f32_e32 v134, 0, v23
	v_mfma_f32_16x16x32_bf16 v[52:55], v[10:13], v[160:163], v[52:55]
	ds_read_b128 v[160:163], v177
	s_waitcnt lgkmcnt(0)
	v_mfma_f32_16x16x32_bf16 v[160:163], v[14:17], v[160:163], 0
	s_nop 4
	v_max_f32_e32 v56, 0, v52
	v_max_f32_e32 v57, 0, v53
	v_max_f32_e32 v23, 0, v54
	v_mfma_f32_16x16x32_bf16 v[160:163], v[10:13], v[164:167], v[160:163]
	v_mul_f32_e32 v52, v49, v23
	s_nop 0
	v_max_f32_e32 v135, 0, v55
	v_pk_mul_f32 v[54:55], v[48:49], v[134:135]
	ds_read2_b32 v[134:135], v137 offset0:176 offset1:192
	s_nop 2
	v_max_f32_e32 v164, 0, v160
	v_max_f32_e32 v165, 0, v161
	v_max_f32_e32 v23, 0, v162
	s_waitcnt lgkmcnt(0)
	v_mul_f32_e32 v166, v134, v23
	v_max_f32_e32 v23, v163, v163
	ds_read_b128 v[160:163], v181
	s_waitcnt lgkmcnt(0)
	v_mfma_f32_16x16x32_bf16 v[14:17], v[14:17], v[160:163], 0
	ds_read_b128 v[160:163], v186
	v_max_f32_e32 v168, 0, v23
	v_mov_b32_e32 v47, v54
	s_waitcnt lgkmcnt(0)
	v_mfma_f32_16x16x32_bf16 v[10:13], v[10:13], v[160:163], v[14:17]
	v_mov_b32_e32 v53, v55
	s_nop 1
	v_pk_fma_f32 v[16:17], v[24:25], v[26:27], 0 op_sel_hi:[0,1,0]
	v_mov_b32_e32 v24, v25
	v_pk_fma_f32 v[16:17], v[24:25], v[32:33], v[16:17] op_sel_hi:[0,1,1]
	v_pk_fma_f32 v[16:17], v[36:37], v[38:39], v[16:17] op_sel_hi:[0,1,1]
	v_mov_b32_e32 v24, v37
	v_pk_fma_f32 v[16:17], v[24:25], v[44:45], v[16:17] op_sel_hi:[0,1,1]
	v_pk_fma_f32 v[16:17], v[48:49], v[50:51], v[16:17] op_sel_hi:[0,1,1]
	v_mov_b32_e32 v24, v49
	v_pk_fma_f32 v[16:17], v[24:25], v[56:57], v[16:17] op_sel_hi:[0,1,1]
	v_max_f32_e32 v10, 0, v10
	v_max_f32_e32 v11, 0, v11
	v_pk_fma_f32 v[16:17], v[134:135], v[164:165], v[16:17] op_sel_hi:[0,1,1]
	v_mov_b32_e32 v24, v135
	v_pk_fma_f32 v[10:11], v[24:25], v[10:11], v[16:17] op_sel_hi:[0,1,1]
	v_and_b32_e32 v17, 0x7fffffff, v11
	v_and_b32_e32 v16, 0x7fffffff, v10
	v_max_f32_e32 v169, 0, v13
	v_xor_b32_e32 v23, -1, v10
	v_pk_add_f32 v[16:17], v[16:17], 0 neg_lo:[1,1] neg_hi:[1,1]
	v_cmp_gt_i32_e32 vcc, 0, v10
	v_pk_mul_f32 v[14:15], v[134:135], v[168:169]
	v_xor_b32_e32 v13, -1, v11
	v_cndmask_b32_e32 v134, v16, v23, vcc
	v_mov_b32_e32 v23, v30
	v_cmp_gt_i32_e64 s[2:3], 0, v11
	v_pk_add_f32 v[10:11], v[22:23], 0 op_sel_hi:[1,0]
	v_pk_add_f32 v[10:11], v[10:11], v[28:29]
	v_max_f32_e32 v12, 0, v12
	v_pk_add_f32 v[10:11], v[10:11], v[34:35]
	v_mov_b32_e32 v167, v14
	v_pk_add_f32 v[10:11], v[10:11], v[40:41]
	v_mul_f32_e32 v12, v135, v12
	v_pk_add_f32 v[10:11], v[10:11], v[46:47]
	v_cndmask_b32_e64 v133, v17, v13, s[2:3]
	v_pk_add_f32 v[10:11], v[10:11], v[52:53]
	v_mov_b32_e32 v13, v15
	v_pk_add_f32 v[10:11], v[10:11], v[166:167]
	s_nop 0
	v_pk_add_f32 v[10:11], v[10:11], v[12:13]
	s_nop 0
	v_xor_b32_e32 v15, -1, v10
	v_and_b32_e32 v12, 0x7fffffff, v10
	v_cmp_gt_i32_e32 vcc, 0, v10
	v_lshrrev_b32_e32 v10, 24, v134
	v_and_b32_e32 v13, 0x7fffffff, v11
	v_lshl_add_u32 v10, v10, 6, v0
	v_pk_add_f32 v[12:13], v[12:13], 0 neg_lo:[1,1] neg_hi:[1,1]
	ds_add_u32 v10, v205 offset:16384
	v_lshrrev_b32_e32 v10, 24, v133
	v_cndmask_b32_e32 v136, v12, v15, vcc
	v_lshl_add_u32 v10, v10, 6, v0
	v_xor_b32_e32 v14, -1, v11
	v_cmp_gt_i32_e64 s[2:3], 0, v11
	ds_add_u32 v10, v205 offset:16384
	v_lshrrev_b32_e32 v10, 24, v136
	v_cndmask_b32_e64 v135, v13, v14, s[2:3]
	v_lshl_add_u32 v10, v10, 6, v0
	ds_add_u32 v10, v205 offset:16384
	v_lshrrev_b32_e32 v10, 24, v135
	v_lshl_add_u32 v10, v10, 6, v0
	ds_add_u32 v10, v205 offset:16384
	ds_read_b128 v[10:13], v144
	ds_read_b128 v[14:17], v145
	ds_read_b128 v[22:25], v141
	ds_read_b128 v[26:29], v142
	ds_read2_b32 v[30:31], v137 offset0:80 offset1:96
	ds_read2_b32 v[38:39], v137 offset0:112 offset1:128
	s_waitcnt vmcnt(1) lgkmcnt(5)
	v_mfma_f32_16x16x32_bf16 v[10:13], v[6:9], v[10:13], 0
	ds_read2_b32 v[50:51], v137 offset0:144 offset1:160
	s_waitcnt vmcnt(0) lgkmcnt(5)
	v_mfma_f32_16x16x32_bf16 v[10:13], v[2:5], v[14:17], v[10:13]
	ds_read_b128 v[14:17], v139
	s_waitcnt lgkmcnt(5)
	v_mfma_f32_16x16x32_bf16 v[22:25], v[6:9], v[22:25], 0
	s_nop 4
	v_max_f32_e32 v32, 0, v10
	v_max_f32_e32 v10, 0, v12
	v_max_f32_e32 v33, 0, v11
	s_waitcnt lgkmcnt(3)
	v_mul_f32_e32 v34, v30, v10
	v_max_f32_e32 v36, 0, v13
	v_mfma_f32_16x16x32_bf16 v[10:13], v[2:5], v[26:29], v[22:25]
	s_nop 2
	ds_read_b128 v[22:25], v138
	s_waitcnt lgkmcnt(1)
	v_mfma_f32_16x16x32_bf16 v[14:17], v[6:9], v[14:17], 0
	s_nop 1
	v_max_f32_e32 v26, 0, v10
	v_max_f32_e32 v27, 0, v11
	v_max_f32_e32 v10, 0, v12
	v_mul_f32_e32 v28, v31, v10
	v_max_f32_e32 v37, 0, v13
	s_waitcnt lgkmcnt(0)
	v_mfma_f32_16x16x32_bf16 v[10:13], v[2:5], v[22:25], v[14:17]
	ds_read_b128 v[22:25], v143
	ds_read2_b32 v[142:143], v137 offset0:176 offset1:192
	v_pk_mul_f32 v[36:37], v[30:31], v[36:37]
	ds_read_b128 v[14:17], v140
	s_waitcnt lgkmcnt(0)
; #define LAS __attribute__((address_space(3)))
; __device__ __forceinline__ unsigned fkey(float f) { const unsigned u = __float_as_uint(f); return (u & 0x80000000u) ? ~u : (u | 0x80000000u); }
; #define SEL_HADD(idx_) __hip_atomic_fetch_add(&hist[(idx_)], 1u, __ATOMIC_RELAXED, __HIP_MEMORY_SCOPE_WORKGROUP)
; __device__ __forceinline__ void sel_unit(LAS char* lds, int b, int u, const bf16_t* QI, const bf16_t* KIDX, const float* WIDX, unsigned long long* MASK) {
;     ...
;     for (int j = 0; j < 8; ++j) {
;         if (j < nj) {
;             int t = wid + 8 * j; asm volatile("" : "+s"(t));
; #pragma unroll
;             for (int kh = 0; kh < 2; ++kh) {
;             bf16x8 kf[2][2];
; #pragma unroll
;             for (int kb = 0; kb < 2; ++kb)
; #pragma unroll
;                 for (int ks = 0; ks < 2; ++ks) kf[kb][ks] = *(const bf16x8*)(KIDX + (rowbase + 64 * t + 32 * kh + 16 * kb + q16) * 64 + 32 * ks + 8 * kg);
; #pragma unroll
;             for (int kb = 0; kb < 2; ++kb) {
;                 f32x4 s = (f32x4){0.f, 0.f, 0.f, 0.f};
; #pragma unroll
;                 for (int hh = 0; hh < 8; ++hh) {
;                     f32x4 a = (f32x4){0.f, 0.f, 0.f, 0.f};
; #pragma unroll
;                     for (int ks = 0; ks < 2; ++ks) {
;                         const bf16x8 qv = *(const LAS bf16x8*)(lds + L_QI + q16 * 1024 + (((hh * 8 + 4 * ks + kg) ^ q16) << 4));
;                         a = __builtin_amdgcn_mfma_f32_16x16x32_bf16(kf[kb][ks], qv, a, 0, 0, 0);
;                     }
;                     const float wh = wl[hh * 16];
; #pragma unroll
;                     for (int i = 0; i < 4; ++i) s[i] += wh * fmaxf(a[i], 0.f);
;                 }
;                 u32x4 kk; kk.x = fkey(s[0]); kk.y = fkey(s[1]); kk.z = fkey(s[2]); kk.w = fkey(s[3]);
;                 sc[j][2 * kh + kb] = kk;
; #pragma unroll
;                 for (int i = 0; i < 4; ++i) SEL_HADD((kk[i] >> 24) * 16 + q16);
;                 __builtin_amdgcn_sched_barrier(0);
	v_mfma_f32_16x16x32_bf16 v[14:17], v[6:9], v[14:17], 0
	s_nop 1
	v_max_f32_e32 v40, 0, v10
	v_max_f32_e32 v41, 0, v11
	v_max_f32_e32 v10, 0, v12
	v_mul_f32_e32 v42, v38, v10
	s_nop 0
	v_max_f32_e32 v44, 0, v13
	v_mfma_f32_16x16x32_bf16 v[10:13], v[2:5], v[22:25], v[14:17]
	ds_read_b128 v[22:25], v147
	v_mov_b32_e32 v35, v36
	v_mov_b32_e32 v29, v37
	ds_read_b128 v[14:17], v146
	s_waitcnt lgkmcnt(0)
	v_mfma_f32_16x16x32_bf16 v[14:17], v[6:9], v[14:17], 0
	s_nop 1
	v_max_f32_e32 v46, 0, v10
	v_max_f32_e32 v47, 0, v11
	v_max_f32_e32 v10, 0, v12
	v_mul_f32_e32 v48, v39, v10
	s_nop 0
	v_max_f32_e32 v45, 0, v13
	v_mfma_f32_16x16x32_bf16 v[10:13], v[2:5], v[22:25], v[14:17]
	ds_read_b128 v[22:25], v149
	v_pk_mul_f32 v[44:45], v[38:39], v[44:45]
	s_nop 0
	ds_read_b128 v[14:17], v148
	s_waitcnt lgkmcnt(0)
	v_mfma_f32_16x16x32_bf16 v[14:17], v[6:9], v[14:17], 0
	s_nop 1
	v_max_f32_e32 v52, 0, v10
	v_max_f32_e32 v53, 0, v11
	v_max_f32_e32 v10, 0, v12
	v_mul_f32_e32 v54, v50, v10
	s_nop 0
	v_max_f32_e32 v56, 0, v13
	v_mfma_f32_16x16x32_bf16 v[10:13], v[2:5], v[22:25], v[14:17]
	ds_read_b128 v[22:25], v178
	v_mov_b32_e32 v43, v44
	v_mov_b32_e32 v49, v45
	ds_read_b128 v[14:17], v177
	s_waitcnt lgkmcnt(0)
	v_mfma_f32_16x16x32_bf16 v[14:17], v[6:9], v[14:17], 0
	s_nop 1
	v_max_f32_e32 v138, 0, v10
	v_max_f32_e32 v139, 0, v11
	v_max_f32_e32 v10, 0, v12
	v_mul_f32_e32 v140, v51, v10
	s_nop 0
	v_max_f32_e32 v57, 0, v13
	v_mfma_f32_16x16x32_bf16 v[10:13], v[2:5], v[22:25], v[14:17]
	ds_read_b128 v[22:25], v186
	v_pk_mul_f32 v[56:57], v[50:51], v[56:57]
	s_nop 0
	ds_read_b128 v[14:17], v181
	s_waitcnt lgkmcnt(0)
	v_mfma_f32_16x16x32_bf16 v[6:9], v[6:9], v[14:17], 0
	s_nop 1
	s_nop 0
	v_max_f32_e32 v14, 0, v13
	s_nop 0
	v_mfma_f32_16x16x32_bf16 v[2:5], v[2:5], v[22:25], v[6:9]
	s_nop 0
	v_max_f32_e32 v10, 0, v10
	v_max_f32_e32 v11, 0, v11
	v_pk_fma_f32 v[8:9], v[30:31], v[32:33], 0 op_sel_hi:[0,1,0]
	s_nop 0
	s_nop 2
	v_max_f32_e32 v15, 0, v5
	v_pk_mul_f32 v[6:7], v[142:143], v[14:15]
	v_mov_b32_e32 v14, v31
	v_pk_fma_f32 v[8:9], v[14:15], v[26:27], v[8:9] op_sel_hi:[0,1,1]
	v_pk_fma_f32 v[8:9], v[38:39], v[40:41], v[8:9] op_sel_hi:[0,1,1]
	v_mov_b32_e32 v14, v39
	v_pk_fma_f32 v[8:9], v[14:15], v[46:47], v[8:9] op_sel_hi:[0,1,1]
	v_pk_fma_f32 v[8:9], v[50:51], v[52:53], v[8:9] op_sel_hi:[0,1,1]
	v_mov_b32_e32 v14, v51
	v_pk_fma_f32 v[8:9], v[14:15], v[138:139], v[8:9] op_sel_hi:[0,1,1]
	v_max_f32_e32 v2, 0, v2
	v_max_f32_e32 v3, 0, v3
	v_pk_fma_f32 v[8:9], v[142:143], v[10:11], v[8:9] op_sel_hi:[0,1,1]
	v_mov_b32_e32 v10, v143
	v_pk_fma_f32 v[2:3], v[10:11], v[2:3], v[8:9] op_sel_hi:[0,1,1]
	v_and_b32_e32 v9, 0x7fffffff, v3
	v_and_b32_e32 v8, 0x7fffffff, v2
	v_xor_b32_e32 v5, -1, v3
	v_pk_add_f32 v[8:9], v[8:9], 0 neg_lo:[1,1] neg_hi:[1,1]
	v_cmp_gt_i32_e32 vcc, 0, v3
	v_xor_b32_e32 v10, -1, v2
	v_mov_b32_e32 v55, v56
	v_cndmask_b32_e32 v138, v9, v5, vcc
	v_cmp_gt_i32_e32 vcc, 0, v2
	v_pk_add_f32 v[2:3], v[34:35], 0 op_sel_hi:[1,0]
	v_max_f32_e32 v12, 0, v12
	v_pk_add_f32 v[2:3], v[2:3], v[28:29]
	v_pk_add_f32 v[2:3], v[2:3], v[42:43]
	v_mov_b32_e32 v141, v57
	v_pk_add_f32 v[2:3], v[2:3], v[48:49]
	v_mul_f32_e32 v12, v142, v12
	v_pk_add_f32 v[2:3], v[2:3], v[54:55]
	v_max_f32_e32 v4, 0, v4
	v_pk_add_f32 v[2:3], v[2:3], v[140:141]
	v_mov_b32_e32 v13, v6
	v_mul_f32_e32 v4, v143, v4
	v_pk_add_f32 v[2:3], v[2:3], v[12:13]
	v_mov_b32_e32 v5, v7
	v_pk_add_f32 v[2:3], v[2:3], v[4:5]
	v_cndmask_b32_e32 v139, v8, v10, vcc
	v_and_b32_e32 v5, 0x7fffffff, v3
	v_and_b32_e32 v4, 0x7fffffff, v2
	v_xor_b32_e32 v6, -1, v3
	v_pk_add_f32 v[4:5], v[4:5], 0 neg_lo:[1,1] neg_hi:[1,1]
	v_cmp_gt_i32_e32 vcc, 0, v3
	v_xor_b32_e32 v7, -1, v2
	s_nop 0
	v_cndmask_b32_e32 v140, v5, v6, vcc
	v_cmp_gt_i32_e32 vcc, 0, v2
	v_lshrrev_b32_e32 v2, 24, v139
	v_lshl_add_u32 v2, v2, 6, v0
	ds_add_u32 v2, v205 offset:16384
	v_lshrrev_b32_e32 v2, 24, v138
	v_cndmask_b32_e32 v141, v4, v7, vcc
	v_lshl_add_u32 v2, v2, 6, v0
	ds_add_u32 v2, v205 offset:16384
	v_lshrrev_b32_e32 v2, 24, v141
	v_lshl_add_u32 v2, v2, 6, v0
	ds_add_u32 v2, v205 offset:16384
	v_lshrrev_b32_e32 v2, 24, v140
	v_lshl_add_u32 v2, v2, 6, v0
	ds_add_u32 v2, v205 offset:16384
.LBB0_666:
	s_cmp_gt_i32 s4, 5
	s_cselect_b64 s[48:49], -1, 0
	s_cmp_lt_i32 s4, 6
	s_cbranch_scc1 .LBB0_668
; #define LAS __attribute__((address_space(3)))
; __device__ __forceinline__ unsigned fkey(float f) { const unsigned u = __float_as_uint(f); return (u & 0x80000000u) ? ~u : (u | 0x80000000u); }
; #define SEL_HADD(idx_) __hip_atomic_fetch_add(&hist[(idx_)], 1u, __ATOMIC_RELAXED, __HIP_MEMORY_SCOPE_WORKGROUP)
; __device__ __forceinline__ void sel_unit(LAS char* lds, int b, int u, const bf16_t* QI, const bf16_t* KIDX, const float* WIDX, unsigned long long* MASK) {
;     ...
;     for (int j = 0; j < 8; ++j) {
;         if (j < nj) {
;             int t = wid + 8 * j; asm volatile("" : "+s"(t));
; #pragma unroll
;             for (int kh = 0; kh < 2; ++kh) {
;             bf16x8 kf[2][2];
; #pragma unroll
;             for (int kb = 0; kb < 2; ++kb)
; #pragma unroll
;                 for (int ks = 0; ks < 2; ++ks) kf[kb][ks] = *(const bf16x8*)(KIDX + (rowbase + 64 * t + 32 * kh + 16 * kb + q16) * 64 + 32 * ks + 8 * kg);
; #pragma unroll
;             for (int kb = 0; kb < 2; ++kb) {
;                 f32x4 s = (f32x4){0.f, 0.f, 0.f, 0.f};
; #pragma unroll
;                 for (int hh = 0; hh < 8; ++hh) {
;                     f32x4 a = (f32x4){0.f, 0.f, 0.f, 0.f};
; #pragma unroll
;                     for (int ks = 0; ks < 2; ++ks) {
;                         const bf16x8 qv = *(const LAS bf16x8*)(lds + L_QI + q16 * 1024 + (((hh * 8 + 4 * ks + kg) ^ q16) << 4));
;                         a = __builtin_amdgcn_mfma_f32_16x16x32_bf16(kf[kb][ks], qv, a, 0, 0, 0);
;                     }
;                     const float wh = wl[hh * 16];
; #pragma unroll
;                     for (int i = 0; i < 4; ++i) s[i] += wh * fmaxf(a[i], 0.f);
;                 }
;                 u32x4 kk; kk.x = fkey(s[0]); kk.y = fkey(s[1]); kk.z = fkey(s[2]); kk.w = fkey(s[3]);
;                 sc[j][2 * kh + kb] = kk;
; #pragma unroll
;                 for (int i = 0; i < 4; ++i) SEL_HADD((kk[i] >> 24) * 16 + q16);
;                 __builtin_amdgcn_sched_barrier(0);
	s_add_i32 s0, s46, 40
	s_lshl_b32 s0, s0, 6
	s_ashr_i32 s1, s0, 31
	v_lshl_add_u64 v[2:3], v[18:19], 0, s[0:1]
	v_lshlrev_b64 v[2:3], 7, v[2:3]
	v_lshl_add_u64 v[22:23], v[20:21], 0, v[2:3]
	global_load_dwordx4 v[14:17], v[22:23], off
	global_load_dwordx4 v[10:13], v[22:23], off offset:64
	v_lshl_add_u32 v193, v182, 4, v150
	v_lshl_add_u32 v194, v183, 4, v150
	v_lshl_add_u32 v191, v185, 4, v150
	v_lshl_add_u32 v187, v180, 4, v150
	v_lshl_add_u32 v192, v159, 4, v150
	v_lshl_add_u32 v190, v184, 4, v150
	ds_read_b128 v[2:5], v193
	v_lshl_add_u32 v188, v179, 4, v150
	ds_read_b128 v[6:9], v194
	ds_read_b128 v[24:27], v190
	v_lshl_add_u32 v189, v176, 4, v150
	ds_read_b128 v[28:31], v191
	ds_read_b128 v[32:35], v188
	ds_read_b128 v[36:39], v187
	ds_read_b128 v[40:43], v189
	v_lshl_add_u32 v195, v158, 4, v150
	ds_read_b128 v[44:47], v192
	ds_read_b128 v[48:51], v195
	v_lshl_add_u32 v196, v157, 4, v150
	ds_read_b128 v[52:55], v196
	v_lshl_add_u32 v197, v156, 4, v150
	v_lshl_add_u32 v198, v155, 4, v150
	ds_read_b128 v[142:145], v197
	ds_read_b128 v[146:149], v198
	v_lshl_add_u32 v199, v154, 4, v150
	v_lshl_add_u32 v218, v153, 4, v150
	v_lshl_add_u32 v219, v152, 4, v150
	v_lshl_add_u32 v220, v151, 4, v150
	s_waitcnt vmcnt(1) lgkmcnt(11)
	v_mfma_f32_16x16x32_bf16 v[2:5], v[14:17], v[2:5], 0
	s_waitcnt lgkmcnt(9)
	v_mfma_f32_16x16x32_bf16 v[24:27], v[14:17], v[24:27], 0
	s_waitcnt lgkmcnt(7)
	v_mfma_f32_16x16x32_bf16 v[32:35], v[14:17], v[32:35], 0
	s_waitcnt lgkmcnt(5)
	v_mfma_f32_16x16x32_bf16 v[40:43], v[14:17], v[40:43], 0
	s_waitcnt lgkmcnt(3)
	v_mfma_f32_16x16x32_bf16 v[48:51], v[14:17], v[48:51], 0
	s_waitcnt vmcnt(0)
	v_mfma_f32_16x16x32_bf16 v[160:163], v[10:13], v[6:9], v[2:5]
	v_mfma_f32_16x16x32_bf16 v[24:27], v[10:13], v[28:31], v[24:27]
	v_mfma_f32_16x16x32_bf16 v[28:31], v[10:13], v[36:39], v[32:35]
	v_mfma_f32_16x16x32_bf16 v[32:35], v[10:13], v[44:47], v[40:43]
	ds_read2_b32 v[44:45], v137 offset0:80 offset1:96
	ds_read2_b32 v[46:47], v137 offset0:112 offset1:128
	s_nop 3
	s_waitcnt lgkmcnt(4)
	v_mfma_f32_16x16x32_bf16 v[36:39], v[10:13], v[52:55], v[48:51]
	ds_read2_b32 v[48:49], v137 offset0:144 offset1:160
	global_load_dwordx4 v[6:9], v[22:23], off offset:2048
	global_load_dwordx4 v[2:5], v[22:23], off offset:2112
	s_waitcnt lgkmcnt(4)
	v_mfma_f32_16x16x32_bf16 v[142:145], v[14:17], v[142:145], 0
	s_nop 0
	s_nop 0
	v_max_f32_e32 v54, v24, v24
	s_waitcnt lgkmcnt(3)
	v_mfma_f32_16x16x32_bf16 v[40:43], v[10:13], v[146:149], v[142:145]
	s_nop 0
	s_nop 0
	v_max_f32_e32 v24, 0, v163
	v_max_f32_e32 v142, v39, v39
	v_max_f32_e32 v39, 0, v25
	s_nop 2
	v_max_f32_e32 v145, 0, v26
	v_max_f32_e32 v25, 0, v27
	v_max_f32_e32 v26, 0, v31
	v_max_f32_e32 v27, 0, v35
	v_max_f32_e32 v50, v160, v160
	v_max_f32_e32 v51, v161, v161
	v_max_f32_e32 v147, v42, v42
	v_max_f32_e32 v42, 0, v162
	v_max_f32_e32 v52, 0, v36
	v_max_f32_e32 v53, 0, v37
	v_max_f32_e32 v55, 0, v41
	s_waitcnt lgkmcnt(2)
	v_mul_f32_e32 v56, v45, v145
	v_pk_mul_f32 v[144:145], v[44:45], v[24:25]
	s_waitcnt lgkmcnt(1)
	v_pk_mul_f32 v[160:161], v[46:47], v[26:27]
	ds_read_b128 v[24:27], v199
	v_max_f32_e32 v143, v40, v40
	v_max_f32_e32 v40, 0, v28
	v_max_f32_e32 v28, 0, v30
	v_max_f32_e32 v41, 0, v29
	v_max_f32_e32 v29, 0, v34
	v_max_f32_e32 v30, 0, v38
	v_mul_f32_e32 v146, v46, v28
	v_max_f32_e32 v28, 0, v147
	v_mul_f32_e32 v148, v47, v29
	s_waitcnt lgkmcnt(1)
	v_mul_f32_e32 v162, v48, v30
	v_mul_f32_e32 v164, v49, v28
	ds_read_b128 v[28:31], v218
	s_waitcnt lgkmcnt(1)
	v_mfma_f32_16x16x32_bf16 v[24:27], v[14:17], v[24:27], 0
	v_max_f32_e32 v37, 0, v51
	s_waitcnt lgkmcnt(0)
	v_mfma_f32_16x16x32_bf16 v[24:27], v[10:13], v[28:31], v[24:27]
	ds_read_b128 v[28:31], v219
	v_max_f32_e32 v51, 0, v33
	v_max_f32_e32 v36, 0, v50
	v_max_f32_e32 v50, 0, v32
	v_max_f32_e32 v32, 0, v142
	v_max_f32_e32 v33, 0, v43
	v_pk_mul_f32 v[166:167], v[48:49], v[32:33]
	ds_read_b128 v[32:35], v220
	s_waitcnt lgkmcnt(1)
	v_mfma_f32_16x16x32_bf16 v[14:17], v[14:17], v[28:31], 0
	v_max_f32_e32 v38, 0, v54
	v_max_f32_e32 v54, 0, v143
	ds_read2_b32 v[142:143], v137 offset0:176 offset1:192
	s_waitcnt lgkmcnt(1)
	v_mfma_f32_16x16x32_bf16 v[10:13], v[10:13], v[32:35], v[14:17]
	s_nop 0
	v_max_f32_e32 v28, 0, v27
	s_nop 0
	v_pk_fma_f32 v[16:17], v[44:45], v[36:37], 0 op_sel_hi:[0,1,0]
	s_nop 0
	s_nop 2
	v_max_f32_e32 v29, 0, v13
	s_waitcnt lgkmcnt(0)
; #define LAS __attribute__((address_space(3)))
; __device__ __forceinline__ unsigned fkey(float f) { const unsigned u = __float_as_uint(f); return (u & 0x80000000u) ? ~u : (u | 0x80000000u); }
; #define SEL_HADD(idx_) __hip_atomic_fetch_add(&hist[(idx_)], 1u, __ATOMIC_RELAXED, __HIP_MEMORY_SCOPE_WORKGROUP)
; __device__ __forceinline__ void sel_unit(LAS char* lds, int b, int u, const bf16_t* QI, const bf16_t* KIDX, const float* WIDX, unsigned long long* MASK) {
;     ...
;                 for (int ks = 0; ks < 2; ++ks) kf[kb][ks] = *(const bf16x8*)(KIDX + (rowbase + 64 * t + 32 * kh + 16 * kb + q16) * 64 + 32 * ks + 8 * kg);
; #pragma unroll
;             for (int kb = 0; kb < 2; ++kb) {
;                 f32x4 s = (f32x4){0.f, 0.f, 0.f, 0.f};
; #pragma unroll
;                 for (int hh = 0; hh < 8; ++hh) {
;                     f32x4 a = (f32x4){0.f, 0.f, 0.f, 0.f};
; #pragma unroll
;                     for (int ks = 0; ks < 2; ++ks) {
;                         const bf16x8 qv = *(const LAS bf16x8*)(lds + L_QI + q16 * 1024 + (((hh * 8 + 4 * ks + kg) ^ q16) << 4));
;                         a = __builtin_amdgcn_mfma_f32_16x16x32_bf16(kf[kb][ks], qv, a, 0, 0, 0);
;                     }
;                     const float wh = wl[hh * 16];
; #pragma unroll
;                     for (int i = 0; i < 4; ++i) s[i] += wh * fmaxf(a[i], 0.f);
;                 }
;                 u32x4 kk; kk.x = fkey(s[0]); kk.y = fkey(s[1]); kk.z = fkey(s[2]); kk.w = fkey(s[3]);
;                 sc[j][2 * kh + kb] = kk;
; #pragma unroll
;                 for (int i = 0; i < 4; ++i) SEL_HADD((kk[i] >> 24) * 16 + q16);
;                 __builtin_amdgcn_sched_barrier(0);
	v_pk_mul_f32 v[14:15], v[142:143], v[28:29]
	v_mov_b32_e32 v28, v45
	v_pk_fma_f32 v[16:17], v[28:29], v[38:39], v[16:17] op_sel_hi:[0,1,1]
	v_pk_fma_f32 v[16:17], v[46:47], v[40:41], v[16:17] op_sel_hi:[0,1,1]
	v_mov_b32_e32 v28, v47
	v_pk_fma_f32 v[16:17], v[28:29], v[50:51], v[16:17] op_sel_hi:[0,1,1]
	v_pk_fma_f32 v[16:17], v[48:49], v[52:53], v[16:17] op_sel_hi:[0,1,1]
	v_mov_b32_e32 v28, v49
	v_max_f32_e32 v24, 0, v24
	v_max_f32_e32 v25, 0, v25
	v_pk_fma_f32 v[16:17], v[28:29], v[54:55], v[16:17] op_sel_hi:[0,1,1]
	v_max_f32_e32 v10, 0, v10
	v_max_f32_e32 v11, 0, v11
	v_pk_fma_f32 v[16:17], v[142:143], v[24:25], v[16:17] op_sel_hi:[0,1,1]
	v_mov_b32_e32 v24, v143
	v_pk_fma_f32 v[10:11], v[24:25], v[10:11], v[16:17] op_sel_hi:[0,1,1]
	v_and_b32_e32 v17, 0x7fffffff, v11
	v_and_b32_e32 v16, 0x7fffffff, v10
	v_mul_f32_e32 v42, v44, v42
	v_max_f32_e32 v26, 0, v26
	v_xor_b32_e32 v13, -1, v11
	v_pk_add_f32 v[16:17], v[16:17], 0 neg_lo:[1,1] neg_hi:[1,1]
	v_cmp_gt_i32_e32 vcc, 0, v11
	v_mov_b32_e32 v43, v144
	v_mul_f32_e32 v26, v142, v26
	v_xor_b32_e32 v24, -1, v10
	v_cndmask_b32_e32 v142, v17, v13, vcc
	v_cmp_gt_i32_e32 vcc, 0, v10
	v_pk_add_f32 v[10:11], v[42:43], 0 op_sel_hi:[1,0]
	v_mov_b32_e32 v57, v145
	v_pk_add_f32 v[10:11], v[10:11], v[56:57]
	v_mov_b32_e32 v147, v160
	v_pk_add_f32 v[10:11], v[10:11], v[146:147]
	v_mov_b32_e32 v149, v161
	v_pk_add_f32 v[10:11], v[10:11], v[148:149]
	v_mov_b32_e32 v163, v166
	v_pk_add_f32 v[10:11], v[10:11], v[162:163]
	v_mov_b32_e32 v165, v167
	v_max_f32_e32 v12, 0, v12
	v_pk_add_f32 v[10:11], v[10:11], v[164:165]
	v_mov_b32_e32 v27, v14
	v_mul_f32_e32 v12, v143, v12
	v_pk_add_f32 v[10:11], v[10:11], v[26:27]
	v_mov_b32_e32 v13, v15
	v_pk_add_f32 v[10:11], v[10:11], v[12:13]
	v_cndmask_b32_e32 v143, v16, v24, vcc
	v_and_b32_e32 v13, 0x7fffffff, v11
	v_and_b32_e32 v12, 0x7fffffff, v10
	v_xor_b32_e32 v14, -1, v11
	v_pk_add_f32 v[12:13], v[12:13], 0 neg_lo:[1,1] neg_hi:[1,1]
	v_cmp_gt_i32_e32 vcc, 0, v11
	v_xor_b32_e32 v15, -1, v10
	s_nop 0
	v_cndmask_b32_e32 v144, v13, v14, vcc
	v_cmp_gt_i32_e32 vcc, 0, v10
	v_lshrrev_b32_e32 v10, 24, v143
	v_lshl_add_u32 v10, v10, 6, v0
	ds_add_u32 v10, v205 offset:16384
	v_lshrrev_b32_e32 v10, 24, v142
	v_cndmask_b32_e32 v145, v12, v15, vcc
	v_lshl_add_u32 v10, v10, 6, v0
	ds_add_u32 v10, v205 offset:16384
	v_lshrrev_b32_e32 v10, 24, v145
	v_lshl_add_u32 v10, v10, 6, v0
	ds_add_u32 v10, v205 offset:16384
	v_lshrrev_b32_e32 v10, 24, v144
	v_lshl_add_u32 v10, v10, 6, v0
	ds_add_u32 v10, v205 offset:16384
	ds_read_b128 v[10:13], v193
	ds_read_b128 v[14:17], v194
	ds_read_b128 v[24:27], v190
	ds_read_b128 v[28:31], v191
	ds_read2_b32 v[32:33], v137 offset0:80 offset1:96
	ds_read2_b32 v[40:41], v137 offset0:112 offset1:128
	s_waitcnt vmcnt(1) lgkmcnt(5)
	v_mfma_f32_16x16x32_bf16 v[10:13], v[6:9], v[10:13], 0
	ds_read2_b32 v[52:53], v137 offset0:144 offset1:160
	s_waitcnt vmcnt(0) lgkmcnt(5)
	v_mfma_f32_16x16x32_bf16 v[10:13], v[2:5], v[14:17], v[10:13]
	ds_read_b128 v[14:17], v188
	s_waitcnt lgkmcnt(5)
	v_mfma_f32_16x16x32_bf16 v[24:27], v[6:9], v[24:27], 0
	s_nop 4
	v_max_f32_e32 v34, 0, v10
	v_max_f32_e32 v10, 0, v12
	v_max_f32_e32 v35, 0, v11
	s_waitcnt lgkmcnt(3)
	v_mul_f32_e32 v36, v32, v10
	v_max_f32_e32 v38, 0, v13
	v_mfma_f32_16x16x32_bf16 v[10:13], v[2:5], v[28:31], v[24:27]
	s_nop 2
	ds_read_b128 v[24:27], v187
	s_waitcnt lgkmcnt(1)
	v_mfma_f32_16x16x32_bf16 v[14:17], v[6:9], v[14:17], 0
	s_nop 1
	v_max_f32_e32 v28, 0, v10
	v_max_f32_e32 v29, 0, v11
	v_max_f32_e32 v10, 0, v12
	v_mul_f32_e32 v30, v33, v10
	v_max_f32_e32 v39, 0, v13
	s_waitcnt lgkmcnt(0)
	v_mfma_f32_16x16x32_bf16 v[10:13], v[2:5], v[24:27], v[14:17]
	ds_read_b128 v[24:27], v192
	v_pk_mul_f32 v[38:39], v[32:33], v[38:39]
	s_nop 0
	ds_read_b128 v[14:17], v189
	s_waitcnt lgkmcnt(0)
	v_mfma_f32_16x16x32_bf16 v[14:17], v[6:9], v[14:17], 0
	s_nop 1
	v_max_f32_e32 v42, 0, v10
	v_max_f32_e32 v43, 0, v11
	v_max_f32_e32 v10, 0, v12
	v_mul_f32_e32 v44, v40, v10
	s_nop 0
	v_max_f32_e32 v46, 0, v13
	v_mfma_f32_16x16x32_bf16 v[10:13], v[2:5], v[24:27], v[14:17]
	ds_read_b128 v[24:27], v196
	v_mov_b32_e32 v37, v38
	v_mov_b32_e32 v31, v39
	ds_read_b128 v[14:17], v195
	s_waitcnt lgkmcnt(0)
	v_mfma_f32_16x16x32_bf16 v[14:17], v[6:9], v[14:17], 0
	s_nop 1
	v_max_f32_e32 v48, 0, v10
	v_max_f32_e32 v49, 0, v11
	v_max_f32_e32 v10, 0, v12
	v_mul_f32_e32 v50, v41, v10
	s_nop 0
	v_max_f32_e32 v47, 0, v13
	v_mfma_f32_16x16x32_bf16 v[10:13], v[2:5], v[24:27], v[14:17]
	ds_read_b128 v[24:27], v198
	v_pk_mul_f32 v[46:47], v[40:41], v[46:47]
	s_nop 0
	ds_read_b128 v[14:17], v197
	s_waitcnt lgkmcnt(0)
	v_mfma_f32_16x16x32_bf16 v[14:17], v[6:9], v[14:17], 0
	s_nop 1
	v_max_f32_e32 v54, 0, v10
	v_max_f32_e32 v55, 0, v11
	v_max_f32_e32 v10, 0, v12
	v_mul_f32_e32 v56, v52, v10
	s_nop 0
	v_max_f32_e32 v146, 0, v13
	v_mfma_f32_16x16x32_bf16 v[10:13], v[2:5], v[24:27], v[14:17]
	ds_read_b128 v[24:27], v218
	v_mov_b32_e32 v45, v46
	v_mov_b32_e32 v51, v47
	ds_read_b128 v[14:17], v199
	s_waitcnt lgkmcnt(0)
	v_mfma_f32_16x16x32_bf16 v[14:17], v[6:9], v[14:17], 0
	s_nop 1
	v_max_f32_e32 v148, 0, v10
	v_max_f32_e32 v149, 0, v11
	v_max_f32_e32 v10, 0, v12
	v_mul_f32_e32 v160, v53, v10
	s_nop 0
	v_max_f32_e32 v147, 0, v13
	v_mfma_f32_16x16x32_bf16 v[10:13], v[2:5], v[24:27], v[14:17]
	ds_read_b128 v[24:27], v220
	v_pk_mul_f32 v[162:163], v[52:53], v[146:147]
	ds_read2_b32 v[146:147], v137 offset0:176 offset1:192
	ds_read_b128 v[14:17], v219
	s_waitcnt lgkmcnt(0)
; #define LAS __attribute__((address_space(3)))
; __device__ __forceinline__ unsigned fkey(float f) { const unsigned u = __float_as_uint(f); return (u & 0x80000000u) ? ~u : (u | 0x80000000u); }
; #define SEL_HADD(idx_) __hip_atomic_fetch_add(&hist[(idx_)], 1u, __ATOMIC_RELAXED, __HIP_MEMORY_SCOPE_WORKGROUP)
; __device__ __forceinline__ void sel_unit(LAS char* lds, int b, int u, const bf16_t* QI, const bf16_t* KIDX, const float* WIDX, unsigned long long* MASK) {
;     ...
;                 for (int ks = 0; ks < 2; ++ks) kf[kb][ks] = *(const bf16x8*)(KIDX + (rowbase + 64 * t + 32 * kh + 16 * kb + q16) * 64 + 32 * ks + 8 * kg);
; #pragma unroll
;             for (int kb = 0; kb < 2; ++kb) {
;                 f32x4 s = (f32x4){0.f, 0.f, 0.f, 0.f};
; #pragma unroll
;                 for (int hh = 0; hh < 8; ++hh) {
;                     f32x4 a = (f32x4){0.f, 0.f, 0.f, 0.f};
; #pragma unroll
;                     for (int ks = 0; ks < 2; ++ks) {
;                         const bf16x8 qv = *(const LAS bf16x8*)(lds + L_QI + q16 * 1024 + (((hh * 8 + 4 * ks + kg) ^ q16) << 4));
;                         a = __builtin_amdgcn_mfma_f32_16x16x32_bf16(kf[kb][ks], qv, a, 0, 0, 0);
;                     }
;                     const float wh = wl[hh * 16];
; #pragma unroll
;                     for (int i = 0; i < 4; ++i) s[i] += wh * fmaxf(a[i], 0.f);
;                 }
;                 u32x4 kk; kk.x = fkey(s[0]); kk.y = fkey(s[1]); kk.z = fkey(s[2]); kk.w = fkey(s[3]);
;                 sc[j][2 * kh + kb] = kk;
; #pragma unroll
;                 for (int i = 0; i < 4; ++i) SEL_HADD((kk[i] >> 24) * 16 + q16);
;                 __builtin_amdgcn_sched_barrier(0);
	v_mfma_f32_16x16x32_bf16 v[6:9], v[6:9], v[14:17], 0
	s_nop 1
	s_nop 0
	v_max_f32_e32 v14, 0, v13
	s_nop 0
	v_mfma_f32_16x16x32_bf16 v[2:5], v[2:5], v[24:27], v[6:9]
	s_nop 0
	v_max_f32_e32 v10, 0, v10
	v_max_f32_e32 v11, 0, v11
	v_pk_fma_f32 v[8:9], v[32:33], v[34:35], 0 op_sel_hi:[0,1,0]
	s_nop 0
	s_nop 2
	v_max_f32_e32 v15, 0, v5
	v_pk_mul_f32 v[6:7], v[146:147], v[14:15]
	v_mov_b32_e32 v14, v33
	v_pk_fma_f32 v[8:9], v[14:15], v[28:29], v[8:9] op_sel_hi:[0,1,1]
	v_pk_fma_f32 v[8:9], v[40:41], v[42:43], v[8:9] op_sel_hi:[0,1,1]
	v_mov_b32_e32 v14, v41
	v_pk_fma_f32 v[8:9], v[14:15], v[48:49], v[8:9] op_sel_hi:[0,1,1]
	v_pk_fma_f32 v[8:9], v[52:53], v[54:55], v[8:9] op_sel_hi:[0,1,1]
	v_mov_b32_e32 v14, v53
	v_pk_fma_f32 v[8:9], v[14:15], v[148:149], v[8:9] op_sel_hi:[0,1,1]
	v_max_f32_e32 v2, 0, v2
	v_max_f32_e32 v3, 0, v3
	v_pk_fma_f32 v[8:9], v[146:147], v[10:11], v[8:9] op_sel_hi:[0,1,1]
	v_mov_b32_e32 v10, v147
	v_pk_fma_f32 v[2:3], v[10:11], v[2:3], v[8:9] op_sel_hi:[0,1,1]
	v_and_b32_e32 v9, 0x7fffffff, v3
	v_and_b32_e32 v8, 0x7fffffff, v2
	v_max_f32_e32 v12, 0, v12
	v_xor_b32_e32 v5, -1, v3
	v_pk_add_f32 v[8:9], v[8:9], 0 neg_lo:[1,1] neg_hi:[1,1]
	v_cmp_gt_i32_e32 vcc, 0, v3
	v_mul_f32_e32 v12, v146, v12
	v_xor_b32_e32 v10, -1, v2
	v_cndmask_b32_e32 v146, v9, v5, vcc
	v_cmp_gt_i32_e32 vcc, 0, v2
	v_pk_add_f32 v[2:3], v[36:37], 0 op_sel_hi:[1,0]
	v_mov_b32_e32 v57, v162
	v_pk_add_f32 v[2:3], v[2:3], v[30:31]
	v_pk_add_f32 v[2:3], v[2:3], v[44:45]
	v_mov_b32_e32 v161, v163
	v_pk_add_f32 v[2:3], v[2:3], v[50:51]
	v_max_f32_e32 v4, 0, v4
	v_pk_add_f32 v[2:3], v[2:3], v[56:57]
	v_mov_b32_e32 v13, v6
	v_pk_add_f32 v[2:3], v[2:3], v[160:161]
	v_mul_f32_e32 v4, v147, v4
	v_pk_add_f32 v[2:3], v[2:3], v[12:13]
	v_mov_b32_e32 v5, v7
	v_pk_add_f32 v[2:3], v[2:3], v[4:5]
	v_cndmask_b32_e32 v147, v8, v10, vcc
	v_and_b32_e32 v5, 0x7fffffff, v3
	v_and_b32_e32 v4, 0x7fffffff, v2
	v_xor_b32_e32 v6, -1, v3
	v_pk_add_f32 v[4:5], v[4:5], 0 neg_lo:[1,1] neg_hi:[1,1]
	v_cmp_gt_i32_e32 vcc, 0, v3
	v_xor_b32_e32 v7, -1, v2
	s_nop 0
	v_cndmask_b32_e32 v148, v5, v6, vcc
	v_cmp_gt_i32_e32 vcc, 0, v2
	v_lshrrev_b32_e32 v2, 24, v147
	v_lshl_add_u32 v2, v2, 6, v0
	ds_add_u32 v2, v205 offset:16384
	v_lshrrev_b32_e32 v2, 24, v146
	v_cndmask_b32_e32 v149, v4, v7, vcc
	v_lshl_add_u32 v2, v2, 6, v0
	ds_add_u32 v2, v205 offset:16384
	v_lshrrev_b32_e32 v2, 24, v149
	v_lshl_add_u32 v2, v2, 6, v0
	ds_add_u32 v2, v205 offset:16384
	v_lshrrev_b32_e32 v2, 24, v148
	v_lshl_add_u32 v2, v2, 6, v0
	ds_add_u32 v2, v205 offset:16384
	v_add_co_u32_e32 v2, vcc, s96, v22
	s_nop 1
	v_addc_co_u32_e32 v3, vcc, 0, v23, vcc
	global_load_dwordx4 v[14:17], v[2:3], off
	global_load_dwordx4 v[10:13], v[2:3], off offset:64
	global_load_dwordx4 v[6:9], v[2:3], off offset:2048
	s_nop 0
	global_load_dwordx4 v[2:5], v[2:3], off offset:2112
	ds_read_b128 v[22:25], v193
	ds_read_b128 v[26:29], v194
	s_waitcnt vmcnt(3) lgkmcnt(1)
	v_mfma_f32_16x16x32_bf16 v[22:25], v[14:17], v[22:25], 0
	ds_read_b128 v[32:35], v191
	ds_read_b128 v[38:41], v187
	ds_read_b128 v[44:47], v192
	s_waitcnt vmcnt(2) lgkmcnt(3)
	v_mfma_f32_16x16x32_bf16 v[26:29], v[10:13], v[26:29], v[22:25]
	ds_read_b128 v[50:53], v196
	ds_read_b128 v[160:163], v198
	s_nop 0
	ds_read2_b32 v[24:25], v137 offset0:80 offset1:96
	s_nop 3
	v_max_f32_e32 v26, 0, v26
	v_max_f32_e32 v27, 0, v27
	v_max_f32_e32 v22, v28, v28
	v_max_f32_e32 v23, v29, v29
	ds_read_b128 v[28:31], v190
	s_waitcnt lgkmcnt(0)
	v_mfma_f32_16x16x32_bf16 v[28:31], v[14:17], v[28:31], 0
	v_max_f32_e32 v36, 0, v23
	v_max_f32_e32 v22, 0, v22
	v_mul_f32_e32 v22, v24, v22
	v_mfma_f32_16x16x32_bf16 v[28:31], v[10:13], v[32:35], v[28:31]
	s_nop 7
	v_max_f32_e32 v32, 0, v28
	v_max_f32_e32 v33, 0, v29
	v_max_f32_e32 v23, 0, v30
	v_mul_f32_e32 v28, v25, v23
	v_max_f32_e32 v37, 0, v31
	v_pk_mul_f32 v[30:31], v[24:25], v[36:37]
	ds_read_b128 v[34:37], v188
	s_waitcnt lgkmcnt(0)
	v_mfma_f32_16x16x32_bf16 v[34:37], v[14:17], v[34:37], 0
	v_mov_b32_e32 v29, v31
	v_mfma_f32_16x16x32_bf16 v[38:41], v[10:13], v[38:41], v[34:37]
	s_nop 5
	ds_read2_b32 v[36:37], v137 offset0:112 offset1:128
	s_nop 0
	v_max_f32_e32 v38, 0, v38
	v_max_f32_e32 v39, 0, v39
	v_max_f32_e32 v23, 0, v40
	s_waitcnt lgkmcnt(0)
	v_mul_f32_e32 v34, v36, v23
	v_max_f32_e32 v23, v41, v41
	ds_read_b128 v[40:43], v189
	s_waitcnt lgkmcnt(0)
	v_mfma_f32_16x16x32_bf16 v[40:43], v[14:17], v[40:43], 0
	v_max_f32_e32 v48, 0, v23
	v_mfma_f32_16x16x32_bf16 v[40:43], v[10:13], v[44:47], v[40:43]
	s_nop 7
	v_max_f32_e32 v44, 0, v40
	v_max_f32_e32 v45, 0, v41
	v_max_f32_e32 v23, 0, v42
	v_mul_f32_e32 v40, v37, v23
	v_max_f32_e32 v49, 0, v43
	v_pk_mul_f32 v[42:43], v[36:37], v[48:49]
	ds_read_b128 v[46:49], v195
	s_waitcnt lgkmcnt(0)
	v_mfma_f32_16x16x32_bf16 v[46:49], v[14:17], v[46:49], 0
	v_mov_b32_e32 v35, v42
	v_mov_b32_e32 v41, v43
	v_mfma_f32_16x16x32_bf16 v[50:53], v[10:13], v[50:53], v[46:49]
	s_nop 4
	ds_read2_b32 v[48:49], v137 offset0:144 offset1:160
	s_nop 1
	v_max_f32_e32 v50, 0, v50
	v_max_f32_e32 v51, 0, v51
	v_max_f32_e32 v23, 0, v52
	s_waitcnt lgkmcnt(0)
	v_mul_f32_e32 v46, v48, v23
	v_max_f32_e32 v23, v53, v53
	ds_read_b128 v[52:55], v197
	s_waitcnt lgkmcnt(0)
	v_mfma_f32_16x16x32_bf16 v[52:55], v[14:17], v[52:55], 0
	v_max_f32_e32 v164, 0, v23
	v_mfma_f32_16x16x32_bf16 v[52:55], v[10:13], v[160:163], v[52:55]
	ds_read_b128 v[160:163], v199
	s_nop 6
	v_max_f32_e32 v56, 0, v52
	v_max_f32_e32 v57, 0, v53
	v_max_f32_e32 v23, 0, v54
	v_mul_f32_e32 v52, v49, v23
	v_max_f32_e32 v165, 0, v55
	v_pk_mul_f32 v[54:55], v[48:49], v[164:165]
	ds_read_b128 v[164:167], v218
	s_waitcnt lgkmcnt(1)
; #define LAS __attribute__((address_space(3)))
; __device__ __forceinline__ unsigned fkey(float f) { const unsigned u = __float_as_uint(f); return (u & 0x80000000u) ? ~u : (u | 0x80000000u); }
; #define SEL_HADD(idx_) __hip_atomic_fetch_add(&hist[(idx_)], 1u, __ATOMIC_RELAXED, __HIP_MEMORY_SCOPE_WORKGROUP)
; __device__ __forceinline__ void sel_unit(LAS char* lds, int b, int u, const bf16_t* QI, const bf16_t* KIDX, const float* WIDX, unsigned long long* MASK) {
;     ...
;                 for (int ks = 0; ks < 2; ++ks) kf[kb][ks] = *(const bf16x8*)(KIDX + (rowbase + 64 * t + 32 * kh + 16 * kb + q16) * 64 + 32 * ks + 8 * kg);
; #pragma unroll
;             for (int kb = 0; kb < 2; ++kb) {
;                 f32x4 s = (f32x4){0.f, 0.f, 0.f, 0.f};
; #pragma unroll
;                 for (int hh = 0; hh < 8; ++hh) {
;                     f32x4 a = (f32x4){0.f, 0.f, 0.f, 0.f};
; #pragma unroll
;                     for (int ks = 0; ks < 2; ++ks) {
;                         const bf16x8 qv = *(const LAS bf16x8*)(lds + L_QI + q16 * 1024 + (((hh * 8 + 4 * ks + kg) ^ q16) << 4));
;                         a = __builtin_amdgcn_mfma_f32_16x16x32_bf16(kf[kb][ks], qv, a, 0, 0, 0);
;                     }
;                     const float wh = wl[hh * 16];
; #pragma unroll
;                     for (int i = 0; i < 4; ++i) s[i] += wh * fmaxf(a[i], 0.f);
;                 }
;                 u32x4 kk; kk.x = fkey(s[0]); kk.y = fkey(s[1]); kk.z = fkey(s[2]); kk.w = fkey(s[3]);
;                 sc[j][2 * kh + kb] = kk;
; #pragma unroll
;                 for (int i = 0; i < 4; ++i) SEL_HADD((kk[i] >> 24) * 16 + q16);
;                 __builtin_amdgcn_sched_barrier(0);
	v_mfma_f32_16x16x32_bf16 v[160:163], v[14:17], v[160:163], 0
	v_mov_b32_e32 v47, v54
	v_mov_b32_e32 v53, v55
	s_waitcnt lgkmcnt(0)
	v_mfma_f32_16x16x32_bf16 v[160:163], v[10:13], v[164:167], v[160:163]
	ds_read2_b32 v[164:165], v137 offset0:176 offset1:192
	s_nop 6
	v_max_f32_e32 v166, 0, v160
	v_max_f32_e32 v167, 0, v161
	v_max_f32_e32 v23, 0, v162
	s_waitcnt lgkmcnt(0)
	v_mul_f32_e32 v168, v164, v23
	v_max_f32_e32 v23, v163, v163
	ds_read_b128 v[160:163], v219
	s_waitcnt lgkmcnt(0)
	v_mfma_f32_16x16x32_bf16 v[14:17], v[14:17], v[160:163], 0
	ds_read_b128 v[160:163], v220
	v_max_f32_e32 v170, 0, v23
	s_waitcnt lgkmcnt(0)
	v_mfma_f32_16x16x32_bf16 v[10:13], v[10:13], v[160:163], v[14:17]
	s_nop 3
	v_fma_f32 v16, v24, v26, 0
	v_fma_f32 v17, v24, v27, 0
	v_mov_b32_e32 v24, v25
	v_pk_fma_f32 v[16:17], v[24:25], v[32:33], v[16:17] op_sel_hi:[0,1,1]
	v_pk_fma_f32 v[16:17], v[36:37], v[38:39], v[16:17] op_sel_hi:[0,1,1]
	v_mov_b32_e32 v24, v37
	v_pk_fma_f32 v[16:17], v[24:25], v[44:45], v[16:17] op_sel_hi:[0,1,1]
	v_pk_fma_f32 v[16:17], v[48:49], v[50:51], v[16:17] op_sel_hi:[0,1,1]
	v_mov_b32_e32 v24, v49
	v_pk_fma_f32 v[16:17], v[24:25], v[56:57], v[16:17] op_sel_hi:[0,1,1]
	v_max_f32_e32 v10, 0, v10
	v_max_f32_e32 v11, 0, v11
	v_pk_fma_f32 v[16:17], v[164:165], v[166:167], v[16:17] op_sel_hi:[0,1,1]
	v_mov_b32_e32 v24, v165
	v_pk_fma_f32 v[10:11], v[24:25], v[10:11], v[16:17] op_sel_hi:[0,1,1]
	v_and_b32_e32 v17, 0x7fffffff, v11
	v_and_b32_e32 v16, 0x7fffffff, v10
	v_xor_b32_e32 v23, -1, v10
	v_pk_add_f32 v[16:17], v[16:17], 0 neg_lo:[1,1] neg_hi:[1,1]
	v_cmp_gt_i32_e32 vcc, 0, v10
	v_max_f32_e32 v171, 0, v13
	s_nop 0
	v_cndmask_b32_e32 v178, v16, v23, vcc
	v_mov_b32_e32 v23, v30
	v_xor_b32_e32 v13, -1, v11
	v_cmp_gt_i32_e64 s[2:3], 0, v11
	v_pk_add_f32 v[10:11], v[22:23], 0 op_sel_hi:[1,0]
	v_pk_add_f32 v[10:11], v[10:11], v[28:29]
	v_pk_mul_f32 v[14:15], v[164:165], v[170:171]
	v_pk_add_f32 v[10:11], v[10:11], v[34:35]
	v_max_f32_e32 v12, 0, v12
	v_pk_add_f32 v[10:11], v[10:11], v[40:41]
	v_mov_b32_e32 v169, v14
	v_pk_add_f32 v[10:11], v[10:11], v[46:47]
	v_mul_f32_e32 v12, v165, v12
	v_pk_add_f32 v[10:11], v[10:11], v[52:53]
	v_cndmask_b32_e64 v177, v17, v13, s[2:3]
	v_pk_add_f32 v[10:11], v[10:11], v[168:169]
	v_mov_b32_e32 v13, v15
	v_pk_add_f32 v[10:11], v[10:11], v[12:13]
	s_nop 0
	v_xor_b32_e32 v15, -1, v10
	v_and_b32_e32 v12, 0x7fffffff, v10
	v_cmp_gt_i32_e32 vcc, 0, v10
	v_lshrrev_b32_e32 v10, 24, v178
	v_and_b32_e32 v13, 0x7fffffff, v11
	v_lshl_add_u32 v10, v10, 6, v0
	v_pk_add_f32 v[12:13], v[12:13], 0 neg_lo:[1,1] neg_hi:[1,1]
	ds_add_u32 v10, v205 offset:16384
	v_lshrrev_b32_e32 v10, 24, v177
	v_cndmask_b32_e32 v186, v12, v15, vcc
	v_lshl_add_u32 v10, v10, 6, v0
	v_xor_b32_e32 v14, -1, v11
	v_cmp_gt_i32_e64 s[2:3], 0, v11
	ds_add_u32 v10, v205 offset:16384
	v_lshrrev_b32_e32 v10, 24, v186
	v_cndmask_b32_e64 v181, v13, v14, s[2:3]
	v_lshl_add_u32 v10, v10, 6, v0
	ds_add_u32 v10, v205 offset:16384
	v_lshrrev_b32_e32 v10, 24, v181
	v_lshl_add_u32 v10, v10, 6, v0
	ds_add_u32 v10, v205 offset:16384
	ds_read_b128 v[10:13], v193
	ds_read_b128 v[14:17], v194
	ds_read_b128 v[22:25], v190
	ds_read_b128 v[26:29], v191
	ds_read2_b32 v[30:31], v137 offset0:80 offset1:96
	ds_read2_b32 v[38:39], v137 offset0:112 offset1:128
	s_waitcnt vmcnt(1) lgkmcnt(5)
	v_mfma_f32_16x16x32_bf16 v[10:13], v[6:9], v[10:13], 0
	ds_read2_b32 v[50:51], v137 offset0:144 offset1:160
	ds_read2_b32 v[164:165], v137 offset0:176 offset1:192
	s_waitcnt vmcnt(0) lgkmcnt(6)
	v_mfma_f32_16x16x32_bf16 v[10:13], v[2:5], v[14:17], v[10:13]
	ds_read_b128 v[14:17], v188
	s_waitcnt lgkmcnt(6)
	v_mfma_f32_16x16x32_bf16 v[22:25], v[6:9], v[22:25], 0
	s_nop 4
	v_max_f32_e32 v32, 0, v10
	v_max_f32_e32 v10, 0, v12
	v_max_f32_e32 v33, 0, v11
	s_waitcnt lgkmcnt(4)
	v_mul_f32_e32 v34, v30, v10
	v_max_f32_e32 v36, 0, v13
	v_mfma_f32_16x16x32_bf16 v[10:13], v[2:5], v[26:29], v[22:25]
	s_nop 2
	ds_read_b128 v[22:25], v187
	s_waitcnt lgkmcnt(1)
	v_mfma_f32_16x16x32_bf16 v[14:17], v[6:9], v[14:17], 0
	s_nop 1
	v_max_f32_e32 v26, 0, v10
	v_max_f32_e32 v27, 0, v11
	v_max_f32_e32 v10, 0, v12
	v_mul_f32_e32 v28, v31, v10
	v_max_f32_e32 v37, 0, v13
	s_waitcnt lgkmcnt(0)
	v_mfma_f32_16x16x32_bf16 v[10:13], v[2:5], v[22:25], v[14:17]
	ds_read_b128 v[22:25], v192
	v_pk_mul_f32 v[36:37], v[30:31], v[36:37]
	s_nop 0
	ds_read_b128 v[14:17], v189
	s_waitcnt lgkmcnt(0)
	v_mfma_f32_16x16x32_bf16 v[14:17], v[6:9], v[14:17], 0
	s_nop 1
	v_max_f32_e32 v40, 0, v10
	v_max_f32_e32 v41, 0, v11
	v_max_f32_e32 v10, 0, v12
	v_mul_f32_e32 v42, v38, v10
	s_nop 0
	v_max_f32_e32 v44, 0, v13
	v_mfma_f32_16x16x32_bf16 v[10:13], v[2:5], v[22:25], v[14:17]
	ds_read_b128 v[22:25], v196
	v_mov_b32_e32 v35, v36
	v_mov_b32_e32 v29, v37
	ds_read_b128 v[14:17], v195
	s_waitcnt lgkmcnt(0)
	v_mfma_f32_16x16x32_bf16 v[14:17], v[6:9], v[14:17], 0
	s_nop 1
	v_max_f32_e32 v46, 0, v10
	v_max_f32_e32 v47, 0, v11
	v_max_f32_e32 v10, 0, v12
	v_mul_f32_e32 v48, v39, v10
	s_nop 0
	v_max_f32_e32 v45, 0, v13
	v_mfma_f32_16x16x32_bf16 v[10:13], v[2:5], v[22:25], v[14:17]
	ds_read_b128 v[22:25], v198
	v_pk_mul_f32 v[44:45], v[38:39], v[44:45]
	s_nop 0
	ds_read_b128 v[14:17], v197
	s_waitcnt lgkmcnt(0)
	v_mfma_f32_16x16x32_bf16 v[14:17], v[6:9], v[14:17], 0
	s_nop 1
	v_max_f32_e32 v52, 0, v10
	v_max_f32_e32 v53, 0, v11
	v_max_f32_e32 v10, 0, v12
	v_mul_f32_e32 v54, v50, v10
	s_nop 0
	v_max_f32_e32 v56, 0, v13
	v_mfma_f32_16x16x32_bf16 v[10:13], v[2:5], v[22:25], v[14:17]
	ds_read_b128 v[22:25], v218
	v_mov_b32_e32 v43, v44
	v_mov_b32_e32 v49, v45
	ds_read_b128 v[14:17], v199
	s_waitcnt lgkmcnt(0)
; #define LAS __attribute__((address_space(3)))
; __device__ __forceinline__ unsigned fkey(float f) { const unsigned u = __float_as_uint(f); return (u & 0x80000000u) ? ~u : (u | 0x80000000u); }
; #define SEL_HADD(idx_) __hip_atomic_fetch_add(&hist[(idx_)], 1u, __ATOMIC_RELAXED, __HIP_MEMORY_SCOPE_WORKGROUP)
; __device__ __forceinline__ void sel_unit(LAS char* lds, int b, int u, const bf16_t* QI, const bf16_t* KIDX, const float* WIDX, unsigned long long* MASK) {
;     ...
;     for (int j = 0; j < 8; ++j) {
;         if (j < nj) {
;             int t = wid + 8 * j; asm volatile("" : "+s"(t));
; #pragma unroll
;             for (int kh = 0; kh < 2; ++kh) {
;             bf16x8 kf[2][2];
; #pragma unroll
;             for (int kb = 0; kb < 2; ++kb)
; #pragma unroll
;                 for (int ks = 0; ks < 2; ++ks) kf[kb][ks] = *(const bf16x8*)(KIDX + (rowbase + 64 * t + 32 * kh + 16 * kb + q16) * 64 + 32 * ks + 8 * kg);
; #pragma unroll
;             for (int kb = 0; kb < 2; ++kb) {
;                 f32x4 s = (f32x4){0.f, 0.f, 0.f, 0.f};
; #pragma unroll
;                 for (int hh = 0; hh < 8; ++hh) {
;                     f32x4 a = (f32x4){0.f, 0.f, 0.f, 0.f};
; #pragma unroll
;                     for (int ks = 0; ks < 2; ++ks) {
;                         const bf16x8 qv = *(const LAS bf16x8*)(lds + L_QI + q16 * 1024 + (((hh * 8 + 4 * ks + kg) ^ q16) << 4));
;                         a = __builtin_amdgcn_mfma_f32_16x16x32_bf16(kf[kb][ks], qv, a, 0, 0, 0);
;                     }
;                     const float wh = wl[hh * 16];
; #pragma unroll
;                     for (int i = 0; i < 4; ++i) s[i] += wh * fmaxf(a[i], 0.f);
;                 }
;                 u32x4 kk; kk.x = fkey(s[0]); kk.y = fkey(s[1]); kk.z = fkey(s[2]); kk.w = fkey(s[3]);
;                 sc[j][2 * kh + kb] = kk;
; #pragma unroll
;                 for (int i = 0; i < 4; ++i) SEL_HADD((kk[i] >> 24) * 16 + q16);
;                 __builtin_amdgcn_sched_barrier(0);
	v_mfma_f32_16x16x32_bf16 v[14:17], v[6:9], v[14:17], 0
	s_nop 1
	v_max_f32_e32 v160, 0, v10
	v_max_f32_e32 v161, 0, v11
	v_max_f32_e32 v10, 0, v12
	v_mul_f32_e32 v162, v51, v10
	s_nop 0
	v_max_f32_e32 v57, 0, v13
	v_mfma_f32_16x16x32_bf16 v[10:13], v[2:5], v[22:25], v[14:17]
	ds_read_b128 v[22:25], v220
	v_pk_mul_f32 v[56:57], v[50:51], v[56:57]
	s_nop 0
	ds_read_b128 v[14:17], v219
	s_waitcnt lgkmcnt(0)
	v_mfma_f32_16x16x32_bf16 v[6:9], v[6:9], v[14:17], 0
	s_nop 1
	s_nop 0
	v_max_f32_e32 v14, 0, v13
	s_nop 0
	v_mfma_f32_16x16x32_bf16 v[2:5], v[2:5], v[22:25], v[6:9]
	s_nop 0
	v_max_f32_e32 v10, 0, v10
	v_max_f32_e32 v11, 0, v11
	v_pk_fma_f32 v[8:9], v[30:31], v[32:33], 0 op_sel_hi:[0,1,0]
	s_nop 0
	s_nop 2
	v_max_f32_e32 v15, 0, v5
	v_pk_mul_f32 v[6:7], v[164:165], v[14:15]
	v_mov_b32_e32 v14, v31
	v_pk_fma_f32 v[8:9], v[14:15], v[26:27], v[8:9] op_sel_hi:[0,1,1]
	v_pk_fma_f32 v[8:9], v[38:39], v[40:41], v[8:9] op_sel_hi:[0,1,1]
	v_mov_b32_e32 v14, v39
	v_pk_fma_f32 v[8:9], v[14:15], v[46:47], v[8:9] op_sel_hi:[0,1,1]
	v_pk_fma_f32 v[8:9], v[50:51], v[52:53], v[8:9] op_sel_hi:[0,1,1]
	v_mov_b32_e32 v14, v51
	v_pk_fma_f32 v[8:9], v[14:15], v[160:161], v[8:9] op_sel_hi:[0,1,1]
	v_max_f32_e32 v2, 0, v2
	v_max_f32_e32 v3, 0, v3
	v_pk_fma_f32 v[8:9], v[164:165], v[10:11], v[8:9] op_sel_hi:[0,1,1]
	v_mov_b32_e32 v10, v165
	v_pk_fma_f32 v[2:3], v[10:11], v[2:3], v[8:9] op_sel_hi:[0,1,1]
	v_and_b32_e32 v9, 0x7fffffff, v3
	v_and_b32_e32 v8, 0x7fffffff, v2
	v_xor_b32_e32 v5, -1, v3
	v_pk_add_f32 v[8:9], v[8:9], 0 neg_lo:[1,1] neg_hi:[1,1]
	v_cmp_gt_i32_e32 vcc, 0, v3
	v_xor_b32_e32 v10, -1, v2
	v_mov_b32_e32 v55, v56
	v_cndmask_b32_e32 v187, v9, v5, vcc
	v_cmp_gt_i32_e32 vcc, 0, v2
	v_pk_add_f32 v[2:3], v[34:35], 0 op_sel_hi:[1,0]
	v_max_f32_e32 v12, 0, v12
	v_pk_add_f32 v[2:3], v[2:3], v[28:29]
	v_pk_add_f32 v[2:3], v[2:3], v[42:43]
	v_mov_b32_e32 v163, v57
	v_pk_add_f32 v[2:3], v[2:3], v[48:49]
	v_mul_f32_e32 v12, v164, v12
	v_pk_add_f32 v[2:3], v[2:3], v[54:55]
	v_max_f32_e32 v4, 0, v4
	v_pk_add_f32 v[2:3], v[2:3], v[162:163]
	v_mov_b32_e32 v13, v6
	v_mul_f32_e32 v4, v165, v4
	v_pk_add_f32 v[2:3], v[2:3], v[12:13]
	v_mov_b32_e32 v5, v7
	v_pk_add_f32 v[2:3], v[2:3], v[4:5]
	v_cndmask_b32_e32 v188, v8, v10, vcc
	v_and_b32_e32 v5, 0x7fffffff, v3
	v_and_b32_e32 v4, 0x7fffffff, v2
	v_xor_b32_e32 v6, -1, v3
	v_pk_add_f32 v[4:5], v[4:5], 0 neg_lo:[1,1] neg_hi:[1,1]
	v_cmp_gt_i32_e32 vcc, 0, v3
	v_xor_b32_e32 v7, -1, v2
	s_nop 0
	v_cndmask_b32_e32 v189, v5, v6, vcc
	v_cmp_gt_i32_e32 vcc, 0, v2
	v_lshrrev_b32_e32 v2, 24, v188
	v_lshl_add_u32 v2, v2, 6, v0
	ds_add_u32 v2, v205 offset:16384
	v_lshrrev_b32_e32 v2, 24, v187
	v_cndmask_b32_e32 v190, v4, v7, vcc
	v_lshl_add_u32 v2, v2, 6, v0
	ds_add_u32 v2, v205 offset:16384
	v_lshrrev_b32_e32 v2, 24, v190
	v_lshl_add_u32 v2, v2, 6, v0
	ds_add_u32 v2, v205 offset:16384
	v_lshrrev_b32_e32 v2, 24, v189
	v_lshl_add_u32 v2, v2, 6, v0
	ds_add_u32 v2, v205 offset:16384
.LBB0_668:
	s_cmp_gt_i32 s4, 6
	s_cselect_b64 s[0:1], -1, 0
	s_cmp_lt_i32 s4, 7
	s_cbranch_scc1 .LBB0_670
	s_add_i32 s2, s46, 48
	s_lshl_b32 s2, s2, 6
	s_ashr_i32 s3, s2, 31
	v_lshl_add_u64 v[2:3], v[18:19], 0, s[2:3]
	v_lshlrev_b64 v[2:3], 7, v[2:3]
	v_lshl_add_u64 v[22:23], v[20:21], 0, v[2:3]
	global_load_dwordx4 v[14:17], v[22:23], off
	global_load_dwordx4 v[10:13], v[22:23], off offset:64
	v_lshl_add_u32 v223, v182, 4, v150
	v_lshl_add_u32 v224, v183, 4, v150
	v_lshl_add_u32 v221, v185, 4, v150
	v_lshl_add_u32 v199, v180, 4, v150
	v_lshl_add_u32 v222, v159, 4, v150
	v_lshl_add_u32 v220, v184, 4, v150
	ds_read_b128 v[2:5], v223
	v_lshl_add_u32 v218, v179, 4, v150
	ds_read_b128 v[6:9], v224
	ds_read_b128 v[24:27], v220
	v_lshl_add_u32 v219, v176, 4, v150
	ds_read_b128 v[28:31], v221
	ds_read_b128 v[32:35], v218
	ds_read_b128 v[36:39], v199
	ds_read_b128 v[40:43], v219
	v_lshl_add_u32 v225, v158, 4, v150
	ds_read_b128 v[44:47], v222
	ds_read_b128 v[48:51], v225
	v_lshl_add_u32 v226, v157, 4, v150
	ds_read_b128 v[52:55], v226
	v_lshl_add_u32 v227, v156, 4, v150
	v_lshl_add_u32 v228, v155, 4, v150
	ds_read_b128 v[160:163], v227
	ds_read_b128 v[164:167], v228
	v_lshl_add_u32 v229, v154, 4, v150
	v_lshl_add_u32 v230, v153, 4, v150
	v_lshl_add_u32 v231, v152, 4, v150
	v_lshl_add_u32 v232, v151, 4, v150
	s_waitcnt vmcnt(1) lgkmcnt(11)
	v_mfma_f32_16x16x32_bf16 v[2:5], v[14:17], v[2:5], 0
	s_waitcnt lgkmcnt(9)
	v_mfma_f32_16x16x32_bf16 v[24:27], v[14:17], v[24:27], 0
	s_waitcnt lgkmcnt(7)
	v_mfma_f32_16x16x32_bf16 v[32:35], v[14:17], v[32:35], 0
	s_waitcnt lgkmcnt(5)
	v_mfma_f32_16x16x32_bf16 v[40:43], v[14:17], v[40:43], 0
	s_waitcnt lgkmcnt(3)
	v_mfma_f32_16x16x32_bf16 v[48:51], v[14:17], v[48:51], 0
	s_waitcnt vmcnt(0)
	v_mfma_f32_16x16x32_bf16 v[168:171], v[10:13], v[6:9], v[2:5]
	v_mfma_f32_16x16x32_bf16 v[24:27], v[10:13], v[28:31], v[24:27]
	v_mfma_f32_16x16x32_bf16 v[28:31], v[10:13], v[36:39], v[32:35]
	v_mfma_f32_16x16x32_bf16 v[32:35], v[10:13], v[44:47], v[40:43]
	ds_read2_b32 v[44:45], v137 offset0:80 offset1:96
	ds_read2_b32 v[46:47], v137 offset0:112 offset1:128
	s_nop 3
	s_waitcnt lgkmcnt(4)
	v_mfma_f32_16x16x32_bf16 v[36:39], v[10:13], v[52:55], v[48:51]
	ds_read2_b32 v[48:49], v137 offset0:144 offset1:160
	global_load_dwordx4 v[6:9], v[22:23], off offset:2048
	global_load_dwordx4 v[2:5], v[22:23], off offset:2112
	s_waitcnt lgkmcnt(4)
	v_mfma_f32_16x16x32_bf16 v[160:163], v[14:17], v[160:163], 0
	s_nop 0
	s_nop 0
	v_max_f32_e32 v54, v24, v24
	s_waitcnt lgkmcnt(3)
; #define LAS __attribute__((address_space(3)))
; __device__ __forceinline__ unsigned fkey(float f) { const unsigned u = __float_as_uint(f); return (u & 0x80000000u) ? ~u : (u | 0x80000000u); }
; #define SEL_HADD(idx_) __hip_atomic_fetch_add(&hist[(idx_)], 1u, __ATOMIC_RELAXED, __HIP_MEMORY_SCOPE_WORKGROUP)
; __device__ __forceinline__ void sel_unit(LAS char* lds, int b, int u, const bf16_t* QI, const bf16_t* KIDX, const float* WIDX, unsigned long long* MASK) {
;     ...
;                 for (int ks = 0; ks < 2; ++ks) kf[kb][ks] = *(const bf16x8*)(KIDX + (rowbase + 64 * t + 32 * kh + 16 * kb + q16) * 64 + 32 * ks + 8 * kg);
; #pragma unroll
;             for (int kb = 0; kb < 2; ++kb) {
;                 f32x4 s = (f32x4){0.f, 0.f, 0.f, 0.f};
; #pragma unroll
;                 for (int hh = 0; hh < 8; ++hh) {
;                     f32x4 a = (f32x4){0.f, 0.f, 0.f, 0.f};
; #pragma unroll
;                     for (int ks = 0; ks < 2; ++ks) {
;                         const bf16x8 qv = *(const LAS bf16x8*)(lds + L_QI + q16 * 1024 + (((hh * 8 + 4 * ks + kg) ^ q16) << 4));
;                         a = __builtin_amdgcn_mfma_f32_16x16x32_bf16(kf[kb][ks], qv, a, 0, 0, 0);
;                     }
;                     const float wh = wl[hh * 16];
; #pragma unroll
;                     for (int i = 0; i < 4; ++i) s[i] += wh * fmaxf(a[i], 0.f);
;                 }
;                 u32x4 kk; kk.x = fkey(s[0]); kk.y = fkey(s[1]); kk.z = fkey(s[2]); kk.w = fkey(s[3]);
;                 sc[j][2 * kh + kb] = kk;
; #pragma unroll
;                 for (int i = 0; i < 4; ++i) SEL_HADD((kk[i] >> 24) * 16 + q16);
;                 __builtin_amdgcn_sched_barrier(0);
	v_mfma_f32_16x16x32_bf16 v[40:43], v[10:13], v[164:167], v[160:163]
	s_nop 0
	v_max_f32_e32 v24, 0, v171
	v_max_f32_e32 v164, 0, v26
	v_max_f32_e32 v160, v39, v39
	v_max_f32_e32 v39, 0, v25
	s_nop 2
	v_max_f32_e32 v25, 0, v27
	v_max_f32_e32 v26, 0, v31
	v_max_f32_e32 v27, 0, v35
	v_max_f32_e32 v55, v36, v36
	v_max_f32_e32 v57, v38, v38
	v_max_f32_e32 v36, 0, v168
	v_max_f32_e32 v38, 0, v54
	v_max_f32_e32 v50, 0, v32
	v_max_f32_e32 v32, 0, v160
	v_max_f32_e32 v54, 0, v40
	s_waitcnt lgkmcnt(2)
	v_pk_mul_f32 v[160:161], v[44:45], v[24:25]
	s_waitcnt lgkmcnt(1)
	v_pk_mul_f32 v[166:167], v[46:47], v[26:27]
	ds_read_b128 v[24:27], v229
	v_max_f32_e32 v162, v41, v41
	v_max_f32_e32 v163, v42, v42
	v_max_f32_e32 v40, 0, v28
	v_max_f32_e32 v28, 0, v30
	v_max_f32_e32 v42, 0, v170
	v_max_f32_e32 v41, 0, v29
	v_max_f32_e32 v29, 0, v34
	v_max_f32_e32 v52, 0, v55
	v_max_f32_e32 v30, 0, v57
	v_max_f32_e32 v55, 0, v162
	v_mul_f32_e32 v162, v46, v28
	v_max_f32_e32 v28, 0, v163
	v_max_f32_e32 v53, 0, v37
	v_mul_f32_e32 v56, v45, v164
	v_mul_f32_e32 v164, v47, v29
	s_waitcnt lgkmcnt(1)
	v_mul_f32_e32 v168, v48, v30
	v_mul_f32_e32 v170, v49, v28
	ds_read_b128 v[28:31], v230
	s_waitcnt lgkmcnt(1)
	v_mfma_f32_16x16x32_bf16 v[24:27], v[14:17], v[24:27], 0
	v_max_f32_e32 v37, 0, v169
	s_waitcnt lgkmcnt(0)
	v_mfma_f32_16x16x32_bf16 v[24:27], v[10:13], v[28:31], v[24:27]
	ds_read_b128 v[28:31], v231
	v_max_f32_e32 v51, 0, v33
	v_max_f32_e32 v33, 0, v43
	v_pk_mul_f32 v[172:173], v[48:49], v[32:33]
	ds_read_b128 v[32:35], v232
	s_waitcnt lgkmcnt(1)
	v_mfma_f32_16x16x32_bf16 v[14:17], v[14:17], v[28:31], 0
	ds_read2_b32 v[174:175], v137 offset0:176 offset1:192
	s_nop 0
	v_max_f32_e32 v28, 0, v27
	s_waitcnt lgkmcnt(1)
	v_mfma_f32_16x16x32_bf16 v[10:13], v[10:13], v[32:35], v[14:17]
	s_nop 0
	s_nop 0
	v_max_f32_e32 v24, 0, v24
	v_pk_fma_f32 v[16:17], v[44:45], v[36:37], 0 op_sel_hi:[0,1,0]
	v_max_f32_e32 v25, 0, v25
	s_nop 2
	v_max_f32_e32 v29, 0, v13
	s_waitcnt lgkmcnt(0)
	v_pk_mul_f32 v[14:15], v[174:175], v[28:29]
	v_mov_b32_e32 v28, v45
	v_pk_fma_f32 v[16:17], v[28:29], v[38:39], v[16:17] op_sel_hi:[0,1,1]
	v_pk_fma_f32 v[16:17], v[46:47], v[40:41], v[16:17] op_sel_hi:[0,1,1]
	v_mov_b32_e32 v28, v47
	v_pk_fma_f32 v[16:17], v[28:29], v[50:51], v[16:17] op_sel_hi:[0,1,1]
	v_pk_fma_f32 v[16:17], v[48:49], v[52:53], v[16:17] op_sel_hi:[0,1,1]
	v_mov_b32_e32 v28, v49
	v_pk_fma_f32 v[16:17], v[28:29], v[54:55], v[16:17] op_sel_hi:[0,1,1]
	v_max_f32_e32 v10, 0, v10
	v_max_f32_e32 v11, 0, v11
	v_pk_fma_f32 v[16:17], v[174:175], v[24:25], v[16:17] op_sel_hi:[0,1,1]
	v_mov_b32_e32 v24, v175
	v_pk_fma_f32 v[10:11], v[24:25], v[10:11], v[16:17] op_sel_hi:[0,1,1]
	v_and_b32_e32 v17, 0x7fffffff, v11
	v_and_b32_e32 v16, 0x7fffffff, v10
	v_mul_f32_e32 v42, v44, v42
	v_xor_b32_e32 v13, -1, v11
	v_pk_add_f32 v[16:17], v[16:17], 0 neg_lo:[1,1] neg_hi:[1,1]
	v_cmp_gt_i32_e32 vcc, 0, v11
	v_mov_b32_e32 v43, v160
	v_xor_b32_e32 v24, -1, v10
	v_cndmask_b32_e32 v191, v17, v13, vcc
	v_cmp_gt_i32_e32 vcc, 0, v10
	v_pk_add_f32 v[10:11], v[42:43], 0 op_sel_hi:[1,0]
	v_mov_b32_e32 v57, v161
	v_pk_add_f32 v[10:11], v[10:11], v[56:57]
	v_mov_b32_e32 v163, v166
	v_pk_add_f32 v[10:11], v[10:11], v[162:163]
	v_mov_b32_e32 v165, v167
	v_pk_add_f32 v[10:11], v[10:11], v[164:165]
	v_mov_b32_e32 v169, v172
	v_max_f32_e32 v26, 0, v26
	v_pk_add_f32 v[10:11], v[10:11], v[168:169]
	v_mov_b32_e32 v171, v173
	v_mul_f32_e32 v26, v174, v26
	v_max_f32_e32 v12, 0, v12
	v_pk_add_f32 v[10:11], v[10:11], v[170:171]
	v_mov_b32_e32 v27, v14
	v_mul_f32_e32 v12, v175, v12
	v_pk_add_f32 v[10:11], v[10:11], v[26:27]
	v_mov_b32_e32 v13, v15
	v_pk_add_f32 v[10:11], v[10:11], v[12:13]
	v_cndmask_b32_e32 v192, v16, v24, vcc
	v_and_b32_e32 v13, 0x7fffffff, v11
	v_and_b32_e32 v12, 0x7fffffff, v10
	v_xor_b32_e32 v14, -1, v11
	v_pk_add_f32 v[12:13], v[12:13], 0 neg_lo:[1,1] neg_hi:[1,1]
	v_cmp_gt_i32_e32 vcc, 0, v11
	v_xor_b32_e32 v15, -1, v10
	s_nop 0
	v_cndmask_b32_e32 v193, v13, v14, vcc
	v_cmp_gt_i32_e32 vcc, 0, v10
	v_lshrrev_b32_e32 v10, 24, v192
	v_lshl_add_u32 v10, v10, 6, v0
	ds_add_u32 v10, v205 offset:16384
	v_lshrrev_b32_e32 v10, 24, v191
	v_cndmask_b32_e32 v194, v12, v15, vcc
	v_lshl_add_u32 v10, v10, 6, v0
	ds_add_u32 v10, v205 offset:16384
	v_lshrrev_b32_e32 v10, 24, v194
	v_lshl_add_u32 v10, v10, 6, v0
	ds_add_u32 v10, v205 offset:16384
	v_lshrrev_b32_e32 v10, 24, v193
	v_lshl_add_u32 v10, v10, 6, v0
	ds_add_u32 v10, v205 offset:16384
	ds_read_b128 v[10:13], v223
	ds_read_b128 v[14:17], v224
	ds_read_b128 v[24:27], v220
	ds_read_b128 v[28:31], v221
	ds_read2_b32 v[32:33], v137 offset0:80 offset1:96
	ds_read2_b32 v[40:41], v137 offset0:112 offset1:128
	s_waitcnt vmcnt(1) lgkmcnt(5)
	v_mfma_f32_16x16x32_bf16 v[10:13], v[6:9], v[10:13], 0
	ds_read2_b32 v[52:53], v137 offset0:144 offset1:160
	ds_read2_b32 v[166:167], v137 offset0:176 offset1:192
	s_waitcnt vmcnt(0) lgkmcnt(6)
	v_mfma_f32_16x16x32_bf16 v[10:13], v[2:5], v[14:17], v[10:13]
	ds_read_b128 v[14:17], v218
	s_waitcnt lgkmcnt(6)
	v_mfma_f32_16x16x32_bf16 v[24:27], v[6:9], v[24:27], 0
	s_nop 4
	v_max_f32_e32 v34, 0, v10
	v_max_f32_e32 v10, 0, v12
	v_max_f32_e32 v35, 0, v11
	s_waitcnt lgkmcnt(4)
	v_mul_f32_e32 v36, v32, v10
	v_max_f32_e32 v38, 0, v13
	v_mfma_f32_16x16x32_bf16 v[10:13], v[2:5], v[28:31], v[24:27]
	s_nop 2
	ds_read_b128 v[24:27], v199
	s_waitcnt lgkmcnt(1)
	v_mfma_f32_16x16x32_bf16 v[14:17], v[6:9], v[14:17], 0
	s_nop 1
	v_max_f32_e32 v28, 0, v10
	v_max_f32_e32 v29, 0, v11
	v_max_f32_e32 v10, 0, v12
	v_mul_f32_e32 v30, v33, v10
	v_max_f32_e32 v39, 0, v13
	s_waitcnt lgkmcnt(0)
; #define LAS __attribute__((address_space(3)))
; __device__ __forceinline__ unsigned fkey(float f) { const unsigned u = __float_as_uint(f); return (u & 0x80000000u) ? ~u : (u | 0x80000000u); }
; #define SEL_HADD(idx_) __hip_atomic_fetch_add(&hist[(idx_)], 1u, __ATOMIC_RELAXED, __HIP_MEMORY_SCOPE_WORKGROUP)
; __device__ __forceinline__ void sel_unit(LAS char* lds, int b, int u, const bf16_t* QI, const bf16_t* KIDX, const float* WIDX, unsigned long long* MASK) {
;     ...
;                 for (int ks = 0; ks < 2; ++ks) kf[kb][ks] = *(const bf16x8*)(KIDX + (rowbase + 64 * t + 32 * kh + 16 * kb + q16) * 64 + 32 * ks + 8 * kg);
; #pragma unroll
;             for (int kb = 0; kb < 2; ++kb) {
;                 f32x4 s = (f32x4){0.f, 0.f, 0.f, 0.f};
; #pragma unroll
;                 for (int hh = 0; hh < 8; ++hh) {
;                     f32x4 a = (f32x4){0.f, 0.f, 0.f, 0.f};
; #pragma unroll
;                     for (int ks = 0; ks < 2; ++ks) {
;                         const bf16x8 qv = *(const LAS bf16x8*)(lds + L_QI + q16 * 1024 + (((hh * 8 + 4 * ks + kg) ^ q16) << 4));
;                         a = __builtin_amdgcn_mfma_f32_16x16x32_bf16(kf[kb][ks], qv, a, 0, 0, 0);
;                     }
;                     const float wh = wl[hh * 16];
; #pragma unroll
;                     for (int i = 0; i < 4; ++i) s[i] += wh * fmaxf(a[i], 0.f);
;                 }
;                 u32x4 kk; kk.x = fkey(s[0]); kk.y = fkey(s[1]); kk.z = fkey(s[2]); kk.w = fkey(s[3]);
;                 sc[j][2 * kh + kb] = kk;
; #pragma unroll
;                 for (int i = 0; i < 4; ++i) SEL_HADD((kk[i] >> 24) * 16 + q16);
;                 __builtin_amdgcn_sched_barrier(0);
	v_mfma_f32_16x16x32_bf16 v[10:13], v[2:5], v[24:27], v[14:17]
	ds_read_b128 v[24:27], v222
	v_pk_mul_f32 v[38:39], v[32:33], v[38:39]
	s_nop 0
	ds_read_b128 v[14:17], v219
	s_waitcnt lgkmcnt(0)
	v_mfma_f32_16x16x32_bf16 v[14:17], v[6:9], v[14:17], 0
	s_nop 1
	v_max_f32_e32 v42, 0, v10
	v_max_f32_e32 v43, 0, v11
	v_max_f32_e32 v10, 0, v12
	v_mul_f32_e32 v44, v40, v10
	s_nop 0
	v_max_f32_e32 v46, 0, v13
	v_mfma_f32_16x16x32_bf16 v[10:13], v[2:5], v[24:27], v[14:17]
	ds_read_b128 v[24:27], v226
	v_mov_b32_e32 v37, v38
	v_mov_b32_e32 v31, v39
	ds_read_b128 v[14:17], v225
	s_waitcnt lgkmcnt(0)
	v_mfma_f32_16x16x32_bf16 v[14:17], v[6:9], v[14:17], 0
	s_nop 1
	v_max_f32_e32 v48, 0, v10
	v_max_f32_e32 v49, 0, v11
	v_max_f32_e32 v10, 0, v12
	v_mul_f32_e32 v50, v41, v10
	s_nop 0
	v_max_f32_e32 v47, 0, v13
	v_mfma_f32_16x16x32_bf16 v[10:13], v[2:5], v[24:27], v[14:17]
	ds_read_b128 v[24:27], v228
	v_pk_mul_f32 v[46:47], v[40:41], v[46:47]
	s_nop 0
	ds_read_b128 v[14:17], v227
	s_waitcnt lgkmcnt(0)
	v_mfma_f32_16x16x32_bf16 v[14:17], v[6:9], v[14:17], 0
	s_nop 1
	v_max_f32_e32 v54, 0, v10
	v_max_f32_e32 v55, 0, v11
	v_max_f32_e32 v10, 0, v12
	v_mul_f32_e32 v56, v52, v10
	s_nop 0
	v_max_f32_e32 v160, 0, v13
	v_mfma_f32_16x16x32_bf16 v[10:13], v[2:5], v[24:27], v[14:17]
	ds_read_b128 v[24:27], v230
	v_mov_b32_e32 v45, v46
	v_mov_b32_e32 v51, v47
	ds_read_b128 v[14:17], v229
	s_waitcnt lgkmcnt(0)
	v_mfma_f32_16x16x32_bf16 v[14:17], v[6:9], v[14:17], 0
	s_nop 1
	v_max_f32_e32 v162, 0, v10
	v_max_f32_e32 v163, 0, v11
	v_max_f32_e32 v10, 0, v12
	v_mul_f32_e32 v164, v53, v10
	s_nop 0
	v_max_f32_e32 v161, 0, v13
	v_mfma_f32_16x16x32_bf16 v[10:13], v[2:5], v[24:27], v[14:17]
	ds_read_b128 v[24:27], v232
	v_pk_mul_f32 v[160:161], v[52:53], v[160:161]
	s_nop 0
	ds_read_b128 v[14:17], v231
	s_waitcnt lgkmcnt(0)
	v_mfma_f32_16x16x32_bf16 v[6:9], v[6:9], v[14:17], 0
	s_nop 1
	s_nop 0
	v_max_f32_e32 v14, 0, v13
	s_nop 0
	v_mfma_f32_16x16x32_bf16 v[2:5], v[2:5], v[24:27], v[6:9]
	s_nop 0
	v_max_f32_e32 v10, 0, v10
	v_max_f32_e32 v11, 0, v11
	v_pk_fma_f32 v[8:9], v[32:33], v[34:35], 0 op_sel_hi:[0,1,0]
	s_nop 0
	s_nop 2
	v_max_f32_e32 v15, 0, v5
	v_pk_mul_f32 v[6:7], v[166:167], v[14:15]
	v_mov_b32_e32 v14, v33
	v_pk_fma_f32 v[8:9], v[14:15], v[28:29], v[8:9] op_sel_hi:[0,1,1]
	v_pk_fma_f32 v[8:9], v[40:41], v[42:43], v[8:9] op_sel_hi:[0,1,1]
	v_mov_b32_e32 v14, v41
	v_pk_fma_f32 v[8:9], v[14:15], v[48:49], v[8:9] op_sel_hi:[0,1,1]
	v_pk_fma_f32 v[8:9], v[52:53], v[54:55], v[8:9] op_sel_hi:[0,1,1]
	v_mov_b32_e32 v14, v53
	v_pk_fma_f32 v[8:9], v[14:15], v[162:163], v[8:9] op_sel_hi:[0,1,1]
	v_max_f32_e32 v2, 0, v2
	v_max_f32_e32 v3, 0, v3
	v_pk_fma_f32 v[8:9], v[166:167], v[10:11], v[8:9] op_sel_hi:[0,1,1]
	v_mov_b32_e32 v10, v167
	v_pk_fma_f32 v[2:3], v[10:11], v[2:3], v[8:9] op_sel_hi:[0,1,1]
	v_and_b32_e32 v9, 0x7fffffff, v3
	v_and_b32_e32 v8, 0x7fffffff, v2
	v_xor_b32_e32 v5, -1, v3
	v_pk_add_f32 v[8:9], v[8:9], 0 neg_lo:[1,1] neg_hi:[1,1]
	v_cmp_gt_i32_e32 vcc, 0, v3
	v_xor_b32_e32 v10, -1, v2
	v_mov_b32_e32 v57, v160
	v_cndmask_b32_e32 v195, v9, v5, vcc
	v_cmp_gt_i32_e32 vcc, 0, v2
	v_pk_add_f32 v[2:3], v[36:37], 0 op_sel_hi:[1,0]
	v_max_f32_e32 v12, 0, v12
	v_pk_add_f32 v[2:3], v[2:3], v[30:31]
	v_pk_add_f32 v[2:3], v[2:3], v[44:45]
	v_mov_b32_e32 v165, v161
	v_pk_add_f32 v[2:3], v[2:3], v[50:51]
	v_mul_f32_e32 v12, v166, v12
	v_pk_add_f32 v[2:3], v[2:3], v[56:57]
	v_max_f32_e32 v4, 0, v4
	v_pk_add_f32 v[2:3], v[2:3], v[164:165]
	v_mov_b32_e32 v13, v6
	v_mul_f32_e32 v4, v167, v4
	v_pk_add_f32 v[2:3], v[2:3], v[12:13]
	v_mov_b32_e32 v5, v7
	v_pk_add_f32 v[2:3], v[2:3], v[4:5]
	v_cndmask_b32_e32 v196, v8, v10, vcc
	v_and_b32_e32 v5, 0x7fffffff, v3
	v_and_b32_e32 v4, 0x7fffffff, v2
	v_xor_b32_e32 v6, -1, v3
	v_pk_add_f32 v[4:5], v[4:5], 0 neg_lo:[1,1] neg_hi:[1,1]
	v_cmp_gt_i32_e32 vcc, 0, v3
	v_xor_b32_e32 v7, -1, v2
	s_nop 0
	v_cndmask_b32_e32 v197, v5, v6, vcc
	v_cmp_gt_i32_e32 vcc, 0, v2
	v_lshrrev_b32_e32 v2, 24, v196
	v_lshl_add_u32 v2, v2, 6, v0
	ds_add_u32 v2, v205 offset:16384
	v_lshrrev_b32_e32 v2, 24, v195
	v_cndmask_b32_e32 v198, v4, v7, vcc
	v_lshl_add_u32 v2, v2, 6, v0
	ds_add_u32 v2, v205 offset:16384
	v_lshrrev_b32_e32 v2, 24, v198
	v_lshl_add_u32 v2, v2, 6, v0
	ds_add_u32 v2, v205 offset:16384
	v_lshrrev_b32_e32 v2, 24, v197
	v_lshl_add_u32 v2, v2, 6, v0
	ds_add_u32 v2, v205 offset:16384
	v_add_co_u32_e32 v2, vcc, s96, v22
	s_nop 1
	v_addc_co_u32_e32 v3, vcc, 0, v23, vcc
	global_load_dwordx4 v[14:17], v[2:3], off
	global_load_dwordx4 v[10:13], v[2:3], off offset:64
	global_load_dwordx4 v[6:9], v[2:3], off offset:2048
	s_nop 0
	global_load_dwordx4 v[2:5], v[2:3], off offset:2112
	ds_read_b128 v[22:25], v223
	ds_read_b128 v[26:29], v224
	s_waitcnt vmcnt(3) lgkmcnt(1)
	v_mfma_f32_16x16x32_bf16 v[22:25], v[14:17], v[22:25], 0
	ds_read_b128 v[32:35], v221
	ds_read_b128 v[38:41], v199
	ds_read_b128 v[44:47], v222
	s_waitcnt vmcnt(2) lgkmcnt(3)
	v_mfma_f32_16x16x32_bf16 v[26:29], v[10:13], v[26:29], v[22:25]
	ds_read_b128 v[50:53], v226
	ds_read_b128 v[160:163], v228
	s_nop 0
	ds_read2_b32 v[24:25], v137 offset0:80 offset1:96
	s_nop 3
	v_max_f32_e32 v26, 0, v26
	v_max_f32_e32 v27, 0, v27
	v_max_f32_e32 v22, v28, v28
	v_max_f32_e32 v23, v29, v29
	ds_read_b128 v[28:31], v220
	s_waitcnt lgkmcnt(0)
	v_mfma_f32_16x16x32_bf16 v[28:31], v[14:17], v[28:31], 0
	v_max_f32_e32 v36, 0, v23
	v_max_f32_e32 v22, 0, v22
	v_mul_f32_e32 v22, v24, v22
	v_mfma_f32_16x16x32_bf16 v[28:31], v[10:13], v[32:35], v[28:31]
	s_nop 7
	v_max_f32_e32 v32, 0, v28
	v_max_f32_e32 v33, 0, v29
	v_max_f32_e32 v23, 0, v30
	v_mul_f32_e32 v28, v25, v23
	v_max_f32_e32 v37, 0, v31
	v_pk_mul_f32 v[30:31], v[24:25], v[36:37]
	ds_read_b128 v[34:37], v218
	s_waitcnt lgkmcnt(0)
; #define LAS __attribute__((address_space(3)))
; __device__ __forceinline__ unsigned fkey(float f) { const unsigned u = __float_as_uint(f); return (u & 0x80000000u) ? ~u : (u | 0x80000000u); }
; #define SEL_HADD(idx_) __hip_atomic_fetch_add(&hist[(idx_)], 1u, __ATOMIC_RELAXED, __HIP_MEMORY_SCOPE_WORKGROUP)
; __device__ __forceinline__ void sel_unit(LAS char* lds, int b, int u, const bf16_t* QI, const bf16_t* KIDX, const float* WIDX, unsigned long long* MASK) {
;     ...
;                 for (int ks = 0; ks < 2; ++ks) kf[kb][ks] = *(const bf16x8*)(KIDX + (rowbase + 64 * t + 32 * kh + 16 * kb + q16) * 64 + 32 * ks + 8 * kg);
; #pragma unroll
;             for (int kb = 0; kb < 2; ++kb) {
;                 f32x4 s = (f32x4){0.f, 0.f, 0.f, 0.f};
; #pragma unroll
;                 for (int hh = 0; hh < 8; ++hh) {
;                     f32x4 a = (f32x4){0.f, 0.f, 0.f, 0.f};
; #pragma unroll
;                     for (int ks = 0; ks < 2; ++ks) {
;                         const bf16x8 qv = *(const LAS bf16x8*)(lds + L_QI + q16 * 1024 + (((hh * 8 + 4 * ks + kg) ^ q16) << 4));
;                         a = __builtin_amdgcn_mfma_f32_16x16x32_bf16(kf[kb][ks], qv, a, 0, 0, 0);
;                     }
;                     const float wh = wl[hh * 16];
; #pragma unroll
;                     for (int i = 0; i < 4; ++i) s[i] += wh * fmaxf(a[i], 0.f);
;                 }
;                 u32x4 kk; kk.x = fkey(s[0]); kk.y = fkey(s[1]); kk.z = fkey(s[2]); kk.w = fkey(s[3]);
;                 sc[j][2 * kh + kb] = kk;
; #pragma unroll
;                 for (int i = 0; i < 4; ++i) SEL_HADD((kk[i] >> 24) * 16 + q16);
;                 __builtin_amdgcn_sched_barrier(0);
	v_mfma_f32_16x16x32_bf16 v[34:37], v[14:17], v[34:37], 0
	v_mov_b32_e32 v29, v31
	v_mfma_f32_16x16x32_bf16 v[38:41], v[10:13], v[38:41], v[34:37]
	s_nop 5
	ds_read2_b32 v[36:37], v137 offset0:112 offset1:128
	s_nop 0
	v_max_f32_e32 v38, 0, v38
	v_max_f32_e32 v39, 0, v39
	v_max_f32_e32 v23, 0, v40
	s_waitcnt lgkmcnt(0)
	v_mul_f32_e32 v34, v36, v23
	v_max_f32_e32 v23, v41, v41
	ds_read_b128 v[40:43], v219
	s_waitcnt lgkmcnt(0)
	v_mfma_f32_16x16x32_bf16 v[40:43], v[14:17], v[40:43], 0
	v_max_f32_e32 v48, 0, v23
	v_mfma_f32_16x16x32_bf16 v[40:43], v[10:13], v[44:47], v[40:43]
	s_nop 7
	v_max_f32_e32 v44, 0, v40
	v_max_f32_e32 v45, 0, v41
	v_max_f32_e32 v23, 0, v42
	v_mul_f32_e32 v40, v37, v23
	v_max_f32_e32 v49, 0, v43
	v_pk_mul_f32 v[42:43], v[36:37], v[48:49]
	ds_read_b128 v[46:49], v225
	s_waitcnt lgkmcnt(0)
	v_mfma_f32_16x16x32_bf16 v[46:49], v[14:17], v[46:49], 0
	v_mov_b32_e32 v35, v42
	v_mov_b32_e32 v41, v43
	v_mfma_f32_16x16x32_bf16 v[50:53], v[10:13], v[50:53], v[46:49]
	s_nop 4
	ds_read2_b32 v[48:49], v137 offset0:144 offset1:160
	s_nop 1
	v_max_f32_e32 v50, 0, v50
	v_max_f32_e32 v51, 0, v51
	v_max_f32_e32 v23, 0, v52
	s_waitcnt lgkmcnt(0)
	v_mul_f32_e32 v46, v48, v23
	v_max_f32_e32 v23, v53, v53
	ds_read_b128 v[52:55], v227
	s_waitcnt lgkmcnt(0)
	v_mfma_f32_16x16x32_bf16 v[52:55], v[14:17], v[52:55], 0
	v_max_f32_e32 v164, 0, v23
	v_mfma_f32_16x16x32_bf16 v[52:55], v[10:13], v[160:163], v[52:55]
	ds_read_b128 v[160:163], v229
	s_nop 6
	v_max_f32_e32 v56, 0, v52
	v_max_f32_e32 v57, 0, v53
	v_max_f32_e32 v23, 0, v54
	v_mul_f32_e32 v52, v49, v23
	v_max_f32_e32 v165, 0, v55
	v_pk_mul_f32 v[54:55], v[48:49], v[164:165]
	ds_read_b128 v[164:167], v230
	s_waitcnt lgkmcnt(1)
	v_mfma_f32_16x16x32_bf16 v[160:163], v[14:17], v[160:163], 0
	v_mov_b32_e32 v47, v54
	v_mov_b32_e32 v53, v55
	s_waitcnt lgkmcnt(0)
	v_mfma_f32_16x16x32_bf16 v[160:163], v[10:13], v[164:167], v[160:163]
	ds_read2_b32 v[164:165], v137 offset0:176 offset1:192
	s_nop 6
	v_max_f32_e32 v166, 0, v160
	v_max_f32_e32 v167, 0, v161
	v_max_f32_e32 v23, 0, v162
	s_waitcnt lgkmcnt(0)
	v_mul_f32_e32 v168, v164, v23
	v_max_f32_e32 v23, v163, v163
	ds_read_b128 v[160:163], v231
	s_waitcnt lgkmcnt(0)
	v_mfma_f32_16x16x32_bf16 v[14:17], v[14:17], v[160:163], 0
	ds_read_b128 v[160:163], v232
	v_max_f32_e32 v170, 0, v23
	s_waitcnt lgkmcnt(0)
	v_mfma_f32_16x16x32_bf16 v[10:13], v[10:13], v[160:163], v[14:17]
	s_nop 3
	v_fma_f32 v16, v24, v26, 0
	v_fma_f32 v17, v24, v27, 0
	v_mov_b32_e32 v24, v25
	v_pk_fma_f32 v[16:17], v[24:25], v[32:33], v[16:17] op_sel_hi:[0,1,1]
	v_pk_fma_f32 v[16:17], v[36:37], v[38:39], v[16:17] op_sel_hi:[0,1,1]
	v_mov_b32_e32 v24, v37
	v_pk_fma_f32 v[16:17], v[24:25], v[44:45], v[16:17] op_sel_hi:[0,1,1]
	v_pk_fma_f32 v[16:17], v[48:49], v[50:51], v[16:17] op_sel_hi:[0,1,1]
	v_mov_b32_e32 v24, v49
	v_pk_fma_f32 v[16:17], v[24:25], v[56:57], v[16:17] op_sel_hi:[0,1,1]
	v_max_f32_e32 v10, 0, v10
	v_max_f32_e32 v11, 0, v11
	v_pk_fma_f32 v[16:17], v[164:165], v[166:167], v[16:17] op_sel_hi:[0,1,1]
	v_mov_b32_e32 v24, v165
	v_pk_fma_f32 v[10:11], v[24:25], v[10:11], v[16:17] op_sel_hi:[0,1,1]
	v_and_b32_e32 v17, 0x7fffffff, v11
	v_and_b32_e32 v16, 0x7fffffff, v10
	v_xor_b32_e32 v23, -1, v10
	v_pk_add_f32 v[16:17], v[16:17], 0 neg_lo:[1,1] neg_hi:[1,1]
	v_cmp_gt_i32_e32 vcc, 0, v10
	v_max_f32_e32 v171, 0, v13
	s_nop 0
	v_cndmask_b32_e32 v57, v16, v23, vcc
	v_mov_b32_e32 v23, v30
	v_xor_b32_e32 v13, -1, v11
	v_cmp_gt_i32_e64 s[2:3], 0, v11
	v_pk_add_f32 v[10:11], v[22:23], 0 op_sel_hi:[1,0]
	v_pk_add_f32 v[10:11], v[10:11], v[28:29]
	v_pk_mul_f32 v[14:15], v[164:165], v[170:171]
	v_pk_add_f32 v[10:11], v[10:11], v[34:35]
	v_max_f32_e32 v12, 0, v12
	v_pk_add_f32 v[10:11], v[10:11], v[40:41]
	v_mov_b32_e32 v169, v14
	v_pk_add_f32 v[10:11], v[10:11], v[46:47]
	v_mul_f32_e32 v12, v165, v12
	v_pk_add_f32 v[10:11], v[10:11], v[52:53]
	v_cndmask_b32_e64 v56, v17, v13, s[2:3]
	v_pk_add_f32 v[10:11], v[10:11], v[168:169]
	v_mov_b32_e32 v13, v15
	v_pk_add_f32 v[10:11], v[10:11], v[12:13]
	s_nop 0
	v_xor_b32_e32 v15, -1, v10
	v_and_b32_e32 v12, 0x7fffffff, v10
	v_cmp_gt_i32_e32 vcc, 0, v10
	v_lshrrev_b32_e32 v10, 24, v57
	v_and_b32_e32 v13, 0x7fffffff, v11
	v_lshl_add_u32 v10, v10, 6, v0
	v_pk_add_f32 v[12:13], v[12:13], 0 neg_lo:[1,1] neg_hi:[1,1]
	ds_add_u32 v10, v205 offset:16384
	v_lshrrev_b32_e32 v10, 24, v56
	v_cndmask_b32_e32 v55, v12, v15, vcc
	v_lshl_add_u32 v10, v10, 6, v0
	v_xor_b32_e32 v14, -1, v11
	v_cmp_gt_i32_e64 s[2:3], 0, v11
	ds_add_u32 v10, v205 offset:16384
	v_lshrrev_b32_e32 v10, 24, v55
	v_cndmask_b32_e64 v54, v13, v14, s[2:3]
	v_lshl_add_u32 v10, v10, 6, v0
	ds_add_u32 v10, v205 offset:16384
	v_lshrrev_b32_e32 v10, 24, v54
	v_lshl_add_u32 v10, v10, 6, v0
	ds_add_u32 v10, v205 offset:16384
	ds_read_b128 v[10:13], v223
	ds_read_b128 v[14:17], v224
	ds_read_b128 v[22:25], v220
	ds_read_b128 v[26:29], v221
	ds_read2_b32 v[30:31], v137 offset0:80 offset1:96
	ds_read2_b32 v[38:39], v137 offset0:112 offset1:128
	s_waitcnt vmcnt(1) lgkmcnt(5)
	v_mfma_f32_16x16x32_bf16 v[10:13], v[6:9], v[10:13], 0
	ds_read2_b32 v[50:51], v137 offset0:144 offset1:160
	ds_read2_b32 v[168:169], v137 offset0:176 offset1:192
	s_waitcnt vmcnt(0) lgkmcnt(6)
	v_mfma_f32_16x16x32_bf16 v[10:13], v[2:5], v[14:17], v[10:13]
	ds_read_b128 v[14:17], v218
	s_waitcnt lgkmcnt(6)
	v_mfma_f32_16x16x32_bf16 v[22:25], v[6:9], v[22:25], 0
	s_nop 4
	v_max_f32_e32 v32, 0, v10
	v_max_f32_e32 v10, 0, v12
	v_max_f32_e32 v33, 0, v11
	s_waitcnt lgkmcnt(4)
	v_mul_f32_e32 v34, v30, v10
	v_max_f32_e32 v36, 0, v13
	v_mfma_f32_16x16x32_bf16 v[10:13], v[2:5], v[26:29], v[22:25]
	s_nop 2
	ds_read_b128 v[22:25], v199
	s_waitcnt lgkmcnt(1)
; #define LAS __attribute__((address_space(3)))
; __device__ __forceinline__ unsigned fkey(float f) { const unsigned u = __float_as_uint(f); return (u & 0x80000000u) ? ~u : (u | 0x80000000u); }
; #define SEL_HADD(idx_) __hip_atomic_fetch_add(&hist[(idx_)], 1u, __ATOMIC_RELAXED, __HIP_MEMORY_SCOPE_WORKGROUP)
; __device__ __forceinline__ void sel_unit(LAS char* lds, int b, int u, const bf16_t* QI, const bf16_t* KIDX, const float* WIDX, unsigned long long* MASK) {
;     ...
;                 for (int ks = 0; ks < 2; ++ks) kf[kb][ks] = *(const bf16x8*)(KIDX + (rowbase + 64 * t + 32 * kh + 16 * kb + q16) * 64 + 32 * ks + 8 * kg);
; #pragma unroll
;             for (int kb = 0; kb < 2; ++kb) {
;                 f32x4 s = (f32x4){0.f, 0.f, 0.f, 0.f};
; #pragma unroll
;                 for (int hh = 0; hh < 8; ++hh) {
;                     f32x4 a = (f32x4){0.f, 0.f, 0.f, 0.f};
; #pragma unroll
;                     for (int ks = 0; ks < 2; ++ks) {
;                         const bf16x8 qv = *(const LAS bf16x8*)(lds + L_QI + q16 * 1024 + (((hh * 8 + 4 * ks + kg) ^ q16) << 4));
;                         a = __builtin_amdgcn_mfma_f32_16x16x32_bf16(kf[kb][ks], qv, a, 0, 0, 0);
;                     }
;                     const float wh = wl[hh * 16];
; #pragma unroll
;                     for (int i = 0; i < 4; ++i) s[i] += wh * fmaxf(a[i], 0.f);
;                 }
;                 u32x4 kk; kk.x = fkey(s[0]); kk.y = fkey(s[1]); kk.z = fkey(s[2]); kk.w = fkey(s[3]);
;                 sc[j][2 * kh + kb] = kk;
; #pragma unroll
;                 for (int i = 0; i < 4; ++i) SEL_HADD((kk[i] >> 24) * 16 + q16);
;                 __builtin_amdgcn_sched_barrier(0);
	v_mfma_f32_16x16x32_bf16 v[14:17], v[6:9], v[14:17], 0
	s_nop 1
	v_max_f32_e32 v26, 0, v10
	v_max_f32_e32 v27, 0, v11
	v_max_f32_e32 v10, 0, v12
	v_mul_f32_e32 v28, v31, v10
	v_max_f32_e32 v37, 0, v13
	s_waitcnt lgkmcnt(0)
	v_mfma_f32_16x16x32_bf16 v[10:13], v[2:5], v[22:25], v[14:17]
	ds_read_b128 v[22:25], v222
	v_pk_mul_f32 v[36:37], v[30:31], v[36:37]
	s_nop 0
	ds_read_b128 v[14:17], v219
	s_waitcnt lgkmcnt(0)
	v_mfma_f32_16x16x32_bf16 v[14:17], v[6:9], v[14:17], 0
	s_nop 1
	v_max_f32_e32 v40, 0, v10
	v_max_f32_e32 v41, 0, v11
	v_max_f32_e32 v10, 0, v12
	v_mul_f32_e32 v42, v38, v10
	s_nop 0
	v_max_f32_e32 v44, 0, v13
	v_mfma_f32_16x16x32_bf16 v[10:13], v[2:5], v[22:25], v[14:17]
	ds_read_b128 v[22:25], v226
	v_mov_b32_e32 v35, v36
	v_mov_b32_e32 v29, v37
	ds_read_b128 v[14:17], v225
	s_waitcnt lgkmcnt(0)
	v_mfma_f32_16x16x32_bf16 v[14:17], v[6:9], v[14:17], 0
	s_nop 1
	v_max_f32_e32 v46, 0, v10
	v_max_f32_e32 v47, 0, v11
	v_max_f32_e32 v10, 0, v12
	v_mul_f32_e32 v48, v39, v10
	s_nop 0
	v_max_f32_e32 v45, 0, v13
	v_mfma_f32_16x16x32_bf16 v[10:13], v[2:5], v[22:25], v[14:17]
	ds_read_b128 v[22:25], v228
	v_pk_mul_f32 v[44:45], v[38:39], v[44:45]
	s_nop 0
	ds_read_b128 v[14:17], v227
	s_waitcnt lgkmcnt(0)
	v_mfma_f32_16x16x32_bf16 v[14:17], v[6:9], v[14:17], 0
	s_nop 1
	v_max_f32_e32 v52, 0, v10
	v_max_f32_e32 v53, 0, v11
	v_max_f32_e32 v10, 0, v12
	v_mul_f32_e32 v160, v50, v10
	s_nop 0
	v_max_f32_e32 v162, 0, v13
	v_mfma_f32_16x16x32_bf16 v[10:13], v[2:5], v[22:25], v[14:17]
	ds_read_b128 v[22:25], v230
	v_mov_b32_e32 v43, v44
	v_mov_b32_e32 v49, v45
	ds_read_b128 v[14:17], v229
	s_waitcnt lgkmcnt(0)
	v_mfma_f32_16x16x32_bf16 v[14:17], v[6:9], v[14:17], 0
	s_nop 1
	v_max_f32_e32 v164, 0, v10
	v_max_f32_e32 v165, 0, v11
	v_max_f32_e32 v10, 0, v12
	v_mul_f32_e32 v166, v51, v10
	s_nop 0
	v_max_f32_e32 v163, 0, v13
	v_mfma_f32_16x16x32_bf16 v[10:13], v[2:5], v[22:25], v[14:17]
	ds_read_b128 v[22:25], v232
	v_pk_mul_f32 v[162:163], v[50:51], v[162:163]
	s_nop 0
	ds_read_b128 v[14:17], v231
	s_waitcnt lgkmcnt(0)
	v_mfma_f32_16x16x32_bf16 v[6:9], v[6:9], v[14:17], 0
	s_nop 1
	s_nop 0
	v_max_f32_e32 v14, 0, v13
	s_nop 0
	v_mfma_f32_16x16x32_bf16 v[2:5], v[2:5], v[22:25], v[6:9]
	s_nop 0
	v_max_f32_e32 v10, 0, v10
	v_max_f32_e32 v11, 0, v11
	v_pk_fma_f32 v[8:9], v[30:31], v[32:33], 0 op_sel_hi:[0,1,0]
	s_nop 0
	s_nop 2
	v_max_f32_e32 v15, 0, v5
	v_pk_mul_f32 v[6:7], v[168:169], v[14:15]
	v_mov_b32_e32 v14, v31
	v_pk_fma_f32 v[8:9], v[14:15], v[26:27], v[8:9] op_sel_hi:[0,1,1]
	v_pk_fma_f32 v[8:9], v[38:39], v[40:41], v[8:9] op_sel_hi:[0,1,1]
	v_mov_b32_e32 v14, v39
	v_pk_fma_f32 v[8:9], v[14:15], v[46:47], v[8:9] op_sel_hi:[0,1,1]
	v_pk_fma_f32 v[8:9], v[50:51], v[52:53], v[8:9] op_sel_hi:[0,1,1]
	v_mov_b32_e32 v14, v51
	v_pk_fma_f32 v[8:9], v[14:15], v[164:165], v[8:9] op_sel_hi:[0,1,1]
	v_max_f32_e32 v2, 0, v2
	v_max_f32_e32 v3, 0, v3
	v_pk_fma_f32 v[8:9], v[168:169], v[10:11], v[8:9] op_sel_hi:[0,1,1]
	v_mov_b32_e32 v10, v169
	v_pk_fma_f32 v[2:3], v[10:11], v[2:3], v[8:9] op_sel_hi:[0,1,1]
	v_and_b32_e32 v9, 0x7fffffff, v3
	v_and_b32_e32 v8, 0x7fffffff, v2
	v_xor_b32_e32 v5, -1, v3
	v_pk_add_f32 v[8:9], v[8:9], 0 neg_lo:[1,1] neg_hi:[1,1]
	v_cmp_gt_i32_e32 vcc, 0, v3
	v_xor_b32_e32 v10, -1, v2
	v_mov_b32_e32 v161, v162
	v_cndmask_b32_e32 v199, v9, v5, vcc
	v_cmp_gt_i32_e32 vcc, 0, v2
	v_pk_add_f32 v[2:3], v[34:35], 0 op_sel_hi:[1,0]
	v_max_f32_e32 v12, 0, v12
	v_pk_add_f32 v[2:3], v[2:3], v[28:29]
	v_pk_add_f32 v[2:3], v[2:3], v[42:43]
	v_mov_b32_e32 v167, v163
	v_pk_add_f32 v[2:3], v[2:3], v[48:49]
	v_mul_f32_e32 v12, v168, v12
	v_pk_add_f32 v[2:3], v[2:3], v[160:161]
	v_max_f32_e32 v4, 0, v4
	v_pk_add_f32 v[2:3], v[2:3], v[166:167]
	v_mov_b32_e32 v13, v6
	v_mul_f32_e32 v4, v169, v4
	v_pk_add_f32 v[2:3], v[2:3], v[12:13]
	v_mov_b32_e32 v5, v7
	v_pk_add_f32 v[2:3], v[2:3], v[4:5]
	v_cndmask_b32_e32 v218, v8, v10, vcc
	v_and_b32_e32 v5, 0x7fffffff, v3
	v_and_b32_e32 v4, 0x7fffffff, v2
	v_xor_b32_e32 v6, -1, v3
	v_pk_add_f32 v[4:5], v[4:5], 0 neg_lo:[1,1] neg_hi:[1,1]
	v_cmp_gt_i32_e32 vcc, 0, v3
	v_xor_b32_e32 v7, -1, v2
	s_nop 0
	v_cndmask_b32_e32 v219, v5, v6, vcc
	v_cmp_gt_i32_e32 vcc, 0, v2
	v_lshrrev_b32_e32 v2, 24, v218
	v_lshl_add_u32 v2, v2, 6, v0
	ds_add_u32 v2, v205 offset:16384
	v_lshrrev_b32_e32 v2, 24, v199
	v_cndmask_b32_e32 v220, v4, v7, vcc
	v_lshl_add_u32 v2, v2, 6, v0
	ds_add_u32 v2, v205 offset:16384
	v_lshrrev_b32_e32 v2, 24, v220
	v_lshl_add_u32 v2, v2, 6, v0
	ds_add_u32 v2, v205 offset:16384
	v_lshrrev_b32_e32 v2, 24, v219
	v_lshl_add_u32 v2, v2, 6, v0
	ds_add_u32 v2, v205 offset:16384
; #define LAS __attribute__((address_space(3)))
; __device__ __forceinline__ unsigned fkey(float f) { const unsigned u = __float_as_uint(f); return (u & 0x80000000u) ? ~u : (u | 0x80000000u); }
; #define SEL_HADD(idx_) __hip_atomic_fetch_add(&hist[(idx_)], 1u, __ATOMIC_RELAXED, __HIP_MEMORY_SCOPE_WORKGROUP)
; __device__ __forceinline__ void sel_unit(LAS char* lds, int b, int u, const bf16_t* QI, const bf16_t* KIDX, const float* WIDX, unsigned long long* MASK) {
;     ...
;     for (int j = 0; j < 8; ++j) {
;         if (j < nj) {
;             int t = wid + 8 * j; asm volatile("" : "+s"(t));
; #pragma unroll
;             for (int kh = 0; kh < 2; ++kh) {
;             bf16x8 kf[2][2];
; #pragma unroll
;             for (int kb = 0; kb < 2; ++kb)
; #pragma unroll
;                 for (int ks = 0; ks < 2; ++ks) kf[kb][ks] = *(const bf16x8*)(KIDX + (rowbase + 64 * t + 32 * kh + 16 * kb + q16) * 64 + 32 * ks + 8 * kg);
; #pragma unroll
;             for (int kb = 0; kb < 2; ++kb) {
;                 f32x4 s = (f32x4){0.f, 0.f, 0.f, 0.f};
; #pragma unroll
;                 for (int hh = 0; hh < 8; ++hh) {
;                     f32x4 a = (f32x4){0.f, 0.f, 0.f, 0.f};
; #pragma unroll
;                     for (int ks = 0; ks < 2; ++ks) {
;                         const bf16x8 qv = *(const LAS bf16x8*)(lds + L_QI + q16 * 1024 + (((hh * 8 + 4 * ks + kg) ^ q16) << 4));
;                         a = __builtin_amdgcn_mfma_f32_16x16x32_bf16(kf[kb][ks], qv, a, 0, 0, 0);
;                     }
;                     const float wh = wl[hh * 16];
; #pragma unroll
;                     for (int i = 0; i < 4; ++i) s[i] += wh * fmaxf(a[i], 0.f);
;                 }
;                 u32x4 kk; kk.x = fkey(s[0]); kk.y = fkey(s[1]); kk.z = fkey(s[2]); kk.w = fkey(s[3]);
;                 sc[j][2 * kh + kb] = kk;
; #pragma unroll
;                 for (int i = 0; i < 4; ++i) SEL_HADD((kk[i] >> 24) * 16 + q16);
;                 __builtin_amdgcn_sched_barrier(0);
.LBB0_670:
	s_cmp_gt_i32 s4, 7
	s_cselect_b64 s[26:27], -1, 0
	s_cmp_lt_i32 s4, 8
	s_cbranch_scc1 .LBB0_672
	s_add_i32 s2, s46, 56
	s_lshl_b32 s2, s2, 6
	s_ashr_i32 s3, s2, 31
	v_lshl_add_u64 v[2:3], v[18:19], 0, s[2:3]
	v_lshlrev_b64 v[2:3], 7, v[2:3]
	v_lshl_add_u64 v[18:19], v[20:21], 0, v[2:3]
	global_load_dwordx4 v[14:17], v[18:19], off
	global_load_dwordx4 v[10:13], v[18:19], off offset:64
	v_lshl_add_u32 v229, v182, 4, v150
	v_lshl_add_u32 v230, v183, 4, v150
	v_lshl_add_u32 v183, v184, 4, v150
	v_lshl_add_u32 v184, v185, 4, v150
	v_lshl_add_u32 v182, v179, 4, v150
	v_lshl_add_u32 v179, v180, 4, v150
	v_lshl_add_u32 v159, v159, 4, v150
	ds_read_b128 v[2:5], v229
	ds_read_b128 v[6:9], v230
	ds_read_b128 v[20:23], v183
	v_lshl_add_u32 v176, v176, 4, v150
	ds_read_b128 v[24:27], v184
	ds_read_b128 v[28:31], v182
	ds_read_b128 v[32:35], v179
	ds_read_b128 v[36:39], v176
	v_lshl_add_u32 v158, v158, 4, v150
	ds_read_b128 v[40:43], v159
	ds_read_b128 v[44:47], v158
	v_lshl_add_u32 v157, v157, 4, v150
	ds_read_b128 v[48:51], v157
	v_lshl_add_u32 v156, v156, 4, v150
	v_lshl_add_u32 v155, v155, 4, v150
	ds_read_b128 v[160:163], v156
	ds_read_b128 v[164:167], v155
	v_lshl_add_u32 v154, v154, 4, v150
	v_lshl_add_u32 v153, v153, 4, v150
	v_lshl_add_u32 v152, v152, 4, v150
	v_lshl_add_u32 v150, v151, 4, v150
	s_waitcnt vmcnt(1) lgkmcnt(11)
	v_mfma_f32_16x16x32_bf16 v[2:5], v[14:17], v[2:5], 0
	s_waitcnt lgkmcnt(9)
	v_mfma_f32_16x16x32_bf16 v[20:23], v[14:17], v[20:23], 0
	s_waitcnt lgkmcnt(7)
	v_mfma_f32_16x16x32_bf16 v[28:31], v[14:17], v[28:31], 0
	s_waitcnt lgkmcnt(5)
	v_mfma_f32_16x16x32_bf16 v[36:39], v[14:17], v[36:39], 0
	s_waitcnt lgkmcnt(3)
	v_mfma_f32_16x16x32_bf16 v[44:47], v[14:17], v[44:47], 0
	s_waitcnt vmcnt(0)
	v_mfma_f32_16x16x32_bf16 v[168:171], v[10:13], v[6:9], v[2:5]
	v_mfma_f32_16x16x32_bf16 v[20:23], v[10:13], v[24:27], v[20:23]
	v_mfma_f32_16x16x32_bf16 v[24:27], v[10:13], v[32:35], v[28:31]
	v_mfma_f32_16x16x32_bf16 v[28:31], v[10:13], v[40:43], v[36:39]
	ds_read2_b32 v[40:41], v137 offset0:80 offset1:96
	ds_read2_b32 v[42:43], v137 offset0:112 offset1:128
	s_nop 3
	s_waitcnt lgkmcnt(4)
	v_mfma_f32_16x16x32_bf16 v[32:35], v[10:13], v[48:51], v[44:47]
	ds_read2_b32 v[44:45], v137 offset0:144 offset1:160
	global_load_dwordx4 v[6:9], v[18:19], off offset:2048
	global_load_dwordx4 v[2:5], v[18:19], off offset:2112
	s_waitcnt lgkmcnt(4)
	v_mfma_f32_16x16x32_bf16 v[160:163], v[14:17], v[160:163], 0
	s_nop 0
	s_nop 0
	v_max_f32_e32 v50, v20, v20
	s_waitcnt lgkmcnt(3)
	v_mfma_f32_16x16x32_bf16 v[36:39], v[10:13], v[164:167], v[160:163]
	s_nop 0
	v_max_f32_e32 v20, 0, v171
	v_max_f32_e32 v164, 0, v22
	v_max_f32_e32 v160, v35, v35
	v_max_f32_e32 v35, 0, v21
	s_nop 2
	v_max_f32_e32 v21, 0, v23
	v_max_f32_e32 v22, 0, v27
	v_max_f32_e32 v23, 0, v31
	v_max_f32_e32 v51, v32, v32
	v_max_f32_e32 v53, v34, v34
	v_max_f32_e32 v32, 0, v168
	v_max_f32_e32 v34, 0, v50
	v_max_f32_e32 v46, 0, v28
	v_max_f32_e32 v28, 0, v160
	v_max_f32_e32 v50, 0, v36
	s_waitcnt lgkmcnt(2)
	v_pk_mul_f32 v[160:161], v[40:41], v[20:21]
	s_waitcnt lgkmcnt(1)
	v_pk_mul_f32 v[166:167], v[42:43], v[22:23]
	ds_read_b128 v[20:23], v154
	v_max_f32_e32 v162, v37, v37
	v_max_f32_e32 v163, v38, v38
	v_max_f32_e32 v36, 0, v24
	v_max_f32_e32 v24, 0, v26
	v_max_f32_e32 v38, 0, v170
	v_max_f32_e32 v37, 0, v25
	v_max_f32_e32 v25, 0, v30
	v_max_f32_e32 v48, 0, v51
	v_max_f32_e32 v26, 0, v53
	v_max_f32_e32 v51, 0, v162
	v_mul_f32_e32 v162, v42, v24
	v_max_f32_e32 v24, 0, v163
	v_max_f32_e32 v49, 0, v33
	v_mul_f32_e32 v52, v41, v164
	v_mul_f32_e32 v164, v43, v25
	s_waitcnt lgkmcnt(1)
	v_mul_f32_e32 v168, v44, v26
	v_mul_f32_e32 v170, v45, v24
	ds_read_b128 v[24:27], v153
	s_waitcnt lgkmcnt(1)
	v_mfma_f32_16x16x32_bf16 v[20:23], v[14:17], v[20:23], 0
	v_max_f32_e32 v33, 0, v169
	s_waitcnt lgkmcnt(0)
	v_mfma_f32_16x16x32_bf16 v[20:23], v[10:13], v[24:27], v[20:23]
	ds_read_b128 v[24:27], v152
	v_max_f32_e32 v47, 0, v29
	v_max_f32_e32 v29, 0, v39
	v_pk_mul_f32 v[172:173], v[44:45], v[28:29]
	ds_read_b128 v[28:31], v150
	s_waitcnt lgkmcnt(1)
	v_mfma_f32_16x16x32_bf16 v[14:17], v[14:17], v[24:27], 0
	ds_read2_b32 v[174:175], v137 offset0:176 offset1:192
	s_nop 0
	v_max_f32_e32 v24, 0, v23
	s_waitcnt lgkmcnt(1)
	v_mfma_f32_16x16x32_bf16 v[10:13], v[10:13], v[28:31], v[14:17]
	s_nop 0
	s_nop 0
	v_max_f32_e32 v20, 0, v20
	v_pk_fma_f32 v[16:17], v[40:41], v[32:33], 0 op_sel_hi:[0,1,0]
	v_max_f32_e32 v21, 0, v21
	s_nop 2
	v_max_f32_e32 v25, 0, v13
	s_waitcnt lgkmcnt(0)
; #define LAS __attribute__((address_space(3)))
; __device__ __forceinline__ unsigned fkey(float f) { const unsigned u = __float_as_uint(f); return (u & 0x80000000u) ? ~u : (u | 0x80000000u); }
; #define SEL_HADD(idx_) __hip_atomic_fetch_add(&hist[(idx_)], 1u, __ATOMIC_RELAXED, __HIP_MEMORY_SCOPE_WORKGROUP)
; __device__ __forceinline__ void sel_unit(LAS char* lds, int b, int u, const bf16_t* QI, const bf16_t* KIDX, const float* WIDX, unsigned long long* MASK) {
;     ...
;                 for (int ks = 0; ks < 2; ++ks) kf[kb][ks] = *(const bf16x8*)(KIDX + (rowbase + 64 * t + 32 * kh + 16 * kb + q16) * 64 + 32 * ks + 8 * kg);
; #pragma unroll
;             for (int kb = 0; kb < 2; ++kb) {
;                 f32x4 s = (f32x4){0.f, 0.f, 0.f, 0.f};
; #pragma unroll
;                 for (int hh = 0; hh < 8; ++hh) {
;                     f32x4 a = (f32x4){0.f, 0.f, 0.f, 0.f};
; #pragma unroll
;                     for (int ks = 0; ks < 2; ++ks) {
;                         const bf16x8 qv = *(const LAS bf16x8*)(lds + L_QI + q16 * 1024 + (((hh * 8 + 4 * ks + kg) ^ q16) << 4));
;                         a = __builtin_amdgcn_mfma_f32_16x16x32_bf16(kf[kb][ks], qv, a, 0, 0, 0);
;                     }
;                     const float wh = wl[hh * 16];
; #pragma unroll
;                     for (int i = 0; i < 4; ++i) s[i] += wh * fmaxf(a[i], 0.f);
;                 }
;                 u32x4 kk; kk.x = fkey(s[0]); kk.y = fkey(s[1]); kk.z = fkey(s[2]); kk.w = fkey(s[3]);
;                 sc[j][2 * kh + kb] = kk;
; #pragma unroll
;                 for (int i = 0; i < 4; ++i) SEL_HADD((kk[i] >> 24) * 16 + q16);
;                 __builtin_amdgcn_sched_barrier(0);
	v_pk_mul_f32 v[14:15], v[174:175], v[24:25]
	v_mov_b32_e32 v24, v41
	v_pk_fma_f32 v[16:17], v[24:25], v[34:35], v[16:17] op_sel_hi:[0,1,1]
	v_pk_fma_f32 v[16:17], v[42:43], v[36:37], v[16:17] op_sel_hi:[0,1,1]
	v_mov_b32_e32 v24, v43
	v_pk_fma_f32 v[16:17], v[24:25], v[46:47], v[16:17] op_sel_hi:[0,1,1]
	v_pk_fma_f32 v[16:17], v[44:45], v[48:49], v[16:17] op_sel_hi:[0,1,1]
	v_mov_b32_e32 v24, v45
	v_pk_fma_f32 v[16:17], v[24:25], v[50:51], v[16:17] op_sel_hi:[0,1,1]
	v_max_f32_e32 v10, 0, v10
	v_max_f32_e32 v11, 0, v11
	v_pk_fma_f32 v[16:17], v[174:175], v[20:21], v[16:17] op_sel_hi:[0,1,1]
	v_mov_b32_e32 v20, v175
	v_pk_fma_f32 v[10:11], v[20:21], v[10:11], v[16:17] op_sel_hi:[0,1,1]
	v_and_b32_e32 v17, 0x7fffffff, v11
	v_and_b32_e32 v16, 0x7fffffff, v10
	v_mul_f32_e32 v38, v40, v38
	v_xor_b32_e32 v13, -1, v11
	v_pk_add_f32 v[16:17], v[16:17], 0 neg_lo:[1,1] neg_hi:[1,1]
	v_cmp_gt_i32_e32 vcc, 0, v11
	v_mov_b32_e32 v39, v160
	v_xor_b32_e32 v20, -1, v10
	v_cndmask_b32_e32 v221, v17, v13, vcc
	v_cmp_gt_i32_e32 vcc, 0, v10
	v_pk_add_f32 v[10:11], v[38:39], 0 op_sel_hi:[1,0]
	v_mov_b32_e32 v53, v161
	v_pk_add_f32 v[10:11], v[10:11], v[52:53]
	v_mov_b32_e32 v163, v166
	v_pk_add_f32 v[10:11], v[10:11], v[162:163]
	v_mov_b32_e32 v165, v167
	v_pk_add_f32 v[10:11], v[10:11], v[164:165]
	v_mov_b32_e32 v169, v172
	v_max_f32_e32 v22, 0, v22
	v_pk_add_f32 v[10:11], v[10:11], v[168:169]
	v_mov_b32_e32 v171, v173
	v_mul_f32_e32 v22, v174, v22
	v_max_f32_e32 v12, 0, v12
	v_pk_add_f32 v[10:11], v[10:11], v[170:171]
	v_mov_b32_e32 v23, v14
	v_mul_f32_e32 v12, v175, v12
	v_pk_add_f32 v[10:11], v[10:11], v[22:23]
	v_mov_b32_e32 v13, v15
	v_pk_add_f32 v[10:11], v[10:11], v[12:13]
	v_cndmask_b32_e32 v222, v16, v20, vcc
	v_and_b32_e32 v13, 0x7fffffff, v11
	v_and_b32_e32 v12, 0x7fffffff, v10
	v_xor_b32_e32 v14, -1, v11
	v_pk_add_f32 v[12:13], v[12:13], 0 neg_lo:[1,1] neg_hi:[1,1]
	v_cmp_gt_i32_e32 vcc, 0, v11
	v_xor_b32_e32 v15, -1, v10
	s_nop 0
	v_cndmask_b32_e32 v223, v13, v14, vcc
	v_cmp_gt_i32_e32 vcc, 0, v10
	v_lshrrev_b32_e32 v10, 24, v222
	v_lshl_add_u32 v10, v10, 6, v0
	ds_add_u32 v10, v205 offset:16384
	v_lshrrev_b32_e32 v10, 24, v221
	v_cndmask_b32_e32 v224, v12, v15, vcc
	v_lshl_add_u32 v10, v10, 6, v0
	ds_add_u32 v10, v205 offset:16384
	v_lshrrev_b32_e32 v10, 24, v224
	v_lshl_add_u32 v10, v10, 6, v0
	ds_add_u32 v10, v205 offset:16384
	v_lshrrev_b32_e32 v10, 24, v223
	v_lshl_add_u32 v10, v10, 6, v0
	ds_add_u32 v10, v205 offset:16384
	ds_read_b128 v[10:13], v229
	ds_read_b128 v[14:17], v230
	ds_read_b128 v[20:23], v183
	ds_read_b128 v[24:27], v184
	ds_read2_b32 v[28:29], v137 offset0:80 offset1:96
	ds_read2_b32 v[36:37], v137 offset0:112 offset1:128
	s_waitcnt vmcnt(1) lgkmcnt(5)
	v_mfma_f32_16x16x32_bf16 v[10:13], v[6:9], v[10:13], 0
	ds_read2_b32 v[48:49], v137 offset0:144 offset1:160
	ds_read2_b32 v[166:167], v137 offset0:176 offset1:192
	s_waitcnt vmcnt(0) lgkmcnt(6)
	v_mfma_f32_16x16x32_bf16 v[10:13], v[2:5], v[14:17], v[10:13]
	ds_read_b128 v[14:17], v182
	s_waitcnt lgkmcnt(6)
	v_mfma_f32_16x16x32_bf16 v[20:23], v[6:9], v[20:23], 0
	s_nop 4
	v_max_f32_e32 v30, 0, v10
	v_max_f32_e32 v10, 0, v12
	v_max_f32_e32 v31, 0, v11
	s_waitcnt lgkmcnt(4)
	v_mul_f32_e32 v32, v28, v10
	v_max_f32_e32 v34, 0, v13
	v_mfma_f32_16x16x32_bf16 v[10:13], v[2:5], v[24:27], v[20:23]
	s_nop 2
	ds_read_b128 v[20:23], v179
	s_waitcnt lgkmcnt(1)
	v_mfma_f32_16x16x32_bf16 v[14:17], v[6:9], v[14:17], 0
	s_nop 1
	v_max_f32_e32 v24, 0, v10
	v_max_f32_e32 v25, 0, v11
	v_max_f32_e32 v10, 0, v12
	v_mul_f32_e32 v26, v29, v10
	v_max_f32_e32 v35, 0, v13
	s_waitcnt lgkmcnt(0)
	v_mfma_f32_16x16x32_bf16 v[10:13], v[2:5], v[20:23], v[14:17]
	ds_read_b128 v[20:23], v159
	v_pk_mul_f32 v[34:35], v[28:29], v[34:35]
	s_nop 0
	ds_read_b128 v[14:17], v176
	s_waitcnt lgkmcnt(0)
	v_mfma_f32_16x16x32_bf16 v[14:17], v[6:9], v[14:17], 0
	s_nop 1
	v_max_f32_e32 v38, 0, v10
	v_max_f32_e32 v39, 0, v11
	v_max_f32_e32 v10, 0, v12
	v_mul_f32_e32 v40, v36, v10
	s_nop 0
	v_max_f32_e32 v42, 0, v13
	v_mfma_f32_16x16x32_bf16 v[10:13], v[2:5], v[20:23], v[14:17]
	ds_read_b128 v[20:23], v157
	v_mov_b32_e32 v33, v34
	v_mov_b32_e32 v27, v35
	ds_read_b128 v[14:17], v158
	s_waitcnt lgkmcnt(0)
	v_mfma_f32_16x16x32_bf16 v[14:17], v[6:9], v[14:17], 0
	s_nop 1
	v_max_f32_e32 v44, 0, v10
	v_max_f32_e32 v45, 0, v11
	v_max_f32_e32 v10, 0, v12
	v_mul_f32_e32 v46, v37, v10
	s_nop 0
	v_max_f32_e32 v43, 0, v13
	v_mfma_f32_16x16x32_bf16 v[10:13], v[2:5], v[20:23], v[14:17]
	ds_read_b128 v[20:23], v155
	v_pk_mul_f32 v[42:43], v[36:37], v[42:43]
	s_nop 0
	ds_read_b128 v[14:17], v156
	s_waitcnt lgkmcnt(0)
	v_mfma_f32_16x16x32_bf16 v[14:17], v[6:9], v[14:17], 0
	s_nop 1
	v_max_f32_e32 v50, 0, v10
	v_max_f32_e32 v51, 0, v11
	v_max_f32_e32 v10, 0, v12
	v_mul_f32_e32 v52, v48, v10
	s_nop 0
	v_max_f32_e32 v160, 0, v13
	v_mfma_f32_16x16x32_bf16 v[10:13], v[2:5], v[20:23], v[14:17]
	ds_read_b128 v[20:23], v153
	v_mov_b32_e32 v41, v42
	v_mov_b32_e32 v47, v43
	ds_read_b128 v[14:17], v154
	s_waitcnt lgkmcnt(0)
	v_mfma_f32_16x16x32_bf16 v[14:17], v[6:9], v[14:17], 0
	s_nop 1
	v_max_f32_e32 v162, 0, v10
	v_max_f32_e32 v163, 0, v11
	v_max_f32_e32 v10, 0, v12
	v_mul_f32_e32 v164, v49, v10
	s_nop 0
	v_max_f32_e32 v161, 0, v13
	v_mfma_f32_16x16x32_bf16 v[10:13], v[2:5], v[20:23], v[14:17]
	ds_read_b128 v[20:23], v150
	v_pk_mul_f32 v[160:161], v[48:49], v[160:161]
	s_nop 0
	ds_read_b128 v[14:17], v152
	s_waitcnt lgkmcnt(0)
; #define LAS __attribute__((address_space(3)))
; __device__ __forceinline__ unsigned fkey(float f) { const unsigned u = __float_as_uint(f); return (u & 0x80000000u) ? ~u : (u | 0x80000000u); }
; #define SEL_HADD(idx_) __hip_atomic_fetch_add(&hist[(idx_)], 1u, __ATOMIC_RELAXED, __HIP_MEMORY_SCOPE_WORKGROUP)
; __device__ __forceinline__ void sel_unit(LAS char* lds, int b, int u, const bf16_t* QI, const bf16_t* KIDX, const float* WIDX, unsigned long long* MASK) {
;     ...
;                 for (int ks = 0; ks < 2; ++ks) kf[kb][ks] = *(const bf16x8*)(KIDX + (rowbase + 64 * t + 32 * kh + 16 * kb + q16) * 64 + 32 * ks + 8 * kg);
; #pragma unroll
;             for (int kb = 0; kb < 2; ++kb) {
;                 f32x4 s = (f32x4){0.f, 0.f, 0.f, 0.f};
; #pragma unroll
;                 for (int hh = 0; hh < 8; ++hh) {
;                     f32x4 a = (f32x4){0.f, 0.f, 0.f, 0.f};
; #pragma unroll
;                     for (int ks = 0; ks < 2; ++ks) {
;                         const bf16x8 qv = *(const LAS bf16x8*)(lds + L_QI + q16 * 1024 + (((hh * 8 + 4 * ks + kg) ^ q16) << 4));
;                         a = __builtin_amdgcn_mfma_f32_16x16x32_bf16(kf[kb][ks], qv, a, 0, 0, 0);
;                     }
;                     const float wh = wl[hh * 16];
; #pragma unroll
;                     for (int i = 0; i < 4; ++i) s[i] += wh * fmaxf(a[i], 0.f);
;                 }
;                 u32x4 kk; kk.x = fkey(s[0]); kk.y = fkey(s[1]); kk.z = fkey(s[2]); kk.w = fkey(s[3]);
;                 sc[j][2 * kh + kb] = kk;
; #pragma unroll
;                 for (int i = 0; i < 4; ++i) SEL_HADD((kk[i] >> 24) * 16 + q16);
;                 __builtin_amdgcn_sched_barrier(0);
	v_mfma_f32_16x16x32_bf16 v[6:9], v[6:9], v[14:17], 0
	s_nop 1
	s_nop 0
	v_max_f32_e32 v14, 0, v13
	s_nop 0
	v_mfma_f32_16x16x32_bf16 v[2:5], v[2:5], v[20:23], v[6:9]
	s_nop 0
	v_max_f32_e32 v10, 0, v10
	v_max_f32_e32 v11, 0, v11
	v_pk_fma_f32 v[8:9], v[28:29], v[30:31], 0 op_sel_hi:[0,1,0]
	s_nop 0
	s_nop 2
	v_max_f32_e32 v15, 0, v5
	v_pk_mul_f32 v[6:7], v[166:167], v[14:15]
	v_mov_b32_e32 v14, v29
	v_pk_fma_f32 v[8:9], v[14:15], v[24:25], v[8:9] op_sel_hi:[0,1,1]
	v_pk_fma_f32 v[8:9], v[36:37], v[38:39], v[8:9] op_sel_hi:[0,1,1]
	v_mov_b32_e32 v14, v37
	v_pk_fma_f32 v[8:9], v[14:15], v[44:45], v[8:9] op_sel_hi:[0,1,1]
	v_pk_fma_f32 v[8:9], v[48:49], v[50:51], v[8:9] op_sel_hi:[0,1,1]
	v_mov_b32_e32 v14, v49
	v_pk_fma_f32 v[8:9], v[14:15], v[162:163], v[8:9] op_sel_hi:[0,1,1]
	v_max_f32_e32 v2, 0, v2
	v_max_f32_e32 v3, 0, v3
	v_pk_fma_f32 v[8:9], v[166:167], v[10:11], v[8:9] op_sel_hi:[0,1,1]
	v_mov_b32_e32 v10, v167
	v_pk_fma_f32 v[2:3], v[10:11], v[2:3], v[8:9] op_sel_hi:[0,1,1]
	v_and_b32_e32 v9, 0x7fffffff, v3
	v_and_b32_e32 v8, 0x7fffffff, v2
	v_xor_b32_e32 v5, -1, v3
	v_pk_add_f32 v[8:9], v[8:9], 0 neg_lo:[1,1] neg_hi:[1,1]
	v_cmp_gt_i32_e32 vcc, 0, v3
	v_xor_b32_e32 v10, -1, v2
	v_mov_b32_e32 v53, v160
	v_cndmask_b32_e32 v225, v9, v5, vcc
	v_cmp_gt_i32_e32 vcc, 0, v2
	v_pk_add_f32 v[2:3], v[32:33], 0 op_sel_hi:[1,0]
	v_max_f32_e32 v12, 0, v12
	v_pk_add_f32 v[2:3], v[2:3], v[26:27]
	v_pk_add_f32 v[2:3], v[2:3], v[40:41]
	v_mov_b32_e32 v165, v161
	v_pk_add_f32 v[2:3], v[2:3], v[46:47]
	v_mul_f32_e32 v12, v166, v12
	v_pk_add_f32 v[2:3], v[2:3], v[52:53]
	v_max_f32_e32 v4, 0, v4
	v_pk_add_f32 v[2:3], v[2:3], v[164:165]
	v_mov_b32_e32 v13, v6
	v_mul_f32_e32 v4, v167, v4
	v_pk_add_f32 v[2:3], v[2:3], v[12:13]
	v_mov_b32_e32 v5, v7
	v_pk_add_f32 v[2:3], v[2:3], v[4:5]
	v_cndmask_b32_e32 v226, v8, v10, vcc
	v_and_b32_e32 v5, 0x7fffffff, v3
	v_and_b32_e32 v4, 0x7fffffff, v2
	v_xor_b32_e32 v6, -1, v3
	v_pk_add_f32 v[4:5], v[4:5], 0 neg_lo:[1,1] neg_hi:[1,1]
	v_cmp_gt_i32_e32 vcc, 0, v3
	v_xor_b32_e32 v7, -1, v2
	s_nop 0
	v_cndmask_b32_e32 v227, v5, v6, vcc
	v_cmp_gt_i32_e32 vcc, 0, v2
	v_lshrrev_b32_e32 v2, 24, v226
	v_lshl_add_u32 v2, v2, 6, v0
	ds_add_u32 v2, v205 offset:16384
	v_lshrrev_b32_e32 v2, 24, v225
	v_cndmask_b32_e32 v228, v4, v7, vcc
	v_lshl_add_u32 v2, v2, 6, v0
	ds_add_u32 v2, v205 offset:16384
	v_lshrrev_b32_e32 v2, 24, v228
	v_lshl_add_u32 v2, v2, 6, v0
	ds_add_u32 v2, v205 offset:16384
	v_lshrrev_b32_e32 v2, 24, v227
	v_lshl_add_u32 v2, v2, 6, v0
	ds_add_u32 v2, v205 offset:16384
	v_add_co_u32_e32 v2, vcc, s96, v18
	s_nop 1
	v_addc_co_u32_e32 v3, vcc, 0, v19, vcc
	global_load_dwordx4 v[14:17], v[2:3], off
	global_load_dwordx4 v[10:13], v[2:3], off offset:64
	global_load_dwordx4 v[6:9], v[2:3], off offset:2048
	s_nop 0
	global_load_dwordx4 v[2:5], v[2:3], off offset:2112
	ds_read_b128 v[18:21], v229
	ds_read_b128 v[22:25], v230
	s_waitcnt vmcnt(3) lgkmcnt(1)
	v_mfma_f32_16x16x32_bf16 v[18:21], v[14:17], v[18:21], 0
	ds_read_b128 v[28:31], v184
	ds_read_b128 v[34:37], v179
	ds_read_b128 v[40:43], v159
	s_waitcnt vmcnt(2) lgkmcnt(3)
	v_mfma_f32_16x16x32_bf16 v[22:25], v[10:13], v[22:25], v[18:21]
	ds_read_b128 v[46:49], v157
	ds_read_b128 v[160:163], v155
	s_nop 0
	ds_read2_b32 v[20:21], v137 offset0:80 offset1:96
	s_nop 3
	v_max_f32_e32 v22, 0, v22
	v_max_f32_e32 v23, 0, v23
	v_max_f32_e32 v18, v24, v24
	v_max_f32_e32 v19, v25, v25
	ds_read_b128 v[24:27], v183
	s_waitcnt lgkmcnt(0)
	v_mfma_f32_16x16x32_bf16 v[24:27], v[14:17], v[24:27], 0
	v_max_f32_e32 v32, 0, v19
	v_max_f32_e32 v18, 0, v18
	v_mul_f32_e32 v18, v20, v18
	v_mfma_f32_16x16x32_bf16 v[24:27], v[10:13], v[28:31], v[24:27]
	s_nop 7
	v_max_f32_e32 v28, 0, v24
	v_max_f32_e32 v29, 0, v25
	v_max_f32_e32 v19, 0, v26
	v_mul_f32_e32 v24, v21, v19
	v_max_f32_e32 v33, 0, v27
	v_pk_mul_f32 v[26:27], v[20:21], v[32:33]
	ds_read_b128 v[30:33], v182
	s_waitcnt lgkmcnt(0)
	v_mfma_f32_16x16x32_bf16 v[30:33], v[14:17], v[30:33], 0
	v_mov_b32_e32 v25, v27
	v_mfma_f32_16x16x32_bf16 v[34:37], v[10:13], v[34:37], v[30:33]
	s_nop 5
	ds_read2_b32 v[32:33], v137 offset0:112 offset1:128
	s_nop 0
	v_max_f32_e32 v34, 0, v34
	v_max_f32_e32 v35, 0, v35
	v_max_f32_e32 v19, 0, v36
	s_waitcnt lgkmcnt(0)
	v_mul_f32_e32 v30, v32, v19
	v_max_f32_e32 v19, v37, v37
	ds_read_b128 v[36:39], v176
	s_waitcnt lgkmcnt(0)
	v_mfma_f32_16x16x32_bf16 v[36:39], v[14:17], v[36:39], 0
	v_max_f32_e32 v44, 0, v19
	v_mfma_f32_16x16x32_bf16 v[36:39], v[10:13], v[40:43], v[36:39]
	s_nop 7
	v_max_f32_e32 v40, 0, v36
	v_max_f32_e32 v41, 0, v37
	v_max_f32_e32 v19, 0, v38
	v_mul_f32_e32 v36, v33, v19
	v_max_f32_e32 v45, 0, v39
	v_pk_mul_f32 v[38:39], v[32:33], v[44:45]
	ds_read_b128 v[42:45], v158
	s_waitcnt lgkmcnt(0)
	v_mfma_f32_16x16x32_bf16 v[42:45], v[14:17], v[42:45], 0
	v_mov_b32_e32 v31, v38
	v_mov_b32_e32 v37, v39
	v_mfma_f32_16x16x32_bf16 v[46:49], v[10:13], v[46:49], v[42:45]
	s_nop 4
	ds_read2_b32 v[44:45], v137 offset0:144 offset1:160
	s_nop 1
	v_max_f32_e32 v46, 0, v46
	v_max_f32_e32 v47, 0, v47
	v_max_f32_e32 v19, 0, v48
	s_waitcnt lgkmcnt(0)
	v_mul_f32_e32 v42, v44, v19
	v_max_f32_e32 v19, v49, v49
	ds_read_b128 v[48:51], v156
	s_waitcnt lgkmcnt(0)
	v_mfma_f32_16x16x32_bf16 v[48:51], v[14:17], v[48:51], 0
	v_max_f32_e32 v164, 0, v19
	v_mfma_f32_16x16x32_bf16 v[48:51], v[10:13], v[160:163], v[48:51]
	ds_read_b128 v[160:163], v154
	s_nop 6
	v_max_f32_e32 v52, 0, v48
	v_max_f32_e32 v53, 0, v49
	v_max_f32_e32 v19, 0, v50
	v_mul_f32_e32 v48, v45, v19
	v_max_f32_e32 v165, 0, v51
	v_pk_mul_f32 v[50:51], v[44:45], v[164:165]
	ds_read_b128 v[164:167], v153
	s_waitcnt lgkmcnt(1)
; #define LAS __attribute__((address_space(3)))
; __device__ __forceinline__ unsigned fkey(float f) { const unsigned u = __float_as_uint(f); return (u & 0x80000000u) ? ~u : (u | 0x80000000u); }
; #define SEL_HADD(idx_) __hip_atomic_fetch_add(&hist[(idx_)], 1u, __ATOMIC_RELAXED, __HIP_MEMORY_SCOPE_WORKGROUP)
; __device__ __forceinline__ void sel_unit(LAS char* lds, int b, int u, const bf16_t* QI, const bf16_t* KIDX, const float* WIDX, unsigned long long* MASK) {
;     ...
;                 for (int ks = 0; ks < 2; ++ks) kf[kb][ks] = *(const bf16x8*)(KIDX + (rowbase + 64 * t + 32 * kh + 16 * kb + q16) * 64 + 32 * ks + 8 * kg);
; #pragma unroll
;             for (int kb = 0; kb < 2; ++kb) {
;                 f32x4 s = (f32x4){0.f, 0.f, 0.f, 0.f};
; #pragma unroll
;                 for (int hh = 0; hh < 8; ++hh) {
;                     f32x4 a = (f32x4){0.f, 0.f, 0.f, 0.f};
; #pragma unroll
;                     for (int ks = 0; ks < 2; ++ks) {
;                         const bf16x8 qv = *(const LAS bf16x8*)(lds + L_QI + q16 * 1024 + (((hh * 8 + 4 * ks + kg) ^ q16) << 4));
;                         a = __builtin_amdgcn_mfma_f32_16x16x32_bf16(kf[kb][ks], qv, a, 0, 0, 0);
;                     }
;                     const float wh = wl[hh * 16];
; #pragma unroll
;                     for (int i = 0; i < 4; ++i) s[i] += wh * fmaxf(a[i], 0.f);
;                 }
;                 u32x4 kk; kk.x = fkey(s[0]); kk.y = fkey(s[1]); kk.z = fkey(s[2]); kk.w = fkey(s[3]);
;                 sc[j][2 * kh + kb] = kk;
; #pragma unroll
;                 for (int i = 0; i < 4; ++i) SEL_HADD((kk[i] >> 24) * 16 + q16);
;                 __builtin_amdgcn_sched_barrier(0);
	v_mfma_f32_16x16x32_bf16 v[160:163], v[14:17], v[160:163], 0
	v_mov_b32_e32 v43, v50
	v_mov_b32_e32 v49, v51
	s_waitcnt lgkmcnt(0)
	v_mfma_f32_16x16x32_bf16 v[160:163], v[10:13], v[164:167], v[160:163]
	ds_read2_b32 v[164:165], v137 offset0:176 offset1:192
	s_nop 6
	v_max_f32_e32 v166, 0, v160
	v_max_f32_e32 v167, 0, v161
	v_max_f32_e32 v19, 0, v162
	s_waitcnt lgkmcnt(0)
	v_mul_f32_e32 v168, v164, v19
	v_max_f32_e32 v19, v163, v163
	ds_read_b128 v[160:163], v152
	s_waitcnt lgkmcnt(0)
	v_mfma_f32_16x16x32_bf16 v[14:17], v[14:17], v[160:163], 0
	ds_read_b128 v[160:163], v150
	v_max_f32_e32 v170, 0, v19
	s_waitcnt lgkmcnt(0)
	v_mfma_f32_16x16x32_bf16 v[10:13], v[10:13], v[160:163], v[14:17]
	s_nop 3
	v_fma_f32 v16, v20, v22, 0
	v_fma_f32 v17, v20, v23, 0
	v_mov_b32_e32 v20, v21
	v_pk_fma_f32 v[16:17], v[20:21], v[28:29], v[16:17] op_sel_hi:[0,1,1]
	v_pk_fma_f32 v[16:17], v[32:33], v[34:35], v[16:17] op_sel_hi:[0,1,1]
	v_mov_b32_e32 v20, v33
	v_pk_fma_f32 v[16:17], v[20:21], v[40:41], v[16:17] op_sel_hi:[0,1,1]
	v_pk_fma_f32 v[16:17], v[44:45], v[46:47], v[16:17] op_sel_hi:[0,1,1]
	v_mov_b32_e32 v20, v45
	v_pk_fma_f32 v[16:17], v[20:21], v[52:53], v[16:17] op_sel_hi:[0,1,1]
	v_max_f32_e32 v10, 0, v10
	v_max_f32_e32 v11, 0, v11
	v_pk_fma_f32 v[16:17], v[164:165], v[166:167], v[16:17] op_sel_hi:[0,1,1]
	v_mov_b32_e32 v20, v165
	v_pk_fma_f32 v[10:11], v[20:21], v[10:11], v[16:17] op_sel_hi:[0,1,1]
	v_and_b32_e32 v17, 0x7fffffff, v11
	v_and_b32_e32 v16, 0x7fffffff, v10
	v_xor_b32_e32 v19, -1, v10
	v_pk_add_f32 v[16:17], v[16:17], 0 neg_lo:[1,1] neg_hi:[1,1]
	v_cmp_gt_i32_e32 vcc, 0, v10
	v_max_f32_e32 v171, 0, v13
	v_xor_b32_e32 v13, -1, v11
	v_cmp_gt_i32_e64 s[2:3], 0, v11
	v_cndmask_b32_e32 v11, v16, v19, vcc
	v_mov_b32_e32 v19, v26
	v_cndmask_b32_e64 v10, v17, v13, s[2:3]
	v_pk_add_f32 v[16:17], v[18:19], 0 op_sel_hi:[1,0]
	v_pk_add_f32 v[16:17], v[16:17], v[24:25]
	v_pk_mul_f32 v[14:15], v[164:165], v[170:171]
	v_pk_add_f32 v[16:17], v[16:17], v[30:31]
	v_max_f32_e32 v12, 0, v12
	v_pk_add_f32 v[16:17], v[16:17], v[36:37]
	v_mov_b32_e32 v169, v14
	v_pk_add_f32 v[16:17], v[16:17], v[42:43]
	v_mul_f32_e32 v12, v165, v12
	v_pk_add_f32 v[16:17], v[16:17], v[48:49]
	v_mov_b32_e32 v13, v15
	v_pk_add_f32 v[16:17], v[16:17], v[168:169]
	s_nop 0
	v_pk_add_f32 v[12:13], v[16:17], v[12:13]
	s_nop 0
	v_and_b32_e32 v15, 0x7fffffff, v13
	v_and_b32_e32 v14, 0x7fffffff, v12
	v_xor_b32_e32 v17, -1, v12
	v_pk_add_f32 v[14:15], v[14:15], 0 neg_lo:[1,1] neg_hi:[1,1]
	v_cmp_gt_i32_e32 vcc, 0, v12
	v_xor_b32_e32 v16, -1, v13
	v_cmp_gt_i32_e64 s[2:3], 0, v13
	v_cndmask_b32_e32 v13, v14, v17, vcc
	v_lshrrev_b32_e32 v14, 24, v11
	v_lshl_add_u32 v14, v14, 6, v0
	ds_add_u32 v14, v205 offset:16384
	v_lshrrev_b32_e32 v14, 24, v10
	v_lshl_add_u32 v14, v14, 6, v0
	ds_add_u32 v14, v205 offset:16384
	v_lshrrev_b32_e32 v14, 24, v13
	v_cndmask_b32_e64 v12, v15, v16, s[2:3]
	v_lshl_add_u32 v14, v14, 6, v0
	ds_add_u32 v14, v205 offset:16384
	v_lshrrev_b32_e32 v14, 24, v12
	v_lshl_add_u32 v14, v14, 6, v0
	ds_add_u32 v14, v205 offset:16384
	ds_read_b128 v[14:17], v229
	ds_read_b128 v[18:21], v230
	ds_read_b128 v[22:25], v183
	ds_read_b128 v[26:29], v184
	ds_read2_b32 v[30:31], v137 offset0:80 offset1:96
	ds_read2_b32 v[38:39], v137 offset0:112 offset1:128
	s_waitcnt vmcnt(1) lgkmcnt(5)
	v_mfma_f32_16x16x32_bf16 v[14:17], v[6:9], v[14:17], 0
	ds_read2_b32 v[50:51], v137 offset0:144 offset1:160
	ds_read2_b32 v[162:163], v137 offset0:176 offset1:192
	s_waitcnt vmcnt(0) lgkmcnt(6)
	v_mfma_f32_16x16x32_bf16 v[14:17], v[2:5], v[18:21], v[14:17]
	ds_read_b128 v[18:21], v182
	s_waitcnt lgkmcnt(6)
	v_mfma_f32_16x16x32_bf16 v[22:25], v[6:9], v[22:25], 0
	s_nop 4
	v_max_f32_e32 v32, 0, v14
	v_max_f32_e32 v14, 0, v16
	v_max_f32_e32 v33, 0, v15
	s_waitcnt lgkmcnt(4)
	v_mul_f32_e32 v34, v30, v14
	v_max_f32_e32 v36, 0, v17
	v_mfma_f32_16x16x32_bf16 v[14:17], v[2:5], v[26:29], v[22:25]
	s_nop 2
	ds_read_b128 v[22:25], v179
	s_waitcnt lgkmcnt(1)
	v_mfma_f32_16x16x32_bf16 v[18:21], v[6:9], v[18:21], 0
	s_nop 1
	v_max_f32_e32 v26, 0, v14
	v_max_f32_e32 v27, 0, v15
	v_max_f32_e32 v14, 0, v16
	v_mul_f32_e32 v28, v31, v14
	v_max_f32_e32 v37, 0, v17
	s_waitcnt lgkmcnt(0)
; #define LAS __attribute__((address_space(3)))
; __device__ __forceinline__ unsigned fkey(float f) { const unsigned u = __float_as_uint(f); return (u & 0x80000000u) ? ~u : (u | 0x80000000u); }
; #define SEL_HADD(idx_) __hip_atomic_fetch_add(&hist[(idx_)], 1u, __ATOMIC_RELAXED, __HIP_MEMORY_SCOPE_WORKGROUP)
; __device__ __forceinline__ void sel_unit(LAS char* lds, int b, int u, const bf16_t* QI, const bf16_t* KIDX, const float* WIDX, unsigned long long* MASK) {
;     ...
;                 for (int ks = 0; ks < 2; ++ks) kf[kb][ks] = *(const bf16x8*)(KIDX + (rowbase + 64 * t + 32 * kh + 16 * kb + q16) * 64 + 32 * ks + 8 * kg);
; #pragma unroll
;             for (int kb = 0; kb < 2; ++kb) {
;                 f32x4 s = (f32x4){0.f, 0.f, 0.f, 0.f};
; #pragma unroll
;                 for (int hh = 0; hh < 8; ++hh) {
;                     f32x4 a = (f32x4){0.f, 0.f, 0.f, 0.f};
; #pragma unroll
;                     for (int ks = 0; ks < 2; ++ks) {
;                         const bf16x8 qv = *(const LAS bf16x8*)(lds + L_QI + q16 * 1024 + (((hh * 8 + 4 * ks + kg) ^ q16) << 4));
;                         a = __builtin_amdgcn_mfma_f32_16x16x32_bf16(kf[kb][ks], qv, a, 0, 0, 0);
;                     }
;                     const float wh = wl[hh * 16];
; #pragma unroll
;                     for (int i = 0; i < 4; ++i) s[i] += wh * fmaxf(a[i], 0.f);
;                 }
;                 u32x4 kk; kk.x = fkey(s[0]); kk.y = fkey(s[1]); kk.z = fkey(s[2]); kk.w = fkey(s[3]);
;                 sc[j][2 * kh + kb] = kk;
; #pragma unroll
;                 for (int i = 0; i < 4; ++i) SEL_HADD((kk[i] >> 24) * 16 + q16);
;                 __builtin_amdgcn_sched_barrier(0);
	v_mfma_f32_16x16x32_bf16 v[14:17], v[2:5], v[22:25], v[18:21]
	ds_read_b128 v[22:25], v159
	v_pk_mul_f32 v[36:37], v[30:31], v[36:37]
	s_nop 0
	ds_read_b128 v[18:21], v176
	s_waitcnt lgkmcnt(0)
	v_mfma_f32_16x16x32_bf16 v[18:21], v[6:9], v[18:21], 0
	s_nop 1
	v_max_f32_e32 v40, 0, v14
	v_max_f32_e32 v41, 0, v15
	v_max_f32_e32 v14, 0, v16
	v_mul_f32_e32 v42, v38, v14
	s_nop 0
	v_max_f32_e32 v44, 0, v17
	v_mfma_f32_16x16x32_bf16 v[14:17], v[2:5], v[22:25], v[18:21]
	ds_read_b128 v[22:25], v157
	v_mov_b32_e32 v35, v36
	v_mov_b32_e32 v29, v37
	ds_read_b128 v[18:21], v158
	s_waitcnt lgkmcnt(0)
	v_mfma_f32_16x16x32_bf16 v[18:21], v[6:9], v[18:21], 0
	s_nop 1
	v_max_f32_e32 v46, 0, v14
	v_max_f32_e32 v47, 0, v15
	v_max_f32_e32 v14, 0, v16
	v_mul_f32_e32 v48, v39, v14
	s_nop 0
	v_max_f32_e32 v45, 0, v17
	v_mfma_f32_16x16x32_bf16 v[14:17], v[2:5], v[22:25], v[18:21]
	ds_read_b128 v[22:25], v155
	v_pk_mul_f32 v[44:45], v[38:39], v[44:45]
	s_nop 0
	ds_read_b128 v[18:21], v156
	s_waitcnt lgkmcnt(0)
	v_mfma_f32_16x16x32_bf16 v[18:21], v[6:9], v[18:21], 0
	s_nop 1
	v_max_f32_e32 v52, 0, v14
	v_max_f32_e32 v53, 0, v15
	v_max_f32_e32 v14, 0, v16
	v_mul_f32_e32 v156, v50, v14
	s_nop 0
	v_max_f32_e32 v158, 0, v17
	v_mfma_f32_16x16x32_bf16 v[14:17], v[2:5], v[22:25], v[18:21]
	ds_read_b128 v[22:25], v153
	v_mov_b32_e32 v43, v44
	v_mov_b32_e32 v49, v45
	ds_read_b128 v[18:21], v154
	s_waitcnt lgkmcnt(0)
	v_mfma_f32_16x16x32_bf16 v[18:21], v[6:9], v[18:21], 0
	s_nop 1
	v_max_f32_e32 v160, 0, v14
	v_max_f32_e32 v161, 0, v15
	v_max_f32_e32 v14, 0, v16
	v_mul_f32_e32 v154, v51, v14
	s_nop 0
	v_max_f32_e32 v159, 0, v17
	v_mfma_f32_16x16x32_bf16 v[14:17], v[2:5], v[22:25], v[18:21]
	ds_read_b128 v[22:25], v150
	v_pk_mul_f32 v[158:159], v[50:51], v[158:159]
	s_nop 0
	ds_read_b128 v[18:21], v152
	s_waitcnt lgkmcnt(0)
	v_mfma_f32_16x16x32_bf16 v[6:9], v[6:9], v[18:21], 0
	s_nop 1
	s_nop 0
	v_max_f32_e32 v18, 0, v17
	s_nop 0
	v_mfma_f32_16x16x32_bf16 v[2:5], v[2:5], v[22:25], v[6:9]
	s_nop 0
	v_max_f32_e32 v14, 0, v14
	v_max_f32_e32 v15, 0, v15
	v_pk_fma_f32 v[8:9], v[30:31], v[32:33], 0 op_sel_hi:[0,1,0]
	s_nop 0
	s_nop 2
	v_max_f32_e32 v19, 0, v5
	v_pk_mul_f32 v[6:7], v[162:163], v[18:19]
	v_mov_b32_e32 v18, v31
	v_pk_fma_f32 v[8:9], v[18:19], v[26:27], v[8:9] op_sel_hi:[0,1,1]
	v_pk_fma_f32 v[8:9], v[38:39], v[40:41], v[8:9] op_sel_hi:[0,1,1]
	v_mov_b32_e32 v18, v39
	v_pk_fma_f32 v[8:9], v[18:19], v[46:47], v[8:9] op_sel_hi:[0,1,1]
	v_pk_fma_f32 v[8:9], v[50:51], v[52:53], v[8:9] op_sel_hi:[0,1,1]
	v_mov_b32_e32 v18, v51
	v_pk_fma_f32 v[8:9], v[18:19], v[160:161], v[8:9] op_sel_hi:[0,1,1]
	v_max_f32_e32 v2, 0, v2
	v_max_f32_e32 v3, 0, v3
	v_pk_fma_f32 v[8:9], v[162:163], v[14:15], v[8:9] op_sel_hi:[0,1,1]
	v_mov_b32_e32 v14, v163
	v_pk_fma_f32 v[2:3], v[14:15], v[2:3], v[8:9] op_sel_hi:[0,1,1]
	v_and_b32_e32 v9, 0x7fffffff, v3
	v_and_b32_e32 v8, 0x7fffffff, v2
	v_xor_b32_e32 v5, -1, v3
	v_pk_add_f32 v[8:9], v[8:9], 0 neg_lo:[1,1] neg_hi:[1,1]
	v_cmp_gt_i32_e32 vcc, 0, v3
	v_xor_b32_e32 v15, -1, v2
	v_mov_b32_e32 v157, v158
	v_cndmask_b32_e32 v14, v9, v5, vcc
	v_cmp_gt_i32_e32 vcc, 0, v2
	v_pk_add_f32 v[2:3], v[34:35], 0 op_sel_hi:[1,0]
	v_max_f32_e32 v16, 0, v16
	v_pk_add_f32 v[2:3], v[2:3], v[28:29]
	v_pk_add_f32 v[2:3], v[2:3], v[42:43]
	v_mov_b32_e32 v155, v159
	v_pk_add_f32 v[2:3], v[2:3], v[48:49]
	v_mul_f32_e32 v16, v162, v16
	v_pk_add_f32 v[2:3], v[2:3], v[156:157]
	v_max_f32_e32 v4, 0, v4
	v_pk_add_f32 v[2:3], v[2:3], v[154:155]
	v_mov_b32_e32 v17, v6
	v_mul_f32_e32 v4, v163, v4
	v_pk_add_f32 v[2:3], v[2:3], v[16:17]
	v_mov_b32_e32 v5, v7
	v_pk_add_f32 v[2:3], v[2:3], v[4:5]
	v_cndmask_b32_e32 v15, v8, v15, vcc
	v_and_b32_e32 v5, 0x7fffffff, v3
	v_and_b32_e32 v4, 0x7fffffff, v2
	v_xor_b32_e32 v6, -1, v3
	v_pk_add_f32 v[4:5], v[4:5], 0 neg_lo:[1,1] neg_hi:[1,1]
	v_cmp_gt_i32_e32 vcc, 0, v3
	v_xor_b32_e32 v7, -1, v2
	s_nop 0
	v_cndmask_b32_e32 v16, v5, v6, vcc
	v_cmp_gt_i32_e32 vcc, 0, v2
	v_lshrrev_b32_e32 v2, 24, v15
	v_lshl_add_u32 v2, v2, 6, v0
	ds_add_u32 v2, v205 offset:16384
	v_lshrrev_b32_e32 v2, 24, v14
	v_cndmask_b32_e32 v17, v4, v7, vcc
	v_lshl_add_u32 v2, v2, 6, v0
	ds_add_u32 v2, v205 offset:16384
	v_lshrrev_b32_e32 v2, 24, v17
	v_lshl_add_u32 v2, v2, 6, v0
	ds_add_u32 v2, v205 offset:16384
	v_lshrrev_b32_e32 v2, 24, v16
	v_lshl_add_u32 v2, v2, 6, v0
	ds_add_u32 v2, v205 offset:16384
